# v19 + in-proj epilogues (even and odd layer): 116 shuffle-xor 16/32 reductions by v_permlane16/32_swap instead of ds_bpermute where EXEC is full and the consumer is a symmetric add
# baseline (speedup 1.0000x reference)
; __device__ __forceinline__ bf16_t f2bf(float f) { return (bf16_t)(pk2(f, 0.f) & 0xffffu); }
; __device__ __forceinline__ float grp_sum(float v) { v += __shfl_xor(v, 16); v += __shfl_xor(v, 32); return v; }
;   __device__ __forceinline__ void operator()(const pg8::f32x4 (&acc)[2][2][4][2], const pg8::Unit& u, int wr, int wc, int fr, int fq) const {
;     ...
;       float rs[4];
; #pragma unroll
;       for (int m = 0; m < 4; ++m) { const f32x4 a = *(const f32x4*)(ssq + (unsigned)(row0 + ai * 128 + m * 16) * 16 + 4 * fq); rs[m] = (a[0] + a[1]) + (a[2] + a[3]); }
; #pragma unroll
;       for (int m = 0; m < 4; ++m) rs[m] = rsqrtf(grp_sum(rs[m]) * (1.f / 1024.f) + EPS);
;     ...
;           const int hv = (gi - 32) >> 1, eh = (gi - 32) & 1;
;           bf16_t* dst = vtb + ((unsigned)(bb * 4 + hv) * 128 + 64 * eh + 8 * fq) * S + pos;
; #pragma unroll
;           for (int bj = 0; bj < 2; ++bj)
; #pragma unroll
;             for (int e = 0; e < 8; ++e) dst[(unsigned)(32 * bj + e) * S] = f2bf(v[bj][e]);
.LBB0_385:
	s_lshl_b32 s7, s52, 8
	v_mov_b32 v157, 0
	v_and_b32_e32 v158, 64, v197
	v_add3_u32 v205, s7, v139, v157
	v_lshlrev_b32_e32 v136, 4, v205
	v_add_u32_e32 v200, 64, v158
	v_lshl_add_u64 v[158:159], v[136:137], 2, v[144:145]
	global_load_dwordx4 v[232:235], v[158:159], off
	global_load_dwordx4 v[236:239], v[158:159], off offset:1024
	global_load_dwordx4 v[240:243], v[158:159], off offset:2048
	global_load_dwordx4 v[158:161], v[158:159], off offset:3072
	v_xor_b32_e32 v156, 16, v197
	v_cmp_lt_i32_e32 vcc, v156, v200
	v_add_u32_e32 v157, v157, v139
	v_and_b32_e32 v206, 0x7f, v157
	v_cndmask_b32_e32 v156, v197, v156, vcc
	v_lshlrev_b32_e32 v201, 2, v156
	v_xor_b32_e32 v156, 32, v197
	v_cmp_lt_i32_e32 vcc, v156, v200
	s_lshl_b32 s6, s54, 2
	s_or_b32 s64, s6, s37
	v_cndmask_b32_e32 v156, v197, v156, vcc
	v_lshlrev_b32_e32 v202, 2, v156
	s_cmp_gt_i32 s64, 7
	s_cselect_b64 s[12:13], -1, 0
	s_cmp_gt_u32 s6, 15
	s_cselect_b64 s[82:83], -1, 0
	s_cmp_gt_u32 s6, 31
	s_cselect_b64 s[80:81], -1, 0
	s_lshl_b32 s76, s64, 6
	s_and_b32 s69, s76, 0x7ff80
	s_add_i32 s69, s69, s0
	s_cmp_gt_u32 s6, 23
	s_cselect_b64 s[78:79], -1, 0
	s_cmp_lt_u32 s6, 24
	s_cselect_b64 s[6:7], -1, 0
	s_and_b64 s[8:9], s[6:7], exec
	s_movk_i32 s8, 0x1ff0
	s_cselect_b32 s8, s8, 0x1fe8
	s_add_i32 s8, s8, s64
	s_lshl_b32 s59, s8, 13
	s_add_i32 s8, s64, -8
	v_cndmask_b32_e64 v204, 1.0, v199, s[6:7]
	v_lshl_or_b32 v203, s8, 13, v138
	v_lshl_or_b32 v156, s8, 6, v138
	s_mov_b64 s[10:11], -1
	s_waitcnt vmcnt(0)
	v_mov_b32_e32 v162, v233
	v_mov_b32_e32 v163, v234
	v_mov_b32_e32 v233, v235
	v_pk_add_f32 v[162:163], v[162:163], v[232:233]
	v_mov_b32_e32 v164, v237
	v_mov_b32_e32 v165, v238
	v_mov_b32_e32 v237, v239
	v_pk_add_f32 v[164:165], v[164:165], v[236:237]
	v_mov_b32_e32 v166, v241
	v_mov_b32_e32 v167, v242
	v_mov_b32_e32 v241, v243
	v_pk_add_f32 v[166:167], v[166:167], v[240:241]
	v_mov_b32_e32 v168, v159
	v_mov_b32_e32 v169, v160
	v_mov_b32_e32 v159, v161
	v_mov_b32_e32 v160, v164
	v_mov_b32_e32 v161, v162
	v_mov_b32_e32 v162, v165
	v_pk_add_f32 v[160:161], v[160:161], v[162:163]
	v_mov_b32_e32 v163, v161
	s_nop 1
	v_permlane16_swap_b32_e32 v161, v163
	v_mov_b32_e32 v162, v160
	s_nop 1
	v_permlane16_swap_b32_e32 v160, v162
	v_pk_add_f32 v[158:159], v[168:169], v[158:159]
	s_waitcnt lgkmcnt(0)
	v_pk_add_f32 v[160:161], v[160:161], v[162:163]
	v_mov_b32_e32 v163, v161
	s_nop 1
	v_permlane32_swap_b32_e32 v161, v163
	v_mov_b32_e32 v162, v160
	s_nop 1
	v_permlane32_swap_b32_e32 v160, v162
	s_waitcnt lgkmcnt(0)
	v_pk_add_f32 v[160:161], v[160:161], v[162:163]
	s_nop 0
	v_pk_fma_f32 v[162:163], v[160:161], s[66:67], v[154:155] op_sel_hi:[1,0,0]
	v_mov_b32_e32 v161, v166
	v_mul_f32_e32 v157, 0x4b800000, v163
	v_cmp_gt_f32_e32 vcc, s3, v163
	v_mov_b32_e32 v166, v159
	v_cmp_gt_f32_e64 s[8:9], s3, v162
	v_cndmask_b32_e32 v157, v163, v157, vcc
	v_rsq_f32_e32 v157, v157
	s_nop 0
	v_mul_f32_e32 v160, 0x45800000, v157
	v_cndmask_b32_e32 v168, v157, v160, vcc
	v_mov_b32_e32 v160, v158
	v_pk_add_f32 v[158:159], v[160:161], v[166:167]
	v_mov_b32_e32 v161, v159
	s_nop 1
	v_permlane16_swap_b32_e32 v159, v161
	v_mov_b32_e32 v160, v158
	s_nop 1
	v_permlane16_swap_b32_e32 v158, v160
	v_pk_mul_f32 v[164:165], v[124:125], v[168:169] op_sel_hi:[1,0]
	v_pk_mul_f32 v[126:127], v[126:127], v[168:169] op_sel_hi:[1,0]
	v_pk_mul_f32 v[124:125], v[120:121], v[168:169] op_sel_hi:[1,0]
	v_pk_mul_f32 v[122:123], v[122:123], v[168:169] op_sel_hi:[1,0]
	s_waitcnt lgkmcnt(0)
	v_pk_add_f32 v[158:159], v[158:159], v[160:161]
	ds_bpermute_b32 v161, v202, v159
	ds_bpermute_b32 v160, v202, v158
	v_pk_mul_f32 v[120:121], v[116:117], v[168:169] op_sel_hi:[1,0]
	v_pk_mul_f32 v[118:119], v[118:119], v[168:169] op_sel_hi:[1,0]
	v_pk_mul_f32 v[116:117], v[112:113], v[168:169] op_sel_hi:[1,0]
	v_pk_mul_f32 v[114:115], v[114:115], v[168:169] op_sel_hi:[1,0]
	s_and_b64 vcc, exec, s[12:13]
	s_cbranch_vccz .LBB0_396
	s_and_b64 vcc, exec, s[82:83]
	s_cbranch_vccz .LBB0_393
	v_ashrrev_i32_e32 v157, 13, v205
	v_and_b32_e32 v163, 0x1fff, v205
	s_and_b64 vcc, exec, s[80:81]
	s_cbranch_vccz .LBB0_389
	s_lshl_b32 s10, s69, 13
	v_lshl_add_u32 v112, v157, 22, s10
	v_or_b32_e32 v112, v112, v180
	v_mov_b32_e32 v113, v137
	v_lshl_add_u64 v[112:113], v[112:113], 1, s[48:49]
	v_lshlrev_b32_e32 v166, 1, v163
	v_mov_b32_e32 v167, v137
	v_lshl_add_u64 v[112:113], v[112:113], 0, v[166:167]
	v_cvt_pk_bf16_f32 v166, v164, s0
	global_store_short v[112:113], v166, off
	v_add_co_u32_e32 v166, vcc, 0x4000, v112
	v_cvt_pk_bf16_f32 v168, v165, s0
	s_nop 0
	v_addc_co_u32_e32 v167, vcc, 0, v113, vcc
	global_store_short v[166:167], v168, off
	v_add_co_u32_e32 v166, vcc, 0x8000, v112
	v_cvt_pk_bf16_f32 v168, v126, s0
	s_nop 0
	v_addc_co_u32_e32 v167, vcc, 0, v113, vcc
	global_store_short v[166:167], v168, off
	v_add_co_u32_e32 v166, vcc, 0xc000, v112
	v_cvt_pk_bf16_f32 v168, v127, s0
	s_nop 0
	v_addc_co_u32_e32 v167, vcc, 0, v113, vcc
	s_mov_b32 s10, 0x10000
	global_store_short v[166:167], v168, off
	v_add_co_u32_e32 v166, vcc, s10, v112
	v_cvt_pk_bf16_f32 v168, v124, s0
	s_nop 0
	v_addc_co_u32_e32 v167, vcc, 0, v113, vcc
	s_mov_b32 s10, 0x14000
	global_store_short v[166:167], v168, off
	v_add_co_u32_e32 v166, vcc, s10, v112
	v_cvt_pk_bf16_f32 v168, v125, s0
	s_nop 0
	v_addc_co_u32_e32 v167, vcc, 0, v113, vcc
	s_mov_b32 s10, 0x18000
	global_store_short v[166:167], v168, off
	v_add_co_u32_e32 v166, vcc, s10, v112
	v_cvt_pk_bf16_f32 v168, v122, s0
	s_nop 0
	v_addc_co_u32_e32 v167, vcc, 0, v113, vcc
	s_mov_b32 s10, 0x1c000
	global_store_short v[166:167], v168, off
	v_add_co_u32_e32 v166, vcc, s10, v112
	v_cvt_pk_bf16_f32 v168, v123, s0
	s_nop 0
; __device__ __forceinline__ bf16_t f2bf(float f) { return (bf16_t)(pk2(f, 0.f) & 0xffffu); }
;   __device__ __forceinline__ void operator()(const pg8::f32x4 (&acc)[2][2][4][2], const pg8::Unit& u, int wr, int wc, int fr, int fq) const {
;     ...
;           const int hv = (gi - 32) >> 1, eh = (gi - 32) & 1;
;           bf16_t* dst = vtb + ((unsigned)(bb * 4 + hv) * 128 + 64 * eh + 8 * fq) * S + pos;
; #pragma unroll
;           for (int bj = 0; bj < 2; ++bj)
; #pragma unroll
;             for (int e = 0; e < 8; ++e) dst[(unsigned)(32 * bj + e) * S] = f2bf(v[bj][e]);
	v_addc_co_u32_e32 v167, vcc, 0, v113, vcc
	s_mov_b32 s10, 0x80000
	global_store_short v[166:167], v168, off
	v_add_co_u32_e32 v166, vcc, s10, v112
	v_cvt_pk_bf16_f32 v168, v120, s0
	s_nop 0
	v_addc_co_u32_e32 v167, vcc, 0, v113, vcc
	s_mov_b32 s10, 0x84000
	global_store_short v[166:167], v168, off
	v_add_co_u32_e32 v166, vcc, s10, v112
	v_cvt_pk_bf16_f32 v168, v121, s0
	s_nop 0
	v_addc_co_u32_e32 v167, vcc, 0, v113, vcc
	s_mov_b32 s10, 0x88000
	global_store_short v[166:167], v168, off
	v_add_co_u32_e32 v166, vcc, s10, v112
	v_cvt_pk_bf16_f32 v168, v118, s0
	s_nop 0
	v_addc_co_u32_e32 v167, vcc, 0, v113, vcc
	s_mov_b32 s10, 0x8c000
	global_store_short v[166:167], v168, off
	v_add_co_u32_e32 v166, vcc, s10, v112
	v_cvt_pk_bf16_f32 v168, v119, s0
	s_nop 0
	v_addc_co_u32_e32 v167, vcc, 0, v113, vcc
	s_mov_b32 s10, 0x90000
	global_store_short v[166:167], v168, off
	v_add_co_u32_e32 v166, vcc, s10, v112
	v_cvt_pk_bf16_f32 v168, v116, s0
	s_nop 0
	v_addc_co_u32_e32 v167, vcc, 0, v113, vcc
	s_mov_b32 s10, 0x94000
	global_store_short v[166:167], v168, off
	v_add_co_u32_e32 v166, vcc, s10, v112
	v_cvt_pk_bf16_f32 v168, v117, s0
	s_nop 0
	v_addc_co_u32_e32 v167, vcc, 0, v113, vcc
	global_store_short v[166:167], v168, off
	v_add_co_u32_e32 v166, vcc, 0x98000, v112
	v_cvt_pk_bf16_f32 v168, v114, s0
	s_nop 0
	v_addc_co_u32_e32 v167, vcc, 0, v113, vcc
	v_add_co_u32_e32 v112, vcc, 0x9c000, v112
	global_store_short v[166:167], v168, off
	v_cvt_pk_bf16_f32 v166, v115, s0
	v_addc_co_u32_e32 v113, vcc, 0, v113, vcc
	global_store_short v[112:113], v166, off
	s_mov_b64 s[10:11], 0
; __device__ __forceinline__ float grp_sum(float v) { v += __shfl_xor(v, 16); v += __shfl_xor(v, 32); return v; }
; __device__ __forceinline__ void st8_bf16(bf16_t* dst, const float (&v)[8]) { u32x4 w; w.x = pk2(v[0], v[1]); w.y = pk2(v[2], v[3]); w.z = pk2(v[4], v[5]); w.w = pk2(v[6], v[7]); *(u32x4*)dst = w; }
;   __device__ __forceinline__ void operator()(const pg8::f32x4 (&acc)[2][2][4][2], const pg8::Unit& u, int wr, int wc, int fr, int fq) const {
;     ...
;           const bool isq = gi < 24; const int hm = isq ? gi - 16 : gi - 24;
;           const float* gn = isq ? q_norm : k_norm;
;           float ss = 0.f;
; #pragma unroll
;           for (int bj = 0; bj < 2; ++bj)
; #pragma unroll
;             for (int e = 0; e < 8; ++e) ss += v[bj][e] * v[bj][e];
;           const float rn = rsqrtf(grp_sum(ss) * (1.f / 64.f) + EPS) * (isq ? 0.125f * LOG2E : 1.f);
;           const f32x4 c0 = *(const f32x4*)(cos64 + (unsigned)pos * 32 + 8 * fq), c1 = *(const f32x4*)(cos64 + (unsigned)pos * 32 + 8 * fq + 4);
;           const f32x4 s0 = *(const f32x4*)(sin64 + (unsigned)pos * 32 + 8 * fq), s1 = *(const f32x4*)(sin64 + (unsigned)pos * 32 + 8 * fq + 4);
;           float kk = 0.f;
; #pragma unroll
;           for (int e = 0; e < 8; ++e) {
;             const float x1 = v[0][e] * rn * gn[8 * fq + e], x2 = v[1][e] * rn * gn[32 + 8 * fq + e];
;             const float cc = e < 4 ? c0[e & 3] : c1[e & 3], sn = e < 4 ? s0[e & 3] : s1[e & 3];
;             v[0][e] = x1 * cc - x2 * sn; v[1][e] = x1 * sn + x2 * cc;
;             kk += v[0][e] * v[0][e] + v[1][e] * v[1][e];
;           }
;           bf16_t* dst = (isq ? qb : kb) + ((unsigned)(bb * 8 + hm) * S + pos) * 64 + 8 * fq;
;           st8_bf16(dst, v[0]); st8_bf16(dst + 32, v[1]);
;           if (!isq) kmx_run = fmaxf(kmx_run, grp_sum(kk));
.LBB0_389:
	s_andn2_b64 vcc, exec, s[10:11]
	v_mov_b32_e32 v207, 0
	s_cbranch_vccnz .LBB0_392
	v_pk_mul_f32 v[112:113], v[164:165], v[164:165]
	v_pk_mul_f32 v[166:167], v[126:127], v[126:127]
	v_add_f32_e32 v112, v112, v113
	v_add_f32_e32 v112, v166, v112
	v_pk_mul_f32 v[168:169], v[124:125], v[124:125]
	v_add_f32_e32 v112, v167, v112
	v_add_f32_e32 v112, v168, v112
	v_pk_mul_f32 v[170:171], v[122:123], v[122:123]
	v_add_f32_e32 v112, v169, v112
	v_add_f32_e32 v112, v170, v112
	v_pk_mul_f32 v[172:173], v[120:121], v[120:121]
	v_add_f32_e32 v112, v171, v112
	v_add_f32_e32 v112, v172, v112
	v_pk_mul_f32 v[174:175], v[118:119], v[118:119]
	v_add_f32_e32 v112, v173, v112
	v_add_f32_e32 v112, v174, v112
	v_pk_mul_f32 v[176:177], v[116:117], v[116:117]
	v_add_f32_e32 v112, v175, v112
	v_add_f32_e32 v112, v176, v112
	v_pk_mul_f32 v[178:179], v[114:115], v[114:115]
	v_add_f32_e32 v112, v177, v112
	v_add_f32_e32 v112, v178, v112
	v_add_f32_e32 v112, v179, v112
	v_mov_b32_e32 v113, v112
	s_nop 1
	v_permlane16_swap_b32_e32 v112, v113
	s_and_b64 s[10:11], s[6:7], exec
	s_cselect_b32 s11, s17, s19
	s_cselect_b32 s10, s16, s18
	v_lshlrev_b32_e32 v207, 2, v138
	s_waitcnt lgkmcnt(0)
	v_add_f32_e32 v112, v112, v113
	v_mov_b32_e32 v113, v112
	s_nop 1
	v_permlane32_swap_b32_e32 v112, v113
	v_lshl_add_u32 v157, v157, 16, s59
	v_or_b32_e32 v157, v157, v163
	s_waitcnt lgkmcnt(0)
	v_add_f32_e32 v112, v112, v113
	v_fmamk_f32 v112, v112, 0x3c800000, v154
	v_cmp_gt_f32_e32 vcc, s3, v112
	v_mul_f32_e32 v113, 0x4b800000, v112
	s_nop 0
	v_cndmask_b32_e32 v112, v112, v113, vcc
	v_rsq_f32_e32 v112, v112
	s_nop 0
	v_mul_f32_e32 v113, 0x45800000, v112
	v_cndmask_b32_e32 v112, v112, v113, vcc
	v_mul_f32_e32 v224, v204, v112
	v_lshlrev_b32_e32 v112, 7, v163
	v_mov_b32_e32 v113, v137
	v_lshl_add_u64 v[166:167], v[140:141], 0, v[112:113]
	v_lshl_add_u64 v[112:113], v[142:143], 0, v[112:113]
	global_load_dwordx4 v[176:179], v[166:167], off offset:16
	global_load_dwordx4 v[168:171], v[166:167], off
	global_load_dwordx4 v[208:211], v[112:113], off offset:16
	global_load_dwordx4 v[172:175], v[112:113], off
	global_load_dwordx4 v[212:215], v207, s[10:11] offset:16
	global_load_dwordx4 v[216:219], v207, s[10:11]
	global_load_dwordx4 v[220:223], v207, s[10:11] offset:144
	global_load_dwordx4 v[228:231], v207, s[10:11] offset:128
	v_pk_mul_f32 v[112:113], v[164:165], v[224:225] op_sel_hi:[1,0]
	s_cselect_b32 s10, s87, s89
	s_cselect_b32 s11, s86, s88
	v_mov_b32_e32 v207, 0
	s_andn2_b64 vcc, exec, s[78:79]
	s_waitcnt vmcnt(2)
	v_pk_mul_f32 v[166:167], v[216:217], v[112:113]
	v_pk_mul_f32 v[112:113], v[120:121], v[224:225] op_sel_hi:[1,0]
	s_waitcnt vmcnt(0)
	v_pk_mul_f32 v[216:217], v[228:229], v[112:113]
	s_nop 0
	v_pk_mul_f32 v[112:113], v[172:173], v[216:217]
	s_nop 0
	v_pk_fma_f32 v[112:113], v[168:169], v[166:167], v[112:113] neg_lo:[0,0,1] neg_hi:[0,0,1]
	v_pk_mul_f32 v[166:167], v[172:173], v[166:167]
	s_nop 0
	v_pk_fma_f32 v[166:167], v[168:169], v[216:217], v[166:167]
	v_pk_mul_f32 v[168:169], v[126:127], v[224:225] op_sel_hi:[1,0]
	s_nop 0
	v_pk_mul_f32 v[172:173], v[168:169], v[218:219]
	v_pk_mul_f32 v[168:169], v[118:119], v[224:225] op_sel_hi:[1,0]
	s_nop 0
	v_pk_mul_f32 v[216:217], v[168:169], v[230:231]
	s_nop 0
	v_pk_mul_f32 v[168:169], v[174:175], v[216:217]
	s_nop 0
	v_pk_fma_f32 v[168:169], v[170:171], v[172:173], v[168:169] neg_lo:[0,0,1] neg_hi:[0,0,1]
	v_pk_mul_f32 v[170:171], v[170:171], v[216:217]
	s_nop 0
	v_pk_fma_f32 v[170:171], v[174:175], v[172:173], v[170:171]
	v_pk_mul_f32 v[172:173], v[124:125], v[224:225] op_sel_hi:[1,0]
	s_nop 0
	v_pk_mul_f32 v[174:175], v[172:173], v[212:213]
	v_pk_mul_f32 v[172:173], v[116:117], v[224:225] op_sel_hi:[1,0]
	s_nop 0
	v_pk_mul_f32 v[212:213], v[172:173], v[220:221]
	s_nop 0
	v_pk_mul_f32 v[172:173], v[208:209], v[212:213]
	s_nop 0
	v_pk_fma_f32 v[172:173], v[176:177], v[174:175], v[172:173] neg_lo:[0,0,1] neg_hi:[0,0,1]
	v_pk_mul_f32 v[176:177], v[176:177], v[212:213]
	s_nop 0
	v_pk_fma_f32 v[174:175], v[208:209], v[174:175], v[176:177]
	v_pk_mul_f32 v[176:177], v[122:123], v[224:225] op_sel_hi:[1,0]
	s_nop 0
	v_pk_mul_f32 v[208:209], v[176:177], v[214:215]
	v_pk_mul_f32 v[176:177], v[114:115], v[224:225] op_sel_hi:[1,0]
	s_nop 0
	v_pk_mul_f32 v[212:213], v[176:177], v[222:223]
	s_nop 0
	v_pk_mul_f32 v[176:177], v[210:211], v[212:213]
	s_nop 0
	v_pk_fma_f32 v[176:177], v[178:179], v[208:209], v[176:177] neg_lo:[0,0,1] neg_hi:[0,0,1]
	v_pk_mul_f32 v[178:179], v[178:179], v[212:213]
	s_nop 0
	v_pk_fma_f32 v[178:179], v[210:211], v[208:209], v[178:179]
	v_mov_b32_e32 v208, s11
	v_mov_b32_e32 v209, s10
	v_lshlrev_b32_e32 v210, 6, v157
	v_mov_b32_e32 v211, v137
	v_lshl_add_u64 v[208:209], v[210:211], 1, v[208:209]
	v_lshlrev_b32_e32 v210, 1, v138
	v_lshl_add_u64 v[212:213], v[208:209], 0, v[210:211]
	v_cvt_pk_bf16_f32 v208, v112, v113
	v_cvt_pk_bf16_f32 v209, v168, v169
	v_cvt_pk_bf16_f32 v210, v172, v173
	v_cvt_pk_bf16_f32 v211, v176, v177
	global_store_dwordx4 v[212:213], v[208:211], off
	s_nop 1
	v_cvt_pk_bf16_f32 v208, v166, v167
	v_cvt_pk_bf16_f32 v209, v170, v171
	v_cvt_pk_bf16_f32 v210, v174, v175
	v_cvt_pk_bf16_f32 v211, v178, v179
	global_store_dwordx4 v[212:213], v[208:211], off offset:64
	s_cbranch_vccnz .LBB0_392
	v_pk_mul_f32 v[166:167], v[166:167], v[166:167]
	s_nop 0
	v_pk_fma_f32 v[112:113], v[112:113], v[112:113], v[166:167]
	v_pk_mul_f32 v[166:167], v[170:171], v[170:171]
	v_add_f32_e32 v112, v112, v113
	v_pk_fma_f32 v[166:167], v[168:169], v[168:169], v[166:167]
	v_pk_mul_f32 v[168:169], v[174:175], v[174:175]
	v_add_f32_e32 v112, v166, v112
	v_pk_fma_f32 v[168:169], v[172:173], v[172:173], v[168:169]
	v_add_f32_e32 v112, v167, v112
	v_pk_mul_f32 v[170:171], v[178:179], v[178:179]
	v_add_f32_e32 v112, v112, v168
	v_pk_fma_f32 v[170:171], v[176:177], v[176:177], v[170:171]
	v_add_f32_e32 v112, v112, v169
	v_add_f32_e32 v112, v112, v170
	v_add_f32_e32 v112, v112, v171
	v_mov_b32_e32 v113, v112
	s_nop 1
	v_permlane16_swap_b32_e32 v112, v113
	s_waitcnt lgkmcnt(0)
	v_add_f32_e32 v112, v112, v113
	v_mov_b32_e32 v113, v112
	s_nop 1
	v_permlane32_swap_b32_e32 v112, v113
	s_waitcnt lgkmcnt(0)
	v_add_f32_e32 v112, v112, v113
	v_max_f32_e32 v207, 0, v112

; __device__ __forceinline__ float gelu_tanh(float x) { const float y = 0.7978845608028654f * (x + 0.044715f * x * x * x); return x * sigm(2.f * y); }
; __device__ __forceinline__ float grp_sum(float v) { v += __shfl_xor(v, 16); v += __shfl_xor(v, 32); return v; }
;   __device__ __forceinline__ void operator()(const pg8::f32x4 (&acc)[2][2][4][2], const pg8::Unit& u, int wr, int wc, int fr, int fq) const {
;     ...
;           const int g = gi - 8; float ss = 0.f;
; #pragma unroll
;           for (int bj = 0; bj < 2; ++bj)
; #pragma unroll
;             for (int e = 0; e < 8; ++e) { v[bj][e] = gelu_tanh(v[bj][e]); ss += v[bj][e] * v[bj][e]; }
;           const float rn = rsqrtf(grp_sum(ss) * (1.f / 64.f) + EPS);
.LBB0_393:
	s_andn2_b64 vcc, exec, s[10:11]
	s_cbranch_vccnz .LBB0_395
	v_mul_f32_e32 v112, 0x3d372713, v164
	v_mul_f32_e32 v112, v164, v112
	v_fma_f32 v112, v164, v112, v164
	v_mul_f32_e32 v112, 0x3f4c422a, v112
	v_add_f32_e32 v112, v112, v112
	v_mul_f32_e32 v112, 0xbfb8aa3b, v112
	v_exp_f32_e32 v112, v112
	v_mul_f32_e32 v113, 0x3d372713, v121
	v_mul_f32_e32 v113, v121, v113
	v_fma_f32 v113, v121, v113, v121
	v_add_f32_e32 v112, 1.0, v112
	v_rcp_f32_e32 v112, v112
	v_mul_f32_e32 v113, 0x3f4c422a, v113
	v_add_f32_e32 v113, v113, v113
	v_mul_f32_e32 v113, 0xbfb8aa3b, v113
	v_mul_f32_e32 v157, v164, v112
	v_mul_f32_e32 v112, 0x3d372713, v165
	v_mul_f32_e32 v112, v165, v112
	v_fma_f32 v112, v165, v112, v165
	v_mul_f32_e32 v112, 0x3f4c422a, v112
	v_add_f32_e32 v112, v112, v112
	v_mul_f32_e32 v112, 0xbfb8aa3b, v112
	v_exp_f32_e32 v112, v112
	v_exp_f32_e32 v113, v113
	v_lshlrev_b32_e32 v208, 1, v206
	v_mov_b32_e32 v209, v137
	v_add_f32_e32 v112, 1.0, v112
	v_rcp_f32_e32 v112, v112
	v_add_f32_e32 v113, 1.0, v113
	v_rcp_f32_e32 v113, v113
	v_mul_f32_e32 v163, v165, v112
	v_mul_f32_e32 v112, 0x3d372713, v126
	v_mul_f32_e32 v112, v126, v112
	v_fma_f32 v112, v126, v112, v126
	v_mul_f32_e32 v112, 0x3f4c422a, v112
	v_add_f32_e32 v112, v112, v112
	v_mul_f32_e32 v112, 0xbfb8aa3b, v112
	v_exp_f32_e32 v112, v112
	v_mul_f32_e32 v168, v163, v163
	v_fmac_f32_e32 v168, v157, v157
	v_add_f32_e32 v112, 1.0, v112
	v_rcp_f32_e32 v112, v112
	s_nop 0
	v_mul_f32_e32 v174, v126, v112
	v_mul_f32_e32 v112, 0x3d372713, v127
	v_mul_f32_e32 v112, v127, v112
	v_fma_f32 v112, v127, v112, v127
	v_mul_f32_e32 v112, 0x3f4c422a, v112
	v_add_f32_e32 v112, v112, v112
	v_mul_f32_e32 v112, 0xbfb8aa3b, v112
	v_exp_f32_e32 v112, v112
	v_fmac_f32_e32 v168, v174, v174
	v_add_f32_e32 v112, 1.0, v112
	v_rcp_f32_e32 v112, v112
	s_nop 0
	v_mul_f32_e32 v175, v127, v112
	v_mul_f32_e32 v112, 0x3d372713, v124
	v_mul_f32_e32 v112, v124, v112
	v_fma_f32 v112, v124, v112, v124
	v_mul_f32_e32 v112, 0x3f4c422a, v112
	v_add_f32_e32 v112, v112, v112
	v_mul_f32_e32 v112, 0xbfb8aa3b, v112
	v_exp_f32_e32 v112, v112
	v_fmac_f32_e32 v168, v175, v175
	v_add_f32_e32 v112, 1.0, v112
	v_rcp_f32_e32 v112, v112
	s_nop 0
	v_mul_f32_e32 v176, v124, v112
	v_mul_f32_e32 v112, 0x3d372713, v125
	v_mul_f32_e32 v112, v125, v112
	v_fma_f32 v112, v125, v112, v125
	v_mul_f32_e32 v112, 0x3f4c422a, v112
	v_add_f32_e32 v112, v112, v112
	v_mul_f32_e32 v112, 0xbfb8aa3b, v112
	v_exp_f32_e32 v112, v112
	v_fmac_f32_e32 v168, v176, v176
	v_add_f32_e32 v112, 1.0, v112
	v_rcp_f32_e32 v112, v112
	s_nop 0
	v_mul_f32_e32 v177, v125, v112
	v_mul_f32_e32 v112, 0x3d372713, v122
	v_mul_f32_e32 v112, v122, v112
	v_fma_f32 v112, v122, v112, v122
	v_mul_f32_e32 v112, 0x3f4c422a, v112
	v_add_f32_e32 v112, v112, v112
	v_mul_f32_e32 v112, 0xbfb8aa3b, v112
	v_exp_f32_e32 v112, v112
	v_fmac_f32_e32 v168, v177, v177
	v_add_f32_e32 v112, 1.0, v112
	v_rcp_f32_e32 v112, v112
	s_nop 0
	v_mul_f32_e32 v178, v122, v112
	v_mul_f32_e32 v112, 0x3d372713, v123
	v_mul_f32_e32 v112, v123, v112
	v_fma_f32 v112, v123, v112, v123
	v_mul_f32_e32 v112, 0x3f4c422a, v112
	v_add_f32_e32 v112, v112, v112
	v_mul_f32_e32 v112, 0xbfb8aa3b, v112
	v_exp_f32_e32 v112, v112
	v_fmac_f32_e32 v168, v178, v178
	v_add_f32_e32 v112, 1.0, v112
	v_rcp_f32_e32 v112, v112
	s_nop 0
	v_mul_f32_e32 v179, v123, v112
	v_mul_f32_e32 v112, 0x3d372713, v120
	v_mul_f32_e32 v112, v120, v112
	v_fma_f32 v112, v120, v112, v120
	v_mul_f32_e32 v112, 0x3f4c422a, v112
	v_add_f32_e32 v112, v112, v112
	v_mul_f32_e32 v112, 0xbfb8aa3b, v112
	v_exp_f32_e32 v112, v112
	v_fmac_f32_e32 v168, v179, v179
	v_add_f32_e32 v112, 1.0, v112
	v_rcp_f32_e32 v112, v112
	s_nop 0
	v_pk_mul_f32 v[112:113], v[120:121], v[112:113]
	s_nop 0
	v_pk_mul_f32 v[166:167], v[112:113], v[112:113]
	s_nop 0
	v_add_f32_e32 v166, v166, v168
	v_add_f32_e32 v170, v167, v166
	v_mul_f32_e32 v166, 0x3d372713, v118
	v_mul_f32_e32 v167, 0x3d372713, v119
	v_mul_f32_e32 v166, v118, v166
	v_mul_f32_e32 v167, v119, v167
	v_fma_f32 v166, v118, v166, v118
	v_fma_f32 v167, v119, v167, v119
	v_mul_f32_e32 v166, 0x3f4c422a, v166
	v_mul_f32_e32 v167, 0x3f4c422a, v167
	v_add_f32_e32 v166, v166, v166
	v_add_f32_e32 v167, v167, v167
	v_mul_f32_e32 v166, 0xbfb8aa3b, v166
	v_mul_f32_e32 v167, 0xbfb8aa3b, v167
	v_exp_f32_e32 v166, v166
	v_exp_f32_e32 v167, v167
	v_add_f32_e32 v166, 1.0, v166
	v_add_f32_e32 v167, 1.0, v167
	v_rcp_f32_e32 v166, v166
	v_rcp_f32_e32 v167, v167
	s_nop 0
	v_pk_mul_f32 v[166:167], v[118:119], v[166:167]
	s_nop 0
	v_pk_mul_f32 v[168:169], v[166:167], v[166:167]
	s_nop 0
	v_add_f32_e32 v168, v168, v170
	v_add_f32_e32 v172, v169, v168
	v_mul_f32_e32 v168, 0x3d372713, v116
	v_mul_f32_e32 v169, 0x3d372713, v117
	v_mul_f32_e32 v168, v116, v168
	v_mul_f32_e32 v169, v117, v169
	v_fma_f32 v168, v116, v168, v116
	v_fma_f32 v169, v117, v169, v117
	v_mul_f32_e32 v168, 0x3f4c422a, v168
	v_mul_f32_e32 v169, 0x3f4c422a, v169
	v_add_f32_e32 v168, v168, v168
	v_add_f32_e32 v169, v169, v169
	v_mul_f32_e32 v168, 0xbfb8aa3b, v168
	v_mul_f32_e32 v169, 0xbfb8aa3b, v169
	v_exp_f32_e32 v168, v168
	v_exp_f32_e32 v169, v169
	v_add_f32_e32 v168, 1.0, v168
	v_add_f32_e32 v169, 1.0, v169
	v_rcp_f32_e32 v168, v168
	v_rcp_f32_e32 v169, v169
	s_nop 0
	v_pk_mul_f32 v[168:169], v[116:117], v[168:169]
	s_nop 0
	v_pk_mul_f32 v[170:171], v[168:169], v[168:169]
	s_nop 0
	v_add_f32_e32 v170, v170, v172
	v_add_f32_e32 v207, v171, v170
	v_mul_f32_e32 v170, 0x3d372713, v114
	v_mul_f32_e32 v171, 0x3d372713, v115
	v_mul_f32_e32 v170, v114, v170
	v_mul_f32_e32 v171, v115, v171
	v_fma_f32 v170, v114, v170, v114
	v_fma_f32 v171, v115, v171, v115
	v_mul_f32_e32 v170, 0x3f4c422a, v170
	v_mul_f32_e32 v171, 0x3f4c422a, v171
	v_add_f32_e32 v170, v170, v170
	v_add_f32_e32 v171, v171, v171
	v_mul_f32_e32 v170, 0xbfb8aa3b, v170
	v_mul_f32_e32 v171, 0xbfb8aa3b, v171
	v_exp_f32_e32 v170, v170
	v_exp_f32_e32 v171, v171
	v_add_f32_e32 v170, 1.0, v170
	v_add_f32_e32 v171, 1.0, v171
	v_rcp_f32_e32 v170, v170
	v_rcp_f32_e32 v171, v171
	s_nop 0
	v_pk_mul_f32 v[170:171], v[114:115], v[170:171]
	s_nop 0
	v_pk_mul_f32 v[172:173], v[170:171], v[170:171]
	s_nop 0
	v_add_f32_e32 v172, v172, v207
	v_add_f32_e32 v172, v173, v172
	v_mov_b32_e32 v173, v172
	s_nop 1
	v_permlane16_swap_b32_e32 v172, v173
	s_waitcnt lgkmcnt(0)
; __device__ __forceinline__ bf16_t f2bf(float f) { return (bf16_t)(pk2(f, 0.f) & 0xffffu); }
; __device__ __forceinline__ float grp_sum(float v) { v += __shfl_xor(v, 16); v += __shfl_xor(v, 32); return v; }
;   __device__ __forceinline__ void operator()(const pg8::f32x4 (&acc)[2][2][4][2], const pg8::Unit& u, int wr, int wc, int fr, int fq) const {
;     ...
;           const float rn = rsqrtf(grp_sum(ss) * (1.f / 64.f) + EPS);
;           bf16_t* dst = vt + ((unsigned)(g * 128 + (tok >> 7)) * 64 + 8 * fq) * 128 + (tok & 127);
; #pragma unroll
;           for (int bj = 0; bj < 2; ++bj)
; #pragma unroll
;             for (int e = 0; e < 8; ++e) dst[(32 * bj + e) * 128] = f2bf(v[bj][e] * rn * sgu_norm[g * 64 + 32 * bj + 8 * fq + e]);
	v_add_f32_e32 v172, v172, v173
	v_mov_b32_e32 v173, v172
	s_nop 1
	v_permlane32_swap_b32_e32 v172, v173
	s_waitcnt lgkmcnt(0)
	v_add_f32_e32 v172, v172, v173
	v_fmamk_f32 v172, v172, 0x3c800000, v154
	v_cmp_gt_f32_e32 vcc, s3, v172
	v_mul_f32_e32 v173, 0x4b800000, v172
	s_nop 0
	v_cndmask_b32_e32 v172, v172, v173, vcc
	v_rsq_f32_e32 v172, v172
	s_nop 0
	v_mul_f32_e32 v173, 0x45800000, v172
	v_cndmask_b32_e32 v207, v172, v173, vcc
	v_lshrrev_b32_e32 v172, 1, v205
	v_and_b32_e32 v172, 0x1ffffc0, v172
	v_add_lshl_u32 v172, v172, v203, 7
	v_mov_b32_e32 v173, v137
	v_mul_f32_e32 v218, v157, v207
	v_mov_b32_e32 v157, v137
	v_lshl_add_u64 v[172:173], v[172:173], 1, s[50:51]
	v_lshl_add_u64 v[216:217], v[156:157], 2, s[56:57]
	v_lshl_add_u64 v[172:173], v[172:173], 0, v[208:209]
	global_load_dwordx4 v[208:211], v[216:217], off offset:16
	global_load_dwordx4 v[212:215], v[216:217], off
	v_mul_f32_e32 v112, v112, v207
	s_waitcnt vmcnt(0)
	v_mul_f32_e32 v157, v212, v218
	v_cvt_pk_bf16_f32 v157, v157, s0
	global_store_short v[172:173], v157, off
	v_mul_f32_e32 v157, v163, v207
	v_mul_f32_e32 v157, v213, v157
	v_cvt_pk_bf16_f32 v157, v157, s0
	global_store_short v[172:173], v157, off offset:256
	v_mul_f32_e32 v157, v174, v207
	v_mul_f32_e32 v157, v214, v157
	v_cvt_pk_bf16_f32 v157, v157, s0
	global_store_short v[172:173], v157, off offset:512
	v_mul_f32_e32 v157, v175, v207
	v_mul_f32_e32 v157, v215, v157
	v_cvt_pk_bf16_f32 v157, v157, s0
	global_store_short v[172:173], v157, off offset:768
	v_mul_f32_e32 v157, v176, v207
	v_mul_f32_e32 v157, v208, v157
	v_cvt_pk_bf16_f32 v157, v157, s0
	global_store_short v[172:173], v157, off offset:1024
	v_mul_f32_e32 v157, v177, v207
	v_mul_f32_e32 v157, v157, v209
	v_cvt_pk_bf16_f32 v157, v157, s0
	global_store_short v[172:173], v157, off offset:1280
	v_mul_f32_e32 v157, v178, v207
	v_mul_f32_e32 v157, v157, v210
	v_cvt_pk_bf16_f32 v157, v157, s0
	global_store_short v[172:173], v157, off offset:1536
	v_mul_f32_e32 v157, v179, v207
	v_mul_f32_e32 v157, v157, v211
	v_cvt_pk_bf16_f32 v157, v157, s0
	global_store_short v[172:173], v157, off offset:1792
	global_load_dwordx4 v[174:177], v[216:217], off offset:144
	global_load_dwordx4 v[208:211], v[216:217], off offset:128
	v_add_co_u32_e32 v172, vcc, s97, v172
	s_waitcnt vmcnt(0)
	v_mul_f32_e32 v112, v112, v208
	v_cvt_pk_bf16_f32 v112, v112, s0
	v_addc_co_u32_e32 v173, vcc, 0, v173, vcc
	global_store_short v[172:173], v112, off
	v_mul_f32_e32 v112, v113, v207
	v_mul_f32_e32 v112, v112, v209
	v_cvt_pk_bf16_f32 v112, v112, s0
	global_store_short v[172:173], v112, off offset:256
	v_mul_f32_e32 v112, v166, v207
	v_mul_f32_e32 v112, v112, v210
	v_cvt_pk_bf16_f32 v112, v112, s0
	global_store_short v[172:173], v112, off offset:512
	v_mul_f32_e32 v112, v167, v207
	v_mul_f32_e32 v112, v112, v211
	v_cvt_pk_bf16_f32 v112, v112, s0
	global_store_short v[172:173], v112, off offset:768
	v_mul_f32_e32 v112, v168, v207
	v_mul_f32_e32 v112, v112, v174
	v_cvt_pk_bf16_f32 v112, v112, s0
	global_store_short v[172:173], v112, off offset:1024
	v_mul_f32_e32 v112, v169, v207
	v_mul_f32_e32 v112, v112, v175
	v_cvt_pk_bf16_f32 v112, v112, s0
	global_store_short v[172:173], v112, off offset:1280
	v_mul_f32_e32 v112, v170, v207
	v_mul_f32_e32 v112, v112, v176
	v_cvt_pk_bf16_f32 v112, v112, s0
	global_store_short v[172:173], v112, off offset:1536
	v_mul_f32_e32 v112, v171, v207
	v_mul_f32_e32 v112, v112, v177
	v_cvt_pk_bf16_f32 v112, v112, s0
	v_mov_b32_e32 v207, 0
	global_store_short v[172:173], v112, off offset:1792

; __device__ __forceinline__ float grp_sum(float v) { v += __shfl_xor(v, 16); v += __shfl_xor(v, 32); return v; }
; __device__ __forceinline__ void st8_bf16(bf16_t* dst, const float (&v)[8]) { u32x4 w; w.x = pk2(v[0], v[1]); w.y = pk2(v[2], v[3]); w.z = pk2(v[4], v[5]); w.w = pk2(v[6], v[7]); *(u32x4*)dst = w; }
;   __device__ __forceinline__ void operator()(const pg8::f32x4 (&acc)[2][2][4][2], const pg8::Unit& u, int wr, int wc, int fr, int fq) const {
;     ...
;           const bool isq = gi < 24; const int hm = isq ? gi - 16 : gi - 24;
;           const float* gn = isq ? q_norm : k_norm;
;           float ss = 0.f;
; #pragma unroll
;           for (int bj = 0; bj < 2; ++bj)
; #pragma unroll
;             for (int e = 0; e < 8; ++e) ss += v[bj][e] * v[bj][e];
;           const float rn = rsqrtf(grp_sum(ss) * (1.f / 64.f) + EPS) * (isq ? 0.125f * LOG2E : 1.f);
;           const f32x4 c0 = *(const f32x4*)(cos64 + (unsigned)pos * 32 + 8 * fq), c1 = *(const f32x4*)(cos64 + (unsigned)pos * 32 + 8 * fq + 4);
;           const f32x4 s0 = *(const f32x4*)(sin64 + (unsigned)pos * 32 + 8 * fq), s1 = *(const f32x4*)(sin64 + (unsigned)pos * 32 + 8 * fq + 4);
;           float kk = 0.f;
; #pragma unroll
;           for (int e = 0; e < 8; ++e) {
;             const float x1 = v[0][e] * rn * gn[8 * fq + e], x2 = v[1][e] * rn * gn[32 + 8 * fq + e];
;             const float cc = e < 4 ? c0[e & 3] : c1[e & 3], sn = e < 4 ? s0[e & 3] : s1[e & 3];
;             v[0][e] = x1 * cc - x2 * sn; v[1][e] = x1 * sn + x2 * cc;
;             kk += v[0][e] * v[0][e] + v[1][e] * v[1][e];
;           }
;           bf16_t* dst = (isq ? qb : kb) + ((unsigned)(bb * 8 + hm) * S + pos) * 64 + 8 * fq;
;           st8_bf16(dst, v[0]); st8_bf16(dst + 32, v[1]);
;           if (!isq) kmx_run = fmaxf(kmx_run, grp_sum(kk));
.LBB0_402:
	s_andn2_b64 vcc, exec, s[12:13]
	v_mov_b32_e32 v164, v207
	s_cbranch_vccnz .LBB0_405
	v_pk_mul_f32 v[98:99], v[114:115], v[114:115]
	v_pk_mul_f32 v[116:117], v[110:111], v[110:111]
	v_add_f32_e32 v98, v98, v99
	v_add_f32_e32 v98, v116, v98
	v_pk_mul_f32 v[118:119], v[108:109], v[108:109]
	v_add_f32_e32 v98, v117, v98
	v_add_f32_e32 v98, v118, v98
	v_pk_mul_f32 v[120:121], v[106:107], v[106:107]
	v_add_f32_e32 v98, v119, v98
	v_add_f32_e32 v98, v120, v98
	v_pk_mul_f32 v[122:123], v[104:105], v[104:105]
	v_add_f32_e32 v98, v121, v98
	v_add_f32_e32 v98, v122, v98
	v_pk_mul_f32 v[124:125], v[102:103], v[102:103]
	v_add_f32_e32 v98, v123, v98
	v_add_f32_e32 v98, v124, v98
	v_pk_mul_f32 v[126:127], v[100:101], v[100:101]
	v_add_f32_e32 v98, v125, v98
	v_add_f32_e32 v98, v126, v98
	v_pk_mul_f32 v[162:163], v[96:97], v[96:97]
	v_add_f32_e32 v98, v127, v98
	v_add_f32_e32 v98, v162, v98
	v_add_f32_e32 v98, v163, v98
	v_mov_b32_e32 v99, v98
	s_nop 1
	v_permlane16_swap_b32_e32 v98, v99
	s_and_b64 s[12:13], s[6:7], exec
	s_cselect_b32 s13, s17, s19
	s_cselect_b32 s12, s16, s18
	v_lshlrev_b32_e32 v127, 2, v138
	s_waitcnt lgkmcnt(0)
	v_add_f32_e32 v98, v98, v99
	v_mov_b32_e32 v99, v98
	s_nop 1
	v_permlane32_swap_b32_e32 v98, v99
	v_lshl_add_u32 v113, v113, 16, s59
	v_or_b32_e32 v113, v113, v157
	v_mov_b32_e32 v164, v207
	s_waitcnt lgkmcnt(0)
	v_add_f32_e32 v98, v98, v99
	v_fmamk_f32 v98, v98, 0x3c800000, v154
	v_cmp_gt_f32_e32 vcc, s3, v98
	v_mul_f32_e32 v99, 0x4b800000, v98
	s_nop 0
	v_cndmask_b32_e32 v98, v98, v99, vcc
	v_rsq_f32_e32 v98, v98
	s_nop 0
	v_mul_f32_e32 v99, 0x45800000, v98
	v_cndmask_b32_e32 v98, v98, v99, vcc
	v_mul_f32_e32 v126, v204, v98
	v_lshlrev_b32_e32 v98, 7, v157
	v_mov_b32_e32 v99, v137
	v_lshl_add_u64 v[116:117], v[140:141], 0, v[98:99]
	v_lshl_add_u64 v[98:99], v[142:143], 0, v[98:99]
	global_load_dwordx4 v[166:169], v[116:117], off offset:16
	global_load_dwordx4 v[118:121], v[116:117], off
	global_load_dwordx4 v[170:173], v[98:99], off offset:16
	global_load_dwordx4 v[122:125], v[98:99], off
	global_load_dwordx4 v[174:177], v127, s[12:13] offset:16
	global_load_dwordx4 v[208:211], v127, s[12:13]
	global_load_dwordx4 v[212:215], v127, s[12:13] offset:144
	global_load_dwordx4 v[216:219], v127, s[12:13] offset:128
	v_pk_mul_f32 v[98:99], v[114:115], v[126:127] op_sel_hi:[1,0]
	s_cselect_b32 s12, s87, s89
	s_cselect_b32 s13, s86, s88
	s_andn2_b64 vcc, exec, s[78:79]
	s_waitcnt vmcnt(2)
	v_pk_mul_f32 v[116:117], v[208:209], v[98:99]
	v_pk_mul_f32 v[98:99], v[104:105], v[126:127] op_sel_hi:[1,0]
	s_waitcnt vmcnt(0)
	v_pk_mul_f32 v[162:163], v[216:217], v[98:99]
	s_nop 0
	v_pk_mul_f32 v[98:99], v[122:123], v[162:163]
	s_nop 0
	v_pk_fma_f32 v[98:99], v[118:119], v[116:117], v[98:99] neg_lo:[0,0,1] neg_hi:[0,0,1]
	v_pk_mul_f32 v[116:117], v[122:123], v[116:117]
	s_nop 0
	v_pk_fma_f32 v[116:117], v[118:119], v[162:163], v[116:117]
	v_pk_mul_f32 v[118:119], v[110:111], v[126:127] op_sel_hi:[1,0]
	s_nop 0
	v_pk_mul_f32 v[122:123], v[118:119], v[210:211]
	v_pk_mul_f32 v[118:119], v[102:103], v[126:127] op_sel_hi:[1,0]
	s_nop 0
	v_pk_mul_f32 v[162:163], v[118:119], v[218:219]
	s_nop 0
	v_pk_mul_f32 v[118:119], v[124:125], v[162:163]
	s_nop 0
	v_pk_fma_f32 v[118:119], v[120:121], v[122:123], v[118:119] neg_lo:[0,0,1] neg_hi:[0,0,1]
	v_pk_mul_f32 v[120:121], v[120:121], v[162:163]
	s_nop 0
	v_pk_fma_f32 v[120:121], v[124:125], v[122:123], v[120:121]
	v_pk_mul_f32 v[122:123], v[108:109], v[126:127] op_sel_hi:[1,0]
	s_nop 0
	v_pk_mul_f32 v[124:125], v[122:123], v[174:175]
	v_pk_mul_f32 v[122:123], v[100:101], v[126:127] op_sel_hi:[1,0]
	s_nop 0
	v_pk_mul_f32 v[162:163], v[122:123], v[212:213]
	s_nop 0
	v_pk_mul_f32 v[122:123], v[170:171], v[162:163]
	v_pk_mul_f32 v[162:163], v[166:167], v[162:163]
	v_pk_fma_f32 v[122:123], v[166:167], v[124:125], v[122:123] neg_lo:[0,0,1] neg_hi:[0,0,1]
	v_pk_fma_f32 v[124:125], v[170:171], v[124:125], v[162:163]
	v_pk_mul_f32 v[162:163], v[106:107], v[126:127] op_sel_hi:[1,0]
	v_pk_mul_f32 v[126:127], v[96:97], v[126:127] op_sel_hi:[1,0]
	v_pk_mul_f32 v[162:163], v[162:163], v[176:177]
	v_pk_mul_f32 v[166:167], v[126:127], v[214:215]
	s_nop 0
	v_pk_mul_f32 v[126:127], v[172:173], v[166:167]
	v_pk_mul_f32 v[166:167], v[168:169], v[166:167]
	v_pk_fma_f32 v[126:127], v[168:169], v[162:163], v[126:127] neg_lo:[0,0,1] neg_hi:[0,0,1]
	v_pk_fma_f32 v[162:163], v[172:173], v[162:163], v[166:167]
	v_mov_b32_e32 v166, s13
	v_mov_b32_e32 v167, s12
	v_lshlrev_b32_e32 v168, 6, v113
	v_mov_b32_e32 v169, v137
	v_lshl_add_u64 v[166:167], v[168:169], 1, v[166:167]
	v_mov_b32_e32 v113, v137
	v_lshl_add_u64 v[170:171], v[166:167], 0, v[112:113]
	v_cvt_pk_bf16_f32 v166, v98, v99
	v_cvt_pk_bf16_f32 v167, v118, v119
	v_cvt_pk_bf16_f32 v168, v122, v123
	v_cvt_pk_bf16_f32 v169, v126, v127
	global_store_dwordx4 v[170:171], v[166:169], off
	s_nop 1
	v_cvt_pk_bf16_f32 v166, v116, v117
	v_cvt_pk_bf16_f32 v167, v120, v121
	v_cvt_pk_bf16_f32 v168, v124, v125
	v_cvt_pk_bf16_f32 v169, v162, v163
	global_store_dwordx4 v[170:171], v[166:169], off offset:64
	s_cbranch_vccnz .LBB0_405
	v_pk_mul_f32 v[116:117], v[116:117], v[116:117]
	s_nop 0
	v_pk_fma_f32 v[98:99], v[98:99], v[98:99], v[116:117]
	v_pk_mul_f32 v[116:117], v[120:121], v[120:121]
	v_add_f32_e32 v98, v98, v99
	v_pk_fma_f32 v[116:117], v[118:119], v[118:119], v[116:117]
	v_pk_mul_f32 v[118:119], v[124:125], v[124:125]
	v_add_f32_e32 v98, v116, v98
	v_pk_fma_f32 v[118:119], v[122:123], v[122:123], v[118:119]
	v_add_f32_e32 v98, v117, v98
	v_pk_mul_f32 v[120:121], v[162:163], v[162:163]
	v_add_f32_e32 v98, v98, v118
	v_pk_fma_f32 v[120:121], v[126:127], v[126:127], v[120:121]
	v_add_f32_e32 v98, v98, v119
	v_add_f32_e32 v98, v98, v120
	v_add_f32_e32 v98, v98, v121
	v_mov_b32_e32 v99, v98
	s_nop 1
	v_permlane16_swap_b32_e32 v98, v99
	s_waitcnt lgkmcnt(0)
	v_add_f32_e32 v98, v98, v99
	v_mov_b32_e32 v99, v98
	s_nop 1
	v_permlane32_swap_b32_e32 v98, v99
	s_waitcnt lgkmcnt(0)
	v_add_f32_e32 v98, v98, v99
	v_max_f32_e32 v99, v207, v207
	v_max_f32_e32 v164, v99, v98

; __device__ __forceinline__ float gelu_tanh(float x) { const float y = 0.7978845608028654f * (x + 0.044715f * x * x * x); return x * sigm(2.f * y); }
; __device__ __forceinline__ float grp_sum(float v) { v += __shfl_xor(v, 16); v += __shfl_xor(v, 32); return v; }
;   __device__ __forceinline__ void operator()(const pg8::f32x4 (&acc)[2][2][4][2], const pg8::Unit& u, int wr, int wc, int fr, int fq) const {
;     ...
;           const int g = gi - 8; float ss = 0.f;
; #pragma unroll
;           for (int bj = 0; bj < 2; ++bj)
; #pragma unroll
;             for (int e = 0; e < 8; ++e) { v[bj][e] = gelu_tanh(v[bj][e]); ss += v[bj][e] * v[bj][e]; }
;           const float rn = rsqrtf(grp_sum(ss) * (1.f / 64.f) + EPS);
.LBB0_406:
	s_andn2_b64 vcc, exec, s[12:13]
	s_cbranch_vccnz .LBB0_408
	v_mul_f32_e32 v98, 0x3d372713, v114
	v_mul_f32_e32 v98, v114, v98
	v_fma_f32 v98, v114, v98, v114
	v_mul_f32_e32 v98, 0x3f4c422a, v98
	v_add_f32_e32 v98, v98, v98
	v_mul_f32_e32 v98, 0xbfb8aa3b, v98
	v_exp_f32_e32 v98, v98
	v_mul_f32_e32 v99, 0x3d372713, v105
	v_mul_f32_e32 v99, v105, v99
	v_fma_f32 v99, v105, v99, v105
	v_add_f32_e32 v98, 1.0, v98
	v_rcp_f32_e32 v98, v98
	v_mul_f32_e32 v99, 0x3f4c422a, v99
	v_add_f32_e32 v99, v99, v99
	v_mul_f32_e32 v99, 0xbfb8aa3b, v99
	v_mul_f32_e32 v157, v114, v98
	v_mul_f32_e32 v98, 0x3d372713, v115
	v_mul_f32_e32 v98, v115, v98
	v_fma_f32 v98, v115, v98, v115
	v_mul_f32_e32 v98, 0x3f4c422a, v98
	v_add_f32_e32 v98, v98, v98
	v_mul_f32_e32 v98, 0xbfb8aa3b, v98
	v_exp_f32_e32 v98, v98
	v_exp_f32_e32 v99, v99
	v_and_b32_e32 v166, 0x7f, v165
	v_lshlrev_b32_e32 v166, 1, v166
	v_add_f32_e32 v98, 1.0, v98
	v_rcp_f32_e32 v98, v98
	v_add_f32_e32 v99, 1.0, v99
	v_rcp_f32_e32 v99, v99
	v_mov_b32_e32 v167, v137
	v_mul_f32_e32 v113, v115, v98
	v_mul_f32_e32 v98, 0x3d372713, v110
	v_mul_f32_e32 v98, v110, v98
	v_fma_f32 v98, v110, v98, v110
	v_mul_f32_e32 v98, 0x3f4c422a, v98
	v_add_f32_e32 v98, v98, v98
	v_mul_f32_e32 v98, 0xbfb8aa3b, v98
	v_exp_f32_e32 v98, v98
	v_mul_f32_e32 v118, v113, v113
	v_fmac_f32_e32 v118, v157, v157
	v_add_f32_e32 v98, 1.0, v98
	v_rcp_f32_e32 v98, v98
	s_nop 0
	v_mul_f32_e32 v124, v110, v98
	v_mul_f32_e32 v98, 0x3d372713, v111
	v_mul_f32_e32 v98, v111, v98
	v_fma_f32 v98, v111, v98, v111
	v_mul_f32_e32 v98, 0x3f4c422a, v98
	v_add_f32_e32 v98, v98, v98
	v_mul_f32_e32 v98, 0xbfb8aa3b, v98
	v_exp_f32_e32 v98, v98
	v_fmac_f32_e32 v118, v124, v124
	v_add_f32_e32 v98, 1.0, v98
	v_rcp_f32_e32 v98, v98
	s_nop 0
	v_mul_f32_e32 v125, v111, v98
	v_mul_f32_e32 v98, 0x3d372713, v108
	v_mul_f32_e32 v98, v108, v98
	v_fma_f32 v98, v108, v98, v108
	v_mul_f32_e32 v98, 0x3f4c422a, v98
	v_add_f32_e32 v98, v98, v98
	v_mul_f32_e32 v98, 0xbfb8aa3b, v98
	v_exp_f32_e32 v98, v98
	v_fmac_f32_e32 v118, v125, v125
	v_add_f32_e32 v98, 1.0, v98
	v_rcp_f32_e32 v98, v98
	s_nop 0
	v_mul_f32_e32 v126, v108, v98
	v_mul_f32_e32 v98, 0x3d372713, v109
	v_mul_f32_e32 v98, v109, v98
	v_fma_f32 v98, v109, v98, v109
	v_mul_f32_e32 v98, 0x3f4c422a, v98
	v_add_f32_e32 v98, v98, v98
	v_mul_f32_e32 v98, 0xbfb8aa3b, v98
	v_exp_f32_e32 v98, v98
	v_fmac_f32_e32 v118, v126, v126
	v_add_f32_e32 v98, 1.0, v98
	v_rcp_f32_e32 v98, v98
	s_nop 0
	v_mul_f32_e32 v127, v109, v98
	v_mul_f32_e32 v98, 0x3d372713, v106
	v_mul_f32_e32 v98, v106, v98
	v_fma_f32 v98, v106, v98, v106
	v_mul_f32_e32 v98, 0x3f4c422a, v98
	v_add_f32_e32 v98, v98, v98
	v_mul_f32_e32 v98, 0xbfb8aa3b, v98
	v_exp_f32_e32 v98, v98
	v_fmac_f32_e32 v118, v127, v127
	v_add_f32_e32 v98, 1.0, v98
	v_rcp_f32_e32 v98, v98
	s_nop 0
	v_mul_f32_e32 v162, v106, v98
	v_mul_f32_e32 v98, 0x3d372713, v107
	v_mul_f32_e32 v98, v107, v98
	v_fma_f32 v98, v107, v98, v107
	v_mul_f32_e32 v98, 0x3f4c422a, v98
	v_add_f32_e32 v98, v98, v98
	v_mul_f32_e32 v98, 0xbfb8aa3b, v98
	v_exp_f32_e32 v98, v98
	v_fmac_f32_e32 v118, v162, v162
	v_add_f32_e32 v98, 1.0, v98
	v_rcp_f32_e32 v98, v98
	s_nop 0
	v_mul_f32_e32 v163, v107, v98
	v_mul_f32_e32 v98, 0x3d372713, v104
	v_mul_f32_e32 v98, v104, v98
	v_fma_f32 v98, v104, v98, v104
	v_mul_f32_e32 v98, 0x3f4c422a, v98
	v_add_f32_e32 v98, v98, v98
	v_mul_f32_e32 v98, 0xbfb8aa3b, v98
	v_exp_f32_e32 v98, v98
	v_fmac_f32_e32 v118, v163, v163
	v_add_f32_e32 v98, 1.0, v98
	v_rcp_f32_e32 v98, v98
	s_nop 0
	v_pk_mul_f32 v[98:99], v[104:105], v[98:99]
	s_nop 0
	v_pk_mul_f32 v[116:117], v[98:99], v[98:99]
	s_nop 0
	v_add_f32_e32 v116, v116, v118
	v_add_f32_e32 v120, v117, v116
	v_mul_f32_e32 v116, 0x3d372713, v102
	v_mul_f32_e32 v117, 0x3d372713, v103
	v_mul_f32_e32 v116, v102, v116
	v_mul_f32_e32 v117, v103, v117
	v_fma_f32 v116, v102, v116, v102
	v_fma_f32 v117, v103, v117, v103
	v_mul_f32_e32 v116, 0x3f4c422a, v116
	v_mul_f32_e32 v117, 0x3f4c422a, v117
	v_add_f32_e32 v116, v116, v116
	v_add_f32_e32 v117, v117, v117
	v_mul_f32_e32 v116, 0xbfb8aa3b, v116
	v_mul_f32_e32 v117, 0xbfb8aa3b, v117
	v_exp_f32_e32 v116, v116
	v_exp_f32_e32 v117, v117
	v_add_f32_e32 v116, 1.0, v116
	v_add_f32_e32 v117, 1.0, v117
	v_rcp_f32_e32 v116, v116
	v_rcp_f32_e32 v117, v117
	s_nop 0
	v_pk_mul_f32 v[116:117], v[102:103], v[116:117]
	s_nop 0
	v_pk_mul_f32 v[118:119], v[116:117], v[116:117]
	s_nop 0
	v_add_f32_e32 v118, v118, v120
	v_add_f32_e32 v122, v119, v118
	v_mul_f32_e32 v118, 0x3d372713, v100
	v_mul_f32_e32 v119, 0x3d372713, v101
	v_mul_f32_e32 v118, v100, v118
	v_mul_f32_e32 v119, v101, v119
	v_fma_f32 v118, v100, v118, v100
	v_fma_f32 v119, v101, v119, v101
	v_mul_f32_e32 v118, 0x3f4c422a, v118
	v_mul_f32_e32 v119, 0x3f4c422a, v119
	v_add_f32_e32 v118, v118, v118
	v_add_f32_e32 v119, v119, v119
	v_mul_f32_e32 v118, 0xbfb8aa3b, v118
	v_mul_f32_e32 v119, 0xbfb8aa3b, v119
	v_exp_f32_e32 v118, v118
	v_exp_f32_e32 v119, v119
	v_add_f32_e32 v118, 1.0, v118
	v_add_f32_e32 v119, 1.0, v119
	v_rcp_f32_e32 v118, v118
	v_rcp_f32_e32 v119, v119
	s_nop 0
	v_pk_mul_f32 v[118:119], v[100:101], v[118:119]
	s_nop 0
	v_pk_mul_f32 v[120:121], v[118:119], v[118:119]
	s_nop 0
	v_add_f32_e32 v120, v120, v122
	v_add_f32_e32 v164, v121, v120
	v_mul_f32_e32 v120, 0x3d372713, v96
	v_mul_f32_e32 v121, 0x3d372713, v97
	v_mul_f32_e32 v120, v96, v120
	v_mul_f32_e32 v121, v97, v121
	v_fma_f32 v120, v96, v120, v96
	v_fma_f32 v121, v97, v121, v97
	v_mul_f32_e32 v120, 0x3f4c422a, v120
	v_mul_f32_e32 v121, 0x3f4c422a, v121
	v_add_f32_e32 v120, v120, v120
	v_add_f32_e32 v121, v121, v121
	v_mul_f32_e32 v120, 0xbfb8aa3b, v120
	v_mul_f32_e32 v121, 0xbfb8aa3b, v121
	v_exp_f32_e32 v120, v120
	v_exp_f32_e32 v121, v121
	v_add_f32_e32 v120, 1.0, v120
	v_add_f32_e32 v121, 1.0, v121
	v_rcp_f32_e32 v120, v120
	v_rcp_f32_e32 v121, v121
	s_nop 0
	v_pk_mul_f32 v[120:121], v[96:97], v[120:121]
	s_nop 0
	v_pk_mul_f32 v[122:123], v[120:121], v[120:121]
	s_nop 0
	v_add_f32_e32 v122, v122, v164
	v_add_f32_e32 v122, v123, v122
	v_mov_b32_e32 v123, v122
	s_nop 1
	v_permlane16_swap_b32_e32 v122, v123
	s_waitcnt lgkmcnt(0)
; __device__ __forceinline__ bf16_t f2bf(float f) { return (bf16_t)(pk2(f, 0.f) & 0xffffu); }
; __device__ __forceinline__ float grp_sum(float v) { v += __shfl_xor(v, 16); v += __shfl_xor(v, 32); return v; }
;   __device__ __forceinline__ void operator()(const pg8::f32x4 (&acc)[2][2][4][2], const pg8::Unit& u, int wr, int wc, int fr, int fq) const {
;     ...
;           const float rn = rsqrtf(grp_sum(ss) * (1.f / 64.f) + EPS);
;           bf16_t* dst = vt + ((unsigned)(g * 128 + (tok >> 7)) * 64 + 8 * fq) * 128 + (tok & 127);
; #pragma unroll
;           for (int bj = 0; bj < 2; ++bj)
; #pragma unroll
;             for (int e = 0; e < 8; ++e) dst[(32 * bj + e) * 128] = f2bf(v[bj][e] * rn * sgu_norm[g * 64 + 32 * bj + 8 * fq + e]);
	v_add_f32_e32 v122, v122, v123
	v_mov_b32_e32 v123, v122
	s_nop 1
	v_permlane32_swap_b32_e32 v122, v123
	s_waitcnt lgkmcnt(0)
	v_add_f32_e32 v122, v122, v123
	v_fmamk_f32 v122, v122, 0x3c800000, v154
	v_cmp_gt_f32_e32 vcc, s3, v122
	v_mul_f32_e32 v123, 0x4b800000, v122
	s_nop 0
	v_cndmask_b32_e32 v122, v122, v123, vcc
	v_rsq_f32_e32 v122, v122
	s_nop 0
	v_mul_f32_e32 v123, 0x45800000, v122
	v_cndmask_b32_e32 v164, v122, v123, vcc
	v_lshrrev_b32_e32 v122, 1, v165
	v_and_b32_e32 v122, 0x1ffffc0, v122
	v_add_lshl_u32 v122, v122, v203, 7
	v_mov_b32_e32 v123, v137
	v_mul_f32_e32 v176, v157, v164
	v_mov_b32_e32 v157, v137
	v_lshl_add_u64 v[122:123], v[122:123], 1, s[50:51]
	v_lshl_add_u64 v[174:175], v[156:157], 2, s[56:57]
	v_lshl_add_u64 v[122:123], v[122:123], 0, v[166:167]
	global_load_dwordx4 v[166:169], v[174:175], off offset:16
	global_load_dwordx4 v[170:173], v[174:175], off
	v_mul_f32_e32 v113, v113, v164
	v_mul_f32_e32 v98, v98, v164
	s_waitcnt vmcnt(0)
	v_mul_f32_e32 v113, v171, v113
	v_cvt_pk_bf16_f32 v113, v113, s0
	global_store_short v[122:123], v113, off offset:256
	v_mul_f32_e32 v113, v124, v164
	v_mul_f32_e32 v113, v172, v113
	v_cvt_pk_bf16_f32 v113, v113, s0
	global_store_short v[122:123], v113, off offset:512
	v_mul_f32_e32 v113, v125, v164
	v_mul_f32_e32 v113, v173, v113
	v_cvt_pk_bf16_f32 v113, v113, s0
	global_store_short v[122:123], v113, off offset:768
	v_mul_f32_e32 v113, v126, v164
	v_mul_f32_e32 v113, v166, v113
	v_cvt_pk_bf16_f32 v113, v113, s0
	global_store_short v[122:123], v113, off offset:1024
	v_mul_f32_e32 v113, v127, v164
	v_mul_f32_e32 v113, v113, v167
	v_cvt_pk_bf16_f32 v113, v113, s0
	global_store_short v[122:123], v113, off offset:1280
	v_mul_f32_e32 v113, v162, v164
	v_mul_f32_e32 v113, v113, v168
	v_cvt_pk_bf16_f32 v113, v113, s0
	global_store_short v[122:123], v113, off offset:1536
	v_mul_f32_e32 v113, v163, v164
	v_mul_f32_e32 v157, v170, v176
	v_mul_f32_e32 v113, v113, v169
	v_cvt_pk_bf16_f32 v157, v157, s0
	v_cvt_pk_bf16_f32 v113, v113, s0
	global_store_short v[122:123], v157, off
	global_store_short v[122:123], v113, off offset:1792
	global_load_dwordx4 v[124:127], v[174:175], off offset:144
	global_load_dwordx4 v[166:169], v[174:175], off offset:128
	v_add_co_u32_e32 v122, vcc, s97, v122
	s_waitcnt vmcnt(0)
	v_mul_f32_e32 v98, v98, v166
	v_cvt_pk_bf16_f32 v98, v98, s0
	v_addc_co_u32_e32 v123, vcc, 0, v123, vcc
	global_store_short v[122:123], v98, off
	v_mul_f32_e32 v98, v99, v164
	v_mul_f32_e32 v98, v98, v167
	v_cvt_pk_bf16_f32 v98, v98, s0
	global_store_short v[122:123], v98, off offset:256
	v_mul_f32_e32 v98, v116, v164
	v_mul_f32_e32 v98, v98, v168
	v_cvt_pk_bf16_f32 v98, v98, s0
	global_store_short v[122:123], v98, off offset:512
	v_mul_f32_e32 v98, v117, v164
	v_mul_f32_e32 v98, v98, v169
	v_cvt_pk_bf16_f32 v98, v98, s0
	global_store_short v[122:123], v98, off offset:768
	v_mul_f32_e32 v98, v118, v164
	v_mul_f32_e32 v98, v98, v124
	v_cvt_pk_bf16_f32 v98, v98, s0
	global_store_short v[122:123], v98, off offset:1024
	v_mul_f32_e32 v98, v119, v164
	v_mul_f32_e32 v98, v98, v125
	v_cvt_pk_bf16_f32 v98, v98, s0
	global_store_short v[122:123], v98, off offset:1280
	v_mul_f32_e32 v98, v120, v164
	v_mul_f32_e32 v98, v98, v126
	v_cvt_pk_bf16_f32 v98, v98, s0
	global_store_short v[122:123], v98, off offset:1536
	v_mul_f32_e32 v98, v121, v164
	v_mul_f32_e32 v98, v98, v127
	v_cvt_pk_bf16_f32 v98, v98, s0
	v_mov_b32_e32 v164, v207
	global_store_short v[122:123], v98, off offset:1792

; __device__ __forceinline__ float grp_sum(float v) { v += __shfl_xor(v, 16); v += __shfl_xor(v, 32); return v; }
; __device__ __forceinline__ void st8_bf16(bf16_t* dst, const float (&v)[8]) { u32x4 w; w.x = pk2(v[0], v[1]); w.y = pk2(v[2], v[3]); w.z = pk2(v[4], v[5]); w.w = pk2(v[6], v[7]); *(u32x4*)dst = w; }
;   __device__ __forceinline__ void operator()(const pg8::f32x4 (&acc)[2][2][4][2], const pg8::Unit& u, int wr, int wc, int fr, int fq) const {
;     ...
;           const bool isq = gi < 24; const int hm = isq ? gi - 16 : gi - 24;
;           const float* gn = isq ? q_norm : k_norm;
;           float ss = 0.f;
; #pragma unroll
;           for (int bj = 0; bj < 2; ++bj)
; #pragma unroll
;             for (int e = 0; e < 8; ++e) ss += v[bj][e] * v[bj][e];
;           const float rn = rsqrtf(grp_sum(ss) * (1.f / 64.f) + EPS) * (isq ? 0.125f * LOG2E : 1.f);
;           const f32x4 c0 = *(const f32x4*)(cos64 + (unsigned)pos * 32 + 8 * fq), c1 = *(const f32x4*)(cos64 + (unsigned)pos * 32 + 8 * fq + 4);
;           const f32x4 s0 = *(const f32x4*)(sin64 + (unsigned)pos * 32 + 8 * fq), s1 = *(const f32x4*)(sin64 + (unsigned)pos * 32 + 8 * fq + 4);
;           float kk = 0.f;
; #pragma unroll
;           for (int e = 0; e < 8; ++e) {
;             const float x1 = v[0][e] * rn * gn[8 * fq + e], x2 = v[1][e] * rn * gn[32 + 8 * fq + e];
;             const float cc = e < 4 ? c0[e & 3] : c1[e & 3], sn = e < 4 ? s0[e & 3] : s1[e & 3];
;             v[0][e] = x1 * cc - x2 * sn; v[1][e] = x1 * sn + x2 * cc;
;             kk += v[0][e] * v[0][e] + v[1][e] * v[1][e];
;           }
;           bf16_t* dst = (isq ? qb : kb) + ((unsigned)(bb * 8 + hm) * S + pos) * 64 + 8 * fq;
;           st8_bf16(dst, v[0]); st8_bf16(dst + 32, v[1]);
;           if (!isq) kmx_run = fmaxf(kmx_run, grp_sum(kk));
.LBB0_415:
	s_andn2_b64 vcc, exec, s[82:83]
	v_mov_b32_e32 v97, v164
	s_cbranch_vccnz .LBB0_418
	v_pk_mul_f32 v[82:83], v[98:99], v[98:99]
	v_pk_mul_f32 v[100:101], v[94:95], v[94:95]
	v_add_f32_e32 v82, v82, v83
	v_add_f32_e32 v82, v100, v82
	v_pk_mul_f32 v[102:103], v[92:93], v[92:93]
	v_add_f32_e32 v82, v101, v82
	v_add_f32_e32 v82, v102, v82
	v_pk_mul_f32 v[104:105], v[90:91], v[90:91]
	v_add_f32_e32 v82, v103, v82
	v_add_f32_e32 v82, v104, v82
	v_pk_mul_f32 v[106:107], v[88:89], v[88:89]
	v_add_f32_e32 v82, v105, v82
	v_add_f32_e32 v82, v106, v82
	v_pk_mul_f32 v[108:109], v[86:87], v[86:87]
	v_add_f32_e32 v82, v107, v82
	v_add_f32_e32 v82, v108, v82
	v_pk_mul_f32 v[110:111], v[84:85], v[84:85]
	v_add_f32_e32 v82, v109, v82
	v_add_f32_e32 v82, v110, v82
	v_pk_mul_f32 v[114:115], v[80:81], v[80:81]
	v_add_f32_e32 v82, v111, v82
	v_add_f32_e32 v82, v114, v82
	v_add_f32_e32 v82, v115, v82
	v_mov_b32_e32 v83, v82
	s_nop 1
	v_permlane16_swap_b32_e32 v82, v83
	s_and_b64 s[82:83], s[6:7], exec
	s_cselect_b32 s83, s17, s19
	s_cselect_b32 s82, s16, s18
	v_lshlrev_b32_e32 v97, 2, v138
	s_waitcnt lgkmcnt(0)
	v_add_f32_e32 v82, v82, v83
	v_mov_b32_e32 v83, v82
	s_nop 1
	v_permlane32_swap_b32_e32 v82, v83
	s_cselect_b32 s71, s87, s89
	s_waitcnt lgkmcnt(0)
	v_add_f32_e32 v82, v82, v83
	v_fmamk_f32 v82, v82, 0x3c800000, v154
	v_cmp_gt_f32_e32 vcc, s3, v82
	v_mul_f32_e32 v83, 0x4b800000, v82
	s_nop 0
	v_cndmask_b32_e32 v82, v82, v83, vcc
	v_rsq_f32_e32 v82, v82
	s_nop 0
	v_mul_f32_e32 v83, 0x45800000, v82
	v_cndmask_b32_e32 v82, v82, v83, vcc
	v_mul_f32_e32 v110, v204, v82
	v_lshlrev_b32_e32 v82, 7, v117
	v_mov_b32_e32 v83, v137
	v_lshl_add_u64 v[100:101], v[140:141], 0, v[82:83]
	v_lshl_add_u64 v[82:83], v[142:143], 0, v[82:83]
	global_load_dwordx4 v[118:121], v[100:101], off offset:16
	global_load_dwordx4 v[102:105], v[100:101], off
	global_load_dwordx4 v[122:125], v[82:83], off offset:16
	global_load_dwordx4 v[106:109], v[82:83], off
	global_load_dwordx4 v[158:161], v97, s[82:83] offset:16
	global_load_dwordx4 v[166:169], v97, s[82:83]
	global_load_dwordx4 v[170:173], v97, s[82:83] offset:144
	global_load_dwordx4 v[174:177], v97, s[82:83] offset:128
	v_pk_mul_f32 v[82:83], v[98:99], v[110:111] op_sel_hi:[1,0]
	v_lshl_add_u32 v97, v113, 16, s59
	s_cselect_b32 s82, s86, s88
	v_or_b32_e32 v97, v97, v117
	v_mov_b32_e32 v113, v137
	s_andn2_b64 vcc, exec, s[78:79]
	s_waitcnt vmcnt(2)
	v_pk_mul_f32 v[100:101], v[166:167], v[82:83]
	v_pk_mul_f32 v[82:83], v[88:89], v[110:111] op_sel_hi:[1,0]
	s_waitcnt vmcnt(0)
	v_pk_mul_f32 v[114:115], v[174:175], v[82:83]
	s_nop 0
	v_pk_mul_f32 v[82:83], v[106:107], v[114:115]
	s_nop 0
	v_pk_fma_f32 v[82:83], v[102:103], v[100:101], v[82:83] neg_lo:[0,0,1] neg_hi:[0,0,1]
	v_pk_mul_f32 v[100:101], v[106:107], v[100:101]
	s_nop 0
	v_pk_fma_f32 v[100:101], v[102:103], v[114:115], v[100:101]
	v_pk_mul_f32 v[102:103], v[94:95], v[110:111] op_sel_hi:[1,0]
	s_nop 0
	v_pk_mul_f32 v[106:107], v[102:103], v[168:169]
	v_pk_mul_f32 v[102:103], v[86:87], v[110:111] op_sel_hi:[1,0]
	s_nop 0
	v_pk_mul_f32 v[114:115], v[102:103], v[176:177]
	s_nop 0
	v_pk_mul_f32 v[102:103], v[108:109], v[114:115]
	s_nop 0
	v_pk_fma_f32 v[102:103], v[104:105], v[106:107], v[102:103] neg_lo:[0,0,1] neg_hi:[0,0,1]
	v_pk_mul_f32 v[104:105], v[104:105], v[114:115]
	s_nop 0
	v_pk_fma_f32 v[104:105], v[108:109], v[106:107], v[104:105]
	v_pk_mul_f32 v[106:107], v[92:93], v[110:111] op_sel_hi:[1,0]
	s_nop 0
	v_pk_mul_f32 v[108:109], v[106:107], v[158:159]
	v_pk_mul_f32 v[106:107], v[84:85], v[110:111] op_sel_hi:[1,0]
	s_nop 0
	v_pk_mul_f32 v[114:115], v[106:107], v[170:171]
	s_nop 0
	v_pk_mul_f32 v[106:107], v[122:123], v[114:115]
	v_pk_mul_f32 v[114:115], v[118:119], v[114:115]
	v_pk_fma_f32 v[106:107], v[118:119], v[108:109], v[106:107] neg_lo:[0,0,1] neg_hi:[0,0,1]
	v_pk_fma_f32 v[108:109], v[122:123], v[108:109], v[114:115]
	v_pk_mul_f32 v[114:115], v[90:91], v[110:111] op_sel_hi:[1,0]
	v_pk_mul_f32 v[110:111], v[80:81], v[110:111] op_sel_hi:[1,0]
	v_pk_mul_f32 v[114:115], v[114:115], v[160:161]
	v_pk_mul_f32 v[118:119], v[110:111], v[172:173]
	s_nop 0
	v_pk_mul_f32 v[110:111], v[124:125], v[118:119]
	v_pk_mul_f32 v[118:119], v[120:121], v[118:119]
	v_pk_fma_f32 v[110:111], v[120:121], v[114:115], v[110:111] neg_lo:[0,0,1] neg_hi:[0,0,1]
	v_pk_fma_f32 v[114:115], v[124:125], v[114:115], v[118:119]
	v_mov_b32_e32 v118, s82
	v_mov_b32_e32 v119, s71
	v_lshlrev_b32_e32 v120, 6, v97
	v_mov_b32_e32 v121, v137
	v_lshl_add_u64 v[118:119], v[120:121], 1, v[118:119]
	v_lshl_add_u64 v[122:123], v[118:119], 0, v[112:113]
	v_cvt_pk_bf16_f32 v118, v82, v83
	v_cvt_pk_bf16_f32 v119, v102, v103
	v_cvt_pk_bf16_f32 v120, v106, v107
	v_cvt_pk_bf16_f32 v121, v110, v111
	global_store_dwordx4 v[122:123], v[118:121], off
	v_mov_b32_e32 v97, v164
	s_nop 0
	v_cvt_pk_bf16_f32 v118, v100, v101
	v_cvt_pk_bf16_f32 v119, v104, v105
	v_cvt_pk_bf16_f32 v120, v108, v109
	v_cvt_pk_bf16_f32 v121, v114, v115
	global_store_dwordx4 v[122:123], v[118:121], off offset:64
	s_cbranch_vccnz .LBB0_418
	v_pk_mul_f32 v[100:101], v[100:101], v[100:101]
	s_nop 0
	v_pk_fma_f32 v[82:83], v[82:83], v[82:83], v[100:101]
	v_pk_mul_f32 v[100:101], v[104:105], v[104:105]
	v_add_f32_e32 v82, v82, v83
	v_pk_fma_f32 v[100:101], v[102:103], v[102:103], v[100:101]
	v_pk_mul_f32 v[102:103], v[108:109], v[108:109]
	v_add_f32_e32 v82, v100, v82
	v_pk_fma_f32 v[102:103], v[106:107], v[106:107], v[102:103]
	v_add_f32_e32 v82, v101, v82
	v_pk_mul_f32 v[104:105], v[114:115], v[114:115]
	v_add_f32_e32 v82, v82, v102
	v_pk_fma_f32 v[104:105], v[110:111], v[110:111], v[104:105]
	v_add_f32_e32 v82, v82, v103
	v_add_f32_e32 v82, v82, v104
	v_add_f32_e32 v82, v82, v105
	v_mov_b32_e32 v83, v82
	s_nop 1
	v_permlane16_swap_b32_e32 v82, v83
	s_waitcnt lgkmcnt(0)
	v_add_f32_e32 v82, v82, v83
	v_mov_b32_e32 v83, v82
	s_nop 1
	v_permlane32_swap_b32_e32 v82, v83
	s_waitcnt lgkmcnt(0)
	v_add_f32_e32 v82, v82, v83
	v_max_f32_e32 v83, v164, v164
	v_max_f32_e32 v97, v83, v82

; __device__ __forceinline__ float gelu_tanh(float x) { const float y = 0.7978845608028654f * (x + 0.044715f * x * x * x); return x * sigm(2.f * y); }
; __device__ __forceinline__ float grp_sum(float v) { v += __shfl_xor(v, 16); v += __shfl_xor(v, 32); return v; }
;   __device__ __forceinline__ void operator()(const pg8::f32x4 (&acc)[2][2][4][2], const pg8::Unit& u, int wr, int wc, int fr, int fq) const {
;     ...
;           const int g = gi - 8; float ss = 0.f;
; #pragma unroll
;           for (int bj = 0; bj < 2; ++bj)
; #pragma unroll
;             for (int e = 0; e < 8; ++e) { v[bj][e] = gelu_tanh(v[bj][e]); ss += v[bj][e] * v[bj][e]; }
;           const float rn = rsqrtf(grp_sum(ss) * (1.f / 64.f) + EPS);
.LBB0_419:
	s_andn2_b64 vcc, exec, s[82:83]
	s_cbranch_vccnz .LBB0_421
	v_mul_f32_e32 v82, 0x3d372713, v98
	v_mul_f32_e32 v82, v98, v82
	v_fma_f32 v82, v98, v82, v98
	v_mul_f32_e32 v82, 0x3f4c422a, v82
	v_add_f32_e32 v82, v82, v82
	v_mul_f32_e32 v82, 0xbfb8aa3b, v82
	v_exp_f32_e32 v82, v82
	v_mul_f32_e32 v83, 0x3d372713, v89
	v_mul_f32_e32 v83, v89, v83
	v_fma_f32 v83, v89, v83, v89
	v_add_f32_e32 v82, 1.0, v82
	v_rcp_f32_e32 v82, v82
	v_mul_f32_e32 v83, 0x3f4c422a, v83
	v_add_f32_e32 v83, v83, v83
	v_mul_f32_e32 v83, 0xbfb8aa3b, v83
	v_mul_f32_e32 v115, v98, v82
	v_mul_f32_e32 v82, 0x3d372713, v99
	v_mul_f32_e32 v82, v99, v82
	v_fma_f32 v82, v99, v82, v99
	v_mul_f32_e32 v82, 0x3f4c422a, v82
	v_add_f32_e32 v82, v82, v82
	v_mul_f32_e32 v82, 0xbfb8aa3b, v82
	v_exp_f32_e32 v82, v82
	v_exp_f32_e32 v83, v83
	v_and_b32_e32 v118, 0x7f, v116
	v_mov_b32_e32 v157, v137
	v_add_f32_e32 v82, 1.0, v82
	v_rcp_f32_e32 v82, v82
	v_add_f32_e32 v83, 1.0, v83
	v_rcp_f32_e32 v83, v83
	v_lshlrev_b32_e32 v118, 1, v118
	v_mul_f32_e32 v97, v99, v82
	v_mul_f32_e32 v82, 0x3d372713, v94
	v_mul_f32_e32 v82, v94, v82
	v_fma_f32 v82, v94, v82, v94
	v_mul_f32_e32 v82, 0x3f4c422a, v82
	v_add_f32_e32 v82, v82, v82
	v_mul_f32_e32 v82, 0xbfb8aa3b, v82
	v_exp_f32_e32 v82, v82
	v_mul_f32_e32 v102, v97, v97
	v_fmac_f32_e32 v102, v115, v115
	v_mov_b32_e32 v119, v137
	v_add_f32_e32 v82, 1.0, v82
	v_rcp_f32_e32 v82, v82
	v_lshl_add_u64 v[126:127], v[156:157], 2, s[56:57]
	v_mul_f32_e32 v108, v94, v82
	v_mul_f32_e32 v82, 0x3d372713, v95
	v_mul_f32_e32 v82, v95, v82
	v_fma_f32 v82, v95, v82, v95
	v_mul_f32_e32 v82, 0x3f4c422a, v82
	v_add_f32_e32 v82, v82, v82
	v_mul_f32_e32 v82, 0xbfb8aa3b, v82
	v_exp_f32_e32 v82, v82
	v_fmac_f32_e32 v102, v108, v108
	v_add_f32_e32 v82, 1.0, v82
	v_rcp_f32_e32 v82, v82
	s_nop 0
	v_mul_f32_e32 v109, v95, v82
	v_mul_f32_e32 v82, 0x3d372713, v92
	v_mul_f32_e32 v82, v92, v82
	v_fma_f32 v82, v92, v82, v92
	v_mul_f32_e32 v82, 0x3f4c422a, v82
	v_add_f32_e32 v82, v82, v82
	v_mul_f32_e32 v82, 0xbfb8aa3b, v82
	v_exp_f32_e32 v82, v82
	v_fmac_f32_e32 v102, v109, v109
	v_add_f32_e32 v82, 1.0, v82
	v_rcp_f32_e32 v82, v82
	s_nop 0
	v_mul_f32_e32 v110, v92, v82
	v_mul_f32_e32 v82, 0x3d372713, v93
	v_mul_f32_e32 v82, v93, v82
	v_fma_f32 v82, v93, v82, v93
	v_mul_f32_e32 v82, 0x3f4c422a, v82
	v_add_f32_e32 v82, v82, v82
	v_mul_f32_e32 v82, 0xbfb8aa3b, v82
	v_exp_f32_e32 v82, v82
	v_fmac_f32_e32 v102, v110, v110
	v_add_f32_e32 v82, 1.0, v82
	v_rcp_f32_e32 v82, v82
	s_nop 0
	v_mul_f32_e32 v111, v93, v82
	v_mul_f32_e32 v82, 0x3d372713, v90
	v_mul_f32_e32 v82, v90, v82
	v_fma_f32 v82, v90, v82, v90
	v_mul_f32_e32 v82, 0x3f4c422a, v82
	v_add_f32_e32 v82, v82, v82
	v_mul_f32_e32 v82, 0xbfb8aa3b, v82
	v_exp_f32_e32 v82, v82
	v_fmac_f32_e32 v102, v111, v111
	v_add_f32_e32 v82, 1.0, v82
	v_rcp_f32_e32 v82, v82
	s_nop 0
	v_mul_f32_e32 v113, v90, v82
	v_mul_f32_e32 v82, 0x3d372713, v91
	v_mul_f32_e32 v82, v91, v82
	v_fma_f32 v82, v91, v82, v91
	v_mul_f32_e32 v82, 0x3f4c422a, v82
	v_add_f32_e32 v82, v82, v82
	v_mul_f32_e32 v82, 0xbfb8aa3b, v82
	v_exp_f32_e32 v82, v82
	v_fmac_f32_e32 v102, v113, v113
	v_add_f32_e32 v82, 1.0, v82
	v_rcp_f32_e32 v82, v82
	s_nop 0
	v_mul_f32_e32 v114, v91, v82
	v_mul_f32_e32 v82, 0x3d372713, v88
	v_mul_f32_e32 v82, v88, v82
	v_fma_f32 v82, v88, v82, v88
	v_mul_f32_e32 v82, 0x3f4c422a, v82
	v_add_f32_e32 v82, v82, v82
	v_mul_f32_e32 v82, 0xbfb8aa3b, v82
	v_exp_f32_e32 v82, v82
	v_fmac_f32_e32 v102, v114, v114
	v_add_f32_e32 v82, 1.0, v82
	v_rcp_f32_e32 v82, v82
	s_nop 0
	v_pk_mul_f32 v[82:83], v[88:89], v[82:83]
	s_nop 0
	v_pk_mul_f32 v[100:101], v[82:83], v[82:83]
	s_nop 0
	v_add_f32_e32 v100, v100, v102
	v_add_f32_e32 v104, v101, v100
	v_mul_f32_e32 v100, 0x3d372713, v86
	v_mul_f32_e32 v101, 0x3d372713, v87
	v_mul_f32_e32 v100, v86, v100
	v_mul_f32_e32 v101, v87, v101
	v_fma_f32 v100, v86, v100, v86
	v_fma_f32 v101, v87, v101, v87
	v_mul_f32_e32 v100, 0x3f4c422a, v100
	v_mul_f32_e32 v101, 0x3f4c422a, v101
	v_add_f32_e32 v100, v100, v100
	v_add_f32_e32 v101, v101, v101
	v_mul_f32_e32 v100, 0xbfb8aa3b, v100
	v_mul_f32_e32 v101, 0xbfb8aa3b, v101
	v_exp_f32_e32 v100, v100
	v_exp_f32_e32 v101, v101
	v_add_f32_e32 v100, 1.0, v100
	v_add_f32_e32 v101, 1.0, v101
	v_rcp_f32_e32 v100, v100
	v_rcp_f32_e32 v101, v101
	s_nop 0
	v_pk_mul_f32 v[100:101], v[86:87], v[100:101]
	s_nop 0
	v_pk_mul_f32 v[102:103], v[100:101], v[100:101]
	s_nop 0
	v_add_f32_e32 v102, v102, v104
	v_add_f32_e32 v106, v103, v102
	v_mul_f32_e32 v102, 0x3d372713, v84
	v_mul_f32_e32 v103, 0x3d372713, v85
	v_mul_f32_e32 v102, v84, v102
	v_mul_f32_e32 v103, v85, v103
	v_fma_f32 v102, v84, v102, v84
	v_fma_f32 v103, v85, v103, v85
	v_mul_f32_e32 v102, 0x3f4c422a, v102
	v_mul_f32_e32 v103, 0x3f4c422a, v103
	v_add_f32_e32 v102, v102, v102
	v_add_f32_e32 v103, v103, v103
	v_mul_f32_e32 v102, 0xbfb8aa3b, v102
	v_mul_f32_e32 v103, 0xbfb8aa3b, v103
	v_exp_f32_e32 v102, v102
	v_exp_f32_e32 v103, v103
	v_add_f32_e32 v102, 1.0, v102
	v_add_f32_e32 v103, 1.0, v103
	v_rcp_f32_e32 v102, v102
	v_rcp_f32_e32 v103, v103
	s_nop 0
	v_pk_mul_f32 v[102:103], v[84:85], v[102:103]
	s_nop 0
	v_pk_mul_f32 v[104:105], v[102:103], v[102:103]
	s_nop 0
	v_add_f32_e32 v104, v104, v106
	v_add_f32_e32 v117, v105, v104
	v_mul_f32_e32 v104, 0x3d372713, v80
	v_mul_f32_e32 v105, 0x3d372713, v81
	v_mul_f32_e32 v104, v80, v104
	v_mul_f32_e32 v105, v81, v105
	v_fma_f32 v104, v80, v104, v80
	v_fma_f32 v105, v81, v105, v81
	v_mul_f32_e32 v104, 0x3f4c422a, v104
	v_mul_f32_e32 v105, 0x3f4c422a, v105
	v_add_f32_e32 v104, v104, v104
	v_add_f32_e32 v105, v105, v105
	v_mul_f32_e32 v104, 0xbfb8aa3b, v104
	v_mul_f32_e32 v105, 0xbfb8aa3b, v105
	v_exp_f32_e32 v104, v104
	v_exp_f32_e32 v105, v105
	v_add_f32_e32 v104, 1.0, v104
	v_add_f32_e32 v105, 1.0, v105
	v_rcp_f32_e32 v104, v104
	v_rcp_f32_e32 v105, v105
	s_nop 0
	v_pk_mul_f32 v[104:105], v[80:81], v[104:105]
	s_nop 0
	v_pk_mul_f32 v[106:107], v[104:105], v[104:105]
	s_nop 0
	v_add_f32_e32 v106, v106, v117
	v_add_f32_e32 v106, v107, v106
	v_mov_b32_e32 v107, v106
	s_nop 1
	v_permlane16_swap_b32_e32 v106, v107
	s_waitcnt lgkmcnt(0)
; __device__ __forceinline__ bf16_t f2bf(float f) { return (bf16_t)(pk2(f, 0.f) & 0xffffu); }
; __device__ __forceinline__ float grp_sum(float v) { v += __shfl_xor(v, 16); v += __shfl_xor(v, 32); return v; }
;   __device__ __forceinline__ void operator()(const pg8::f32x4 (&acc)[2][2][4][2], const pg8::Unit& u, int wr, int wc, int fr, int fq) const {
;     ...
;           const float rn = rsqrtf(grp_sum(ss) * (1.f / 64.f) + EPS);
;           bf16_t* dst = vt + ((unsigned)(g * 128 + (tok >> 7)) * 64 + 8 * fq) * 128 + (tok & 127);
; #pragma unroll
;           for (int bj = 0; bj < 2; ++bj)
; #pragma unroll
;             for (int e = 0; e < 8; ++e) dst[(32 * bj + e) * 128] = f2bf(v[bj][e] * rn * sgu_norm[g * 64 + 32 * bj + 8 * fq + e]);
	v_add_f32_e32 v106, v106, v107
	v_mov_b32_e32 v107, v106
	s_nop 1
	v_permlane32_swap_b32_e32 v106, v107
	s_waitcnt lgkmcnt(0)
	v_add_f32_e32 v106, v106, v107
	v_fmamk_f32 v106, v106, 0x3c800000, v154
	v_cmp_gt_f32_e32 vcc, s3, v106
	v_mul_f32_e32 v107, 0x4b800000, v106
	s_nop 0
	v_cndmask_b32_e32 v106, v106, v107, vcc
	v_rsq_f32_e32 v106, v106
	s_nop 0
	v_mul_f32_e32 v107, 0x45800000, v106
	v_cndmask_b32_e32 v117, v106, v107, vcc
	v_lshrrev_b32_e32 v106, 1, v116
	v_and_b32_e32 v106, 0x1ffffc0, v106
	v_add_lshl_u32 v106, v106, v203, 7
	v_mov_b32_e32 v107, v137
	v_lshl_add_u64 v[106:107], v[106:107], 1, s[50:51]
	v_lshl_add_u64 v[106:107], v[106:107], 0, v[118:119]
	global_load_dwordx4 v[118:121], v[126:127], off offset:16
	global_load_dwordx4 v[122:125], v[126:127], off
	v_mul_f32_e32 v97, v97, v117
	v_mul_f32_e32 v115, v115, v117
	v_mul_f32_e32 v82, v82, v117
	s_waitcnt vmcnt(0)
	v_mul_f32_e32 v97, v123, v97
	v_cvt_pk_bf16_f32 v97, v97, s0
	global_store_short v[106:107], v97, off offset:256
	v_mul_f32_e32 v97, v108, v117
	v_mul_f32_e32 v97, v124, v97
	v_cvt_pk_bf16_f32 v97, v97, s0
	global_store_short v[106:107], v97, off offset:512
	v_mul_f32_e32 v97, v109, v117
	v_mul_f32_e32 v97, v125, v97
	v_cvt_pk_bf16_f32 v97, v97, s0
	global_store_short v[106:107], v97, off offset:768
	v_mul_f32_e32 v97, v110, v117
	v_mul_f32_e32 v97, v118, v97
	v_cvt_pk_bf16_f32 v97, v97, s0
	global_store_short v[106:107], v97, off offset:1024
	v_mul_f32_e32 v97, v111, v117
	v_mul_f32_e32 v97, v97, v119
	v_cvt_pk_bf16_f32 v97, v97, s0
	global_store_short v[106:107], v97, off offset:1280
	v_mul_f32_e32 v97, v113, v117
	v_mul_f32_e32 v97, v97, v120
	v_cvt_pk_bf16_f32 v97, v97, s0
	global_store_short v[106:107], v97, off offset:1536
	v_mul_f32_e32 v97, v114, v117
	v_mul_f32_e32 v115, v122, v115
	v_mul_f32_e32 v97, v97, v121
	v_cvt_pk_bf16_f32 v115, v115, s0
	v_cvt_pk_bf16_f32 v97, v97, s0
	global_store_short v[106:107], v115, off
	global_store_short v[106:107], v97, off offset:1792
	global_load_dwordx4 v[108:111], v[126:127], off offset:144
	global_load_dwordx4 v[118:121], v[126:127], off offset:128
	v_add_co_u32_e32 v106, vcc, s97, v106
	v_mov_b32_e32 v97, v164
	s_nop 0
	v_addc_co_u32_e32 v107, vcc, 0, v107, vcc
	s_waitcnt vmcnt(0)
	v_mul_f32_e32 v82, v82, v118
	v_cvt_pk_bf16_f32 v82, v82, s0
	global_store_short v[106:107], v82, off
	v_mul_f32_e32 v82, v83, v117
	v_mul_f32_e32 v82, v82, v119
	v_cvt_pk_bf16_f32 v82, v82, s0
	global_store_short v[106:107], v82, off offset:256
	v_mul_f32_e32 v82, v100, v117
	v_mul_f32_e32 v82, v82, v120
	v_cvt_pk_bf16_f32 v82, v82, s0
	global_store_short v[106:107], v82, off offset:512
	v_mul_f32_e32 v82, v101, v117
	v_mul_f32_e32 v82, v82, v121
	v_cvt_pk_bf16_f32 v82, v82, s0
	global_store_short v[106:107], v82, off offset:768
	v_mul_f32_e32 v82, v102, v117
	v_mul_f32_e32 v82, v82, v108
	v_cvt_pk_bf16_f32 v82, v82, s0
	global_store_short v[106:107], v82, off offset:1024
	v_mul_f32_e32 v82, v103, v117
	v_mul_f32_e32 v82, v82, v109
	v_cvt_pk_bf16_f32 v82, v82, s0
	global_store_short v[106:107], v82, off offset:1280
	v_mul_f32_e32 v82, v104, v117
	v_mul_f32_e32 v82, v82, v110
	v_cvt_pk_bf16_f32 v82, v82, s0
	global_store_short v[106:107], v82, off offset:1536
	v_mul_f32_e32 v82, v105, v117
	v_mul_f32_e32 v82, v82, v111
	v_cvt_pk_bf16_f32 v82, v82, s0
	global_store_short v[106:107], v82, off offset:1792

; __device__ __forceinline__ float grp_sum(float v) { v += __shfl_xor(v, 16); v += __shfl_xor(v, 32); return v; }
; __device__ __forceinline__ void st8_bf16(bf16_t* dst, const float (&v)[8]) { u32x4 w; w.x = pk2(v[0], v[1]); w.y = pk2(v[2], v[3]); w.z = pk2(v[4], v[5]); w.w = pk2(v[6], v[7]); *(u32x4*)dst = w; }
;   __device__ __forceinline__ void operator()(const pg8::f32x4 (&acc)[2][2][4][2], const pg8::Unit& u, int wr, int wc, int fr, int fq) const {
;     ...
;           const bool isq = gi < 24; const int hm = isq ? gi - 16 : gi - 24;
;           const float* gn = isq ? q_norm : k_norm;
;           float ss = 0.f;
; #pragma unroll
;           for (int bj = 0; bj < 2; ++bj)
; #pragma unroll
;             for (int e = 0; e < 8; ++e) ss += v[bj][e] * v[bj][e];
;           const float rn = rsqrtf(grp_sum(ss) * (1.f / 64.f) + EPS) * (isq ? 0.125f * LOG2E : 1.f);
;           const f32x4 c0 = *(const f32x4*)(cos64 + (unsigned)pos * 32 + 8 * fq), c1 = *(const f32x4*)(cos64 + (unsigned)pos * 32 + 8 * fq + 4);
;           const f32x4 s0 = *(const f32x4*)(sin64 + (unsigned)pos * 32 + 8 * fq), s1 = *(const f32x4*)(sin64 + (unsigned)pos * 32 + 8 * fq + 4);
;           float kk = 0.f;
; #pragma unroll
;           for (int e = 0; e < 8; ++e) {
;             const float x1 = v[0][e] * rn * gn[8 * fq + e], x2 = v[1][e] * rn * gn[32 + 8 * fq + e];
;             const float cc = e < 4 ? c0[e & 3] : c1[e & 3], sn = e < 4 ? s0[e & 3] : s1[e & 3];
;             v[0][e] = x1 * cc - x2 * sn; v[1][e] = x1 * sn + x2 * cc;
;             kk += v[0][e] * v[0][e] + v[1][e] * v[1][e];
;           }
;           bf16_t* dst = (isq ? qb : kb) + ((unsigned)(bb * 8 + hm) * S + pos) * 64 + 8 * fq;
;           st8_bf16(dst, v[0]); st8_bf16(dst + 32, v[1]);
;           if (!isq) kmx_run = fmaxf(kmx_run, grp_sum(kk));
.LBB0_428:
	s_andn2_b64 vcc, exec, s[12:13]
	v_mov_b32_e32 v96, v97
	s_cbranch_vccnz .LBB0_431
	v_pk_mul_f32 v[66:67], v[80:81], v[80:81]
	v_pk_mul_f32 v[82:83], v[78:79], v[78:79]
	v_add_f32_e32 v66, v66, v67
	v_add_f32_e32 v66, v82, v66
	v_pk_mul_f32 v[84:85], v[76:77], v[76:77]
	v_add_f32_e32 v66, v83, v66
	v_add_f32_e32 v66, v84, v66
	v_pk_mul_f32 v[86:87], v[74:75], v[74:75]
	v_add_f32_e32 v66, v85, v66
	v_add_f32_e32 v66, v86, v66
	v_pk_mul_f32 v[88:89], v[72:73], v[72:73]
	v_add_f32_e32 v66, v87, v66
	v_add_f32_e32 v66, v88, v66
	v_pk_mul_f32 v[90:91], v[70:71], v[70:71]
	v_add_f32_e32 v66, v89, v66
	v_add_f32_e32 v66, v90, v66
	v_pk_mul_f32 v[92:93], v[68:69], v[68:69]
	v_add_f32_e32 v66, v91, v66
	v_add_f32_e32 v66, v92, v66
	v_pk_mul_f32 v[94:95], v[64:65], v[64:65]
	v_add_f32_e32 v66, v93, v66
	v_add_f32_e32 v66, v94, v66
	v_add_f32_e32 v66, v95, v66
	v_mov_b32_e32 v67, v66
	s_nop 1
	v_permlane16_swap_b32_e32 v66, v67
	s_and_b64 s[12:13], s[6:7], exec
	s_cselect_b32 s13, s17, s19
	s_cselect_b32 s12, s16, s18
	v_lshlrev_b32_e32 v101, 2, v138
	s_waitcnt lgkmcnt(0)
	v_add_f32_e32 v66, v66, v67
	v_mov_b32_e32 v67, v66
	s_nop 1
	v_permlane32_swap_b32_e32 v66, v67
	v_mov_b32_e32 v113, v137
	s_waitcnt lgkmcnt(0)
	v_add_f32_e32 v66, v66, v67
	v_fmamk_f32 v66, v66, 0x3c800000, v154
	v_cmp_gt_f32_e32 vcc, s3, v66
	v_mul_f32_e32 v67, 0x4b800000, v66
	s_nop 0
	v_cndmask_b32_e32 v66, v66, v67, vcc
	v_rsq_f32_e32 v66, v66
	s_nop 0
	v_mul_f32_e32 v67, 0x45800000, v66
	v_cndmask_b32_e32 v66, v66, v67, vcc
	v_mul_f32_e32 v96, v204, v66
	v_lshlrev_b32_e32 v66, 7, v100
	v_mov_b32_e32 v67, v137
	v_lshl_add_u64 v[82:83], v[140:141], 0, v[66:67]
	v_lshl_add_u64 v[66:67], v[142:143], 0, v[66:67]
	global_load_dwordx4 v[92:95], v[82:83], off offset:16
	global_load_dwordx4 v[84:87], v[82:83], off
	global_load_dwordx4 v[102:105], v[66:67], off offset:16
	global_load_dwordx4 v[88:91], v[66:67], off
	global_load_dwordx4 v[106:109], v101, s[12:13] offset:16
	global_load_dwordx4 v[114:117], v101, s[12:13]
	global_load_dwordx4 v[118:121], v101, s[12:13] offset:144
	global_load_dwordx4 v[122:125], v101, s[12:13] offset:128
	v_pk_mul_f32 v[66:67], v[80:81], v[96:97] op_sel_hi:[1,0]
	s_cselect_b32 s12, s87, s89
	s_cselect_b32 s13, s86, s88
	v_mov_b32_e32 v101, v137
	s_andn2_b64 vcc, exec, s[78:79]
	s_waitcnt vmcnt(2)
	v_pk_mul_f32 v[82:83], v[114:115], v[66:67]
	v_pk_mul_f32 v[66:67], v[72:73], v[96:97] op_sel_hi:[1,0]
	s_waitcnt vmcnt(0)
	v_pk_mul_f32 v[110:111], v[122:123], v[66:67]
	s_nop 0
	v_pk_mul_f32 v[66:67], v[88:89], v[110:111]
	s_nop 0
	v_pk_fma_f32 v[66:67], v[84:85], v[82:83], v[66:67] neg_lo:[0,0,1] neg_hi:[0,0,1]
	v_pk_mul_f32 v[82:83], v[88:89], v[82:83]
	s_nop 0
	v_pk_fma_f32 v[82:83], v[84:85], v[110:111], v[82:83]
	v_pk_mul_f32 v[84:85], v[78:79], v[96:97] op_sel_hi:[1,0]
	s_nop 0
	v_pk_mul_f32 v[88:89], v[84:85], v[116:117]
	v_pk_mul_f32 v[84:85], v[70:71], v[96:97] op_sel_hi:[1,0]
	s_nop 0
	v_pk_mul_f32 v[110:111], v[84:85], v[124:125]
	s_nop 0
	v_pk_mul_f32 v[84:85], v[90:91], v[110:111]
	s_nop 0
	v_pk_fma_f32 v[84:85], v[86:87], v[88:89], v[84:85] neg_lo:[0,0,1] neg_hi:[0,0,1]
	v_pk_mul_f32 v[86:87], v[86:87], v[110:111]
	s_nop 0
	v_pk_fma_f32 v[86:87], v[90:91], v[88:89], v[86:87]
	v_pk_mul_f32 v[88:89], v[76:77], v[96:97] op_sel_hi:[1,0]
	s_nop 0
	v_pk_mul_f32 v[90:91], v[88:89], v[106:107]
	v_pk_mul_f32 v[88:89], v[68:69], v[96:97] op_sel_hi:[1,0]
	s_nop 0
	v_pk_mul_f32 v[106:107], v[88:89], v[118:119]
	s_nop 0
	v_pk_mul_f32 v[88:89], v[102:103], v[106:107]
	s_nop 0
	v_pk_fma_f32 v[88:89], v[92:93], v[90:91], v[88:89] neg_lo:[0,0,1] neg_hi:[0,0,1]
	v_pk_mul_f32 v[92:93], v[92:93], v[106:107]
	s_nop 0
	v_pk_fma_f32 v[90:91], v[102:103], v[90:91], v[92:93]
	v_pk_mul_f32 v[92:93], v[74:75], v[96:97] op_sel_hi:[1,0]
	s_nop 0
	v_pk_mul_f32 v[102:103], v[92:93], v[108:109]
	v_pk_mul_f32 v[92:93], v[64:65], v[96:97] op_sel_hi:[1,0]
	v_lshl_add_u32 v96, v99, 16, s59
	v_pk_mul_f32 v[106:107], v[92:93], v[120:121]
	v_or_b32_e32 v96, v96, v100
	v_pk_mul_f32 v[92:93], v[104:105], v[106:107]
	v_lshlrev_b32_e32 v100, 6, v96
	v_pk_fma_f32 v[92:93], v[94:95], v[102:103], v[92:93] neg_lo:[0,0,1] neg_hi:[0,0,1]
	v_pk_mul_f32 v[94:95], v[94:95], v[106:107]
	v_mov_b32_e32 v96, v97
	v_pk_fma_f32 v[94:95], v[104:105], v[102:103], v[94:95]
	v_mov_b32_e32 v102, s13
	v_mov_b32_e32 v103, s12
	v_lshl_add_u64 v[100:101], v[100:101], 1, v[102:103]
	v_lshl_add_u64 v[104:105], v[100:101], 0, v[112:113]
	v_cvt_pk_bf16_f32 v100, v66, v67
	v_cvt_pk_bf16_f32 v101, v84, v85
	v_cvt_pk_bf16_f32 v102, v88, v89
	v_cvt_pk_bf16_f32 v103, v92, v93
	global_store_dwordx4 v[104:105], v[100:103], off
	s_nop 1
	v_cvt_pk_bf16_f32 v100, v82, v83
	v_cvt_pk_bf16_f32 v101, v86, v87
	v_cvt_pk_bf16_f32 v102, v90, v91
	v_cvt_pk_bf16_f32 v103, v94, v95
	global_store_dwordx4 v[104:105], v[100:103], off offset:64
	s_cbranch_vccnz .LBB0_431
	v_pk_mul_f32 v[82:83], v[82:83], v[82:83]
	s_nop 0
	v_pk_fma_f32 v[66:67], v[66:67], v[66:67], v[82:83]
	v_pk_mul_f32 v[82:83], v[86:87], v[86:87]
	v_add_f32_e32 v66, v66, v67
	v_pk_fma_f32 v[82:83], v[84:85], v[84:85], v[82:83]
	v_pk_mul_f32 v[84:85], v[90:91], v[90:91]
	v_add_f32_e32 v66, v82, v66
	v_pk_fma_f32 v[84:85], v[88:89], v[88:89], v[84:85]
	v_add_f32_e32 v66, v83, v66
	v_pk_mul_f32 v[86:87], v[94:95], v[94:95]
	v_add_f32_e32 v66, v66, v84
	v_pk_fma_f32 v[86:87], v[92:93], v[92:93], v[86:87]
	v_add_f32_e32 v66, v66, v85
	v_add_f32_e32 v66, v66, v86
	v_add_f32_e32 v66, v66, v87
	v_mov_b32_e32 v67, v66
	s_nop 1
	v_permlane16_swap_b32_e32 v66, v67
	s_waitcnt lgkmcnt(0)
	v_add_f32_e32 v66, v66, v67
	v_mov_b32_e32 v67, v66
	s_nop 1
	v_permlane32_swap_b32_e32 v66, v67
	s_waitcnt lgkmcnt(0)
	v_add_f32_e32 v66, v66, v67
	v_max_f32_e32 v67, v97, v97
	v_max_f32_e32 v96, v67, v66

; __device__ __forceinline__ float gelu_tanh(float x) { const float y = 0.7978845608028654f * (x + 0.044715f * x * x * x); return x * sigm(2.f * y); }
; __device__ __forceinline__ float grp_sum(float v) { v += __shfl_xor(v, 16); v += __shfl_xor(v, 32); return v; }
;   __device__ __forceinline__ void operator()(const pg8::f32x4 (&acc)[2][2][4][2], const pg8::Unit& u, int wr, int wc, int fr, int fq) const {
;     ...
;           const int g = gi - 8; float ss = 0.f;
; #pragma unroll
;           for (int bj = 0; bj < 2; ++bj)
; #pragma unroll
;             for (int e = 0; e < 8; ++e) { v[bj][e] = gelu_tanh(v[bj][e]); ss += v[bj][e] * v[bj][e]; }
;           const float rn = rsqrtf(grp_sum(ss) * (1.f / 64.f) + EPS);
.LBB0_432:
	s_andn2_b64 vcc, exec, s[12:13]
	s_cbranch_vccnz .LBB0_434
	v_mul_f32_e32 v66, 0x3d372713, v80
	v_mul_f32_e32 v66, v80, v66
	v_fma_f32 v66, v80, v66, v80
	v_mul_f32_e32 v66, 0x3f4c422a, v66
	v_add_f32_e32 v66, v66, v66
	v_mul_f32_e32 v66, 0xbfb8aa3b, v66
	v_exp_f32_e32 v66, v66
	v_mul_f32_e32 v67, 0x3d372713, v73
	v_mul_f32_e32 v67, v73, v67
	v_fma_f32 v67, v73, v67, v73
	v_add_f32_e32 v66, 1.0, v66
	v_rcp_f32_e32 v66, v66
	v_mul_f32_e32 v67, 0x3f4c422a, v67
	v_add_f32_e32 v67, v67, v67
	v_mul_f32_e32 v67, 0xbfb8aa3b, v67
	v_mul_f32_e32 v99, v80, v66
	v_mul_f32_e32 v66, 0x3d372713, v81
	v_mul_f32_e32 v66, v81, v66
	v_fma_f32 v66, v81, v66, v81
	v_mul_f32_e32 v66, 0x3f4c422a, v66
	v_add_f32_e32 v66, v66, v66
	v_mul_f32_e32 v66, 0xbfb8aa3b, v66
	v_exp_f32_e32 v66, v66
	v_exp_f32_e32 v67, v67
	v_mov_b32_e32 v157, v137
	v_mov_b32_e32 v101, v137
	v_add_f32_e32 v66, 1.0, v66
	v_rcp_f32_e32 v66, v66
	v_add_f32_e32 v67, 1.0, v67
	v_rcp_f32_e32 v67, v67
	v_lshl_add_u64 v[108:109], v[156:157], 2, s[56:57]
	v_mul_f32_e32 v90, v81, v66
	v_mul_f32_e32 v66, 0x3d372713, v78
	v_mul_f32_e32 v66, v78, v66
	v_fma_f32 v66, v78, v66, v78
	v_mul_f32_e32 v66, 0x3f4c422a, v66
	v_add_f32_e32 v66, v66, v66
	v_mul_f32_e32 v66, 0xbfb8aa3b, v66
	v_exp_f32_e32 v66, v66
	v_mul_f32_e32 v84, v90, v90
	v_fmac_f32_e32 v84, v99, v99
	v_add_f32_e32 v66, 1.0, v66
	v_rcp_f32_e32 v66, v66
	s_nop 0
	v_mul_f32_e32 v91, v78, v66
	v_mul_f32_e32 v66, 0x3d372713, v79
	v_mul_f32_e32 v66, v79, v66
	v_fma_f32 v66, v79, v66, v79
	v_mul_f32_e32 v66, 0x3f4c422a, v66
	v_add_f32_e32 v66, v66, v66
	v_mul_f32_e32 v66, 0xbfb8aa3b, v66
	v_exp_f32_e32 v66, v66
	v_fmac_f32_e32 v84, v91, v91
	v_add_f32_e32 v66, 1.0, v66
	v_rcp_f32_e32 v66, v66
	s_nop 0
	v_mul_f32_e32 v92, v79, v66
	v_mul_f32_e32 v66, 0x3d372713, v76
	v_mul_f32_e32 v66, v76, v66
	v_fma_f32 v66, v76, v66, v76
	v_mul_f32_e32 v66, 0x3f4c422a, v66
	v_add_f32_e32 v66, v66, v66
	v_mul_f32_e32 v66, 0xbfb8aa3b, v66
	v_exp_f32_e32 v66, v66
	v_fmac_f32_e32 v84, v92, v92
	v_add_f32_e32 v66, 1.0, v66
	v_rcp_f32_e32 v66, v66
	s_nop 0
	v_mul_f32_e32 v93, v76, v66
	v_mul_f32_e32 v66, 0x3d372713, v77
	v_mul_f32_e32 v66, v77, v66
	v_fma_f32 v66, v77, v66, v77
	v_mul_f32_e32 v66, 0x3f4c422a, v66
	v_add_f32_e32 v66, v66, v66
	v_mul_f32_e32 v66, 0xbfb8aa3b, v66
	v_exp_f32_e32 v66, v66
	v_fmac_f32_e32 v84, v93, v93
	v_add_f32_e32 v66, 1.0, v66
	v_rcp_f32_e32 v66, v66
	s_nop 0
	v_mul_f32_e32 v94, v77, v66
	v_mul_f32_e32 v66, 0x3d372713, v74
	v_mul_f32_e32 v66, v74, v66
	v_fma_f32 v66, v74, v66, v74
	v_mul_f32_e32 v66, 0x3f4c422a, v66
	v_add_f32_e32 v66, v66, v66
	v_mul_f32_e32 v66, 0xbfb8aa3b, v66
	v_exp_f32_e32 v66, v66
	v_fmac_f32_e32 v84, v94, v94
	v_add_f32_e32 v66, 1.0, v66
	v_rcp_f32_e32 v66, v66
	s_nop 0
	v_mul_f32_e32 v95, v74, v66
	v_mul_f32_e32 v66, 0x3d372713, v75
	v_mul_f32_e32 v66, v75, v66
	v_fma_f32 v66, v75, v66, v75
	v_mul_f32_e32 v66, 0x3f4c422a, v66
	v_add_f32_e32 v66, v66, v66
	v_mul_f32_e32 v66, 0xbfb8aa3b, v66
	v_exp_f32_e32 v66, v66
	v_fmac_f32_e32 v84, v95, v95
	v_add_f32_e32 v66, 1.0, v66
	v_rcp_f32_e32 v66, v66
	s_nop 0
	v_mul_f32_e32 v96, v75, v66
	v_mul_f32_e32 v66, 0x3d372713, v72
	v_mul_f32_e32 v66, v72, v66
	v_fma_f32 v66, v72, v66, v72
	v_mul_f32_e32 v66, 0x3f4c422a, v66
	v_add_f32_e32 v66, v66, v66
	v_mul_f32_e32 v66, 0xbfb8aa3b, v66
	v_exp_f32_e32 v66, v66
	v_fmac_f32_e32 v84, v96, v96
	v_add_f32_e32 v66, 1.0, v66
	v_rcp_f32_e32 v66, v66
	s_nop 0
	v_pk_mul_f32 v[66:67], v[72:73], v[66:67]
	s_nop 0
	v_pk_mul_f32 v[82:83], v[66:67], v[66:67]
	s_nop 0
	v_add_f32_e32 v82, v82, v84
	v_add_f32_e32 v86, v83, v82
	v_mul_f32_e32 v82, 0x3d372713, v70
	v_mul_f32_e32 v83, 0x3d372713, v71
	v_mul_f32_e32 v82, v70, v82
	v_mul_f32_e32 v83, v71, v83
	v_fma_f32 v82, v70, v82, v70
	v_fma_f32 v83, v71, v83, v71
	v_mul_f32_e32 v82, 0x3f4c422a, v82
	v_mul_f32_e32 v83, 0x3f4c422a, v83
	v_add_f32_e32 v82, v82, v82
	v_add_f32_e32 v83, v83, v83
	v_mul_f32_e32 v82, 0xbfb8aa3b, v82
	v_mul_f32_e32 v83, 0xbfb8aa3b, v83
	v_exp_f32_e32 v82, v82
	v_exp_f32_e32 v83, v83
	v_add_f32_e32 v82, 1.0, v82
	v_add_f32_e32 v83, 1.0, v83
	v_rcp_f32_e32 v82, v82
	v_rcp_f32_e32 v83, v83
	s_nop 0
	v_pk_mul_f32 v[82:83], v[70:71], v[82:83]
	s_nop 0
	v_pk_mul_f32 v[84:85], v[82:83], v[82:83]
	s_nop 0
	v_add_f32_e32 v84, v84, v86
	v_add_f32_e32 v88, v85, v84
	v_mul_f32_e32 v84, 0x3d372713, v68
	v_mul_f32_e32 v85, 0x3d372713, v69
	v_mul_f32_e32 v84, v68, v84
	v_mul_f32_e32 v85, v69, v85
	v_fma_f32 v84, v68, v84, v68
	v_fma_f32 v85, v69, v85, v69
	v_mul_f32_e32 v84, 0x3f4c422a, v84
	v_mul_f32_e32 v85, 0x3f4c422a, v85
	v_add_f32_e32 v84, v84, v84
	v_add_f32_e32 v85, v85, v85
	v_mul_f32_e32 v84, 0xbfb8aa3b, v84
	v_mul_f32_e32 v85, 0xbfb8aa3b, v85
	v_exp_f32_e32 v84, v84
	v_exp_f32_e32 v85, v85
	v_add_f32_e32 v84, 1.0, v84
	v_add_f32_e32 v85, 1.0, v85
	v_rcp_f32_e32 v84, v84
	v_rcp_f32_e32 v85, v85
	s_nop 0
	v_pk_mul_f32 v[84:85], v[68:69], v[84:85]
	s_nop 0
	v_pk_mul_f32 v[86:87], v[84:85], v[84:85]
	s_nop 0
	v_add_f32_e32 v86, v86, v88
	v_add_f32_e32 v100, v87, v86
	v_mul_f32_e32 v86, 0x3d372713, v64
	v_mul_f32_e32 v87, 0x3d372713, v65
	v_mul_f32_e32 v86, v64, v86
	v_mul_f32_e32 v87, v65, v87
	v_fma_f32 v86, v64, v86, v64
	v_fma_f32 v87, v65, v87, v65
	v_mul_f32_e32 v86, 0x3f4c422a, v86
	v_mul_f32_e32 v87, 0x3f4c422a, v87
	v_add_f32_e32 v86, v86, v86
	v_add_f32_e32 v87, v87, v87
	v_mul_f32_e32 v86, 0xbfb8aa3b, v86
	v_mul_f32_e32 v87, 0xbfb8aa3b, v87
	v_exp_f32_e32 v86, v86
	v_exp_f32_e32 v87, v87
	v_add_f32_e32 v86, 1.0, v86
	v_add_f32_e32 v87, 1.0, v87
	v_rcp_f32_e32 v86, v86
	v_rcp_f32_e32 v87, v87
	s_nop 0
	v_pk_mul_f32 v[86:87], v[64:65], v[86:87]
	s_nop 0
	v_pk_mul_f32 v[88:89], v[86:87], v[86:87]
	s_nop 0
	v_add_f32_e32 v88, v88, v100
	v_add_f32_e32 v88, v89, v88
	v_mov_b32_e32 v89, v88
	s_nop 1
	v_permlane16_swap_b32_e32 v88, v89
	v_and_b32_e32 v100, 0x7f, v98
	v_lshlrev_b32_e32 v100, 1, v100
	s_waitcnt lgkmcnt(0)
; __device__ __forceinline__ bf16_t f2bf(float f) { return (bf16_t)(pk2(f, 0.f) & 0xffffu); }
; __device__ __forceinline__ float grp_sum(float v) { v += __shfl_xor(v, 16); v += __shfl_xor(v, 32); return v; }
;   __device__ __forceinline__ void operator()(const pg8::f32x4 (&acc)[2][2][4][2], const pg8::Unit& u, int wr, int wc, int fr, int fq) const {
;     ...
;           const float rn = rsqrtf(grp_sum(ss) * (1.f / 64.f) + EPS);
;           bf16_t* dst = vt + ((unsigned)(g * 128 + (tok >> 7)) * 64 + 8 * fq) * 128 + (tok & 127);
; #pragma unroll
;           for (int bj = 0; bj < 2; ++bj)
; #pragma unroll
;             for (int e = 0; e < 8; ++e) dst[(32 * bj + e) * 128] = f2bf(v[bj][e] * rn * sgu_norm[g * 64 + 32 * bj + 8 * fq + e]);
	v_add_f32_e32 v88, v88, v89
	v_mov_b32_e32 v89, v88
	s_nop 1
	v_permlane32_swap_b32_e32 v88, v89
	s_waitcnt lgkmcnt(0)
	v_add_f32_e32 v88, v88, v89
	v_fmamk_f32 v88, v88, 0x3c800000, v154
	v_cmp_gt_f32_e32 vcc, s3, v88
	v_mul_f32_e32 v89, 0x4b800000, v88
	s_nop 0
	v_cndmask_b32_e32 v88, v88, v89, vcc
	v_rsq_f32_e32 v88, v88
	s_nop 0
	v_mul_f32_e32 v89, 0x45800000, v88
	v_cndmask_b32_e32 v110, v88, v89, vcc
	v_lshrrev_b32_e32 v88, 1, v98
	v_and_b32_e32 v88, 0x1ffffc0, v88
	v_add_lshl_u32 v88, v88, v203, 7
	v_mov_b32_e32 v89, v137
	v_lshl_add_u64 v[88:89], v[88:89], 1, s[50:51]
	v_lshl_add_u64 v[88:89], v[88:89], 0, v[100:101]
	global_load_dwordx4 v[100:103], v[108:109], off offset:16
	global_load_dwordx4 v[104:107], v[108:109], off
	v_mul_f32_e32 v90, v90, v110
	v_mul_f32_e32 v99, v99, v110
	v_mul_f32_e32 v66, v66, v110
	s_waitcnt vmcnt(0)
	v_mul_f32_e32 v90, v105, v90
	v_cvt_pk_bf16_f32 v90, v90, s0
	global_store_short v[88:89], v90, off offset:256
	v_mul_f32_e32 v90, v91, v110
	v_mul_f32_e32 v90, v106, v90
	v_cvt_pk_bf16_f32 v90, v90, s0
	global_store_short v[88:89], v90, off offset:512
	v_mul_f32_e32 v90, v92, v110
	v_mul_f32_e32 v90, v107, v90
	v_cvt_pk_bf16_f32 v90, v90, s0
	global_store_short v[88:89], v90, off offset:768
	v_mul_f32_e32 v90, v93, v110
	v_mul_f32_e32 v90, v100, v90
	v_cvt_pk_bf16_f32 v90, v90, s0
	global_store_short v[88:89], v90, off offset:1024
	v_mul_f32_e32 v90, v94, v110
	v_mul_f32_e32 v90, v90, v101
	v_cvt_pk_bf16_f32 v90, v90, s0
	global_store_short v[88:89], v90, off offset:1280
	v_mul_f32_e32 v90, v95, v110
	v_mul_f32_e32 v90, v90, v102
	v_cvt_pk_bf16_f32 v90, v90, s0
	global_store_short v[88:89], v90, off offset:1536
	v_mul_f32_e32 v90, v96, v110
	v_mul_f32_e32 v99, v104, v99
	v_mul_f32_e32 v90, v90, v103
	v_cvt_pk_bf16_f32 v99, v99, s0
	v_cvt_pk_bf16_f32 v90, v90, s0
	global_store_short v[88:89], v99, off
	global_store_short v[88:89], v90, off offset:1792
	global_load_dwordx4 v[90:93], v[108:109], off offset:144
	s_nop 0
	global_load_dwordx4 v[100:103], v[108:109], off offset:128
	v_add_co_u32_e32 v88, vcc, s97, v88
	v_mov_b32_e32 v96, v97
	s_nop 0
	v_addc_co_u32_e32 v89, vcc, 0, v89, vcc
	s_waitcnt vmcnt(0)
	v_mul_f32_e32 v66, v66, v100
	v_cvt_pk_bf16_f32 v66, v66, s0
	global_store_short v[88:89], v66, off
	v_mul_f32_e32 v66, v67, v110
	v_mul_f32_e32 v66, v66, v101
	v_cvt_pk_bf16_f32 v66, v66, s0
	global_store_short v[88:89], v66, off offset:256
	v_mul_f32_e32 v66, v82, v110
	v_mul_f32_e32 v66, v66, v102
	v_cvt_pk_bf16_f32 v66, v66, s0
	global_store_short v[88:89], v66, off offset:512
	v_mul_f32_e32 v66, v83, v110
	v_mul_f32_e32 v66, v66, v103
	v_cvt_pk_bf16_f32 v66, v66, s0
	global_store_short v[88:89], v66, off offset:768
	v_mul_f32_e32 v66, v84, v110
	v_mul_f32_e32 v66, v66, v90
	v_cvt_pk_bf16_f32 v66, v66, s0
	global_store_short v[88:89], v66, off offset:1024
	v_mul_f32_e32 v66, v85, v110
	v_mul_f32_e32 v66, v66, v91
	v_cvt_pk_bf16_f32 v66, v66, s0
	global_store_short v[88:89], v66, off offset:1280
	v_mul_f32_e32 v66, v86, v110
	v_mul_f32_e32 v66, v66, v92
	v_cvt_pk_bf16_f32 v66, v66, s0
	global_store_short v[88:89], v66, off offset:1536
	v_mul_f32_e32 v66, v87, v110
	v_mul_f32_e32 v66, v66, v93
	v_cvt_pk_bf16_f32 v66, v66, s0
	global_store_short v[88:89], v66, off offset:1792

; __device__ __forceinline__ bf16_t f2bf(float f) { return (bf16_t)(pk2(f, 0.f) & 0xffffu); }
; __device__ __forceinline__ float grp_sum(float v) { v += __shfl_xor(v, 16); v += __shfl_xor(v, 32); return v; }
;   __device__ __forceinline__ void operator()(const pg8::f32x4 (&acc)[2][2][4][2], const pg8::Unit& u, int wr, int wc, int fr, int fq) const {
;     ...
;       for (int m = 0; m < 4; ++m) { const f32x4 a = *(const f32x4*)(ssq + (unsigned)(row0 + ai * 128 + m * 16) * 16 + 4 * fq); rs[m] = (a[0] + a[1]) + (a[2] + a[3]); }
; #pragma unroll
;       for (int m = 0; m < 4; ++m) rs[m] = rsqrtf(grp_sum(rs[m]) * (1.f / 1024.f) + EPS);
; #pragma unroll
;       for (int m = 0; m < 4; ++m) {
;         const int tok = row0 + ai * 128 + m * 16, bb = tok >> 13, pos = tok & (S - 1);
;         float v[2][8];
; #pragma unroll
;         for (int bj = 0; bj < 2; ++bj)
; #pragma unroll
;           for (int n = 0; n < 2; ++n)
; #pragma unroll
;             for (int c = 0; c < 4; ++c) v[bj][4 * n + c] = acc[ai][bj][m][n][c] * rs[m];
;     ...
;           const int hv = (gi - 32) >> 1, eh = (gi - 32) & 1;
;           bf16_t* dst = vtb + ((unsigned)(bb * 4 + hv) * 128 + 64 * eh + 8 * fq) * S + pos;
; #pragma unroll
;           for (int bj = 0; bj < 2; ++bj)
; #pragma unroll
;             for (int e = 0; e < 8; ++e) dst[(unsigned)(32 * bj + e) * S] = f2bf(v[bj][e]);
.LBB0_437:
	s_nop 1
	v_add_u32_e32 v64, 0x800, v136
	v_mov_b32_e32 v65, v137
	v_lshl_add_u64 v[64:65], v[64:65], 2, v[144:145]
	global_load_dwordx4 v[232:235], v[64:65], off
	global_load_dwordx4 v[236:239], v[64:65], off offset:1024
	global_load_dwordx4 v[240:243], v[64:65], off offset:2048
	global_load_dwordx4 v[64:67], v[64:65], off offset:3072
	v_add_u32_e32 v86, 0x80, v205
	s_mov_b64 s[82:83], -1
	s_waitcnt vmcnt(0)
	v_mov_b32_e32 v68, v233
	v_mov_b32_e32 v69, v234
	v_mov_b32_e32 v233, v235
	v_pk_add_f32 v[68:69], v[68:69], v[232:233]
	v_mov_b32_e32 v70, v237
	v_mov_b32_e32 v71, v238
	v_mov_b32_e32 v237, v239
	v_pk_add_f32 v[70:71], v[70:71], v[236:237]
	v_add_u32_e32 v136, 0xb00, v136
	v_mov_b32_e32 v72, v241
	v_mov_b32_e32 v73, v242
	v_mov_b32_e32 v241, v243
	v_pk_add_f32 v[72:73], v[72:73], v[240:241]
	v_mov_b32_e32 v74, v65
	v_mov_b32_e32 v75, v66
	v_mov_b32_e32 v65, v67
	v_mov_b32_e32 v66, v70
	v_mov_b32_e32 v67, v68
	v_mov_b32_e32 v68, v71
	v_pk_add_f32 v[66:67], v[66:67], v[68:69]
	v_mov_b32_e32 v69, v67
	s_nop 1
	v_permlane16_swap_b32_e32 v67, v69
	v_mov_b32_e32 v68, v66
	s_nop 1
	v_permlane16_swap_b32_e32 v66, v68
	v_pk_add_f32 v[64:65], v[74:75], v[64:65]
	s_waitcnt lgkmcnt(0)
	v_pk_add_f32 v[66:67], v[66:67], v[68:69]
	v_mov_b32_e32 v69, v67
	s_nop 1
	v_permlane32_swap_b32_e32 v67, v69
	v_mov_b32_e32 v68, v66
	s_nop 1
	v_permlane32_swap_b32_e32 v66, v68
	s_waitcnt lgkmcnt(0)
	v_pk_add_f32 v[66:67], v[66:67], v[68:69]
	s_nop 0
	v_pk_fma_f32 v[68:69], v[66:67], s[66:67], v[154:155] op_sel_hi:[1,0,0]
	s_nop 0
	v_mul_f32_e32 v66, 0x4b800000, v69
	v_cmp_gt_f32_e32 vcc, s3, v69
	v_cmp_gt_f32_e64 s[12:13], s3, v68
	s_nop 0
	v_cndmask_b32_e32 v66, v69, v66, vcc
	v_rsq_f32_e32 v66, v66
	s_nop 0
	v_mul_f32_e32 v67, 0x45800000, v66
	v_cndmask_b32_e32 v74, v66, v67, vcc
	v_mov_b32_e32 v66, v64
	v_mov_b32_e32 v67, v72
	v_mov_b32_e32 v72, v65
	v_pk_add_f32 v[64:65], v[66:67], v[72:73]
	v_mov_b32_e32 v67, v65
	s_nop 1
	v_permlane16_swap_b32_e32 v65, v67
	v_mov_b32_e32 v66, v64
	s_nop 1
	v_permlane16_swap_b32_e32 v64, v66
	v_pk_mul_f32 v[70:71], v[60:61], v[74:75] op_sel_hi:[1,0]
	v_pk_mul_f32 v[62:63], v[62:63], v[74:75] op_sel_hi:[1,0]
	v_pk_mul_f32 v[60:61], v[56:57], v[74:75] op_sel_hi:[1,0]
	v_pk_mul_f32 v[58:59], v[58:59], v[74:75] op_sel_hi:[1,0]
	s_waitcnt lgkmcnt(0)
	v_pk_add_f32 v[64:65], v[64:65], v[66:67]
	ds_bpermute_b32 v67, v202, v65
	ds_bpermute_b32 v66, v202, v64
	v_pk_mul_f32 v[56:57], v[52:53], v[74:75] op_sel_hi:[1,0]
	v_pk_mul_f32 v[54:55], v[54:55], v[74:75] op_sel_hi:[1,0]
	v_pk_mul_f32 v[52:53], v[48:49], v[74:75] op_sel_hi:[1,0]
	v_pk_mul_f32 v[48:49], v[50:51], v[74:75] op_sel_hi:[1,0]
	s_and_b64 vcc, exec, s[10:11]
	s_cbranch_vccnz .LBB0_448
	s_and_b64 vcc, exec, s[8:9]
	s_cbranch_vccnz .LBB0_445
	v_ashrrev_i32_e32 v87, 13, v86
	v_and_b32_e32 v88, 0x1fff, v86
	s_andn2_b64 vcc, exec, s[80:81]
	s_cbranch_vccnz .LBB0_441
	s_lshl_b32 s71, s69, 13
	v_lshl_add_u32 v50, v87, 22, s71
	v_or_b32_e32 v136, v50, v180
	v_lshl_add_u64 v[50:51], v[136:137], 1, s[48:49]
	v_lshlrev_b32_e32 v136, 1, v88
	v_lshl_add_u64 v[50:51], v[50:51], 0, v[136:137]
	v_cvt_pk_bf16_f32 v69, v70, s0
	v_add_co_u32_e32 v72, vcc, 0x4000, v50
	global_store_short v[50:51], v69, off
	v_cvt_pk_bf16_f32 v69, v71, s0
	v_addc_co_u32_e32 v73, vcc, 0, v51, vcc
	global_store_short v[72:73], v69, off
	v_add_co_u32_e32 v72, vcc, 0x8000, v50
	v_cvt_pk_bf16_f32 v69, v62, s0
	s_nop 0
	v_addc_co_u32_e32 v73, vcc, 0, v51, vcc
	global_store_short v[72:73], v69, off
	v_add_co_u32_e32 v72, vcc, 0xc000, v50
	v_cvt_pk_bf16_f32 v69, v63, s0
	s_nop 0
	v_addc_co_u32_e32 v73, vcc, 0, v51, vcc
	s_mov_b32 s71, 0x10000
	global_store_short v[72:73], v69, off
	v_add_co_u32_e32 v72, vcc, s71, v50
	v_cvt_pk_bf16_f32 v69, v60, s0
	s_nop 0
	v_addc_co_u32_e32 v73, vcc, 0, v51, vcc
	s_mov_b32 s71, 0x14000
	global_store_short v[72:73], v69, off
	v_add_co_u32_e32 v72, vcc, s71, v50
	v_cvt_pk_bf16_f32 v69, v61, s0
	s_nop 0
	v_addc_co_u32_e32 v73, vcc, 0, v51, vcc
	s_mov_b32 s71, 0x18000
	global_store_short v[72:73], v69, off
	v_add_co_u32_e32 v72, vcc, s71, v50
	v_cvt_pk_bf16_f32 v69, v58, s0
	s_nop 0
	v_addc_co_u32_e32 v73, vcc, 0, v51, vcc
	s_mov_b32 s71, 0x1c000
	global_store_short v[72:73], v69, off
	v_add_co_u32_e32 v72, vcc, s71, v50
	v_cvt_pk_bf16_f32 v69, v59, s0
	s_nop 0
	v_addc_co_u32_e32 v73, vcc, 0, v51, vcc
	s_mov_b32 s71, 0x80000
	global_store_short v[72:73], v69, off
	v_add_co_u32_e32 v72, vcc, s71, v50
	v_cvt_pk_bf16_f32 v69, v56, s0
	s_nop 0
	v_addc_co_u32_e32 v73, vcc, 0, v51, vcc
	s_mov_b32 s71, 0x84000
	global_store_short v[72:73], v69, off
	v_add_co_u32_e32 v72, vcc, s71, v50
	v_cvt_pk_bf16_f32 v69, v57, s0
	s_nop 0
	v_addc_co_u32_e32 v73, vcc, 0, v51, vcc
	s_mov_b32 s71, 0x88000
	global_store_short v[72:73], v69, off
	v_add_co_u32_e32 v72, vcc, s71, v50
	v_cvt_pk_bf16_f32 v69, v54, s0
	s_nop 0
	v_addc_co_u32_e32 v73, vcc, 0, v51, vcc
	s_mov_b32 s71, 0x8c000
	global_store_short v[72:73], v69, off
	v_add_co_u32_e32 v72, vcc, s71, v50
	v_cvt_pk_bf16_f32 v69, v55, s0
	s_nop 0
	v_addc_co_u32_e32 v73, vcc, 0, v51, vcc
	s_mov_b32 s71, 0x90000
	global_store_short v[72:73], v69, off
	v_add_co_u32_e32 v72, vcc, s71, v50
	v_cvt_pk_bf16_f32 v69, v52, s0
	s_nop 0
	v_addc_co_u32_e32 v73, vcc, 0, v51, vcc
	s_mov_b32 s71, 0x94000
	global_store_short v[72:73], v69, off
	v_add_co_u32_e32 v72, vcc, s71, v50
	v_cvt_pk_bf16_f32 v69, v53, s0
	s_nop 0
	v_addc_co_u32_e32 v73, vcc, 0, v51, vcc
	global_store_short v[72:73], v69, off
	v_add_co_u32_e32 v72, vcc, 0x98000, v50
	v_cvt_pk_bf16_f32 v69, v48, s0
	s_nop 0
	v_addc_co_u32_e32 v73, vcc, 0, v51, vcc
	v_add_co_u32_e32 v50, vcc, 0x9c000, v50
	global_store_short v[72:73], v69, off
	v_cvt_pk_bf16_f32 v69, v49, s0
	v_addc_co_u32_e32 v51, vcc, 0, v51, vcc
	s_mov_b64 s[82:83], 0
	global_store_short v[50:51], v69, off
; __device__ __forceinline__ float grp_sum(float v) { v += __shfl_xor(v, 16); v += __shfl_xor(v, 32); return v; }
; __device__ __forceinline__ void st8_bf16(bf16_t* dst, const float (&v)[8]) { u32x4 w; w.x = pk2(v[0], v[1]); w.y = pk2(v[2], v[3]); w.z = pk2(v[4], v[5]); w.w = pk2(v[6], v[7]); *(u32x4*)dst = w; }
;   __device__ __forceinline__ void operator()(const pg8::f32x4 (&acc)[2][2][4][2], const pg8::Unit& u, int wr, int wc, int fr, int fq) const {
;     ...
;           const bool isq = gi < 24; const int hm = isq ? gi - 16 : gi - 24;
;           const float* gn = isq ? q_norm : k_norm;
;           float ss = 0.f;
; #pragma unroll
;           for (int bj = 0; bj < 2; ++bj)
; #pragma unroll
;             for (int e = 0; e < 8; ++e) ss += v[bj][e] * v[bj][e];
;           const float rn = rsqrtf(grp_sum(ss) * (1.f / 64.f) + EPS) * (isq ? 0.125f * LOG2E : 1.f);
;           const f32x4 c0 = *(const f32x4*)(cos64 + (unsigned)pos * 32 + 8 * fq), c1 = *(const f32x4*)(cos64 + (unsigned)pos * 32 + 8 * fq + 4);
;           const f32x4 s0 = *(const f32x4*)(sin64 + (unsigned)pos * 32 + 8 * fq), s1 = *(const f32x4*)(sin64 + (unsigned)pos * 32 + 8 * fq + 4);
;           float kk = 0.f;
; #pragma unroll
;           for (int e = 0; e < 8; ++e) {
;             const float x1 = v[0][e] * rn * gn[8 * fq + e], x2 = v[1][e] * rn * gn[32 + 8 * fq + e];
;             const float cc = e < 4 ? c0[e & 3] : c1[e & 3], sn = e < 4 ? s0[e & 3] : s1[e & 3];
;             v[0][e] = x1 * cc - x2 * sn; v[1][e] = x1 * sn + x2 * cc;
;             kk += v[0][e] * v[0][e] + v[1][e] * v[1][e];
;           }
;           bf16_t* dst = (isq ? qb : kb) + ((unsigned)(bb * 8 + hm) * S + pos) * 64 + 8 * fq;
;           st8_bf16(dst, v[0]); st8_bf16(dst + 32, v[1]);
;           if (!isq) kmx_run = fmaxf(kmx_run, grp_sum(kk));
.LBB0_441:
	s_andn2_b64 vcc, exec, s[82:83]
	v_mov_b32_e32 v69, v96
	s_cbranch_vccnz .LBB0_444
	v_pk_mul_f32 v[50:51], v[70:71], v[70:71]
	v_pk_mul_f32 v[72:73], v[62:63], v[62:63]
	v_add_f32_e32 v50, v50, v51
	v_add_f32_e32 v50, v72, v50
	v_pk_mul_f32 v[74:75], v[60:61], v[60:61]
	v_add_f32_e32 v50, v73, v50
	v_add_f32_e32 v50, v74, v50
	v_pk_mul_f32 v[76:77], v[58:59], v[58:59]
	v_add_f32_e32 v50, v75, v50
	v_add_f32_e32 v50, v76, v50
	v_pk_mul_f32 v[78:79], v[56:57], v[56:57]
	v_add_f32_e32 v50, v77, v50
	v_add_f32_e32 v50, v78, v50
	v_pk_mul_f32 v[80:81], v[54:55], v[54:55]
	v_add_f32_e32 v50, v79, v50
	v_add_f32_e32 v50, v80, v50
	v_pk_mul_f32 v[82:83], v[52:53], v[52:53]
	v_add_f32_e32 v50, v81, v50
	v_add_f32_e32 v50, v82, v50
	v_pk_mul_f32 v[84:85], v[48:49], v[48:49]
	v_add_f32_e32 v50, v83, v50
	v_add_f32_e32 v50, v84, v50
	v_add_f32_e32 v50, v85, v50
	v_mov_b32_e32 v51, v50
	s_nop 1
	v_permlane16_swap_b32_e32 v50, v51
	v_lshlrev_b32_e32 v136, 7, v88
	s_and_b64 s[82:83], s[6:7], exec
	s_cselect_b32 s83, s17, s19
	s_cselect_b32 s82, s16, s18
	s_waitcnt lgkmcnt(0)
	v_add_f32_e32 v50, v50, v51
	v_mov_b32_e32 v51, v50
	s_nop 1
	v_permlane32_swap_b32_e32 v50, v51
	v_lshlrev_b32_e32 v69, 2, v138
	s_cselect_b32 s71, s87, s89
	v_mov_b32_e32 v113, v137
	s_waitcnt lgkmcnt(0)
	v_add_f32_e32 v50, v50, v51
	v_fmamk_f32 v50, v50, 0x3c800000, v154
	v_cmp_gt_f32_e32 vcc, s3, v50
	v_mul_f32_e32 v51, 0x4b800000, v50
	s_nop 0
	v_cndmask_b32_e32 v50, v50, v51, vcc
	v_rsq_f32_e32 v50, v50
	s_nop 0
	v_mul_f32_e32 v51, 0x45800000, v50
	v_cndmask_b32_e32 v50, v50, v51, vcc
	v_mul_f32_e32 v94, v204, v50
	v_lshl_add_u64 v[50:51], v[140:141], 0, v[136:137]
	global_load_dwordx4 v[82:85], v[50:51], off offset:16
	global_load_dwordx4 v[74:77], v[50:51], off
	v_lshl_add_u64 v[50:51], v[142:143], 0, v[136:137]
	global_load_dwordx4 v[90:93], v[50:51], off offset:16
	global_load_dwordx4 v[78:81], v[50:51], off
	global_load_dwordx4 v[98:101], v69, s[82:83] offset:16
	global_load_dwordx4 v[102:105], v69, s[82:83]
	global_load_dwordx4 v[106:109], v69, s[82:83] offset:144
	global_load_dwordx4 v[114:117], v69, s[82:83] offset:128
	v_pk_mul_f32 v[50:51], v[70:71], v[94:95] op_sel_hi:[1,0]
	v_lshl_add_u32 v69, v87, 16, s59
	s_cselect_b32 s82, s86, s88
	v_or_b32_e32 v69, v69, v88
	v_lshlrev_b32_e32 v136, 6, v69
	s_andn2_b64 vcc, exec, s[78:79]
	v_mov_b32_e32 v69, v96
	s_waitcnt vmcnt(2)
	v_pk_mul_f32 v[72:73], v[102:103], v[50:51]
	v_pk_mul_f32 v[50:51], v[56:57], v[94:95] op_sel_hi:[1,0]
	s_waitcnt vmcnt(0)
	v_pk_mul_f32 v[102:103], v[114:115], v[50:51]
	s_nop 0
	v_pk_mul_f32 v[50:51], v[78:79], v[102:103]
	s_nop 0
	v_pk_fma_f32 v[50:51], v[74:75], v[72:73], v[50:51] neg_lo:[0,0,1] neg_hi:[0,0,1]
	v_pk_mul_f32 v[72:73], v[78:79], v[72:73]
	s_nop 0
	v_pk_fma_f32 v[72:73], v[74:75], v[102:103], v[72:73]
	v_pk_mul_f32 v[74:75], v[62:63], v[94:95] op_sel_hi:[1,0]
	s_nop 0
	v_pk_mul_f32 v[78:79], v[74:75], v[104:105]
	v_pk_mul_f32 v[74:75], v[54:55], v[94:95] op_sel_hi:[1,0]
	s_nop 0
	v_pk_mul_f32 v[102:103], v[74:75], v[116:117]
	s_nop 0
	v_pk_mul_f32 v[74:75], v[80:81], v[102:103]
	s_nop 0
	v_pk_fma_f32 v[74:75], v[76:77], v[78:79], v[74:75] neg_lo:[0,0,1] neg_hi:[0,0,1]
	v_pk_mul_f32 v[76:77], v[76:77], v[102:103]
	s_nop 0
	v_pk_fma_f32 v[76:77], v[80:81], v[78:79], v[76:77]
	v_pk_mul_f32 v[78:79], v[60:61], v[94:95] op_sel_hi:[1,0]
	s_nop 0
	v_pk_mul_f32 v[80:81], v[78:79], v[98:99]
	v_pk_mul_f32 v[78:79], v[52:53], v[94:95] op_sel_hi:[1,0]
	s_nop 0
	v_pk_mul_f32 v[98:99], v[78:79], v[106:107]
	s_nop 0
	v_pk_mul_f32 v[78:79], v[90:91], v[98:99]
	s_nop 0
	v_pk_fma_f32 v[78:79], v[82:83], v[80:81], v[78:79] neg_lo:[0,0,1] neg_hi:[0,0,1]
	v_pk_mul_f32 v[82:83], v[82:83], v[98:99]
	s_nop 0
	v_pk_fma_f32 v[80:81], v[90:91], v[80:81], v[82:83]
	v_pk_mul_f32 v[82:83], v[58:59], v[94:95] op_sel_hi:[1,0]
	s_nop 0
	v_pk_mul_f32 v[90:91], v[82:83], v[100:101]
	v_pk_mul_f32 v[82:83], v[48:49], v[94:95] op_sel_hi:[1,0]
	s_nop 0
	v_pk_mul_f32 v[94:95], v[82:83], v[108:109]
	s_nop 0
	v_pk_mul_f32 v[82:83], v[92:93], v[94:95]
	s_nop 0
	v_pk_fma_f32 v[82:83], v[84:85], v[90:91], v[82:83] neg_lo:[0,0,1] neg_hi:[0,0,1]
	v_pk_mul_f32 v[84:85], v[84:85], v[94:95]
	s_nop 0
	v_pk_fma_f32 v[84:85], v[92:93], v[90:91], v[84:85]
	v_mov_b32_e32 v90, s82
	v_mov_b32_e32 v91, s71
	v_lshl_add_u64 v[88:89], v[136:137], 1, v[90:91]
	v_lshl_add_u64 v[92:93], v[88:89], 0, v[112:113]
	v_cvt_pk_bf16_f32 v88, v50, v51
	v_cvt_pk_bf16_f32 v89, v74, v75
	v_cvt_pk_bf16_f32 v90, v78, v79
	v_cvt_pk_bf16_f32 v91, v82, v83
	global_store_dwordx4 v[92:93], v[88:91], off
	s_nop 1
	v_cvt_pk_bf16_f32 v88, v72, v73
	v_cvt_pk_bf16_f32 v89, v76, v77
	v_cvt_pk_bf16_f32 v90, v80, v81
	v_cvt_pk_bf16_f32 v91, v84, v85
	global_store_dwordx4 v[92:93], v[88:91], off offset:64
	s_cbranch_vccnz .LBB0_444
	v_pk_mul_f32 v[72:73], v[72:73], v[72:73]
	s_nop 0
	v_pk_fma_f32 v[50:51], v[50:51], v[50:51], v[72:73]
	v_pk_mul_f32 v[72:73], v[76:77], v[76:77]
	v_add_f32_e32 v50, v50, v51
	v_pk_fma_f32 v[72:73], v[74:75], v[74:75], v[72:73]
	v_pk_mul_f32 v[74:75], v[80:81], v[80:81]
	v_add_f32_e32 v50, v72, v50
	v_pk_fma_f32 v[74:75], v[78:79], v[78:79], v[74:75]
	v_add_f32_e32 v50, v73, v50
	v_pk_mul_f32 v[76:77], v[84:85], v[84:85]
	v_add_f32_e32 v50, v50, v74
	v_pk_fma_f32 v[76:77], v[82:83], v[82:83], v[76:77]
	v_add_f32_e32 v50, v50, v75
	v_add_f32_e32 v50, v50, v76
	v_add_f32_e32 v50, v50, v77
	v_mov_b32_e32 v51, v50
	s_nop 1
	v_permlane16_swap_b32_e32 v50, v51
	s_waitcnt lgkmcnt(0)
	v_add_f32_e32 v50, v50, v51
	v_mov_b32_e32 v51, v50
	s_nop 1
	v_permlane32_swap_b32_e32 v50, v51
	s_waitcnt lgkmcnt(0)
	v_add_f32_e32 v50, v50, v51
	v_max_f32_e32 v51, v96, v96
	v_max_f32_e32 v69, v51, v50

; __device__ __forceinline__ float fexp2(float x) { return __builtin_amdgcn_exp2f(x); }
; __device__ __forceinline__ float frcp(float x) { return __builtin_amdgcn_rcpf(x); }
; __device__ __forceinline__ float gelu_tanh(float x) { const float y = 0.7978845608028654f * (x + 0.044715f * x * x * x); return x * sigm(2.f * y); }
; __device__ __forceinline__ float grp_sum(float v) { v += __shfl_xor(v, 16); v += __shfl_xor(v, 32); return v; }
; __device__ __forceinline__ float sigm(float x) { return frcp(1.f + fexp2(-LOG2E * x)); }
;   __device__ __forceinline__ void operator()(const pg8::f32x4 (&acc)[2][2][4][2], const pg8::Unit& u, int wr, int wc, int fr, int fq) const {
;     ...
;           const int g = gi - 8; float ss = 0.f;
; #pragma unroll
;           for (int bj = 0; bj < 2; ++bj)
; #pragma unroll
;             for (int e = 0; e < 8; ++e) { v[bj][e] = gelu_tanh(v[bj][e]); ss += v[bj][e] * v[bj][e]; }
;           const float rn = rsqrtf(grp_sum(ss) * (1.f / 64.f) + EPS);
.LBB0_445:
	s_andn2_b64 vcc, exec, s[82:83]
	s_cbranch_vccnz .LBB0_447
	v_mul_f32_e32 v50, 0x3d372713, v70
	v_mul_f32_e32 v50, v70, v50
	v_fma_f32 v50, v70, v50, v70
	v_mul_f32_e32 v50, 0x3f4c422a, v50
	v_add_f32_e32 v50, v50, v50
	v_mul_f32_e32 v50, 0xbfb8aa3b, v50
	v_exp_f32_e32 v50, v50
	v_mul_f32_e32 v51, 0x3d372713, v57
	v_mul_f32_e32 v51, v57, v51
	v_fma_f32 v51, v57, v51, v57
	v_add_f32_e32 v50, 1.0, v50
	v_rcp_f32_e32 v50, v50
	v_mul_f32_e32 v51, 0x3f4c422a, v51
	v_add_f32_e32 v51, v51, v51
	v_mul_f32_e32 v51, 0xbfb8aa3b, v51
	v_mul_f32_e32 v87, v70, v50
	v_mul_f32_e32 v50, 0x3d372713, v71
	v_mul_f32_e32 v50, v71, v50
	v_fma_f32 v50, v71, v50, v71
	v_mul_f32_e32 v50, 0x3f4c422a, v50
	v_add_f32_e32 v50, v50, v50
	v_mul_f32_e32 v50, 0xbfb8aa3b, v50
	v_exp_f32_e32 v50, v50
	v_exp_f32_e32 v51, v51
	v_mov_b32_e32 v157, v137
	v_lshl_add_u64 v[98:99], v[156:157], 2, s[56:57]
	v_add_f32_e32 v50, 1.0, v50
	v_rcp_f32_e32 v50, v50
	v_add_f32_e32 v51, 1.0, v51
	v_rcp_f32_e32 v51, v51
	v_mul_f32_e32 v69, v71, v50
	v_mul_f32_e32 v50, 0x3d372713, v62
	v_mul_f32_e32 v50, v62, v50
	v_fma_f32 v50, v62, v50, v62
	v_mul_f32_e32 v50, 0x3f4c422a, v50
	v_add_f32_e32 v50, v50, v50
	v_mul_f32_e32 v50, 0xbfb8aa3b, v50
	v_exp_f32_e32 v50, v50
	v_mul_f32_e32 v74, v69, v69
	v_fmac_f32_e32 v74, v87, v87
	v_add_f32_e32 v50, 1.0, v50
	v_rcp_f32_e32 v50, v50
	s_nop 0
	v_mul_f32_e32 v80, v62, v50
	v_mul_f32_e32 v50, 0x3d372713, v63
	v_mul_f32_e32 v50, v63, v50
	v_fma_f32 v50, v63, v50, v63
	v_mul_f32_e32 v50, 0x3f4c422a, v50
	v_add_f32_e32 v50, v50, v50
	v_mul_f32_e32 v50, 0xbfb8aa3b, v50
	v_exp_f32_e32 v50, v50
	v_fmac_f32_e32 v74, v80, v80
	v_add_f32_e32 v50, 1.0, v50
	v_rcp_f32_e32 v50, v50
	s_nop 0
	v_mul_f32_e32 v81, v63, v50
	v_mul_f32_e32 v50, 0x3d372713, v60
	v_mul_f32_e32 v50, v60, v50
	v_fma_f32 v50, v60, v50, v60
	v_mul_f32_e32 v50, 0x3f4c422a, v50
	v_add_f32_e32 v50, v50, v50
	v_mul_f32_e32 v50, 0xbfb8aa3b, v50
	v_exp_f32_e32 v50, v50
	v_fmac_f32_e32 v74, v81, v81
	v_add_f32_e32 v50, 1.0, v50
	v_rcp_f32_e32 v50, v50
	s_nop 0
	v_mul_f32_e32 v82, v60, v50
	v_mul_f32_e32 v50, 0x3d372713, v61
	v_mul_f32_e32 v50, v61, v50
	v_fma_f32 v50, v61, v50, v61
	v_mul_f32_e32 v50, 0x3f4c422a, v50
	v_add_f32_e32 v50, v50, v50
	v_mul_f32_e32 v50, 0xbfb8aa3b, v50
	v_exp_f32_e32 v50, v50
	v_fmac_f32_e32 v74, v82, v82
	v_add_f32_e32 v50, 1.0, v50
	v_rcp_f32_e32 v50, v50
	s_nop 0
	v_mul_f32_e32 v83, v61, v50
	v_mul_f32_e32 v50, 0x3d372713, v58
	v_mul_f32_e32 v50, v58, v50
	v_fma_f32 v50, v58, v50, v58
	v_mul_f32_e32 v50, 0x3f4c422a, v50
	v_add_f32_e32 v50, v50, v50
	v_mul_f32_e32 v50, 0xbfb8aa3b, v50
	v_exp_f32_e32 v50, v50
	v_fmac_f32_e32 v74, v83, v83
	v_add_f32_e32 v50, 1.0, v50
	v_rcp_f32_e32 v50, v50
	s_nop 0
	v_mul_f32_e32 v84, v58, v50
	v_mul_f32_e32 v50, 0x3d372713, v59
	v_mul_f32_e32 v50, v59, v50
	v_fma_f32 v50, v59, v50, v59
	v_mul_f32_e32 v50, 0x3f4c422a, v50
	v_add_f32_e32 v50, v50, v50
	v_mul_f32_e32 v50, 0xbfb8aa3b, v50
	v_exp_f32_e32 v50, v50
	v_fmac_f32_e32 v74, v84, v84
	v_add_f32_e32 v50, 1.0, v50
	v_rcp_f32_e32 v50, v50
	s_nop 0
	v_mul_f32_e32 v85, v59, v50
	v_mul_f32_e32 v50, 0x3d372713, v56
	v_mul_f32_e32 v50, v56, v50
	v_fma_f32 v50, v56, v50, v56
	v_mul_f32_e32 v50, 0x3f4c422a, v50
	v_add_f32_e32 v50, v50, v50
	v_mul_f32_e32 v50, 0xbfb8aa3b, v50
	v_exp_f32_e32 v50, v50
	v_fmac_f32_e32 v74, v85, v85
	v_add_f32_e32 v50, 1.0, v50
	v_rcp_f32_e32 v50, v50
	s_nop 0
	v_pk_mul_f32 v[50:51], v[56:57], v[50:51]
	s_nop 0
	v_pk_mul_f32 v[72:73], v[50:51], v[50:51]
	s_nop 0
	v_add_f32_e32 v72, v72, v74
	v_add_f32_e32 v76, v73, v72
	v_mul_f32_e32 v72, 0x3d372713, v54
	v_mul_f32_e32 v73, 0x3d372713, v55
	v_mul_f32_e32 v72, v54, v72
	v_mul_f32_e32 v73, v55, v73
	v_fma_f32 v72, v54, v72, v54
	v_fma_f32 v73, v55, v73, v55
	v_mul_f32_e32 v72, 0x3f4c422a, v72
	v_mul_f32_e32 v73, 0x3f4c422a, v73
	v_add_f32_e32 v72, v72, v72
	v_add_f32_e32 v73, v73, v73
	v_mul_f32_e32 v72, 0xbfb8aa3b, v72
	v_mul_f32_e32 v73, 0xbfb8aa3b, v73
	v_exp_f32_e32 v72, v72
	v_exp_f32_e32 v73, v73
	v_add_f32_e32 v72, 1.0, v72
	v_add_f32_e32 v73, 1.0, v73
	v_rcp_f32_e32 v72, v72
	v_rcp_f32_e32 v73, v73
	s_nop 0
	v_pk_mul_f32 v[72:73], v[54:55], v[72:73]
	s_nop 0
	v_pk_mul_f32 v[74:75], v[72:73], v[72:73]
	s_nop 0
	v_add_f32_e32 v74, v74, v76
	v_add_f32_e32 v78, v75, v74
	v_mul_f32_e32 v74, 0x3d372713, v52
	v_mul_f32_e32 v75, 0x3d372713, v53
	v_mul_f32_e32 v74, v52, v74
	v_mul_f32_e32 v75, v53, v75
	v_fma_f32 v74, v52, v74, v52
	v_fma_f32 v75, v53, v75, v53
	v_mul_f32_e32 v74, 0x3f4c422a, v74
	v_mul_f32_e32 v75, 0x3f4c422a, v75
	v_add_f32_e32 v74, v74, v74
	v_add_f32_e32 v75, v75, v75
	v_mul_f32_e32 v74, 0xbfb8aa3b, v74
	v_mul_f32_e32 v75, 0xbfb8aa3b, v75
	v_exp_f32_e32 v74, v74
	v_exp_f32_e32 v75, v75
	v_add_f32_e32 v74, 1.0, v74
	v_add_f32_e32 v75, 1.0, v75
	v_rcp_f32_e32 v74, v74
	v_rcp_f32_e32 v75, v75
	s_nop 0
	v_pk_mul_f32 v[74:75], v[52:53], v[74:75]
	s_nop 0
	v_pk_mul_f32 v[76:77], v[74:75], v[74:75]
	s_nop 0
	v_add_f32_e32 v76, v76, v78
	v_add_f32_e32 v88, v77, v76
	v_mul_f32_e32 v76, 0x3d372713, v48
	v_mul_f32_e32 v77, 0x3d372713, v49
	v_mul_f32_e32 v76, v48, v76
	v_mul_f32_e32 v77, v49, v77
	v_fma_f32 v76, v48, v76, v48
	v_fma_f32 v77, v49, v77, v49
	v_mul_f32_e32 v76, 0x3f4c422a, v76
	v_mul_f32_e32 v77, 0x3f4c422a, v77
	v_add_f32_e32 v76, v76, v76
	v_add_f32_e32 v77, v77, v77
	v_mul_f32_e32 v76, 0xbfb8aa3b, v76
	v_mul_f32_e32 v77, 0xbfb8aa3b, v77
	v_exp_f32_e32 v76, v76
	v_exp_f32_e32 v77, v77
	v_add_f32_e32 v76, 1.0, v76
	v_add_f32_e32 v77, 1.0, v77
	v_rcp_f32_e32 v76, v76
	v_rcp_f32_e32 v77, v77
	s_nop 0
	v_pk_mul_f32 v[76:77], v[48:49], v[76:77]
	s_nop 0
	v_pk_mul_f32 v[78:79], v[76:77], v[76:77]
	s_nop 0
	v_add_f32_e32 v78, v78, v88
	global_load_dwordx4 v[88:91], v[98:99], off offset:16
	global_load_dwordx4 v[92:95], v[98:99], off
	v_add_f32_e32 v78, v79, v78
	v_mov_b32_e32 v79, v78
	s_nop 1
	v_permlane16_swap_b32_e32 v78, v79
	s_waitcnt lgkmcnt(0)
; __device__ __forceinline__ bf16_t f2bf(float f) { return (bf16_t)(pk2(f, 0.f) & 0xffffu); }
; __device__ __forceinline__ float grp_sum(float v) { v += __shfl_xor(v, 16); v += __shfl_xor(v, 32); return v; }
;   __device__ __forceinline__ void operator()(const pg8::f32x4 (&acc)[2][2][4][2], const pg8::Unit& u, int wr, int wc, int fr, int fq) const {
;     ...
;           const float rn = rsqrtf(grp_sum(ss) * (1.f / 64.f) + EPS);
;           bf16_t* dst = vt + ((unsigned)(g * 128 + (tok >> 7)) * 64 + 8 * fq) * 128 + (tok & 127);
; #pragma unroll
;           for (int bj = 0; bj < 2; ++bj)
; #pragma unroll
;             for (int e = 0; e < 8; ++e) dst[(32 * bj + e) * 128] = f2bf(v[bj][e] * rn * sgu_norm[g * 64 + 32 * bj + 8 * fq + e]);
	v_add_f32_e32 v78, v78, v79
	v_mov_b32_e32 v79, v78
	s_nop 1
	v_permlane32_swap_b32_e32 v78, v79
	s_waitcnt lgkmcnt(0)
	v_add_f32_e32 v78, v78, v79
	v_fmamk_f32 v78, v78, 0x3c800000, v154
	v_cmp_gt_f32_e32 vcc, s3, v78
	v_mul_f32_e32 v79, 0x4b800000, v78
	s_nop 0
	v_cndmask_b32_e32 v78, v78, v79, vcc
	v_rsq_f32_e32 v78, v78
	s_nop 0
	v_mul_f32_e32 v79, 0x45800000, v78
	v_cndmask_b32_e32 v97, v78, v79, vcc
	v_lshrrev_b32_e32 v78, 1, v86
	v_and_b32_e32 v78, 0x1ffffc0, v78
	v_add_lshl_u32 v136, v78, v203, 7
	v_mul_f32_e32 v69, v69, v97
	v_lshl_add_u64 v[78:79], v[136:137], 1, s[50:51]
	v_lshlrev_b32_e32 v136, 1, v206
	v_lshl_add_u64 v[78:79], v[78:79], 0, v[136:137]
	v_mul_f32_e32 v87, v87, v97
	v_mul_f32_e32 v50, v50, v97
	s_waitcnt vmcnt(0)
	v_mul_f32_e32 v69, v93, v69
	v_cvt_pk_bf16_f32 v69, v69, s0
	global_store_short v[78:79], v69, off offset:256
	v_mul_f32_e32 v69, v80, v97
	v_mul_f32_e32 v69, v94, v69
	v_cvt_pk_bf16_f32 v69, v69, s0
	global_store_short v[78:79], v69, off offset:512
	v_mul_f32_e32 v69, v81, v97
	v_mul_f32_e32 v69, v95, v69
	v_cvt_pk_bf16_f32 v69, v69, s0
	global_store_short v[78:79], v69, off offset:768
	v_mul_f32_e32 v69, v82, v97
	v_mul_f32_e32 v69, v88, v69
	v_cvt_pk_bf16_f32 v69, v69, s0
	global_store_short v[78:79], v69, off offset:1024
	v_mul_f32_e32 v69, v83, v97
	v_mul_f32_e32 v69, v69, v89
	v_cvt_pk_bf16_f32 v69, v69, s0
	global_store_short v[78:79], v69, off offset:1280
	v_mul_f32_e32 v69, v84, v97
	v_mul_f32_e32 v69, v69, v90
	v_cvt_pk_bf16_f32 v69, v69, s0
	global_store_short v[78:79], v69, off offset:1536
	v_mul_f32_e32 v69, v85, v97
	v_mul_f32_e32 v87, v92, v87
	v_mul_f32_e32 v69, v69, v91
	v_cvt_pk_bf16_f32 v87, v87, s0
	v_cvt_pk_bf16_f32 v69, v69, s0
	global_store_short v[78:79], v87, off
	global_store_short v[78:79], v69, off offset:1792
	global_load_dwordx4 v[80:83], v[98:99], off offset:144
	global_load_dwordx4 v[88:91], v[98:99], off offset:128
	v_add_co_u32_e32 v78, vcc, s97, v78
	v_mov_b32_e32 v69, v96
	s_nop 0
	v_addc_co_u32_e32 v79, vcc, 0, v79, vcc
	s_waitcnt vmcnt(0)
	v_mul_f32_e32 v50, v50, v88
	v_cvt_pk_bf16_f32 v50, v50, s0
	global_store_short v[78:79], v50, off
	v_mul_f32_e32 v50, v51, v97
	v_mul_f32_e32 v50, v50, v89
	v_cvt_pk_bf16_f32 v50, v50, s0
	global_store_short v[78:79], v50, off offset:256
	v_mul_f32_e32 v50, v72, v97
	v_mul_f32_e32 v50, v50, v90
	v_cvt_pk_bf16_f32 v50, v50, s0
	global_store_short v[78:79], v50, off offset:512
	v_mul_f32_e32 v50, v73, v97
	v_mul_f32_e32 v50, v50, v91
	v_cvt_pk_bf16_f32 v50, v50, s0
	global_store_short v[78:79], v50, off offset:768
	v_mul_f32_e32 v50, v74, v97
	v_mul_f32_e32 v50, v50, v80
	v_cvt_pk_bf16_f32 v50, v50, s0
	global_store_short v[78:79], v50, off offset:1024
	v_mul_f32_e32 v50, v75, v97
	v_mul_f32_e32 v50, v50, v81
	v_cvt_pk_bf16_f32 v50, v50, s0
	global_store_short v[78:79], v50, off offset:1280
	v_mul_f32_e32 v50, v76, v97
	v_mul_f32_e32 v50, v50, v82
	v_cvt_pk_bf16_f32 v50, v50, s0
	global_store_short v[78:79], v50, off offset:1536
	v_mul_f32_e32 v50, v77, v97
	v_mul_f32_e32 v50, v50, v83
	v_cvt_pk_bf16_f32 v50, v50, s0
	global_store_short v[78:79], v50, off offset:1792

; __device__ __forceinline__ float grp_sum(float v) { v += __shfl_xor(v, 16); v += __shfl_xor(v, 32); return v; }
; __device__ __forceinline__ void st8_bf16(bf16_t* dst, const float (&v)[8]) { u32x4 w; w.x = pk2(v[0], v[1]); w.y = pk2(v[2], v[3]); w.z = pk2(v[4], v[5]); w.w = pk2(v[6], v[7]); *(u32x4*)dst = w; }
;   __device__ __forceinline__ void operator()(const pg8::f32x4 (&acc)[2][2][4][2], const pg8::Unit& u, int wr, int wc, int fr, int fq) const {
;     ...
;           const bool isq = gi < 24; const int hm = isq ? gi - 16 : gi - 24;
;           const float* gn = isq ? q_norm : k_norm;
;           float ss = 0.f;
; #pragma unroll
;           for (int bj = 0; bj < 2; ++bj)
; #pragma unroll
;             for (int e = 0; e < 8; ++e) ss += v[bj][e] * v[bj][e];
;           const float rn = rsqrtf(grp_sum(ss) * (1.f / 64.f) + EPS) * (isq ? 0.125f * LOG2E : 1.f);
;           const f32x4 c0 = *(const f32x4*)(cos64 + (unsigned)pos * 32 + 8 * fq), c1 = *(const f32x4*)(cos64 + (unsigned)pos * 32 + 8 * fq + 4);
;           const f32x4 s0 = *(const f32x4*)(sin64 + (unsigned)pos * 32 + 8 * fq), s1 = *(const f32x4*)(sin64 + (unsigned)pos * 32 + 8 * fq + 4);
;           float kk = 0.f;
; #pragma unroll
;           for (int e = 0; e < 8; ++e) {
;             const float x1 = v[0][e] * rn * gn[8 * fq + e], x2 = v[1][e] * rn * gn[32 + 8 * fq + e];
;             const float cc = e < 4 ? c0[e & 3] : c1[e & 3], sn = e < 4 ? s0[e & 3] : s1[e & 3];
;             v[0][e] = x1 * cc - x2 * sn; v[1][e] = x1 * sn + x2 * cc;
;             kk += v[0][e] * v[0][e] + v[1][e] * v[1][e];
;           }
;           bf16_t* dst = (isq ? qb : kb) + ((unsigned)(bb * 8 + hm) * S + pos) * 64 + 8 * fq;
;           st8_bf16(dst, v[0]); st8_bf16(dst + 32, v[1]);
;           if (!isq) kmx_run = fmaxf(kmx_run, grp_sum(kk));
.LBB0_454:
	s_andn2_b64 vcc, exec, s[12:13]
	v_mov_b32_e32 v68, v69
	s_cbranch_vccnz .LBB0_457
	v_pk_mul_f32 v[34:35], v[48:49], v[48:49]
	v_pk_mul_f32 v[50:51], v[46:47], v[46:47]
	v_add_f32_e32 v34, v34, v35
	v_add_f32_e32 v34, v50, v34
	v_pk_mul_f32 v[52:53], v[44:45], v[44:45]
	v_add_f32_e32 v34, v51, v34
	v_add_f32_e32 v34, v52, v34
	v_pk_mul_f32 v[54:55], v[42:43], v[42:43]
	v_add_f32_e32 v34, v53, v34
	v_add_f32_e32 v34, v54, v34
	v_pk_mul_f32 v[56:57], v[40:41], v[40:41]
	v_add_f32_e32 v34, v55, v34
	v_add_f32_e32 v34, v56, v34
	v_pk_mul_f32 v[58:59], v[38:39], v[38:39]
	v_add_f32_e32 v34, v57, v34
	v_add_f32_e32 v34, v58, v34
	v_pk_mul_f32 v[60:61], v[36:37], v[36:37]
	v_add_f32_e32 v34, v59, v34
	v_add_f32_e32 v34, v60, v34
	v_pk_mul_f32 v[62:63], v[32:33], v[32:33]
	v_add_f32_e32 v34, v61, v34
	v_add_f32_e32 v34, v62, v34
	v_add_f32_e32 v34, v63, v34
	v_mov_b32_e32 v35, v34
	s_nop 1
	v_permlane16_swap_b32_e32 v34, v35
	v_lshlrev_b32_e32 v136, 7, v72
	s_and_b64 s[12:13], s[6:7], exec
	s_cselect_b32 s13, s17, s19
	s_cselect_b32 s12, s16, s18
	s_waitcnt lgkmcnt(0)
	v_add_f32_e32 v34, v34, v35
	v_mov_b32_e32 v35, v34
	s_nop 1
	v_permlane32_swap_b32_e32 v34, v35
	v_lshlrev_b32_e32 v73, 2, v138
	v_mov_b32_e32 v113, v137
	s_waitcnt lgkmcnt(0)
	v_add_f32_e32 v34, v34, v35
	v_fmamk_f32 v34, v34, 0x3c800000, v154
	v_cmp_gt_f32_e32 vcc, s3, v34
	v_mul_f32_e32 v35, 0x4b800000, v34
	s_nop 0
	v_cndmask_b32_e32 v34, v34, v35, vcc
	v_rsq_f32_e32 v34, v34
	s_nop 0
	v_mul_f32_e32 v35, 0x45800000, v34
	v_cndmask_b32_e32 v34, v34, v35, vcc
	v_mul_f32_e32 v68, v204, v34
	v_lshl_add_u64 v[34:35], v[140:141], 0, v[136:137]
	global_load_dwordx4 v[60:63], v[34:35], off offset:16
	global_load_dwordx4 v[52:55], v[34:35], off
	v_lshl_add_u64 v[34:35], v[142:143], 0, v[136:137]
	global_load_dwordx4 v[74:77], v[34:35], off offset:16
	global_load_dwordx4 v[56:59], v[34:35], off
	global_load_dwordx4 v[78:81], v73, s[12:13] offset:16
	global_load_dwordx4 v[82:85], v73, s[12:13]
	global_load_dwordx4 v[86:89], v73, s[12:13] offset:144
	global_load_dwordx4 v[90:93], v73, s[12:13] offset:128
	v_pk_mul_f32 v[34:35], v[48:49], v[68:69] op_sel_hi:[1,0]
	s_cselect_b32 s12, s87, s89
	s_cselect_b32 s13, s86, s88
	s_andn2_b64 vcc, exec, s[78:79]
	s_waitcnt vmcnt(2)
	v_pk_mul_f32 v[50:51], v[82:83], v[34:35]
	v_pk_mul_f32 v[34:35], v[40:41], v[68:69] op_sel_hi:[1,0]
	s_waitcnt vmcnt(0)
	v_pk_mul_f32 v[82:83], v[90:91], v[34:35]
	s_nop 0
	v_pk_mul_f32 v[34:35], v[56:57], v[82:83]
	s_nop 0
	v_pk_fma_f32 v[34:35], v[52:53], v[50:51], v[34:35] neg_lo:[0,0,1] neg_hi:[0,0,1]
	v_pk_mul_f32 v[50:51], v[56:57], v[50:51]
	s_nop 0
	v_pk_fma_f32 v[50:51], v[52:53], v[82:83], v[50:51]
	v_pk_mul_f32 v[52:53], v[46:47], v[68:69] op_sel_hi:[1,0]
	s_nop 0
	v_pk_mul_f32 v[56:57], v[52:53], v[84:85]
	v_pk_mul_f32 v[52:53], v[38:39], v[68:69] op_sel_hi:[1,0]
	s_nop 0
	v_pk_mul_f32 v[82:83], v[52:53], v[92:93]
	s_nop 0
	v_pk_mul_f32 v[52:53], v[58:59], v[82:83]
	s_nop 0
	v_pk_fma_f32 v[52:53], v[54:55], v[56:57], v[52:53] neg_lo:[0,0,1] neg_hi:[0,0,1]
	v_pk_mul_f32 v[54:55], v[54:55], v[82:83]
	s_nop 0
	v_pk_fma_f32 v[54:55], v[58:59], v[56:57], v[54:55]
	v_pk_mul_f32 v[56:57], v[44:45], v[68:69] op_sel_hi:[1,0]
	s_nop 0
	v_pk_mul_f32 v[58:59], v[56:57], v[78:79]
	v_pk_mul_f32 v[56:57], v[36:37], v[68:69] op_sel_hi:[1,0]
	s_nop 0
	v_pk_mul_f32 v[78:79], v[56:57], v[86:87]
	s_nop 0
	v_pk_mul_f32 v[56:57], v[74:75], v[78:79]
	s_nop 0
	v_pk_fma_f32 v[56:57], v[60:61], v[58:59], v[56:57] neg_lo:[0,0,1] neg_hi:[0,0,1]
	v_pk_mul_f32 v[60:61], v[60:61], v[78:79]
	s_nop 0
	v_pk_fma_f32 v[58:59], v[74:75], v[58:59], v[60:61]
	v_pk_mul_f32 v[60:61], v[42:43], v[68:69] op_sel_hi:[1,0]
	s_nop 0
	v_pk_mul_f32 v[74:75], v[60:61], v[80:81]
	v_pk_mul_f32 v[60:61], v[32:33], v[68:69] op_sel_hi:[1,0]
	v_lshl_add_u32 v68, v71, 16, s59
	v_pk_mul_f32 v[78:79], v[60:61], v[88:89]
	v_or_b32_e32 v68, v68, v72
	v_pk_mul_f32 v[60:61], v[76:77], v[78:79]
	v_lshlrev_b32_e32 v136, 6, v68
	v_pk_fma_f32 v[60:61], v[62:63], v[74:75], v[60:61] neg_lo:[0,0,1] neg_hi:[0,0,1]
	v_pk_mul_f32 v[62:63], v[62:63], v[78:79]
	v_mov_b32_e32 v68, v69
	v_pk_fma_f32 v[62:63], v[76:77], v[74:75], v[62:63]
	v_mov_b32_e32 v74, s13
	v_mov_b32_e32 v75, s12
	v_lshl_add_u64 v[72:73], v[136:137], 1, v[74:75]
	v_lshl_add_u64 v[76:77], v[72:73], 0, v[112:113]
	v_cvt_pk_bf16_f32 v72, v34, v35
	v_cvt_pk_bf16_f32 v73, v52, v53
	v_cvt_pk_bf16_f32 v74, v56, v57
	v_cvt_pk_bf16_f32 v75, v60, v61
	global_store_dwordx4 v[76:77], v[72:75], off
	s_nop 1
	v_cvt_pk_bf16_f32 v72, v50, v51
	v_cvt_pk_bf16_f32 v73, v54, v55
	v_cvt_pk_bf16_f32 v74, v58, v59
	v_cvt_pk_bf16_f32 v75, v62, v63
	global_store_dwordx4 v[76:77], v[72:75], off offset:64
	s_cbranch_vccnz .LBB0_457
	v_pk_mul_f32 v[50:51], v[50:51], v[50:51]
	s_nop 0
	v_pk_fma_f32 v[34:35], v[34:35], v[34:35], v[50:51]
	v_pk_mul_f32 v[50:51], v[54:55], v[54:55]
	v_add_f32_e32 v34, v34, v35
	v_pk_fma_f32 v[50:51], v[52:53], v[52:53], v[50:51]
	v_pk_mul_f32 v[52:53], v[58:59], v[58:59]
	v_add_f32_e32 v34, v50, v34
	v_pk_fma_f32 v[52:53], v[56:57], v[56:57], v[52:53]
	v_add_f32_e32 v34, v51, v34
	v_pk_mul_f32 v[54:55], v[62:63], v[62:63]
	v_add_f32_e32 v34, v34, v52
	v_pk_fma_f32 v[54:55], v[60:61], v[60:61], v[54:55]
	v_add_f32_e32 v34, v34, v53
	v_add_f32_e32 v34, v34, v54
	v_add_f32_e32 v34, v34, v55
	v_mov_b32_e32 v35, v34
	s_nop 1
	v_permlane16_swap_b32_e32 v34, v35
	s_waitcnt lgkmcnt(0)
	v_add_f32_e32 v34, v34, v35
	v_mov_b32_e32 v35, v34
	s_nop 1
	v_permlane32_swap_b32_e32 v34, v35
	s_waitcnt lgkmcnt(0)
	v_add_f32_e32 v34, v34, v35
	v_max_f32_e32 v35, v69, v69
	v_max_f32_e32 v68, v35, v34

; __device__ __forceinline__ float fexp2(float x) { return __builtin_amdgcn_exp2f(x); }
; __device__ __forceinline__ float frcp(float x) { return __builtin_amdgcn_rcpf(x); }
; __device__ __forceinline__ float gelu_tanh(float x) { const float y = 0.7978845608028654f * (x + 0.044715f * x * x * x); return x * sigm(2.f * y); }
; __device__ __forceinline__ float grp_sum(float v) { v += __shfl_xor(v, 16); v += __shfl_xor(v, 32); return v; }
; __device__ __forceinline__ float sigm(float x) { return frcp(1.f + fexp2(-LOG2E * x)); }
;   __device__ __forceinline__ void operator()(const pg8::f32x4 (&acc)[2][2][4][2], const pg8::Unit& u, int wr, int wc, int fr, int fq) const {
;     ...
;           const int g = gi - 8; float ss = 0.f;
; #pragma unroll
;           for (int bj = 0; bj < 2; ++bj)
; #pragma unroll
;             for (int e = 0; e < 8; ++e) { v[bj][e] = gelu_tanh(v[bj][e]); ss += v[bj][e] * v[bj][e]; }
;           const float rn = rsqrtf(grp_sum(ss) * (1.f / 64.f) + EPS);
.LBB0_458:
	s_andn2_b64 vcc, exec, s[12:13]
	s_cbranch_vccnz .LBB0_460
	v_mul_f32_e32 v34, 0x3d372713, v48
	v_mul_f32_e32 v34, v48, v34
	v_fma_f32 v34, v48, v34, v48
	v_mul_f32_e32 v34, 0x3f4c422a, v34
	v_add_f32_e32 v34, v34, v34
	v_mul_f32_e32 v34, 0xbfb8aa3b, v34
	v_exp_f32_e32 v34, v34
	v_mul_f32_e32 v35, 0x3d372713, v41
	v_mul_f32_e32 v35, v41, v35
	v_fma_f32 v35, v41, v35, v41
	v_add_f32_e32 v34, 1.0, v34
	v_rcp_f32_e32 v34, v34
	v_mul_f32_e32 v35, 0x3f4c422a, v35
	v_add_f32_e32 v35, v35, v35
	v_mul_f32_e32 v35, 0xbfb8aa3b, v35
	v_mul_f32_e32 v71, v48, v34
	v_mul_f32_e32 v34, 0x3d372713, v49
	v_mul_f32_e32 v34, v49, v34
	v_fma_f32 v34, v49, v34, v49
	v_mul_f32_e32 v34, 0x3f4c422a, v34
	v_add_f32_e32 v34, v34, v34
	v_mul_f32_e32 v34, 0xbfb8aa3b, v34
	v_exp_f32_e32 v34, v34
	v_exp_f32_e32 v35, v35
	v_mov_b32_e32 v157, v137
	v_lshl_add_u64 v[80:81], v[156:157], 2, s[56:57]
	v_add_f32_e32 v34, 1.0, v34
	v_rcp_f32_e32 v34, v34
	v_add_f32_e32 v35, 1.0, v35
	v_rcp_f32_e32 v35, v35
	v_mul_f32_e32 v58, v49, v34
	v_mul_f32_e32 v34, 0x3d372713, v46
	v_mul_f32_e32 v34, v46, v34
	v_fma_f32 v34, v46, v34, v46
	v_mul_f32_e32 v34, 0x3f4c422a, v34
	v_add_f32_e32 v34, v34, v34
	v_mul_f32_e32 v34, 0xbfb8aa3b, v34
	v_exp_f32_e32 v34, v34
	v_mul_f32_e32 v52, v58, v58
	v_fmac_f32_e32 v52, v71, v71
	v_add_f32_e32 v34, 1.0, v34
	v_rcp_f32_e32 v34, v34
	s_nop 0
	v_mul_f32_e32 v59, v46, v34
	v_mul_f32_e32 v34, 0x3d372713, v47
	v_mul_f32_e32 v34, v47, v34
	v_fma_f32 v34, v47, v34, v47
	v_mul_f32_e32 v34, 0x3f4c422a, v34
	v_add_f32_e32 v34, v34, v34
	v_mul_f32_e32 v34, 0xbfb8aa3b, v34
	v_exp_f32_e32 v34, v34
	v_fmac_f32_e32 v52, v59, v59
	v_add_f32_e32 v34, 1.0, v34
	v_rcp_f32_e32 v34, v34
	s_nop 0
	v_mul_f32_e32 v60, v47, v34
	v_mul_f32_e32 v34, 0x3d372713, v44
	v_mul_f32_e32 v34, v44, v34
	v_fma_f32 v34, v44, v34, v44
	v_mul_f32_e32 v34, 0x3f4c422a, v34
	v_add_f32_e32 v34, v34, v34
	v_mul_f32_e32 v34, 0xbfb8aa3b, v34
	v_exp_f32_e32 v34, v34
	v_fmac_f32_e32 v52, v60, v60
	v_add_f32_e32 v34, 1.0, v34
	v_rcp_f32_e32 v34, v34
	s_nop 0
	v_mul_f32_e32 v61, v44, v34
	v_mul_f32_e32 v34, 0x3d372713, v45
	v_mul_f32_e32 v34, v45, v34
	v_fma_f32 v34, v45, v34, v45
	v_mul_f32_e32 v34, 0x3f4c422a, v34
	v_add_f32_e32 v34, v34, v34
	v_mul_f32_e32 v34, 0xbfb8aa3b, v34
	v_exp_f32_e32 v34, v34
	v_fmac_f32_e32 v52, v61, v61
	v_add_f32_e32 v34, 1.0, v34
	v_rcp_f32_e32 v34, v34
	s_nop 0
	v_mul_f32_e32 v62, v45, v34
	v_mul_f32_e32 v34, 0x3d372713, v42
	v_mul_f32_e32 v34, v42, v34
	v_fma_f32 v34, v42, v34, v42
	v_mul_f32_e32 v34, 0x3f4c422a, v34
	v_add_f32_e32 v34, v34, v34
	v_mul_f32_e32 v34, 0xbfb8aa3b, v34
	v_exp_f32_e32 v34, v34
	v_fmac_f32_e32 v52, v62, v62
	v_add_f32_e32 v34, 1.0, v34
	v_rcp_f32_e32 v34, v34
	s_nop 0
	v_mul_f32_e32 v63, v42, v34
	v_mul_f32_e32 v34, 0x3d372713, v43
	v_mul_f32_e32 v34, v43, v34
	v_fma_f32 v34, v43, v34, v43
	v_mul_f32_e32 v34, 0x3f4c422a, v34
	v_add_f32_e32 v34, v34, v34
	v_mul_f32_e32 v34, 0xbfb8aa3b, v34
	v_exp_f32_e32 v34, v34
	v_fmac_f32_e32 v52, v63, v63
	v_add_f32_e32 v34, 1.0, v34
	v_rcp_f32_e32 v34, v34
	s_nop 0
	v_mul_f32_e32 v68, v43, v34
	v_mul_f32_e32 v34, 0x3d372713, v40
	v_mul_f32_e32 v34, v40, v34
	v_fma_f32 v34, v40, v34, v40
	v_mul_f32_e32 v34, 0x3f4c422a, v34
	v_add_f32_e32 v34, v34, v34
	v_mul_f32_e32 v34, 0xbfb8aa3b, v34
	v_exp_f32_e32 v34, v34
	v_fmac_f32_e32 v52, v68, v68
	v_add_f32_e32 v34, 1.0, v34
	v_rcp_f32_e32 v34, v34
	s_nop 0
	v_pk_mul_f32 v[34:35], v[40:41], v[34:35]
	s_nop 0
	v_pk_mul_f32 v[50:51], v[34:35], v[34:35]
	s_nop 0
	v_add_f32_e32 v50, v50, v52
	v_add_f32_e32 v54, v51, v50
	v_mul_f32_e32 v50, 0x3d372713, v38
	v_mul_f32_e32 v51, 0x3d372713, v39
	v_mul_f32_e32 v50, v38, v50
	v_mul_f32_e32 v51, v39, v51
	v_fma_f32 v50, v38, v50, v38
	v_fma_f32 v51, v39, v51, v39
	v_mul_f32_e32 v50, 0x3f4c422a, v50
	v_mul_f32_e32 v51, 0x3f4c422a, v51
	v_add_f32_e32 v50, v50, v50
	v_add_f32_e32 v51, v51, v51
	v_mul_f32_e32 v50, 0xbfb8aa3b, v50
	v_mul_f32_e32 v51, 0xbfb8aa3b, v51
	v_exp_f32_e32 v50, v50
	v_exp_f32_e32 v51, v51
	v_add_f32_e32 v50, 1.0, v50
	v_add_f32_e32 v51, 1.0, v51
	v_rcp_f32_e32 v50, v50
	v_rcp_f32_e32 v51, v51
	s_nop 0
	v_pk_mul_f32 v[50:51], v[38:39], v[50:51]
	s_nop 0
	v_pk_mul_f32 v[52:53], v[50:51], v[50:51]
	s_nop 0
	v_add_f32_e32 v52, v52, v54
	v_add_f32_e32 v56, v53, v52
	v_mul_f32_e32 v52, 0x3d372713, v36
	v_mul_f32_e32 v53, 0x3d372713, v37
	v_mul_f32_e32 v52, v36, v52
	v_mul_f32_e32 v53, v37, v53
	v_fma_f32 v52, v36, v52, v36
	v_fma_f32 v53, v37, v53, v37
	v_mul_f32_e32 v52, 0x3f4c422a, v52
	v_mul_f32_e32 v53, 0x3f4c422a, v53
	v_add_f32_e32 v52, v52, v52
	v_add_f32_e32 v53, v53, v53
	v_mul_f32_e32 v52, 0xbfb8aa3b, v52
	v_mul_f32_e32 v53, 0xbfb8aa3b, v53
	v_exp_f32_e32 v52, v52
	v_exp_f32_e32 v53, v53
	v_add_f32_e32 v52, 1.0, v52
	v_add_f32_e32 v53, 1.0, v53
	v_rcp_f32_e32 v52, v52
	v_rcp_f32_e32 v53, v53
	s_nop 0
	v_pk_mul_f32 v[52:53], v[36:37], v[52:53]
	s_nop 0
	v_pk_mul_f32 v[54:55], v[52:53], v[52:53]
	s_nop 0
	v_add_f32_e32 v54, v54, v56
	v_add_f32_e32 v72, v55, v54
	v_mul_f32_e32 v54, 0x3d372713, v32
	v_mul_f32_e32 v55, 0x3d372713, v33
	v_mul_f32_e32 v54, v32, v54
	v_mul_f32_e32 v55, v33, v55
	v_fma_f32 v54, v32, v54, v32
	v_fma_f32 v55, v33, v55, v33
	v_mul_f32_e32 v54, 0x3f4c422a, v54
	v_mul_f32_e32 v55, 0x3f4c422a, v55
	v_add_f32_e32 v54, v54, v54
	v_add_f32_e32 v55, v55, v55
	v_mul_f32_e32 v54, 0xbfb8aa3b, v54
	v_mul_f32_e32 v55, 0xbfb8aa3b, v55
	v_exp_f32_e32 v54, v54
	v_exp_f32_e32 v55, v55
	v_add_f32_e32 v54, 1.0, v54
	v_add_f32_e32 v55, 1.0, v55
	v_rcp_f32_e32 v54, v54
	v_rcp_f32_e32 v55, v55
	s_nop 0
	v_pk_mul_f32 v[54:55], v[32:33], v[54:55]
	s_nop 0
	v_pk_mul_f32 v[56:57], v[54:55], v[54:55]
	s_nop 0
	v_add_f32_e32 v56, v56, v72
	v_add_f32_e32 v56, v57, v56
	v_mov_b32_e32 v57, v56
	s_nop 1
	v_permlane16_swap_b32_e32 v56, v57
	v_and_b32_e32 v72, 0x7f, v70
	s_waitcnt lgkmcnt(0)
; __device__ __forceinline__ bf16_t f2bf(float f) { return (bf16_t)(pk2(f, 0.f) & 0xffffu); }
; __device__ __forceinline__ float grp_sum(float v) { v += __shfl_xor(v, 16); v += __shfl_xor(v, 32); return v; }
;   __device__ __forceinline__ void operator()(const pg8::f32x4 (&acc)[2][2][4][2], const pg8::Unit& u, int wr, int wc, int fr, int fq) const {
;     ...
;           const float rn = rsqrtf(grp_sum(ss) * (1.f / 64.f) + EPS);
;           bf16_t* dst = vt + ((unsigned)(g * 128 + (tok >> 7)) * 64 + 8 * fq) * 128 + (tok & 127);
; #pragma unroll
;           for (int bj = 0; bj < 2; ++bj)
; #pragma unroll
;             for (int e = 0; e < 8; ++e) dst[(32 * bj + e) * 128] = f2bf(v[bj][e] * rn * sgu_norm[g * 64 + 32 * bj + 8 * fq + e]);
	v_add_f32_e32 v56, v56, v57
	v_mov_b32_e32 v57, v56
	s_nop 1
	v_permlane32_swap_b32_e32 v56, v57
	s_waitcnt lgkmcnt(0)
	v_add_f32_e32 v56, v56, v57
	v_fmamk_f32 v56, v56, 0x3c800000, v154
	v_cmp_gt_f32_e32 vcc, s3, v56
	v_mul_f32_e32 v57, 0x4b800000, v56
	s_nop 0
	v_cndmask_b32_e32 v56, v56, v57, vcc
	v_rsq_f32_e32 v56, v56
	s_nop 0
	v_mul_f32_e32 v57, 0x45800000, v56
	v_cndmask_b32_e32 v82, v56, v57, vcc
	v_lshrrev_b32_e32 v56, 1, v70
	v_and_b32_e32 v56, 0x1ffffc0, v56
	v_add_lshl_u32 v136, v56, v203, 7
	v_lshl_add_u64 v[56:57], v[136:137], 1, s[50:51]
	v_lshlrev_b32_e32 v136, 1, v72
	global_load_dwordx4 v[72:75], v[80:81], off offset:16
	global_load_dwordx4 v[76:79], v[80:81], off
	v_mul_f32_e32 v58, v58, v82
	v_lshl_add_u64 v[56:57], v[56:57], 0, v[136:137]
	v_mul_f32_e32 v71, v71, v82
	v_mul_f32_e32 v34, v34, v82
	s_waitcnt vmcnt(0)
	v_mul_f32_e32 v58, v77, v58
	v_cvt_pk_bf16_f32 v58, v58, s0
	global_store_short v[56:57], v58, off offset:256
	v_mul_f32_e32 v58, v59, v82
	v_mul_f32_e32 v58, v78, v58
	v_cvt_pk_bf16_f32 v58, v58, s0
	global_store_short v[56:57], v58, off offset:512
	v_mul_f32_e32 v58, v60, v82
	v_mul_f32_e32 v58, v79, v58
	v_cvt_pk_bf16_f32 v58, v58, s0
	global_store_short v[56:57], v58, off offset:768
	v_mul_f32_e32 v58, v61, v82
	v_mul_f32_e32 v58, v72, v58
	v_cvt_pk_bf16_f32 v58, v58, s0
	global_store_short v[56:57], v58, off offset:1024
	v_mul_f32_e32 v58, v62, v82
	v_mul_f32_e32 v58, v58, v73
	v_cvt_pk_bf16_f32 v58, v58, s0
	global_store_short v[56:57], v58, off offset:1280
	v_mul_f32_e32 v58, v63, v82
	v_mul_f32_e32 v58, v58, v74
	v_cvt_pk_bf16_f32 v58, v58, s0
	global_store_short v[56:57], v58, off offset:1536
	v_mul_f32_e32 v58, v68, v82
	v_mul_f32_e32 v71, v76, v71
	v_mul_f32_e32 v58, v58, v75
	v_cvt_pk_bf16_f32 v71, v71, s0
	v_cvt_pk_bf16_f32 v58, v58, s0
	global_store_short v[56:57], v71, off
	global_store_short v[56:57], v58, off offset:1792
	global_load_dwordx4 v[58:61], v[80:81], off offset:144
	s_nop 0
	global_load_dwordx4 v[72:75], v[80:81], off offset:128
	v_add_co_u32_e32 v56, vcc, s97, v56
	v_mov_b32_e32 v68, v69
	s_nop 0
	v_addc_co_u32_e32 v57, vcc, 0, v57, vcc
	s_waitcnt vmcnt(0)
	v_mul_f32_e32 v34, v34, v72
	v_cvt_pk_bf16_f32 v34, v34, s0
	global_store_short v[56:57], v34, off
	v_mul_f32_e32 v34, v35, v82
	v_mul_f32_e32 v34, v34, v73
	v_cvt_pk_bf16_f32 v34, v34, s0
	global_store_short v[56:57], v34, off offset:256
	v_mul_f32_e32 v34, v50, v82
	v_mul_f32_e32 v34, v34, v74
	v_cvt_pk_bf16_f32 v34, v34, s0
	global_store_short v[56:57], v34, off offset:512
	v_mul_f32_e32 v34, v51, v82
	v_mul_f32_e32 v34, v34, v75
	v_cvt_pk_bf16_f32 v34, v34, s0
	global_store_short v[56:57], v34, off offset:768
	v_mul_f32_e32 v34, v52, v82
	v_mul_f32_e32 v34, v34, v58
	v_cvt_pk_bf16_f32 v34, v34, s0
	global_store_short v[56:57], v34, off offset:1024
	v_mul_f32_e32 v34, v53, v82
	v_mul_f32_e32 v34, v34, v59
	v_cvt_pk_bf16_f32 v34, v34, s0
	global_store_short v[56:57], v34, off offset:1280
	v_mul_f32_e32 v34, v54, v82
	v_mul_f32_e32 v34, v34, v60
	v_cvt_pk_bf16_f32 v34, v34, s0
	global_store_short v[56:57], v34, off offset:1536
	v_mul_f32_e32 v34, v55, v82
	v_mul_f32_e32 v34, v34, v61
	v_cvt_pk_bf16_f32 v34, v34, s0
	global_store_short v[56:57], v34, off offset:1792

; __device__ __forceinline__ float grp_sum(float v) { v += __shfl_xor(v, 16); v += __shfl_xor(v, 32); return v; }
; __device__ __forceinline__ void st8_bf16(bf16_t* dst, const float (&v)[8]) { u32x4 w; w.x = pk2(v[0], v[1]); w.y = pk2(v[2], v[3]); w.z = pk2(v[4], v[5]); w.w = pk2(v[6], v[7]); *(u32x4*)dst = w; }
;   __device__ __forceinline__ void operator()(const pg8::f32x4 (&acc)[2][2][4][2], const pg8::Unit& u, int wr, int wc, int fr, int fq) const {
;     ...
;           const bool isq = gi < 24; const int hm = isq ? gi - 16 : gi - 24;
;           const float* gn = isq ? q_norm : k_norm;
;           float ss = 0.f;
; #pragma unroll
;           for (int bj = 0; bj < 2; ++bj)
; #pragma unroll
;             for (int e = 0; e < 8; ++e) ss += v[bj][e] * v[bj][e];
;           const float rn = rsqrtf(grp_sum(ss) * (1.f / 64.f) + EPS) * (isq ? 0.125f * LOG2E : 1.f);
;           const f32x4 c0 = *(const f32x4*)(cos64 + (unsigned)pos * 32 + 8 * fq), c1 = *(const f32x4*)(cos64 + (unsigned)pos * 32 + 8 * fq + 4);
;           const f32x4 s0 = *(const f32x4*)(sin64 + (unsigned)pos * 32 + 8 * fq), s1 = *(const f32x4*)(sin64 + (unsigned)pos * 32 + 8 * fq + 4);
;           float kk = 0.f;
; #pragma unroll
;           for (int e = 0; e < 8; ++e) {
;             const float x1 = v[0][e] * rn * gn[8 * fq + e], x2 = v[1][e] * rn * gn[32 + 8 * fq + e];
;             const float cc = e < 4 ? c0[e & 3] : c1[e & 3], sn = e < 4 ? s0[e & 3] : s1[e & 3];
;             v[0][e] = x1 * cc - x2 * sn; v[1][e] = x1 * sn + x2 * cc;
;             kk += v[0][e] * v[0][e] + v[1][e] * v[1][e];
;           }
;           bf16_t* dst = (isq ? qb : kb) + ((unsigned)(bb * 8 + hm) * S + pos) * 64 + 8 * fq;
;           st8_bf16(dst, v[0]); st8_bf16(dst + 32, v[1]);
;           if (!isq) kmx_run = fmaxf(kmx_run, grp_sum(kk));
.LBB0_467:
	s_andn2_b64 vcc, exec, s[82:83]
	v_mov_b32_e32 v33, v68
	s_cbranch_vccnz .LBB0_470
	v_pk_mul_f32 v[18:19], v[34:35], v[34:35]
	v_pk_mul_f32 v[36:37], v[30:31], v[30:31]
	v_add_f32_e32 v18, v18, v19
	v_add_f32_e32 v18, v36, v18
	v_pk_mul_f32 v[38:39], v[28:29], v[28:29]
	v_add_f32_e32 v18, v37, v18
	v_add_f32_e32 v18, v38, v18
	v_pk_mul_f32 v[40:41], v[26:27], v[26:27]
	v_add_f32_e32 v18, v39, v18
	v_add_f32_e32 v18, v40, v18
	v_pk_mul_f32 v[42:43], v[24:25], v[24:25]
	v_add_f32_e32 v18, v41, v18
	v_add_f32_e32 v18, v42, v18
	v_pk_mul_f32 v[44:45], v[22:23], v[22:23]
	v_add_f32_e32 v18, v43, v18
	v_add_f32_e32 v18, v44, v18
	v_pk_mul_f32 v[46:47], v[20:21], v[20:21]
	v_add_f32_e32 v18, v45, v18
	v_add_f32_e32 v18, v46, v18
	v_pk_mul_f32 v[48:49], v[16:17], v[16:17]
	v_add_f32_e32 v18, v47, v18
	v_add_f32_e32 v18, v48, v18
	v_add_f32_e32 v18, v49, v18
	v_mov_b32_e32 v19, v18
	s_nop 1
	v_permlane16_swap_b32_e32 v18, v19
	v_lshlrev_b32_e32 v136, 7, v52
	s_and_b64 s[82:83], s[6:7], exec
	s_cselect_b32 s83, s17, s19
	s_cselect_b32 s82, s16, s18
	s_waitcnt lgkmcnt(0)
	v_add_f32_e32 v18, v18, v19
	v_mov_b32_e32 v19, v18
	s_nop 1
	v_permlane32_swap_b32_e32 v18, v19
	v_lshlrev_b32_e32 v33, 2, v138
	s_cselect_b32 s71, s87, s89
	v_mov_b32_e32 v113, v137
	s_waitcnt lgkmcnt(0)
	v_add_f32_e32 v18, v18, v19
	v_fmamk_f32 v18, v18, 0x3c800000, v154
	v_cmp_gt_f32_e32 vcc, s3, v18
	v_mul_f32_e32 v19, 0x4b800000, v18
	s_nop 0
	v_cndmask_b32_e32 v18, v18, v19, vcc
	v_rsq_f32_e32 v18, v18
	s_nop 0
	v_mul_f32_e32 v19, 0x45800000, v18
	v_cndmask_b32_e32 v18, v18, v19, vcc
	v_mul_f32_e32 v66, v204, v18
	v_lshl_add_u64 v[18:19], v[140:141], 0, v[136:137]
	global_load_dwordx4 v[46:49], v[18:19], off offset:16
	global_load_dwordx4 v[38:41], v[18:19], off
	v_lshl_add_u64 v[18:19], v[142:143], 0, v[136:137]
	global_load_dwordx4 v[54:57], v[18:19], off offset:16
	global_load_dwordx4 v[42:45], v[18:19], off
	global_load_dwordx4 v[58:61], v33, s[82:83] offset:16
	global_load_dwordx4 v[62:65], v33, s[82:83]
	global_load_dwordx4 v[70:73], v33, s[82:83] offset:144
	global_load_dwordx4 v[74:77], v33, s[82:83] offset:128
	v_pk_mul_f32 v[18:19], v[34:35], v[66:67] op_sel_hi:[1,0]
	v_lshl_add_u32 v33, v51, 16, s59
	s_cselect_b32 s82, s86, s88
	v_or_b32_e32 v33, v33, v52
	v_lshlrev_b32_e32 v136, 6, v33
	s_andn2_b64 vcc, exec, s[78:79]
	v_mov_b32_e32 v33, v68
	s_waitcnt vmcnt(2)
	v_pk_mul_f32 v[36:37], v[62:63], v[18:19]
	v_pk_mul_f32 v[18:19], v[24:25], v[66:67] op_sel_hi:[1,0]
	s_waitcnt vmcnt(0)
	v_pk_mul_f32 v[62:63], v[74:75], v[18:19]
	s_nop 0
	v_pk_mul_f32 v[18:19], v[42:43], v[62:63]
	s_nop 0
	v_pk_fma_f32 v[18:19], v[38:39], v[36:37], v[18:19] neg_lo:[0,0,1] neg_hi:[0,0,1]
	v_pk_mul_f32 v[36:37], v[42:43], v[36:37]
	s_nop 0
	v_pk_fma_f32 v[36:37], v[38:39], v[62:63], v[36:37]
	v_pk_mul_f32 v[38:39], v[30:31], v[66:67] op_sel_hi:[1,0]
	s_nop 0
	v_pk_mul_f32 v[42:43], v[38:39], v[64:65]
	v_pk_mul_f32 v[38:39], v[22:23], v[66:67] op_sel_hi:[1,0]
	s_nop 0
	v_pk_mul_f32 v[62:63], v[38:39], v[76:77]
	s_nop 0
	v_pk_mul_f32 v[38:39], v[44:45], v[62:63]
	s_nop 0
	v_pk_fma_f32 v[38:39], v[40:41], v[42:43], v[38:39] neg_lo:[0,0,1] neg_hi:[0,0,1]
	v_pk_mul_f32 v[40:41], v[40:41], v[62:63]
	s_nop 0
	v_pk_fma_f32 v[40:41], v[44:45], v[42:43], v[40:41]
	v_pk_mul_f32 v[42:43], v[28:29], v[66:67] op_sel_hi:[1,0]
	s_nop 0
	v_pk_mul_f32 v[44:45], v[42:43], v[58:59]
	v_pk_mul_f32 v[42:43], v[20:21], v[66:67] op_sel_hi:[1,0]
	s_nop 0
	v_pk_mul_f32 v[58:59], v[42:43], v[70:71]
	s_nop 0
	v_pk_mul_f32 v[42:43], v[54:55], v[58:59]
	s_nop 0
	v_pk_fma_f32 v[42:43], v[46:47], v[44:45], v[42:43] neg_lo:[0,0,1] neg_hi:[0,0,1]
	v_pk_mul_f32 v[46:47], v[46:47], v[58:59]
	s_nop 0
	v_pk_fma_f32 v[44:45], v[54:55], v[44:45], v[46:47]
	v_pk_mul_f32 v[46:47], v[26:27], v[66:67] op_sel_hi:[1,0]
	s_nop 0
	v_pk_mul_f32 v[54:55], v[46:47], v[60:61]
	v_pk_mul_f32 v[46:47], v[16:17], v[66:67] op_sel_hi:[1,0]
	s_nop 0
	v_pk_mul_f32 v[58:59], v[46:47], v[72:73]
	s_nop 0
	v_pk_mul_f32 v[46:47], v[56:57], v[58:59]
	s_nop 0
	v_pk_fma_f32 v[46:47], v[48:49], v[54:55], v[46:47] neg_lo:[0,0,1] neg_hi:[0,0,1]
	v_pk_mul_f32 v[48:49], v[48:49], v[58:59]
	s_nop 0
	v_pk_fma_f32 v[48:49], v[56:57], v[54:55], v[48:49]
	v_mov_b32_e32 v54, s82
	v_mov_b32_e32 v55, s71
	v_lshl_add_u64 v[52:53], v[136:137], 1, v[54:55]
	v_lshl_add_u64 v[56:57], v[52:53], 0, v[112:113]
	v_cvt_pk_bf16_f32 v52, v18, v19
	v_cvt_pk_bf16_f32 v53, v38, v39
	v_cvt_pk_bf16_f32 v54, v42, v43
	v_cvt_pk_bf16_f32 v55, v46, v47
	global_store_dwordx4 v[56:57], v[52:55], off
	s_nop 1
	v_cvt_pk_bf16_f32 v52, v36, v37
	v_cvt_pk_bf16_f32 v53, v40, v41
	v_cvt_pk_bf16_f32 v54, v44, v45
	v_cvt_pk_bf16_f32 v55, v48, v49
	global_store_dwordx4 v[56:57], v[52:55], off offset:64
	s_cbranch_vccnz .LBB0_470
	v_pk_mul_f32 v[36:37], v[36:37], v[36:37]
	s_nop 0
	v_pk_fma_f32 v[18:19], v[18:19], v[18:19], v[36:37]
	v_pk_mul_f32 v[36:37], v[40:41], v[40:41]
	v_add_f32_e32 v18, v18, v19
	v_pk_fma_f32 v[36:37], v[38:39], v[38:39], v[36:37]
	v_pk_mul_f32 v[38:39], v[44:45], v[44:45]
	v_add_f32_e32 v18, v36, v18
	v_pk_fma_f32 v[38:39], v[42:43], v[42:43], v[38:39]
	v_add_f32_e32 v18, v37, v18
	v_pk_mul_f32 v[40:41], v[48:49], v[48:49]
	v_add_f32_e32 v18, v18, v38
	v_pk_fma_f32 v[40:41], v[46:47], v[46:47], v[40:41]
	v_add_f32_e32 v18, v18, v39
	v_add_f32_e32 v18, v18, v40
	v_add_f32_e32 v18, v18, v41
	v_mov_b32_e32 v19, v18
	s_nop 1
	v_permlane16_swap_b32_e32 v18, v19
	s_waitcnt lgkmcnt(0)
	v_add_f32_e32 v18, v18, v19
	v_mov_b32_e32 v19, v18
	s_nop 1
	v_permlane32_swap_b32_e32 v18, v19
	s_waitcnt lgkmcnt(0)
	v_add_f32_e32 v18, v18, v19
	v_max_f32_e32 v19, v68, v68
	v_max_f32_e32 v33, v19, v18

; __device__ __forceinline__ float fexp2(float x) { return __builtin_amdgcn_exp2f(x); }
; __device__ __forceinline__ float frcp(float x) { return __builtin_amdgcn_rcpf(x); }
; __device__ __forceinline__ float gelu_tanh(float x) { const float y = 0.7978845608028654f * (x + 0.044715f * x * x * x); return x * sigm(2.f * y); }
; __device__ __forceinline__ float grp_sum(float v) { v += __shfl_xor(v, 16); v += __shfl_xor(v, 32); return v; }
; __device__ __forceinline__ float sigm(float x) { return frcp(1.f + fexp2(-LOG2E * x)); }
;   __device__ __forceinline__ void operator()(const pg8::f32x4 (&acc)[2][2][4][2], const pg8::Unit& u, int wr, int wc, int fr, int fq) const {
;     ...
;           const int g = gi - 8; float ss = 0.f;
; #pragma unroll
;           for (int bj = 0; bj < 2; ++bj)
; #pragma unroll
;             for (int e = 0; e < 8; ++e) { v[bj][e] = gelu_tanh(v[bj][e]); ss += v[bj][e] * v[bj][e]; }
;           const float rn = rsqrtf(grp_sum(ss) * (1.f / 64.f) + EPS);
.LBB0_471:
	s_andn2_b64 vcc, exec, s[82:83]
	s_cbranch_vccnz .LBB0_473
	v_mul_f32_e32 v18, 0x3d372713, v34
	v_mul_f32_e32 v18, v34, v18
	v_fma_f32 v18, v34, v18, v34
	v_mul_f32_e32 v18, 0x3f4c422a, v18
	v_add_f32_e32 v18, v18, v18
	v_mul_f32_e32 v18, 0xbfb8aa3b, v18
	v_exp_f32_e32 v18, v18
	v_mul_f32_e32 v19, 0x3d372713, v25
	v_mul_f32_e32 v19, v25, v19
	v_fma_f32 v19, v25, v19, v25
	v_add_f32_e32 v18, 1.0, v18
	v_rcp_f32_e32 v18, v18
	v_mul_f32_e32 v19, 0x3f4c422a, v19
	v_add_f32_e32 v19, v19, v19
	v_mul_f32_e32 v19, 0xbfb8aa3b, v19
	v_mul_f32_e32 v51, v34, v18
	v_mul_f32_e32 v18, 0x3d372713, v35
	v_mul_f32_e32 v18, v35, v18
	v_fma_f32 v18, v35, v18, v35
	v_mul_f32_e32 v18, 0x3f4c422a, v18
	v_add_f32_e32 v18, v18, v18
	v_mul_f32_e32 v18, 0xbfb8aa3b, v18
	v_exp_f32_e32 v18, v18
	v_exp_f32_e32 v19, v19
	v_mov_b32_e32 v157, v137
	v_lshl_add_u64 v[60:61], v[156:157], 2, s[56:57]
	v_add_f32_e32 v18, 1.0, v18
	v_rcp_f32_e32 v18, v18
	v_add_f32_e32 v19, 1.0, v19
	v_rcp_f32_e32 v19, v19
	v_mul_f32_e32 v33, v35, v18
	v_mul_f32_e32 v18, 0x3d372713, v30
	v_mul_f32_e32 v18, v30, v18
	v_fma_f32 v18, v30, v18, v30
	v_mul_f32_e32 v18, 0x3f4c422a, v18
	v_add_f32_e32 v18, v18, v18
	v_mul_f32_e32 v18, 0xbfb8aa3b, v18
	v_exp_f32_e32 v18, v18
	v_mul_f32_e32 v38, v33, v33
	v_fmac_f32_e32 v38, v51, v51
	v_add_f32_e32 v18, 1.0, v18
	v_rcp_f32_e32 v18, v18
	s_nop 0
	v_mul_f32_e32 v44, v30, v18
	v_mul_f32_e32 v18, 0x3d372713, v31
	v_mul_f32_e32 v18, v31, v18
	v_fma_f32 v18, v31, v18, v31
	v_mul_f32_e32 v18, 0x3f4c422a, v18
	v_add_f32_e32 v18, v18, v18
	v_mul_f32_e32 v18, 0xbfb8aa3b, v18
	v_exp_f32_e32 v18, v18
	v_fmac_f32_e32 v38, v44, v44
	v_add_f32_e32 v18, 1.0, v18
	v_rcp_f32_e32 v18, v18
	s_nop 0
	v_mul_f32_e32 v45, v31, v18
	v_mul_f32_e32 v18, 0x3d372713, v28
	v_mul_f32_e32 v18, v28, v18
	v_fma_f32 v18, v28, v18, v28
	v_mul_f32_e32 v18, 0x3f4c422a, v18
	v_add_f32_e32 v18, v18, v18
	v_mul_f32_e32 v18, 0xbfb8aa3b, v18
	v_exp_f32_e32 v18, v18
	v_fmac_f32_e32 v38, v45, v45
	v_add_f32_e32 v18, 1.0, v18
	v_rcp_f32_e32 v18, v18
	s_nop 0
	v_mul_f32_e32 v46, v28, v18
	v_mul_f32_e32 v18, 0x3d372713, v29
	v_mul_f32_e32 v18, v29, v18
	v_fma_f32 v18, v29, v18, v29
	v_mul_f32_e32 v18, 0x3f4c422a, v18
	v_add_f32_e32 v18, v18, v18
	v_mul_f32_e32 v18, 0xbfb8aa3b, v18
	v_exp_f32_e32 v18, v18
	v_fmac_f32_e32 v38, v46, v46
	v_add_f32_e32 v18, 1.0, v18
	v_rcp_f32_e32 v18, v18
	s_nop 0
	v_mul_f32_e32 v47, v29, v18
	v_mul_f32_e32 v18, 0x3d372713, v26
	v_mul_f32_e32 v18, v26, v18
	v_fma_f32 v18, v26, v18, v26
	v_mul_f32_e32 v18, 0x3f4c422a, v18
	v_add_f32_e32 v18, v18, v18
	v_mul_f32_e32 v18, 0xbfb8aa3b, v18
	v_exp_f32_e32 v18, v18
	v_fmac_f32_e32 v38, v47, v47
	v_add_f32_e32 v18, 1.0, v18
	v_rcp_f32_e32 v18, v18
	s_nop 0
	v_mul_f32_e32 v48, v26, v18
	v_mul_f32_e32 v18, 0x3d372713, v27
	v_mul_f32_e32 v18, v27, v18
	v_fma_f32 v18, v27, v18, v27
	v_mul_f32_e32 v18, 0x3f4c422a, v18
	v_add_f32_e32 v18, v18, v18
	v_mul_f32_e32 v18, 0xbfb8aa3b, v18
	v_exp_f32_e32 v18, v18
	v_fmac_f32_e32 v38, v48, v48
	v_add_f32_e32 v18, 1.0, v18
	v_rcp_f32_e32 v18, v18
	s_nop 0
	v_mul_f32_e32 v49, v27, v18
	v_mul_f32_e32 v18, 0x3d372713, v24
	v_mul_f32_e32 v18, v24, v18
	v_fma_f32 v18, v24, v18, v24
	v_mul_f32_e32 v18, 0x3f4c422a, v18
	v_add_f32_e32 v18, v18, v18
	v_mul_f32_e32 v18, 0xbfb8aa3b, v18
	v_exp_f32_e32 v18, v18
	v_fmac_f32_e32 v38, v49, v49
	v_add_f32_e32 v18, 1.0, v18
	v_rcp_f32_e32 v18, v18
	s_nop 0
	v_pk_mul_f32 v[18:19], v[24:25], v[18:19]
	s_nop 0
	v_pk_mul_f32 v[36:37], v[18:19], v[18:19]
	s_nop 0
	v_add_f32_e32 v36, v36, v38
	v_add_f32_e32 v40, v37, v36
	v_mul_f32_e32 v36, 0x3d372713, v22
	v_mul_f32_e32 v37, 0x3d372713, v23
	v_mul_f32_e32 v36, v22, v36
	v_mul_f32_e32 v37, v23, v37
	v_fma_f32 v36, v22, v36, v22
	v_fma_f32 v37, v23, v37, v23
	v_mul_f32_e32 v36, 0x3f4c422a, v36
	v_mul_f32_e32 v37, 0x3f4c422a, v37
	v_add_f32_e32 v36, v36, v36
	v_add_f32_e32 v37, v37, v37
	v_mul_f32_e32 v36, 0xbfb8aa3b, v36
	v_mul_f32_e32 v37, 0xbfb8aa3b, v37
	v_exp_f32_e32 v36, v36
	v_exp_f32_e32 v37, v37
	v_add_f32_e32 v36, 1.0, v36
	v_add_f32_e32 v37, 1.0, v37
	v_rcp_f32_e32 v36, v36
	v_rcp_f32_e32 v37, v37
	s_nop 0
	v_pk_mul_f32 v[36:37], v[22:23], v[36:37]
	s_nop 0
	v_pk_mul_f32 v[38:39], v[36:37], v[36:37]
	s_nop 0
	v_add_f32_e32 v38, v38, v40
	v_add_f32_e32 v42, v39, v38
	v_mul_f32_e32 v38, 0x3d372713, v20
	v_mul_f32_e32 v39, 0x3d372713, v21
	v_mul_f32_e32 v38, v20, v38
	v_mul_f32_e32 v39, v21, v39
	v_fma_f32 v38, v20, v38, v20
	v_fma_f32 v39, v21, v39, v21
	v_mul_f32_e32 v38, 0x3f4c422a, v38
	v_mul_f32_e32 v39, 0x3f4c422a, v39
	v_add_f32_e32 v38, v38, v38
	v_add_f32_e32 v39, v39, v39
	v_mul_f32_e32 v38, 0xbfb8aa3b, v38
	v_mul_f32_e32 v39, 0xbfb8aa3b, v39
	v_exp_f32_e32 v38, v38
	v_exp_f32_e32 v39, v39
	v_add_f32_e32 v38, 1.0, v38
	v_add_f32_e32 v39, 1.0, v39
	v_rcp_f32_e32 v38, v38
	v_rcp_f32_e32 v39, v39
	s_nop 0
	v_pk_mul_f32 v[38:39], v[20:21], v[38:39]
	s_nop 0
	v_pk_mul_f32 v[40:41], v[38:39], v[38:39]
	s_nop 0
	v_add_f32_e32 v40, v40, v42
	v_add_f32_e32 v52, v41, v40
	v_mul_f32_e32 v40, 0x3d372713, v16
	v_mul_f32_e32 v41, 0x3d372713, v17
	v_mul_f32_e32 v40, v16, v40
	v_mul_f32_e32 v41, v17, v41
	v_fma_f32 v40, v16, v40, v16
	v_fma_f32 v41, v17, v41, v17
	v_mul_f32_e32 v40, 0x3f4c422a, v40
	v_mul_f32_e32 v41, 0x3f4c422a, v41
	v_add_f32_e32 v40, v40, v40
	v_add_f32_e32 v41, v41, v41
	v_mul_f32_e32 v40, 0xbfb8aa3b, v40
	v_mul_f32_e32 v41, 0xbfb8aa3b, v41
	v_exp_f32_e32 v40, v40
	v_exp_f32_e32 v41, v41
	v_add_f32_e32 v40, 1.0, v40
	v_add_f32_e32 v41, 1.0, v41
	v_rcp_f32_e32 v40, v40
	v_rcp_f32_e32 v41, v41
	s_nop 0
	v_pk_mul_f32 v[40:41], v[16:17], v[40:41]
	s_nop 0
	v_pk_mul_f32 v[42:43], v[40:41], v[40:41]
	s_nop 0
	v_add_f32_e32 v42, v42, v52
	v_add_f32_e32 v42, v43, v42
	v_mov_b32_e32 v43, v42
	s_nop 1
	v_permlane16_swap_b32_e32 v42, v43
	v_and_b32_e32 v52, 0x7f, v50
	s_waitcnt lgkmcnt(0)
; __device__ __forceinline__ bf16_t f2bf(float f) { return (bf16_t)(pk2(f, 0.f) & 0xffffu); }
; __device__ __forceinline__ float grp_sum(float v) { v += __shfl_xor(v, 16); v += __shfl_xor(v, 32); return v; }
;   __device__ __forceinline__ void operator()(const pg8::f32x4 (&acc)[2][2][4][2], const pg8::Unit& u, int wr, int wc, int fr, int fq) const {
;     ...
;           const float rn = rsqrtf(grp_sum(ss) * (1.f / 64.f) + EPS);
;           bf16_t* dst = vt + ((unsigned)(g * 128 + (tok >> 7)) * 64 + 8 * fq) * 128 + (tok & 127);
; #pragma unroll
;           for (int bj = 0; bj < 2; ++bj)
; #pragma unroll
;             for (int e = 0; e < 8; ++e) dst[(32 * bj + e) * 128] = f2bf(v[bj][e] * rn * sgu_norm[g * 64 + 32 * bj + 8 * fq + e]);
	v_add_f32_e32 v42, v42, v43
	v_mov_b32_e32 v43, v42
	s_nop 1
	v_permlane32_swap_b32_e32 v42, v43
	s_waitcnt lgkmcnt(0)
	v_add_f32_e32 v42, v42, v43
	v_fmamk_f32 v42, v42, 0x3c800000, v154
	v_cmp_gt_f32_e32 vcc, s3, v42
	v_mul_f32_e32 v43, 0x4b800000, v42
	s_nop 0
	v_cndmask_b32_e32 v42, v42, v43, vcc
	v_rsq_f32_e32 v42, v42
	s_nop 0
	v_mul_f32_e32 v43, 0x45800000, v42
	v_cndmask_b32_e32 v62, v42, v43, vcc
	v_lshrrev_b32_e32 v42, 1, v50
	v_and_b32_e32 v42, 0x1ffffc0, v42
	v_add_lshl_u32 v136, v42, v203, 7
	v_lshl_add_u64 v[42:43], v[136:137], 1, s[50:51]
	v_lshlrev_b32_e32 v136, 1, v52
	global_load_dwordx4 v[52:55], v[60:61], off offset:16
	global_load_dwordx4 v[56:59], v[60:61], off
	v_mul_f32_e32 v33, v33, v62
	v_lshl_add_u64 v[42:43], v[42:43], 0, v[136:137]
	v_mul_f32_e32 v51, v51, v62
	v_mul_f32_e32 v18, v18, v62
	s_waitcnt vmcnt(0)
	v_mul_f32_e32 v33, v57, v33
	v_cvt_pk_bf16_f32 v33, v33, s0
	global_store_short v[42:43], v33, off offset:256
	v_mul_f32_e32 v33, v44, v62
	v_mul_f32_e32 v33, v58, v33
	v_cvt_pk_bf16_f32 v33, v33, s0
	global_store_short v[42:43], v33, off offset:512
	v_mul_f32_e32 v33, v45, v62
	v_mul_f32_e32 v33, v59, v33
	v_cvt_pk_bf16_f32 v33, v33, s0
	global_store_short v[42:43], v33, off offset:768
	v_mul_f32_e32 v33, v46, v62
	v_mul_f32_e32 v33, v52, v33
	v_cvt_pk_bf16_f32 v33, v33, s0
	global_store_short v[42:43], v33, off offset:1024
	v_mul_f32_e32 v33, v47, v62
	v_mul_f32_e32 v33, v33, v53
	v_cvt_pk_bf16_f32 v33, v33, s0
	global_store_short v[42:43], v33, off offset:1280
	v_mul_f32_e32 v33, v48, v62
	v_mul_f32_e32 v33, v33, v54
	v_cvt_pk_bf16_f32 v33, v33, s0
	global_store_short v[42:43], v33, off offset:1536
	v_mul_f32_e32 v33, v49, v62
	v_mul_f32_e32 v51, v56, v51
	v_mul_f32_e32 v33, v33, v55
	v_cvt_pk_bf16_f32 v51, v51, s0
	v_cvt_pk_bf16_f32 v33, v33, s0
	global_store_short v[42:43], v51, off
	global_store_short v[42:43], v33, off offset:1792
	global_load_dwordx4 v[44:47], v[60:61], off offset:144
	global_load_dwordx4 v[52:55], v[60:61], off offset:128
	v_add_co_u32_e32 v42, vcc, s97, v42
	v_mov_b32_e32 v33, v68
	s_nop 0
	v_addc_co_u32_e32 v43, vcc, 0, v43, vcc
	s_waitcnt vmcnt(0)
	v_mul_f32_e32 v18, v18, v52
	v_cvt_pk_bf16_f32 v18, v18, s0
	global_store_short v[42:43], v18, off
	v_mul_f32_e32 v18, v19, v62
	v_mul_f32_e32 v18, v18, v53
	v_cvt_pk_bf16_f32 v18, v18, s0
	global_store_short v[42:43], v18, off offset:256
	v_mul_f32_e32 v18, v36, v62
	v_mul_f32_e32 v18, v18, v54
	v_cvt_pk_bf16_f32 v18, v18, s0
	global_store_short v[42:43], v18, off offset:512
	v_mul_f32_e32 v18, v37, v62
	v_mul_f32_e32 v18, v18, v55
	v_cvt_pk_bf16_f32 v18, v18, s0
	global_store_short v[42:43], v18, off offset:768
	v_mul_f32_e32 v18, v38, v62
	v_mul_f32_e32 v18, v18, v44
	v_cvt_pk_bf16_f32 v18, v18, s0
	global_store_short v[42:43], v18, off offset:1024
	v_mul_f32_e32 v18, v39, v62
	v_mul_f32_e32 v18, v18, v45
	v_cvt_pk_bf16_f32 v18, v18, s0
	global_store_short v[42:43], v18, off offset:1280
	v_mul_f32_e32 v18, v40, v62
	v_mul_f32_e32 v18, v18, v46
	v_cvt_pk_bf16_f32 v18, v18, s0
	global_store_short v[42:43], v18, off offset:1536
	v_mul_f32_e32 v18, v41, v62
	v_mul_f32_e32 v18, v18, v47
	v_cvt_pk_bf16_f32 v18, v18, s0
	global_store_short v[42:43], v18, off offset:1792

; __device__ __forceinline__ float grp_sum(float v) { v += __shfl_xor(v, 16); v += __shfl_xor(v, 32); return v; }
; __device__ __forceinline__ void st8_bf16(bf16_t* dst, const float (&v)[8]) { u32x4 w; w.x = pk2(v[0], v[1]); w.y = pk2(v[2], v[3]); w.z = pk2(v[4], v[5]); w.w = pk2(v[6], v[7]); *(u32x4*)dst = w; }
;   __device__ __forceinline__ void operator()(const pg8::f32x4 (&acc)[2][2][4][2], const pg8::Unit& u, int wr, int wc, int fr, int fq) const {
;     ...
;           const bool isq = gi < 24; const int hm = isq ? gi - 16 : gi - 24;
;           const float* gn = isq ? q_norm : k_norm;
;           float ss = 0.f;
; #pragma unroll
;           for (int bj = 0; bj < 2; ++bj)
; #pragma unroll
;             for (int e = 0; e < 8; ++e) ss += v[bj][e] * v[bj][e];
;           const float rn = rsqrtf(grp_sum(ss) * (1.f / 64.f) + EPS) * (isq ? 0.125f * LOG2E : 1.f);
;           const f32x4 c0 = *(const f32x4*)(cos64 + (unsigned)pos * 32 + 8 * fq), c1 = *(const f32x4*)(cos64 + (unsigned)pos * 32 + 8 * fq + 4);
;           const f32x4 s0 = *(const f32x4*)(sin64 + (unsigned)pos * 32 + 8 * fq), s1 = *(const f32x4*)(sin64 + (unsigned)pos * 32 + 8 * fq + 4);
;           float kk = 0.f;
; #pragma unroll
;           for (int e = 0; e < 8; ++e) {
;             const float x1 = v[0][e] * rn * gn[8 * fq + e], x2 = v[1][e] * rn * gn[32 + 8 * fq + e];
;             const float cc = e < 4 ? c0[e & 3] : c1[e & 3], sn = e < 4 ? s0[e & 3] : s1[e & 3];
;             v[0][e] = x1 * cc - x2 * sn; v[1][e] = x1 * sn + x2 * cc;
;             kk += v[0][e] * v[0][e] + v[1][e] * v[1][e];
;           }
;           bf16_t* dst = (isq ? qb : kb) + ((unsigned)(bb * 8 + hm) * S + pos) * 64 + 8 * fq;
;           st8_bf16(dst, v[0]); st8_bf16(dst + 32, v[1]);
;           if (!isq) kmx_run = fmaxf(kmx_run, grp_sum(kk));
.LBB0_480:
	s_andn2_b64 vcc, exec, s[8:9]
	v_mov_b32_e32 v36, v33
	s_cbranch_vccnz .LBB0_483
	v_pk_mul_f32 v[2:3], v[16:17], v[16:17]
	v_pk_mul_f32 v[18:19], v[14:15], v[14:15]
	v_add_f32_e32 v2, v2, v3
	v_add_f32_e32 v2, v18, v2
	v_pk_mul_f32 v[20:21], v[12:13], v[12:13]
	v_add_f32_e32 v2, v19, v2
	v_add_f32_e32 v2, v20, v2
	v_pk_mul_f32 v[22:23], v[10:11], v[10:11]
	v_add_f32_e32 v2, v21, v2
	v_add_f32_e32 v2, v22, v2
	v_pk_mul_f32 v[24:25], v[8:9], v[8:9]
	v_add_f32_e32 v2, v23, v2
	v_add_f32_e32 v2, v24, v2
	v_pk_mul_f32 v[26:27], v[6:7], v[6:7]
	v_add_f32_e32 v2, v25, v2
	v_add_f32_e32 v2, v26, v2
	v_pk_mul_f32 v[28:29], v[4:5], v[4:5]
	v_add_f32_e32 v2, v27, v2
	v_add_f32_e32 v2, v28, v2
	v_pk_mul_f32 v[30:31], v[0:1], v[0:1]
	v_add_f32_e32 v2, v29, v2
	v_add_f32_e32 v2, v30, v2
	v_add_f32_e32 v2, v31, v2
	v_mov_b32_e32 v3, v2
	s_nop 1
	v_permlane16_swap_b32_e32 v2, v3
	v_lshlrev_b32_e32 v136, 7, v35
	s_and_b64 s[6:7], s[6:7], exec
	s_cselect_b32 s7, s17, s19
	s_cselect_b32 s6, s16, s18
	s_waitcnt lgkmcnt(0)
	v_add_f32_e32 v2, v2, v3
	v_mov_b32_e32 v3, v2
	s_nop 1
	v_permlane32_swap_b32_e32 v2, v3
	v_lshlrev_b32_e32 v52, 2, v138
	v_lshl_add_u32 v34, v34, 16, s59
	v_or_b32_e32 v34, v34, v35
	v_mov_b32_e32 v113, v137
	s_waitcnt lgkmcnt(0)
	v_add_f32_e32 v2, v2, v3
	v_fmamk_f32 v2, v2, 0x3c800000, v154
	v_cmp_gt_f32_e32 vcc, s3, v2
	v_mul_f32_e32 v3, 0x4b800000, v2
	s_nop 0
	v_cndmask_b32_e32 v2, v2, v3, vcc
	v_rsq_f32_e32 v2, v2
	s_nop 0
	v_mul_f32_e32 v3, 0x45800000, v2
	v_cndmask_b32_e32 v2, v2, v3, vcc
	v_mul_f32_e32 v56, v204, v2
	v_lshl_add_u64 v[2:3], v[140:141], 0, v[136:137]
	global_load_dwordx4 v[28:31], v[2:3], off offset:16
	global_load_dwordx4 v[20:23], v[2:3], off
	v_lshl_add_u64 v[2:3], v[142:143], 0, v[136:137]
	global_load_dwordx4 v[36:39], v[2:3], off offset:16
	global_load_dwordx4 v[24:27], v[2:3], off
	global_load_dwordx4 v[40:43], v52, s[6:7] offset:16
	global_load_dwordx4 v[44:47], v52, s[6:7]
	global_load_dwordx4 v[48:51], v52, s[6:7] offset:144
	s_nop 0
	global_load_dwordx4 v[52:55], v52, s[6:7] offset:128
	v_pk_mul_f32 v[2:3], v[16:17], v[56:57] op_sel_hi:[1,0]
	s_cselect_b32 s6, s87, s89
	s_cselect_b32 s7, s86, s88
	v_lshlrev_b32_e32 v136, 6, v34
	s_andn2_b64 vcc, exec, s[78:79]
	s_waitcnt vmcnt(2)
	v_pk_mul_f32 v[18:19], v[44:45], v[2:3]
	v_pk_mul_f32 v[2:3], v[8:9], v[56:57] op_sel_hi:[1,0]
	s_waitcnt vmcnt(0)
	v_pk_mul_f32 v[44:45], v[52:53], v[2:3]
	s_nop 0
	v_pk_mul_f32 v[2:3], v[24:25], v[44:45]
	s_nop 0
	v_pk_fma_f32 v[2:3], v[20:21], v[18:19], v[2:3] neg_lo:[0,0,1] neg_hi:[0,0,1]
	v_pk_mul_f32 v[18:19], v[24:25], v[18:19]
	s_nop 0
	v_pk_fma_f32 v[18:19], v[20:21], v[44:45], v[18:19]
	v_pk_mul_f32 v[20:21], v[14:15], v[56:57] op_sel_hi:[1,0]
	s_nop 0
	v_pk_mul_f32 v[24:25], v[20:21], v[46:47]
	v_pk_mul_f32 v[20:21], v[6:7], v[56:57] op_sel_hi:[1,0]
	s_nop 0
	v_pk_mul_f32 v[44:45], v[20:21], v[54:55]
	s_nop 0
	v_pk_mul_f32 v[20:21], v[26:27], v[44:45]
	s_nop 0
	v_pk_fma_f32 v[20:21], v[22:23], v[24:25], v[20:21] neg_lo:[0,0,1] neg_hi:[0,0,1]
	v_pk_mul_f32 v[22:23], v[22:23], v[44:45]
	s_nop 0
	v_pk_fma_f32 v[22:23], v[26:27], v[24:25], v[22:23]
	v_pk_mul_f32 v[24:25], v[12:13], v[56:57] op_sel_hi:[1,0]
	s_nop 0
	v_pk_mul_f32 v[26:27], v[24:25], v[40:41]
	v_pk_mul_f32 v[24:25], v[4:5], v[56:57] op_sel_hi:[1,0]
	s_nop 0
	v_pk_mul_f32 v[40:41], v[24:25], v[48:49]
	s_nop 0
	v_pk_mul_f32 v[24:25], v[36:37], v[40:41]
	s_nop 0
	v_pk_fma_f32 v[24:25], v[28:29], v[26:27], v[24:25] neg_lo:[0,0,1] neg_hi:[0,0,1]
	v_pk_mul_f32 v[28:29], v[28:29], v[40:41]
	s_nop 0
	v_pk_fma_f32 v[26:27], v[36:37], v[26:27], v[28:29]
	v_pk_mul_f32 v[28:29], v[10:11], v[56:57] op_sel_hi:[1,0]
	s_nop 0
	v_pk_mul_f32 v[36:37], v[28:29], v[42:43]
	v_pk_mul_f32 v[28:29], v[0:1], v[56:57] op_sel_hi:[1,0]
	s_nop 0
	v_pk_mul_f32 v[40:41], v[28:29], v[50:51]
	s_nop 0
	v_pk_mul_f32 v[28:29], v[38:39], v[40:41]
	s_nop 0
	v_pk_fma_f32 v[28:29], v[30:31], v[36:37], v[28:29] neg_lo:[0,0,1] neg_hi:[0,0,1]
	v_pk_mul_f32 v[30:31], v[30:31], v[40:41]
	s_nop 0
	v_pk_fma_f32 v[30:31], v[38:39], v[36:37], v[30:31]
	v_mov_b32_e32 v36, s7
	v_mov_b32_e32 v37, s6
	v_lshl_add_u64 v[34:35], v[136:137], 1, v[36:37]
	v_lshl_add_u64 v[38:39], v[34:35], 0, v[112:113]
	v_cvt_pk_bf16_f32 v34, v2, v3
	v_cvt_pk_bf16_f32 v35, v20, v21
	v_cvt_pk_bf16_f32 v36, v24, v25
	v_cvt_pk_bf16_f32 v37, v28, v29
	global_store_dwordx4 v[38:39], v[34:37], off
	s_nop 1
	v_cvt_pk_bf16_f32 v34, v18, v19
	v_cvt_pk_bf16_f32 v35, v22, v23
	v_cvt_pk_bf16_f32 v36, v26, v27
	v_cvt_pk_bf16_f32 v37, v30, v31
	global_store_dwordx4 v[38:39], v[34:37], off offset:64
	s_nop 1
	v_mov_b32_e32 v36, v33
	s_cbranch_vccnz .LBB0_483
	v_pk_mul_f32 v[18:19], v[18:19], v[18:19]
	s_nop 0
	v_pk_fma_f32 v[2:3], v[2:3], v[2:3], v[18:19]
	v_pk_mul_f32 v[18:19], v[22:23], v[22:23]
	v_add_f32_e32 v2, v2, v3
	v_pk_fma_f32 v[18:19], v[20:21], v[20:21], v[18:19]
	v_pk_mul_f32 v[20:21], v[26:27], v[26:27]
	v_add_f32_e32 v2, v18, v2
	v_pk_fma_f32 v[20:21], v[24:25], v[24:25], v[20:21]
	v_add_f32_e32 v2, v19, v2
	v_pk_mul_f32 v[22:23], v[30:31], v[30:31]
	v_add_f32_e32 v2, v2, v20
	v_pk_fma_f32 v[22:23], v[28:29], v[28:29], v[22:23]
	v_add_f32_e32 v2, v2, v21
	v_add_f32_e32 v2, v2, v22
	v_add_f32_e32 v2, v2, v23
	v_mov_b32_e32 v3, v2
	s_nop 1
	v_permlane16_swap_b32_e32 v2, v3
	s_waitcnt lgkmcnt(0)
	v_add_f32_e32 v2, v2, v3
	v_mov_b32_e32 v3, v2
	s_nop 1
	v_permlane32_swap_b32_e32 v2, v3
	s_waitcnt lgkmcnt(0)
	v_add_f32_e32 v2, v2, v3
	v_max_f32_e32 v3, v33, v33
	v_max_f32_e32 v36, v3, v2

; __device__ __forceinline__ float fexp2(float x) { return __builtin_amdgcn_exp2f(x); }
; __device__ __forceinline__ float frcp(float x) { return __builtin_amdgcn_rcpf(x); }
; __device__ __forceinline__ float gelu_tanh(float x) { const float y = 0.7978845608028654f * (x + 0.044715f * x * x * x); return x * sigm(2.f * y); }
; __device__ __forceinline__ float grp_sum(float v) { v += __shfl_xor(v, 16); v += __shfl_xor(v, 32); return v; }
; __device__ __forceinline__ float sigm(float x) { return frcp(1.f + fexp2(-LOG2E * x)); }
;   __device__ __forceinline__ void operator()(const pg8::f32x4 (&acc)[2][2][4][2], const pg8::Unit& u, int wr, int wc, int fr, int fq) const {
;     ...
;           const int g = gi - 8; float ss = 0.f;
; #pragma unroll
;           for (int bj = 0; bj < 2; ++bj)
; #pragma unroll
;             for (int e = 0; e < 8; ++e) { v[bj][e] = gelu_tanh(v[bj][e]); ss += v[bj][e] * v[bj][e]; }
;           const float rn = rsqrtf(grp_sum(ss) * (1.f / 64.f) + EPS);
.LBB0_484:
	s_andn2_b64 vcc, exec, s[8:9]
	s_cbranch_vccnz .LBB0_486
	v_mul_f32_e32 v2, 0x3d372713, v16
	v_mul_f32_e32 v2, v16, v2
	v_fma_f32 v2, v16, v2, v16
	v_mul_f32_e32 v2, 0x3f4c422a, v2
	v_add_f32_e32 v2, v2, v2
	v_mul_f32_e32 v2, 0xbfb8aa3b, v2
	v_exp_f32_e32 v2, v2
	v_mul_f32_e32 v3, 0x3d372713, v9
	v_mul_f32_e32 v3, v9, v3
	v_fma_f32 v3, v9, v3, v9
	v_add_f32_e32 v2, 1.0, v2
	v_rcp_f32_e32 v2, v2
	v_mul_f32_e32 v3, 0x3f4c422a, v3
	v_add_f32_e32 v3, v3, v3
	v_mul_f32_e32 v3, 0xbfb8aa3b, v3
	v_mul_f32_e32 v35, v16, v2
	v_mul_f32_e32 v2, 0x3d372713, v17
	v_mul_f32_e32 v2, v17, v2
	v_fma_f32 v2, v17, v2, v17
	v_mul_f32_e32 v2, 0x3f4c422a, v2
	v_add_f32_e32 v2, v2, v2
	v_mul_f32_e32 v2, 0xbfb8aa3b, v2
	v_exp_f32_e32 v2, v2
	v_exp_f32_e32 v3, v3
	v_mov_b32_e32 v157, v137
	v_lshl_add_u64 v[44:45], v[156:157], 2, s[56:57]
	v_add_f32_e32 v2, 1.0, v2
	v_rcp_f32_e32 v2, v2
	v_add_f32_e32 v3, 1.0, v3
	v_rcp_f32_e32 v3, v3
	v_mul_f32_e32 v26, v17, v2
	v_mul_f32_e32 v2, 0x3d372713, v14
	v_mul_f32_e32 v2, v14, v2
	v_fma_f32 v2, v14, v2, v14
	v_mul_f32_e32 v2, 0x3f4c422a, v2
	v_add_f32_e32 v2, v2, v2
	v_mul_f32_e32 v2, 0xbfb8aa3b, v2
	v_exp_f32_e32 v2, v2
	v_mul_f32_e32 v20, v26, v26
	v_fmac_f32_e32 v20, v35, v35
	v_add_f32_e32 v2, 1.0, v2
	v_rcp_f32_e32 v2, v2
	s_nop 0
	v_mul_f32_e32 v27, v14, v2
	v_mul_f32_e32 v2, 0x3d372713, v15
	v_mul_f32_e32 v2, v15, v2
	v_fma_f32 v2, v15, v2, v15
	v_mul_f32_e32 v2, 0x3f4c422a, v2
	v_add_f32_e32 v2, v2, v2
	v_mul_f32_e32 v2, 0xbfb8aa3b, v2
	v_exp_f32_e32 v2, v2
	v_fmac_f32_e32 v20, v27, v27
	v_add_f32_e32 v2, 1.0, v2
	v_rcp_f32_e32 v2, v2
	s_nop 0
	v_mul_f32_e32 v28, v15, v2
	v_mul_f32_e32 v2, 0x3d372713, v12
	v_mul_f32_e32 v2, v12, v2
	v_fma_f32 v2, v12, v2, v12
	v_mul_f32_e32 v2, 0x3f4c422a, v2
	v_add_f32_e32 v2, v2, v2
	v_mul_f32_e32 v2, 0xbfb8aa3b, v2
	v_exp_f32_e32 v2, v2
	v_fmac_f32_e32 v20, v28, v28
	v_add_f32_e32 v2, 1.0, v2
	v_rcp_f32_e32 v2, v2
	s_nop 0
	v_mul_f32_e32 v29, v12, v2
	v_mul_f32_e32 v2, 0x3d372713, v13
	v_mul_f32_e32 v2, v13, v2
	v_fma_f32 v2, v13, v2, v13
	v_mul_f32_e32 v2, 0x3f4c422a, v2
	v_add_f32_e32 v2, v2, v2
	v_mul_f32_e32 v2, 0xbfb8aa3b, v2
	v_exp_f32_e32 v2, v2
	v_fmac_f32_e32 v20, v29, v29
	v_add_f32_e32 v2, 1.0, v2
	v_rcp_f32_e32 v2, v2
	s_nop 0
	v_mul_f32_e32 v30, v13, v2
	v_mul_f32_e32 v2, 0x3d372713, v10
	v_mul_f32_e32 v2, v10, v2
	v_fma_f32 v2, v10, v2, v10
	v_mul_f32_e32 v2, 0x3f4c422a, v2
	v_add_f32_e32 v2, v2, v2
	v_mul_f32_e32 v2, 0xbfb8aa3b, v2
	v_exp_f32_e32 v2, v2
	v_fmac_f32_e32 v20, v30, v30
	v_add_f32_e32 v2, 1.0, v2
	v_rcp_f32_e32 v2, v2
	s_nop 0
	v_mul_f32_e32 v31, v10, v2
	v_mul_f32_e32 v2, 0x3d372713, v11
	v_mul_f32_e32 v2, v11, v2
	v_fma_f32 v2, v11, v2, v11
	v_mul_f32_e32 v2, 0x3f4c422a, v2
	v_add_f32_e32 v2, v2, v2
	v_mul_f32_e32 v2, 0xbfb8aa3b, v2
	v_exp_f32_e32 v2, v2
	v_fmac_f32_e32 v20, v31, v31
	v_add_f32_e32 v2, 1.0, v2
	v_rcp_f32_e32 v2, v2
	s_nop 0
	v_mul_f32_e32 v34, v11, v2
	v_mul_f32_e32 v2, 0x3d372713, v8
	v_mul_f32_e32 v2, v8, v2
	v_fma_f32 v2, v8, v2, v8
	v_mul_f32_e32 v2, 0x3f4c422a, v2
	v_add_f32_e32 v2, v2, v2
	v_mul_f32_e32 v2, 0xbfb8aa3b, v2
	v_exp_f32_e32 v2, v2
	v_fmac_f32_e32 v20, v34, v34
	v_add_f32_e32 v2, 1.0, v2
	v_rcp_f32_e32 v2, v2
	s_nop 0
	v_pk_mul_f32 v[2:3], v[8:9], v[2:3]
	s_nop 0
	v_pk_mul_f32 v[18:19], v[2:3], v[2:3]
	s_nop 0
	v_add_f32_e32 v18, v18, v20
	v_add_f32_e32 v22, v19, v18
	v_mul_f32_e32 v18, 0x3d372713, v6
	v_mul_f32_e32 v19, 0x3d372713, v7
	v_mul_f32_e32 v18, v6, v18
	v_mul_f32_e32 v19, v7, v19
	v_fma_f32 v18, v6, v18, v6
	v_fma_f32 v19, v7, v19, v7
	v_mul_f32_e32 v18, 0x3f4c422a, v18
	v_mul_f32_e32 v19, 0x3f4c422a, v19
	v_add_f32_e32 v18, v18, v18
	v_add_f32_e32 v19, v19, v19
	v_mul_f32_e32 v18, 0xbfb8aa3b, v18
	v_mul_f32_e32 v19, 0xbfb8aa3b, v19
	v_exp_f32_e32 v18, v18
	v_exp_f32_e32 v19, v19
	v_add_f32_e32 v18, 1.0, v18
	v_add_f32_e32 v19, 1.0, v19
	v_rcp_f32_e32 v18, v18
	v_rcp_f32_e32 v19, v19
	s_nop 0
	v_pk_mul_f32 v[18:19], v[6:7], v[18:19]
	s_nop 0
	v_pk_mul_f32 v[20:21], v[18:19], v[18:19]
	s_nop 0
	v_add_f32_e32 v20, v20, v22
	v_add_f32_e32 v24, v21, v20
	v_mul_f32_e32 v20, 0x3d372713, v4
	v_mul_f32_e32 v21, 0x3d372713, v5
	v_mul_f32_e32 v20, v4, v20
	v_mul_f32_e32 v21, v5, v21
	v_fma_f32 v20, v4, v20, v4
	v_fma_f32 v21, v5, v21, v5
	v_mul_f32_e32 v20, 0x3f4c422a, v20
	v_mul_f32_e32 v21, 0x3f4c422a, v21
	v_add_f32_e32 v20, v20, v20
	v_add_f32_e32 v21, v21, v21
	v_mul_f32_e32 v20, 0xbfb8aa3b, v20
	v_mul_f32_e32 v21, 0xbfb8aa3b, v21
	v_exp_f32_e32 v20, v20
	v_exp_f32_e32 v21, v21
	v_add_f32_e32 v20, 1.0, v20
	v_add_f32_e32 v21, 1.0, v21
	v_rcp_f32_e32 v20, v20
	v_rcp_f32_e32 v21, v21
	s_nop 0
	v_pk_mul_f32 v[20:21], v[4:5], v[20:21]
	s_nop 0
	v_pk_mul_f32 v[22:23], v[20:21], v[20:21]
	s_nop 0
	v_add_f32_e32 v22, v22, v24
	v_add_f32_e32 v36, v23, v22
	v_mul_f32_e32 v22, 0x3d372713, v0
	v_mul_f32_e32 v23, 0x3d372713, v1
	v_mul_f32_e32 v22, v0, v22
	v_mul_f32_e32 v23, v1, v23
	v_fma_f32 v22, v0, v22, v0
	v_fma_f32 v23, v1, v23, v1
	v_mul_f32_e32 v22, 0x3f4c422a, v22
	v_mul_f32_e32 v23, 0x3f4c422a, v23
	v_add_f32_e32 v22, v22, v22
	v_add_f32_e32 v23, v23, v23
	v_mul_f32_e32 v22, 0xbfb8aa3b, v22
	v_mul_f32_e32 v23, 0xbfb8aa3b, v23
	v_exp_f32_e32 v22, v22
	v_exp_f32_e32 v23, v23
	v_add_f32_e32 v22, 1.0, v22
	v_add_f32_e32 v23, 1.0, v23
	v_rcp_f32_e32 v22, v22
	v_rcp_f32_e32 v23, v23
	s_nop 0
	v_pk_mul_f32 v[22:23], v[0:1], v[22:23]
	s_nop 0
	v_pk_mul_f32 v[24:25], v[22:23], v[22:23]
	s_nop 0
	v_add_f32_e32 v24, v24, v36
	v_add_f32_e32 v24, v25, v24
	v_mov_b32_e32 v25, v24
	s_nop 1
	v_permlane16_swap_b32_e32 v24, v25
	v_and_b32_e32 v36, 0x7f, v32
	s_waitcnt lgkmcnt(0)
; __device__ __forceinline__ bf16_t f2bf(float f) { return (bf16_t)(pk2(f, 0.f) & 0xffffu); }
; __device__ __forceinline__ float grp_sum(float v) { v += __shfl_xor(v, 16); v += __shfl_xor(v, 32); return v; }
;   __device__ __forceinline__ void operator()(const pg8::f32x4 (&acc)[2][2][4][2], const pg8::Unit& u, int wr, int wc, int fr, int fq) const {
;     ...
;           const float rn = rsqrtf(grp_sum(ss) * (1.f / 64.f) + EPS);
;           bf16_t* dst = vt + ((unsigned)(g * 128 + (tok >> 7)) * 64 + 8 * fq) * 128 + (tok & 127);
; #pragma unroll
;           for (int bj = 0; bj < 2; ++bj)
; #pragma unroll
;             for (int e = 0; e < 8; ++e) dst[(32 * bj + e) * 128] = f2bf(v[bj][e] * rn * sgu_norm[g * 64 + 32 * bj + 8 * fq + e]);
	v_add_f32_e32 v24, v24, v25
	v_mov_b32_e32 v25, v24
	s_nop 1
	v_permlane32_swap_b32_e32 v24, v25
	s_waitcnt lgkmcnt(0)
	v_add_f32_e32 v24, v24, v25
	v_fmamk_f32 v24, v24, 0x3c800000, v154
	v_cmp_gt_f32_e32 vcc, s3, v24
	v_mul_f32_e32 v25, 0x4b800000, v24
	s_nop 0
	v_cndmask_b32_e32 v24, v24, v25, vcc
	v_rsq_f32_e32 v24, v24
	s_nop 0
	v_mul_f32_e32 v25, 0x45800000, v24
	v_cndmask_b32_e32 v46, v24, v25, vcc
	v_lshrrev_b32_e32 v24, 1, v32
	v_and_b32_e32 v24, 0x1ffffc0, v24
	v_add_lshl_u32 v136, v24, v203, 7
	v_lshl_add_u64 v[24:25], v[136:137], 1, s[50:51]
	v_lshlrev_b32_e32 v136, 1, v36
	global_load_dwordx4 v[36:39], v[44:45], off offset:16
	global_load_dwordx4 v[40:43], v[44:45], off
	v_mul_f32_e32 v26, v26, v46
	v_lshl_add_u64 v[24:25], v[24:25], 0, v[136:137]
	v_mul_f32_e32 v35, v35, v46
	v_mul_f32_e32 v2, v2, v46
	s_waitcnt vmcnt(0)
	v_mul_f32_e32 v26, v41, v26
	v_cvt_pk_bf16_f32 v26, v26, s0
	global_store_short v[24:25], v26, off offset:256
	v_mul_f32_e32 v26, v27, v46
	v_mul_f32_e32 v26, v42, v26
	v_cvt_pk_bf16_f32 v26, v26, s0
	global_store_short v[24:25], v26, off offset:512
	v_mul_f32_e32 v26, v28, v46
	v_mul_f32_e32 v26, v43, v26
	v_cvt_pk_bf16_f32 v26, v26, s0
	global_store_short v[24:25], v26, off offset:768
	v_mul_f32_e32 v26, v29, v46
	v_mul_f32_e32 v26, v36, v26
	v_cvt_pk_bf16_f32 v26, v26, s0
	global_store_short v[24:25], v26, off offset:1024
	v_mul_f32_e32 v26, v30, v46
	v_mul_f32_e32 v26, v26, v37
	v_cvt_pk_bf16_f32 v26, v26, s0
	global_store_short v[24:25], v26, off offset:1280
	v_mul_f32_e32 v26, v31, v46
	v_mul_f32_e32 v26, v26, v38
	v_cvt_pk_bf16_f32 v26, v26, s0
	global_store_short v[24:25], v26, off offset:1536
	v_mul_f32_e32 v26, v34, v46
	v_mul_f32_e32 v35, v40, v35
	v_mul_f32_e32 v26, v26, v39
	v_cvt_pk_bf16_f32 v35, v35, s0
	v_cvt_pk_bf16_f32 v26, v26, s0
	global_store_short v[24:25], v35, off
	global_store_short v[24:25], v26, off offset:1792
	global_load_dwordx4 v[26:29], v[44:45], off offset:144
	s_nop 0
	global_load_dwordx4 v[34:37], v[44:45], off offset:128
	v_add_co_u32_e32 v24, vcc, s97, v24
	s_waitcnt vmcnt(0)
	v_mul_f32_e32 v2, v2, v34
	v_cvt_pk_bf16_f32 v2, v2, s0
	v_addc_co_u32_e32 v25, vcc, 0, v25, vcc
	global_store_short v[24:25], v2, off
	v_mul_f32_e32 v2, v3, v46
	v_mul_f32_e32 v2, v2, v35
	v_cvt_pk_bf16_f32 v2, v2, s0
	global_store_short v[24:25], v2, off offset:256
	v_mul_f32_e32 v2, v18, v46
	v_mul_f32_e32 v2, v2, v36
	v_cvt_pk_bf16_f32 v2, v2, s0
	global_store_short v[24:25], v2, off offset:512
	v_mul_f32_e32 v2, v19, v46
	v_mul_f32_e32 v2, v2, v37
	v_cvt_pk_bf16_f32 v2, v2, s0
	global_store_short v[24:25], v2, off offset:768
	v_mul_f32_e32 v2, v20, v46
	v_mul_f32_e32 v2, v2, v26
	v_cvt_pk_bf16_f32 v2, v2, s0
	global_store_short v[24:25], v2, off offset:1024
	v_mul_f32_e32 v2, v21, v46
	v_mul_f32_e32 v2, v2, v27
	v_cvt_pk_bf16_f32 v2, v2, s0
	global_store_short v[24:25], v2, off offset:1280
	v_mul_f32_e32 v2, v22, v46
	v_mul_f32_e32 v2, v2, v28
	v_cvt_pk_bf16_f32 v2, v2, s0
	global_store_short v[24:25], v2, off offset:1536
	v_mul_f32_e32 v2, v23, v46
	v_mul_f32_e32 v2, v2, v29
	v_cvt_pk_bf16_f32 v2, v2, s0
	v_mov_b32_e32 v36, v33
	global_store_short v[24:25], v2, off offset:1792

; __device__ __forceinline__ float grp_sum(float v) { v += __shfl_xor(v, 16); v += __shfl_xor(v, 32); return v; }
;   __device__ __forceinline__ void operator()(const pg8::f32x4 (&acc)[2][2][4][2], const pg8::Unit& u, int wr, int wc, int fr, int fq0) const {
;     ...
;     const int gi = 4 * u.pn + wc;
;     if (gi >= 19) return;
;     const int lane = fr + 16 * fq;
;     const int row0 = u.pm * 256 + wr * 64 + 4 * fr + z;
;     float kmx_run = 0.f;
; #pragma unroll
;     for (int ai = 0; ai < 2; ++ai) {
;       float rs[4];
; #pragma unroll
;       for (int m = 0; m < 4; ++m) { const f32x4 a = *(const f32x4*)(ssq + (unsigned)(row0 + ai * 128 + m) * 16 + 4 * fq); rs[m] = (a[0] + a[1]) + (a[2] + a[3]); }
; #pragma unroll
;       for (int m = 0; m < 4; ++m) rs[m] = rsqrtf(grp_sum(rs[m]) * (1.f / 1024.f) + EPS);
;     ...
;         for (int bj = 0; bj < 2; ++bj)
; #pragma unroll
;           for (int n = 0; n < 2; ++n)
; #pragma unroll
;             for (int c = 0; c < 4; ++c) v[bj][4 * n + c] = acc[ai][bj][m][n][c] * rs[m];
;         if (gi < 6) {
.LBB0_1121:
	s_lshl_b32 s8, s8, 2
	s_or_b32 s68, s8, s5
	s_cmp_gt_i32 s68, 18
	v_mov_b32 v128, 0
	s_cbranch_scc1 .LBB0_1233
	v_and_b32_e32 v132, 64, v208
	v_xor_b32_e32 v131, 16, v208
	v_add_u32_e32 v210, 64, v132
	v_add_u32_e32 v216, v128, v186
	s_lshl_b32 s8, s60, 8
	v_cmp_lt_i32_e32 vcc, v131, v210
	v_add3_u32 v215, v189, s8, v128
	v_lshlrev_b32_e32 v128, 2, v216
	v_cndmask_b32_e32 v131, v208, v131, vcc
	v_ashrrev_i32_e32 v129, 31, v128
	v_lshlrev_b32_e32 v211, 2, v131
	v_xor_b32_e32 v131, 32, v208
	v_add_u32_e32 v219, 1, v215
	v_cmp_lt_i32_e32 vcc, v131, v210
	v_lshl_add_u64 v[158:159], v[128:129], 2, s[42:43]
	v_lshlrev_b32_e32 v156, 4, v215
	v_mov_b32_e32 v157, v145
	v_lshlrev_b32_e32 v144, 4, v219
	v_lshlrev_b32_e32 v130, 4, v216
	v_cndmask_b32_e32 v131, v208, v131, vcc
	v_lshl_add_u64 v[128:129], v[156:157], 2, v[158:159]
	v_lshl_add_u64 v[132:133], v[144:145], 2, v[158:159]
	v_lshlrev_b32_e32 v212, 2, v131
	v_cmp_lt_i32_e64 s[12:13], v130, v188
	global_load_dwordx4 v[128:131], v[128:129], off
	v_add_u32_e32 v218, 2, v215
	global_load_dwordx4 v[132:135], v[132:133], off
	v_lshlrev_b32_e32 v166, 4, v218
	v_mov_b32_e32 v167, v145
	v_add_u32_e32 v217, 3, v215
	v_lshl_add_u64 v[160:161], v[166:167], 2, v[158:159]
	v_lshlrev_b32_e32 v164, 4, v217
	v_mov_b32_e32 v165, v145
	global_load_dwordx4 v[168:171], v[160:161], off
	v_lshl_add_u64 v[160:161], v[164:165], 2, v[158:159]
	global_load_dwordx4 v[172:175], v[160:161], off
	s_cmp_lt_i32 s68, 17
	s_cselect_b64 s[18:19], -1, 0
	s_cmp_gt_i32 s68, 5
	s_cselect_b64 s[88:89], -1, 0
	s_cmp_lg_u32 s68, 6
	s_cselect_b64 s[90:91], -1, 0
	s_cmp_gt_u32 s68, 14
	s_cselect_b64 s[86:87], -1, 0
	s_cmp_lt_u32 s68, 15
	s_cselect_b64 s[14:15], -1, 0
	s_lshl_b32 s62, s68, 13
	s_add_i32 s24, s62, 0x3fe2000
	s_add_i32 s62, s62, 0x3ff2000
	s_cmp_lt_i32 s68, 4
	s_cselect_b64 s[84:85], -1, 0
	s_lshl_b32 s77, s68, 6
	s_add_i32 s79, s77, 0xffffff00
	s_ashr_i32 s25, s77, 31
	v_lshlrev_b32_e32 v154, 3, v216
	s_cmp_gt_i32 s68, 16
	v_cndmask_b32_e64 v214, 1.0, v209, s[14:15]
	v_and_b32_e32 v213, 8, v154
	v_cmp_gt_i32_e64 s[10:11], 2, v216
	v_ashrrev_i32_e32 v155, 31, v154
	v_cmp_eq_u32_e64 s[8:9], 0, v216
	s_waitcnt vmcnt(0)
	v_mov_b32_e32 v160, v128
	v_mov_b32_e32 v161, v132
	v_mov_b32_e32 v132, v129
	v_pk_add_f32 v[128:129], v[160:161], v[132:133]
	v_mov_b32_e32 v132, v130
	v_mov_b32_e32 v133, v134
	v_mov_b32_e32 v134, v131
	v_pk_add_f32 v[130:131], v[132:133], v[134:135]
	s_nop 0
	v_pk_add_f32 v[128:129], v[128:129], v[130:131]
	v_mov_b32_e32 v130, v128
	s_nop 1
	v_permlane16_swap_b32_e32 v128, v130
	v_mov_b32_e32 v131, v129
	s_nop 1
	v_permlane16_swap_b32_e32 v129, v131
	s_waitcnt lgkmcnt(0)
	v_pk_add_f32 v[128:129], v[128:129], v[130:131]
	v_mov_b32_e32 v130, v128
	s_nop 1
	v_permlane32_swap_b32_e32 v128, v130
	v_mov_b32_e32 v131, v129
	s_nop 1
	v_permlane32_swap_b32_e32 v129, v131
	s_waitcnt lgkmcnt(0)
	v_pk_add_f32 v[128:129], v[128:129], v[130:131]
	v_mov_b64_e32 v[130:131], s[56:57]
	v_pk_fma_f32 v[128:129], v[128:129], s[70:71], v[130:131] op_sel_hi:[1,0,0]
	s_nop 0
	v_mul_f32_e32 v132, 0x4b800000, v128
	v_cmp_gt_f32_e64 s[16:17], s21, v128
	v_cmp_gt_f32_e32 vcc, s21, v129
	s_nop 0
	v_cndmask_b32_e64 v128, v128, v132, s[16:17]
	v_mul_f32_e32 v132, 0x4b800000, v129
	v_cndmask_b32_e32 v129, v129, v132, vcc
	v_rsq_f32_e32 v128, v128
	v_rsq_f32_e32 v129, v129
	s_nop 0
	v_pk_mul_f32 v[132:133], v[128:129], s[74:75] op_sel_hi:[1,0]
	s_nop 0
	v_cndmask_b32_e32 v161, v129, v133, vcc
	v_cndmask_b32_e64 v160, v128, v132, s[16:17]
	v_mov_b32_e32 v128, v168
	v_mov_b32_e32 v129, v172
	v_mov_b32_e32 v172, v169
	v_mov_b32_e32 v132, v170
	v_mov_b32_e32 v133, v174
	v_mov_b32_e32 v174, v171
	v_pk_add_f32 v[128:129], v[128:129], v[172:173]
	v_pk_add_f32 v[132:133], v[132:133], v[174:175]
	s_nop 0
	v_pk_add_f32 v[128:129], v[128:129], v[132:133]
	v_mov_b32_e32 v132, v128
	s_nop 1
	v_permlane16_swap_b32_e32 v128, v132
	v_mov_b32_e32 v133, v129
	s_nop 1
	v_permlane16_swap_b32_e32 v129, v133
	s_waitcnt lgkmcnt(0)
	v_pk_add_f32 v[128:129], v[128:129], v[132:133]
	v_mov_b32_e32 v132, v128
	s_nop 1
	v_permlane32_swap_b32_e32 v128, v132
	v_mov_b32_e32 v133, v129
	s_nop 1
	v_permlane32_swap_b32_e32 v129, v133
	s_waitcnt lgkmcnt(0)
	v_pk_add_f32 v[128:129], v[128:129], v[132:133]
	s_nop 0
	v_pk_fma_f32 v[128:129], v[128:129], s[70:71], v[130:131] op_sel_hi:[1,0,0]
	s_nop 0
	v_mul_f32_e32 v130, 0x4b800000, v128
	v_cmp_gt_f32_e64 s[16:17], s21, v128
	v_cmp_gt_f32_e32 vcc, s21, v129
	s_nop 0
	v_cndmask_b32_e64 v128, v128, v130, s[16:17]
	v_mul_f32_e32 v130, 0x4b800000, v129
	v_cndmask_b32_e32 v129, v129, v130, vcc
	v_rsq_f32_e32 v128, v128
	v_rsq_f32_e32 v129, v129
	s_nop 0
	v_pk_mul_f32 v[130:131], v[128:129], s[74:75] op_sel_hi:[1,0]
	s_nop 0
	v_cndmask_b32_e32 v163, v129, v131, vcc
	v_cndmask_b32_e64 v162, v128, v130, s[16:17]
	s_mov_b64 s[16:17], -1
	s_cbranch_scc1 .LBB0_1172
	v_pk_mul_f32 v[128:129], v[124:125], v[160:161] op_sel_hi:[1,0]
	v_pk_mul_f32 v[130:131], v[126:127], v[160:161] op_sel_hi:[1,0]
	v_pk_mul_f32 v[132:133], v[108:109], v[160:161] op_sel_hi:[1,0]
	v_pk_mul_f32 v[134:135], v[110:111], v[160:161] op_sel_hi:[1,0]
	v_pk_mul_f32 v[168:169], v[92:93], v[160:161] op_sel_hi:[1,0]
	v_pk_mul_f32 v[170:171], v[94:95], v[160:161] op_sel_hi:[1,0]
	v_pk_mul_f32 v[172:173], v[76:77], v[160:161] op_sel_hi:[1,0]
	v_pk_mul_f32 v[174:175], v[78:79], v[160:161] op_sel_hi:[1,0]
	s_and_b64 vcc, exec, s[88:89]
	s_cbranch_vccz .LBB0_1131
	s_and_b64 vcc, exec, s[90:91]
	s_cbranch_vccz .LBB0_1128
; __device__ __forceinline__ float grp_sum(float v) { v += __shfl_xor(v, 16); v += __shfl_xor(v, 32); return v; }
;   __device__ __forceinline__ void operator()(const pg8::f32x4 (&acc)[2][2][4][2], const pg8::Unit& u, int wr, int wc, int fr, int fq0) const {
;     ...
;           const bool isq = gi < 15; const float* gn = isq ? gq_norm : gk_norm;
;           float ss = 0.f;
; #pragma unroll
;           for (int bj = 0; bj < 2; ++bj)
; #pragma unroll
;             for (int e = 0; e < 8; ++e) ss += v[bj][e] * v[bj][e];
;           const float rn = rsqrtf(grp_sum(ss) * (1.f / 64.f) + EPS) * (isq ? 0.125f * LOG2E : 1.f);
;           float kk = 0.f;
; #pragma unroll
;           for (int bj = 0; bj < 2; ++bj) {
;             const unsigned ao = (unsigned)(bj == 0 ? (pos >> 6) : (pos & 63)) * 16 + 8 * (fq & 1);
;             const f32x4 c0 = *(const f32x4*)(cos32 + ao), c1 = *(const f32x4*)(cos32 + ao + 4), s0 = *(const f32x4*)(sin32 + ao), s1 = *(const f32x4*)(sin32 + ao + 4);
; #pragma unroll
;             for (int e = 0; e < 8; ++e) {
;               const float own = v[bj][e] * rn * gn[32 * bj + 8 * fq + e];
;               const float oth = lane32_partner(own, lane);
;               const float cc = e < 4 ? c0[e & 3] : c1[e & 3], sn = e < 4 ? s0[e & 3] : s1[e & 3];
;               v[bj][e] = (fq < 2) ? own * cc - oth * sn : oth * sn + own * cc;
;               kk += v[bj][e] * v[bj][e];
;             }
;           }
	v_pk_mul_f32 v[176:177], v[128:129], v[128:129]
	v_pk_mul_f32 v[180:181], v[130:131], v[130:131]
	v_add_f32_e32 v167, v176, v177
	v_add_f32_e32 v167, v180, v167
	v_pk_mul_f32 v[182:183], v[132:133], v[132:133]
	v_add_f32_e32 v167, v181, v167
	v_add_f32_e32 v167, v182, v167
	v_pk_mul_f32 v[184:185], v[134:135], v[134:135]
	v_add_f32_e32 v167, v183, v167
	v_add_f32_e32 v167, v184, v167
	v_pk_mul_f32 v[220:221], v[168:169], v[168:169]
	v_add_f32_e32 v167, v185, v167
	v_add_f32_e32 v167, v220, v167
	v_pk_mul_f32 v[222:223], v[170:171], v[170:171]
	v_add_f32_e32 v167, v221, v167
	v_add_f32_e32 v167, v222, v167
	v_pk_mul_f32 v[224:225], v[172:173], v[172:173]
	v_add_f32_e32 v167, v223, v167
	v_add_f32_e32 v167, v224, v167
	v_pk_mul_f32 v[228:229], v[174:175], v[174:175]
	v_add_f32_e32 v167, v225, v167
	v_add_f32_e32 v167, v228, v167
	v_add_f32_e32 v167, v229, v167
	v_mov_b32_e32 v176, v167
	s_nop 1
	v_permlane16_swap_b32_e32 v167, v176
	s_and_b64 s[16:17], s[14:15], exec
	v_readlane_b32 s16, v252, 21
	v_readlane_b32 s17, v252, 22
	s_load_dwordx4 s[56:59], s[16:17], 0xe0
	s_waitcnt lgkmcnt(0)
	v_add_f32_e32 v167, v167, v176
	v_mov_b32_e32 v176, v167
	s_nop 1
	v_permlane32_swap_b32_e32 v167, v176
	v_readlane_b32 s63, v252, 16
	v_readlane_b32 s92, v252, 6
	s_cselect_b32 s16, s57, s59
	s_cselect_b32 s17, s56, s58
	s_waitcnt lgkmcnt(0)
	v_add_f32_e32 v167, v167, v176
	v_fmamk_f32 v167, v167, 0x3c800000, v206
	v_cmp_gt_f32_e32 vcc, s21, v167
	v_mul_f32_e32 v176, 0x4b800000, v167
	v_mov_b32_e32 v179, s16
	v_cndmask_b32_e32 v167, v167, v176, vcc
	v_rsq_f32_e32 v167, v167
	s_movk_i32 s16, 0x7f0
	v_mov_b32_e32 v178, s17
	v_lshl_add_u64 v[180:181], v[154:155], 2, v[178:179]
	v_mul_f32_e32 v176, 0x45800000, v167
	v_cndmask_b32_e32 v167, v167, v176, vcc
	v_mul_f32_e32 v176, v214, v167
	v_lshrrev_b32_e32 v167, 2, v215
	v_and_or_b32 v167, v167, s16, v213
	v_lshlrev_b32_e32 v167, 2, v167
	global_load_dwordx4 v[182:185], v167, s[54:55] offset:16
	global_load_dwordx4 v[220:223], v167, s[54:55]
	global_load_dwordx4 v[228:231], v167, s[50:51] offset:16
	global_load_dwordx4 v[232:235], v167, s[50:51]
	global_load_dwordx4 v[236:239], v[180:181], off offset:16
	global_load_dwordx4 v[240:243], v[180:181], off
	v_mul_f32_e32 v167, v128, v176
	s_movk_i32 s16, 0x3f0
	v_ashrrev_i32_e32 v157, 13, v215
	v_and_b32_e32 v165, 0x1fff, v215
	s_cselect_b32 s17, 22, 20
	s_cselect_b32 s63, s63, s92
	v_readlane_b32 s92, v252, 14
	v_readlane_b32 s93, v252, 4
	s_cselect_b32 s92, s92, s93
	v_lshlrev_b32_e32 v157, s17, v157
	s_waitcnt vmcnt(0)
	v_mul_f32_e32 v177, v240, v167
	v_mov_b32_e32 v167, v177
	v_mov_b32_e32 v178, v177
	s_nop 1
	v_permlane32_swap_b32_e32 v167, v178
	v_cndmask_b32_e64 v167, v167, v178, s[12:13]
	v_mul_f32_e32 v167, v232, v167
	v_cndmask_b32_e64 v167, v167, -v167, s[10:11]
	v_fmac_f32_e32 v167, v220, v177
	v_mul_f32_e32 v177, v129, v176
	v_mul_f32_e32 v177, v241, v177
	v_mov_b32_e32 v178, v177
	v_mov_b32_e32 v179, v177
	s_nop 1
	v_permlane32_swap_b32_e32 v178, v179
	v_cndmask_b32_e64 v178, v178, v179, s[12:13]
	v_mul_f32_e32 v178, v233, v178
	v_cndmask_b32_e64 v220, v178, -v178, s[10:11]
	v_fmac_f32_e32 v220, v221, v177
	v_mul_f32_e32 v177, v130, v176
	v_mul_f32_e32 v177, v242, v177
	v_mov_b32_e32 v178, v177
	v_mov_b32_e32 v179, v177
	s_nop 1
	v_permlane32_swap_b32_e32 v178, v179
	v_cndmask_b32_e64 v178, v178, v179, s[12:13]
	v_mul_f32_e32 v178, v234, v178
	v_cndmask_b32_e64 v221, v178, -v178, s[10:11]
	v_fmac_f32_e32 v221, v222, v177
	v_mul_f32_e32 v177, v131, v176
	v_mul_f32_e32 v177, v177, v243
	v_mov_b32_e32 v178, v177
	v_mov_b32_e32 v179, v177
	s_nop 1
	v_permlane32_swap_b32_e32 v178, v179
	v_cndmask_b32_e64 v178, v178, v179, s[12:13]
	v_mul_f32_e32 v178, v235, v178
	v_cndmask_b32_e64 v222, v178, -v178, s[10:11]
	v_fmac_f32_e32 v222, v223, v177
	v_mul_f32_e32 v177, v132, v176
	v_mul_f32_e32 v177, v177, v236
	v_mov_b32_e32 v178, v177
	v_mov_b32_e32 v179, v177
	s_nop 1
	v_permlane32_swap_b32_e32 v178, v179
	v_cndmask_b32_e64 v178, v178, v179, s[12:13]
	v_mul_f32_e32 v178, v228, v178
	v_cndmask_b32_e64 v223, v178, -v178, s[10:11]
	v_fmac_f32_e32 v223, v182, v177
	v_mul_f32_e32 v177, v133, v176
	v_mul_f32_e32 v177, v177, v237
	v_mov_b32_e32 v178, v177
	v_mov_b32_e32 v179, v177
	s_nop 1
	v_permlane32_swap_b32_e32 v178, v179
	v_cndmask_b32_e64 v178, v178, v179, s[12:13]
	v_mul_f32_e32 v178, v229, v178
	v_cndmask_b32_e64 v224, v178, -v178, s[10:11]
	v_pk_mul_f32 v[178:179], v[134:135], v[176:177] op_sel_hi:[1,0]
	v_fmac_f32_e32 v224, v183, v177
	v_pk_mul_f32 v[178:179], v[178:179], v[238:239]
	s_nop 0
	v_mov_b32_e32 v177, v178
	v_mov_b32_e32 v182, v178
	v_mov_b32_e32 v183, v179
	v_mov_b32_e32 v225, v179
	v_permlane32_swap_b32_e32 v177, v182
	s_nop 0
	v_permlane32_swap_b32_e32 v183, v225
	v_cndmask_b32_e64 v183, v183, v225, s[12:13]
	v_cndmask_b32_e64 v182, v177, v182, s[12:13]
	v_pk_mul_f32 v[182:183], v[230:231], v[182:183]
	v_and_or_b32 v177, v156, s16, v213
	v_cndmask_b32_e64 v183, v183, -v183, s[10:11]
	v_cndmask_b32_e64 v182, v182, -v182, s[10:11]
	v_lshlrev_b32_e32 v177, 2, v177
	v_pk_fma_f32 v[178:179], v[184:185], v[178:179], v[182:183]
	global_load_dwordx4 v[228:231], v177, s[54:55] offset:16
	global_load_dwordx4 v[182:185], v177, s[54:55]
	global_load_dwordx4 v[232:235], v177, s[50:51] offset:16
	global_load_dwordx4 v[236:239], v177, s[50:51]
	global_load_dwordx4 v[240:243], v[180:181], off offset:144
	global_load_dwordx4 v[244:247], v[180:181], off offset:128
	v_pk_mul_f32 v[248:249], v[168:169], v[176:177] op_sel_hi:[1,0]
	s_cselect_b32 s16, s62, s24
	v_or_b32_e32 v165, s16, v165
	s_andn2_b64 vcc, exec, s[86:87]
	s_waitcnt vmcnt(0)
; __device__ __forceinline__ float grp_sum(float v) { v += __shfl_xor(v, 16); v += __shfl_xor(v, 32); return v; }
; __device__ __forceinline__ void st8_bf16(bf16_t* dst, const float (&v)[8]) { u32x4 w; w.x = pk2(v[0], v[1]); w.y = pk2(v[2], v[3]); w.z = pk2(v[4], v[5]); w.w = pk2(v[6], v[7]); *(u32x4*)dst = w; }
;   __device__ __forceinline__ void operator()(const pg8::f32x4 (&acc)[2][2][4][2], const pg8::Unit& u, int wr, int wc, int fr, int fq0) const {
;     ...
;             for (int e = 0; e < 8; ++e) {
;               const float own = v[bj][e] * rn * gn[32 * bj + 8 * fq + e];
;               const float oth = lane32_partner(own, lane);
;               const float cc = e < 4 ? c0[e & 3] : c1[e & 3], sn = e < 4 ? s0[e & 3] : s1[e & 3];
;               v[bj][e] = (fq < 2) ? own * cc - oth * sn : oth * sn + own * cc;
;               kk += v[bj][e] * v[bj][e];
;             }
;           }
;           bf16_t* dst = isq ? qd + ((unsigned)(bb * 8 + (gi - 7)) * S + pos) * 64 + 8 * fq : kd + ((unsigned)(bb * 2 + (gi - 15)) * S + pos) * 64 + 8 * fq;
;           st8_bf16(dst, v[0]); st8_bf16(dst + 32, v[1]);
;           if (!isq) kmx_run = fmaxf(kmx_run, grp_sum(kk));
	v_pk_mul_f32 v[180:181], v[248:249], v[244:245]
	s_nop 0
	v_mov_b32_e32 v177, v180
	v_mov_b32_e32 v225, v180
	v_mov_b32_e32 v227, v181
	v_mov_b32_e32 v244, v181
	v_permlane32_swap_b32_e32 v177, v225
	s_nop 0
	v_permlane32_swap_b32_e32 v227, v244
	v_cndmask_b32_e64 v245, v227, v244, s[12:13]
	v_cndmask_b32_e64 v244, v177, v225, s[12:13]
	v_pk_mul_f32 v[236:237], v[236:237], v[244:245]
	s_nop 0
	v_cndmask_b32_e64 v237, v237, -v237, s[10:11]
	v_cndmask_b32_e64 v236, v236, -v236, s[10:11]
	v_pk_fma_f32 v[180:181], v[182:183], v[180:181], v[236:237]
	v_pk_mul_f32 v[182:183], v[170:171], v[176:177] op_sel_hi:[1,0]
	s_nop 0
	v_pk_mul_f32 v[182:183], v[182:183], v[246:247]
	s_nop 0
	v_mov_b32_e32 v177, v182
	v_mov_b32_e32 v225, v182
	v_mov_b32_e32 v227, v183
	v_mov_b32_e32 v236, v183
	v_permlane32_swap_b32_e32 v177, v225
	s_nop 0
	v_permlane32_swap_b32_e32 v227, v236
	v_cndmask_b32_e64 v237, v227, v236, s[12:13]
	v_cndmask_b32_e64 v236, v177, v225, s[12:13]
	v_pk_mul_f32 v[236:237], v[238:239], v[236:237]
	s_nop 0
	v_cndmask_b32_e64 v237, v237, -v237, s[10:11]
	v_cndmask_b32_e64 v236, v236, -v236, s[10:11]
	v_pk_fma_f32 v[182:183], v[184:185], v[182:183], v[236:237]
	v_pk_mul_f32 v[184:185], v[172:173], v[176:177] op_sel_hi:[1,0]
	s_nop 0
	v_pk_mul_f32 v[184:185], v[184:185], v[240:241]
	s_nop 0
	v_mov_b32_e32 v177, v184
	v_mov_b32_e32 v225, v184
	v_mov_b32_e32 v227, v185
	v_mov_b32_e32 v236, v185
	v_permlane32_swap_b32_e32 v177, v225
	s_nop 0
	v_permlane32_swap_b32_e32 v227, v236
	v_cndmask_b32_e64 v237, v227, v236, s[12:13]
	v_cndmask_b32_e64 v236, v177, v225, s[12:13]
	v_pk_mul_f32 v[232:233], v[232:233], v[236:237]
	v_pk_mul_f32 v[176:177], v[174:175], v[176:177] op_sel_hi:[1,0]
	v_cndmask_b32_e64 v233, v233, -v233, s[10:11]
	v_cndmask_b32_e64 v232, v232, -v232, s[10:11]
	v_pk_mul_f32 v[176:177], v[176:177], v[242:243]
	v_pk_fma_f32 v[184:185], v[228:229], v[184:185], v[232:233]
	v_mov_b32_e32 v225, v176
	v_mov_b32_e32 v227, v176
	v_mov_b32_e32 v228, v177
	v_mov_b32_e32 v229, v177
	v_permlane32_swap_b32_e32 v225, v227
	s_nop 0
	v_permlane32_swap_b32_e32 v228, v229
	v_cndmask_b32_e64 v229, v228, v229, s[12:13]
	v_cndmask_b32_e64 v228, v225, v227, s[12:13]
	v_pk_mul_f32 v[228:229], v[234:235], v[228:229]
	s_nop 0
	v_cndmask_b32_e64 v229, v229, -v229, s[10:11]
	v_cndmask_b32_e64 v228, v228, -v228, s[10:11]
	v_pk_fma_f32 v[176:177], v[230:231], v[176:177], v[228:229]
	v_mov_b32_e32 v228, s92
	v_mov_b32_e32 v229, s63
	v_lshl_add_u32 v230, v165, 6, v157
	v_mov_b32_e32 v231, v145
	v_lshl_add_u64 v[228:229], v[230:231], 1, v[228:229]
	v_lshl_add_u64 v[232:233], v[154:155], 1, v[228:229]
	v_cvt_pk_bf16_f32 v228, v167, v220
	v_cvt_pk_bf16_f32 v229, v221, v222
	v_cvt_pk_bf16_f32 v230, v223, v224
	v_cvt_pk_bf16_f32 v231, v178, v179
	global_store_dwordx4 v[232:233], v[228:231], off
	v_mov_b32_e32 v157, 0
	s_nop 0
	v_cvt_pk_bf16_f32 v228, v180, v181
	v_cvt_pk_bf16_f32 v229, v182, v183
	v_cvt_pk_bf16_f32 v230, v184, v185
	v_cvt_pk_bf16_f32 v231, v176, v177
	global_store_dwordx4 v[232:233], v[228:231], off offset:64
	s_cbranch_vccnz .LBB0_1127
	v_mul_f32_e32 v157, v220, v220
	v_fmac_f32_e32 v157, v167, v167
	v_fmac_f32_e32 v157, v221, v221
	v_fmac_f32_e32 v157, v222, v222
	v_fmac_f32_e32 v157, v223, v223
	v_fmac_f32_e32 v157, v224, v224
	v_pk_mul_f32 v[178:179], v[178:179], v[178:179]
	v_pk_mul_f32 v[176:177], v[176:177], v[176:177]
	v_add_f32_e32 v157, v157, v178
	v_add_f32_e32 v157, v157, v179
	v_pk_mul_f32 v[178:179], v[180:181], v[180:181]
	s_nop 0
	v_add_f32_e32 v157, v157, v178
	v_add_f32_e32 v157, v157, v179
	v_pk_mul_f32 v[178:179], v[182:183], v[182:183]
	s_nop 0
	v_add_f32_e32 v157, v157, v178
	v_add_f32_e32 v157, v157, v179
	v_pk_mul_f32 v[178:179], v[184:185], v[184:185]
	s_nop 0
	v_add_f32_e32 v157, v157, v178
	v_add_f32_e32 v157, v157, v179
	v_add_f32_e32 v157, v157, v176
	v_add_f32_e32 v157, v157, v177
	v_mov_b32_e32 v165, v157
	s_nop 1
	v_permlane16_swap_b32_e32 v157, v165
	s_waitcnt lgkmcnt(0)
	v_add_f32_e32 v157, v157, v165
	v_mov_b32_e32 v165, v157
	s_nop 1
	v_permlane32_swap_b32_e32 v157, v165
	s_waitcnt lgkmcnt(0)
	v_add_f32_e32 v157, v157, v165
	v_max_f32_e32 v157, 0, v157

; __device__ __forceinline__ float grp_sum(float v) { v += __shfl_xor(v, 16); v += __shfl_xor(v, 32); return v; }
;   __device__ __forceinline__ void operator()(const pg8::f32x4 (&acc)[2][2][4][2], const pg8::Unit& u, int wr, int wc, int fr, int fq0) const {
;     ...
;         if (gi < 6) {
;           float ss = 0.f;
; #pragma unroll
;           for (int bj = 0; bj < 2; ++bj)
; #pragma unroll
;             for (int e = 0; e < 8; ++e) ss += v[bj][e] * v[bj][e];
;           ss = grp_sum(ss);
;           if (fq == 0) ssq2[(unsigned)tok * 8 + gi] = ss;
.LBB0_1131:
	s_andn2_b64 vcc, exec, s[16:17]
	s_cbranch_vccnz .LBB0_1135
	v_pk_mul_f32 v[176:177], v[128:129], v[128:129]
	v_pk_mul_f32 v[178:179], v[130:131], v[130:131]
	v_add_f32_e32 v157, v176, v177
	v_add_f32_e32 v157, v178, v157
	v_pk_mul_f32 v[180:181], v[132:133], v[132:133]
	v_add_f32_e32 v157, v179, v157
	v_add_f32_e32 v157, v180, v157
	v_pk_mul_f32 v[182:183], v[134:135], v[134:135]
	v_add_f32_e32 v157, v181, v157
	v_add_f32_e32 v157, v182, v157
	v_pk_mul_f32 v[184:185], v[168:169], v[168:169]
	v_add_f32_e32 v157, v183, v157
	v_add_f32_e32 v157, v184, v157
	v_pk_mul_f32 v[220:221], v[170:171], v[170:171]
	v_add_f32_e32 v157, v185, v157
	v_add_f32_e32 v157, v220, v157
	v_pk_mul_f32 v[222:223], v[172:173], v[172:173]
	v_add_f32_e32 v157, v221, v157
	v_add_f32_e32 v157, v222, v157
	v_pk_mul_f32 v[224:225], v[174:175], v[174:175]
	v_add_f32_e32 v157, v223, v157
	v_add_f32_e32 v157, v224, v157
	v_add_f32_e32 v157, v225, v157
	v_mov_b32_e32 v165, v157
	s_nop 1
	v_permlane16_swap_b32_e32 v157, v165
	s_waitcnt lgkmcnt(0)
	v_add_f32_e32 v157, v157, v165
	ds_bpermute_b32 v165, v212, v157
	s_and_saveexec_b64 s[16:17], s[8:9]
	s_cbranch_execz .LBB0_1134
	v_lshl_add_u32 v176, v215, 3, s68
	v_mov_b32_e32 v177, v145
	s_waitcnt lgkmcnt(0)
	v_add_f32_e32 v157, v157, v165
	v_lshl_add_u64 v[176:177], v[176:177], 2, s[52:53]
	global_store_dword v[176:177], v157, off

; __device__ __forceinline__ float grp_sum(float v) { v += __shfl_xor(v, 16); v += __shfl_xor(v, 32); return v; }
;   __device__ __forceinline__ void operator()(const pg8::f32x4 (&acc)[2][2][4][2], const pg8::Unit& u, int wr, int wc, int fr, int fq0) const {
;     ...
;         for (int bj = 0; bj < 2; ++bj)
; #pragma unroll
;           for (int n = 0; n < 2; ++n)
; #pragma unroll
;             for (int c = 0; c < 4; ++c) v[bj][4 * n + c] = acc[ai][bj][m][n][c] * rs[m];
;     ...
;           const bool isq = gi < 15; const float* gn = isq ? gq_norm : gk_norm;
;           float ss = 0.f;
; #pragma unroll
;           for (int bj = 0; bj < 2; ++bj)
; #pragma unroll
;             for (int e = 0; e < 8; ++e) ss += v[bj][e] * v[bj][e];
;           const float rn = rsqrtf(grp_sum(ss) * (1.f / 64.f) + EPS) * (isq ? 0.125f * LOG2E : 1.f);
;           float kk = 0.f;
; #pragma unroll
;           for (int bj = 0; bj < 2; ++bj) {
;             const unsigned ao = (unsigned)(bj == 0 ? (pos >> 6) : (pos & 63)) * 16 + 8 * (fq & 1);
;             const f32x4 c0 = *(const f32x4*)(cos32 + ao), c1 = *(const f32x4*)(cos32 + ao + 4), s0 = *(const f32x4*)(sin32 + ao), s1 = *(const f32x4*)(sin32 + ao + 4);
; #pragma unroll
;             for (int e = 0; e < 8; ++e) {
;               const float own = v[bj][e] * rn * gn[32 * bj + 8 * fq + e];
;               const float oth = lane32_partner(own, lane);
;               const float cc = e < 4 ? c0[e & 3] : c1[e & 3], sn = e < 4 ? s0[e & 3] : s1[e & 3];
;               v[bj][e] = (fq < 2) ? own * cc - oth * sn : oth * sn + own * cc;
;               kk += v[bj][e] * v[bj][e];
;             }
;           }
.LBB0_1135:
	s_waitcnt lgkmcnt(0)
	v_cndmask_b32_e64 v165, 0, 1, s[88:89]
	v_pk_mul_f32 v[128:129], v[120:121], v[160:161] op_sel:[0,1]
	v_pk_mul_f32 v[130:131], v[122:123], v[160:161] op_sel:[0,1]
	v_pk_mul_f32 v[132:133], v[104:105], v[160:161] op_sel:[0,1]
	v_pk_mul_f32 v[134:135], v[106:107], v[160:161] op_sel:[0,1]
	v_pk_mul_f32 v[168:169], v[88:89], v[160:161] op_sel:[0,1]
	v_pk_mul_f32 v[170:171], v[90:91], v[160:161] op_sel:[0,1]
	v_pk_mul_f32 v[172:173], v[72:73], v[160:161] op_sel:[0,1]
	v_pk_mul_f32 v[174:175], v[74:75], v[160:161] op_sel:[0,1]
	v_cmp_ne_u32_e64 s[16:17], 1, v165
	s_andn2_b64 vcc, exec, s[88:89]
	s_mov_b64 s[92:93], -1
	s_cbranch_vccnz .LBB0_1143
	s_andn2_b64 vcc, exec, s[90:91]
	s_cbranch_vccnz .LBB0_1140
	v_pk_mul_f32 v[176:177], v[128:129], v[128:129]
	v_pk_mul_f32 v[180:181], v[130:131], v[130:131]
	v_add_f32_e32 v176, v176, v177
	v_add_f32_e32 v176, v180, v176
	v_pk_mul_f32 v[182:183], v[132:133], v[132:133]
	v_add_f32_e32 v176, v181, v176
	v_add_f32_e32 v176, v182, v176
	v_pk_mul_f32 v[184:185], v[134:135], v[134:135]
	v_add_f32_e32 v176, v183, v176
	v_add_f32_e32 v176, v184, v176
	v_pk_mul_f32 v[220:221], v[168:169], v[168:169]
	v_add_f32_e32 v176, v185, v176
	v_add_f32_e32 v176, v220, v176
	v_pk_mul_f32 v[222:223], v[170:171], v[170:171]
	v_add_f32_e32 v176, v221, v176
	v_add_f32_e32 v176, v222, v176
	v_pk_mul_f32 v[224:225], v[172:173], v[172:173]
	v_add_f32_e32 v176, v223, v176
	v_add_f32_e32 v176, v224, v176
	v_pk_mul_f32 v[228:229], v[174:175], v[174:175]
	v_add_f32_e32 v176, v225, v176
	v_add_f32_e32 v176, v228, v176
	v_add_f32_e32 v176, v229, v176
	v_mov_b32_e32 v177, v176
	s_nop 1
	v_permlane16_swap_b32_e32 v176, v177
	s_and_b64 s[92:93], s[14:15], exec
	v_readlane_b32 s92, v252, 21
	v_readlane_b32 s93, v252, 22
	s_load_dwordx4 s[56:59], s[92:93], 0xe0
	s_waitcnt lgkmcnt(0)
	v_add_f32_e32 v176, v176, v177
	v_mov_b32_e32 v177, v176
	s_nop 1
	v_permlane32_swap_b32_e32 v176, v177
	v_readlane_b32 s93, v252, 16
	v_ashrrev_i32_e32 v165, 13, v219
	s_cselect_b32 s63, s57, s59
	s_cselect_b32 s92, s56, s58
	s_waitcnt lgkmcnt(0)
	v_add_f32_e32 v176, v176, v177
	v_fmamk_f32 v176, v176, 0x3c800000, v206
	v_cmp_gt_f32_e32 vcc, s21, v176
	v_mul_f32_e32 v177, 0x4b800000, v176
	s_movk_i32 s56, 0x7f0
	v_cndmask_b32_e32 v176, v176, v177, vcc
	v_rsq_f32_e32 v176, v176
	v_mov_b32_e32 v178, s92
	v_mov_b32_e32 v179, s63
	v_lshl_add_u64 v[180:181], v[154:155], 2, v[178:179]
	v_mul_f32_e32 v177, 0x45800000, v176
	v_cndmask_b32_e32 v176, v176, v177, vcc
	v_lshrrev_b32_e32 v177, 2, v219
	v_and_or_b32 v177, v177, s56, v213
	v_lshlrev_b32_e32 v177, 2, v177
	global_load_dwordx4 v[182:185], v177, s[54:55] offset:16
	global_load_dwordx4 v[222:225], v177, s[54:55]
	global_load_dwordx4 v[228:231], v177, s[50:51] offset:16
	global_load_dwordx4 v[232:235], v177, s[50:51]
	global_load_dwordx4 v[236:239], v[180:181], off offset:16
	global_load_dwordx4 v[240:243], v[180:181], off
	v_mul_f32_e32 v176, v214, v176
	v_mul_f32_e32 v177, v128, v176
	s_movk_i32 s56, 0x3f0
	v_and_or_b32 v144, v144, s56, v213
	v_lshlrev_b32_e32 v144, 2, v144
	v_readlane_b32 vcc_lo, v252, 6
	v_and_b32_e32 v167, 0x1fff, v219
	s_cselect_b32 s63, s62, s24
	s_cselect_b32 s92, 22, 20
	s_cselect_b32 s93, s93, vcc_lo
	v_readlane_b32 vcc_lo, v252, 14
	v_readlane_b32 vcc_hi, v252, 4
	s_cselect_b32 vcc_lo, vcc_lo, vcc_hi
	v_lshlrev_b32_e32 v165, s92, v165
	s_waitcnt vmcnt(0)
	v_mul_f32_e32 v177, v240, v177
	v_mov_b32_e32 v178, v177
	v_mov_b32_e32 v179, v177
	s_nop 1
	v_permlane32_swap_b32_e32 v178, v179
	v_cndmask_b32_e64 v178, v178, v179, s[12:13]
	v_mul_f32_e32 v178, v232, v178
	v_cndmask_b32_e64 v220, v178, -v178, s[10:11]
	v_fmac_f32_e32 v220, v222, v177
	v_mul_f32_e32 v177, v129, v176
	v_mul_f32_e32 v177, v241, v177
	v_mov_b32_e32 v178, v177
	v_mov_b32_e32 v179, v177
	s_nop 1
	v_permlane32_swap_b32_e32 v178, v179
	v_cndmask_b32_e64 v178, v178, v179, s[12:13]
	v_mul_f32_e32 v178, v233, v178
	v_cndmask_b32_e64 v221, v178, -v178, s[10:11]
	v_fmac_f32_e32 v221, v223, v177
	v_mul_f32_e32 v177, v130, v176
	v_mul_f32_e32 v177, v242, v177
	v_mov_b32_e32 v178, v177
	v_mov_b32_e32 v179, v177
	s_nop 1
	v_permlane32_swap_b32_e32 v178, v179
	v_cndmask_b32_e64 v178, v178, v179, s[12:13]
	v_mul_f32_e32 v178, v234, v178
	v_cndmask_b32_e64 v222, v178, -v178, s[10:11]
	v_fmac_f32_e32 v222, v224, v177
	v_mul_f32_e32 v177, v131, v176
	v_mul_f32_e32 v177, v177, v243
	v_mov_b32_e32 v178, v177
	v_mov_b32_e32 v179, v177
	s_nop 1
	v_permlane32_swap_b32_e32 v178, v179
	v_cndmask_b32_e64 v178, v178, v179, s[12:13]
	v_mul_f32_e32 v178, v235, v178
	v_cndmask_b32_e64 v223, v178, -v178, s[10:11]
	v_fmac_f32_e32 v223, v225, v177
	v_mul_f32_e32 v177, v132, v176
	v_mul_f32_e32 v177, v177, v236
	v_mov_b32_e32 v178, v177
	v_mov_b32_e32 v179, v177
	s_nop 1
	v_permlane32_swap_b32_e32 v178, v179
	v_cndmask_b32_e64 v178, v178, v179, s[12:13]
	v_mul_f32_e32 v178, v228, v178
	v_cndmask_b32_e64 v224, v178, -v178, s[10:11]
	v_fmac_f32_e32 v224, v182, v177
	v_mul_f32_e32 v177, v133, v176
	v_mul_f32_e32 v177, v177, v237
	v_mov_b32_e32 v178, v177
	v_mov_b32_e32 v179, v177
	s_nop 1
	v_permlane32_swap_b32_e32 v178, v179
	v_cndmask_b32_e64 v178, v178, v179, s[12:13]
	v_mul_f32_e32 v178, v229, v178
	v_cndmask_b32_e64 v225, v178, -v178, s[10:11]
	v_pk_mul_f32 v[178:179], v[134:135], v[176:177] op_sel_hi:[1,0]
	v_fmac_f32_e32 v225, v183, v177
	v_pk_mul_f32 v[178:179], v[178:179], v[238:239]
	s_nop 0
	v_mov_b32_e32 v177, v178
	v_mov_b32_e32 v182, v178
	v_mov_b32_e32 v183, v179
	v_mov_b32_e32 v227, v179
	v_permlane32_swap_b32_e32 v177, v182
	s_nop 0
	v_permlane32_swap_b32_e32 v183, v227
	v_cndmask_b32_e64 v183, v183, v227, s[12:13]
	v_cndmask_b32_e64 v182, v177, v182, s[12:13]
	v_pk_mul_f32 v[182:183], v[230:231], v[182:183]
	v_pk_mul_f32 v[248:249], v[168:169], v[176:177] op_sel_hi:[1,0]
	v_cndmask_b32_e64 v183, v183, -v183, s[10:11]
	v_cndmask_b32_e64 v182, v182, -v182, s[10:11]
	v_pk_fma_f32 v[178:179], v[184:185], v[178:179], v[182:183]
	global_load_dwordx4 v[228:231], v144, s[54:55] offset:16
	global_load_dwordx4 v[182:185], v144, s[54:55]
	global_load_dwordx4 v[232:235], v144, s[50:51] offset:16
	global_load_dwordx4 v[236:239], v144, s[50:51]
	global_load_dwordx4 v[240:243], v[180:181], off offset:144
	global_load_dwordx4 v[244:247], v[180:181], off offset:128
	s_waitcnt vmcnt(0)
; __device__ __forceinline__ float grp_sum(float v) { v += __shfl_xor(v, 16); v += __shfl_xor(v, 32); return v; }
; __device__ __forceinline__ void st8_bf16(bf16_t* dst, const float (&v)[8]) { u32x4 w; w.x = pk2(v[0], v[1]); w.y = pk2(v[2], v[3]); w.z = pk2(v[4], v[5]); w.w = pk2(v[6], v[7]); *(u32x4*)dst = w; }
;   __device__ __forceinline__ void operator()(const pg8::f32x4 (&acc)[2][2][4][2], const pg8::Unit& u, int wr, int wc, int fr, int fq0) const {
;     ...
;             for (int e = 0; e < 8; ++e) {
;               const float own = v[bj][e] * rn * gn[32 * bj + 8 * fq + e];
;               const float oth = lane32_partner(own, lane);
;               const float cc = e < 4 ? c0[e & 3] : c1[e & 3], sn = e < 4 ? s0[e & 3] : s1[e & 3];
;               v[bj][e] = (fq < 2) ? own * cc - oth * sn : oth * sn + own * cc;
;               kk += v[bj][e] * v[bj][e];
;             }
;           }
;           bf16_t* dst = isq ? qd + ((unsigned)(bb * 8 + (gi - 7)) * S + pos) * 64 + 8 * fq : kd + ((unsigned)(bb * 2 + (gi - 15)) * S + pos) * 64 + 8 * fq;
;           st8_bf16(dst, v[0]); st8_bf16(dst + 32, v[1]);
;           if (!isq) kmx_run = fmaxf(kmx_run, grp_sum(kk));
	v_pk_mul_f32 v[180:181], v[248:249], v[244:245]
	s_nop 0
	v_mov_b32_e32 v144, v180
	v_mov_b32_e32 v177, v180
	v_mov_b32_e32 v227, v181
	v_mov_b32_e32 v244, v181
	v_permlane32_swap_b32_e32 v144, v177
	s_nop 0
	v_permlane32_swap_b32_e32 v227, v244
	v_cndmask_b32_e64 v245, v227, v244, s[12:13]
	v_cndmask_b32_e64 v244, v144, v177, s[12:13]
	v_pk_mul_f32 v[236:237], v[236:237], v[244:245]
	s_nop 0
	v_cndmask_b32_e64 v237, v237, -v237, s[10:11]
	v_cndmask_b32_e64 v236, v236, -v236, s[10:11]
	v_pk_fma_f32 v[180:181], v[182:183], v[180:181], v[236:237]
	v_pk_mul_f32 v[182:183], v[170:171], v[176:177] op_sel_hi:[1,0]
	s_nop 0
	v_pk_mul_f32 v[182:183], v[182:183], v[246:247]
	s_nop 0
	v_mov_b32_e32 v144, v182
	v_mov_b32_e32 v177, v182
	v_mov_b32_e32 v227, v183
	v_mov_b32_e32 v236, v183
	v_permlane32_swap_b32_e32 v144, v177
	s_nop 0
	v_permlane32_swap_b32_e32 v227, v236
	v_cndmask_b32_e64 v237, v227, v236, s[12:13]
	v_cndmask_b32_e64 v236, v144, v177, s[12:13]
	v_pk_mul_f32 v[236:237], v[238:239], v[236:237]
	s_nop 0
	v_cndmask_b32_e64 v237, v237, -v237, s[10:11]
	v_cndmask_b32_e64 v236, v236, -v236, s[10:11]
	v_pk_fma_f32 v[182:183], v[184:185], v[182:183], v[236:237]
	v_pk_mul_f32 v[184:185], v[172:173], v[176:177] op_sel_hi:[1,0]
	s_nop 0
	v_pk_mul_f32 v[184:185], v[184:185], v[240:241]
	s_nop 0
	v_mov_b32_e32 v144, v184
	v_mov_b32_e32 v177, v184
	v_mov_b32_e32 v227, v185
	v_mov_b32_e32 v236, v185
	v_permlane32_swap_b32_e32 v144, v177
	s_nop 0
	v_permlane32_swap_b32_e32 v227, v236
	v_cndmask_b32_e64 v237, v227, v236, s[12:13]
	v_cndmask_b32_e64 v236, v144, v177, s[12:13]
	v_pk_mul_f32 v[232:233], v[232:233], v[236:237]
	v_pk_mul_f32 v[176:177], v[174:175], v[176:177] op_sel_hi:[1,0]
	v_cndmask_b32_e64 v233, v233, -v233, s[10:11]
	v_cndmask_b32_e64 v232, v232, -v232, s[10:11]
	v_pk_mul_f32 v[176:177], v[176:177], v[242:243]
	v_pk_fma_f32 v[184:185], v[228:229], v[184:185], v[232:233]
	v_mov_b32_e32 v144, v176
	v_mov_b32_e32 v227, v176
	v_mov_b32_e32 v228, v177
	v_mov_b32_e32 v229, v177
	v_permlane32_swap_b32_e32 v144, v227
	s_nop 0
	v_permlane32_swap_b32_e32 v228, v229
	v_cndmask_b32_e64 v229, v228, v229, s[12:13]
	v_cndmask_b32_e64 v228, v144, v227, s[12:13]
	v_pk_mul_f32 v[228:229], v[234:235], v[228:229]
	v_or_b32_e32 v144, s63, v167
	v_cndmask_b32_e64 v229, v229, -v229, s[10:11]
	v_cndmask_b32_e64 v228, v228, -v228, s[10:11]
	v_pk_fma_f32 v[176:177], v[230:231], v[176:177], v[228:229]
	v_mov_b32_e32 v228, vcc_lo
	v_mov_b32_e32 v229, s93
	v_lshl_add_u32 v144, v144, 6, v165
	v_lshl_add_u64 v[228:229], v[144:145], 1, v[228:229]
	v_lshl_add_u64 v[232:233], v[154:155], 1, v[228:229]
	v_cvt_pk_bf16_f32 v228, v220, v221
	v_cvt_pk_bf16_f32 v229, v222, v223
	v_cvt_pk_bf16_f32 v230, v224, v225
	v_cvt_pk_bf16_f32 v231, v178, v179
	global_store_dwordx4 v[232:233], v[228:231], off
	s_andn2_b64 vcc, exec, s[86:87]
	v_mov_b32_e32 v165, v157
	v_cvt_pk_bf16_f32 v228, v180, v181
	v_cvt_pk_bf16_f32 v229, v182, v183
	v_cvt_pk_bf16_f32 v230, v184, v185
	v_cvt_pk_bf16_f32 v231, v176, v177
	global_store_dwordx4 v[232:233], v[228:231], off offset:64
	s_cbranch_vccnz .LBB0_1139
	v_mul_f32_e32 v144, v221, v221
	v_fmac_f32_e32 v144, v220, v220
	v_fmac_f32_e32 v144, v222, v222
	v_fmac_f32_e32 v144, v223, v223
	v_fmac_f32_e32 v144, v224, v224
	v_fmac_f32_e32 v144, v225, v225
	v_pk_mul_f32 v[178:179], v[178:179], v[178:179]
	v_pk_mul_f32 v[176:177], v[176:177], v[176:177]
	v_add_f32_e32 v144, v144, v178
	v_add_f32_e32 v144, v144, v179
	v_pk_mul_f32 v[178:179], v[180:181], v[180:181]
	s_nop 0
	v_add_f32_e32 v144, v144, v178
	v_add_f32_e32 v144, v144, v179
	v_pk_mul_f32 v[178:179], v[182:183], v[182:183]
	s_nop 0
	v_add_f32_e32 v144, v144, v178
	v_add_f32_e32 v144, v144, v179
	v_pk_mul_f32 v[178:179], v[184:185], v[184:185]
	s_nop 0
	v_add_f32_e32 v144, v144, v178
	v_add_f32_e32 v144, v144, v179
	v_add_f32_e32 v144, v144, v176
	v_add_f32_e32 v144, v144, v177
	v_mov_b32_e32 v165, v144
	s_nop 1
	v_permlane16_swap_b32_e32 v144, v165
	s_waitcnt lgkmcnt(0)
	v_add_f32_e32 v144, v144, v165
	v_mov_b32_e32 v165, v144
	s_nop 1
	v_permlane32_swap_b32_e32 v144, v165
	s_waitcnt lgkmcnt(0)
	v_add_f32_e32 v144, v144, v165
	v_max_f32_e32 v165, v157, v157
	v_max_f32_e32 v165, v165, v144

; __device__ __forceinline__ float grp_sum(float v) { v += __shfl_xor(v, 16); v += __shfl_xor(v, 32); return v; }
;   __device__ __forceinline__ void operator()(const pg8::f32x4 (&acc)[2][2][4][2], const pg8::Unit& u, int wr, int wc, int fr, int fq0) const {
;     ...
;         if (gi < 6) {
;           float ss = 0.f;
; #pragma unroll
;           for (int bj = 0; bj < 2; ++bj)
; #pragma unroll
;             for (int e = 0; e < 8; ++e) ss += v[bj][e] * v[bj][e];
;           ss = grp_sum(ss);
;           if (fq == 0) ssq2[(unsigned)tok * 8 + gi] = ss;
.LBB0_1143:
	s_andn2_b64 vcc, exec, s[92:93]
	s_cbranch_vccnz .LBB0_1147
	v_pk_mul_f32 v[176:177], v[128:129], v[128:129]
	v_pk_mul_f32 v[178:179], v[130:131], v[130:131]
	v_add_f32_e32 v144, v176, v177
	v_add_f32_e32 v144, v178, v144
	v_pk_mul_f32 v[180:181], v[132:133], v[132:133]
	v_add_f32_e32 v144, v179, v144
	v_add_f32_e32 v144, v180, v144
	v_pk_mul_f32 v[182:183], v[134:135], v[134:135]
	v_add_f32_e32 v144, v181, v144
	v_add_f32_e32 v144, v182, v144
	v_pk_mul_f32 v[184:185], v[168:169], v[168:169]
	v_add_f32_e32 v144, v183, v144
	v_add_f32_e32 v144, v184, v144
	v_pk_mul_f32 v[220:221], v[170:171], v[170:171]
	v_add_f32_e32 v144, v185, v144
	v_add_f32_e32 v144, v220, v144
	v_pk_mul_f32 v[222:223], v[172:173], v[172:173]
	v_add_f32_e32 v144, v221, v144
	v_add_f32_e32 v144, v222, v144
	v_pk_mul_f32 v[224:225], v[174:175], v[174:175]
	v_add_f32_e32 v144, v223, v144
	v_add_f32_e32 v144, v224, v144
	v_add_f32_e32 v144, v225, v144
	v_mov_b32_e32 v165, v144
	s_nop 1
	v_permlane16_swap_b32_e32 v144, v165
	s_waitcnt lgkmcnt(0)
	v_add_f32_e32 v144, v144, v165
	ds_bpermute_b32 v165, v212, v144
	s_and_saveexec_b64 s[92:93], s[8:9]
	s_cbranch_execz .LBB0_1146
	s_waitcnt lgkmcnt(0)
	v_add_f32_e32 v165, v144, v165
	v_lshl_add_u32 v144, v219, 3, s68
	v_lshl_add_u64 v[176:177], v[144:145], 2, s[52:53]
	global_store_dword v[176:177], v165, off

; __device__ __forceinline__ float grp_sum(float v) { v += __shfl_xor(v, 16); v += __shfl_xor(v, 32); return v; }
;   __device__ __forceinline__ void operator()(const pg8::f32x4 (&acc)[2][2][4][2], const pg8::Unit& u, int wr, int wc, int fr, int fq0) const {
;     ...
;         for (int bj = 0; bj < 2; ++bj)
; #pragma unroll
;           for (int n = 0; n < 2; ++n)
; #pragma unroll
;             for (int c = 0; c < 4; ++c) v[bj][4 * n + c] = acc[ai][bj][m][n][c] * rs[m];
;     ...
;           const bool isq = gi < 15; const float* gn = isq ? gq_norm : gk_norm;
;           float ss = 0.f;
; #pragma unroll
;           for (int bj = 0; bj < 2; ++bj)
; #pragma unroll
;             for (int e = 0; e < 8; ++e) ss += v[bj][e] * v[bj][e];
;           const float rn = rsqrtf(grp_sum(ss) * (1.f / 64.f) + EPS) * (isq ? 0.125f * LOG2E : 1.f);
;           float kk = 0.f;
; #pragma unroll
;           for (int bj = 0; bj < 2; ++bj) {
;             const unsigned ao = (unsigned)(bj == 0 ? (pos >> 6) : (pos & 63)) * 16 + 8 * (fq & 1);
;             const f32x4 c0 = *(const f32x4*)(cos32 + ao), c1 = *(const f32x4*)(cos32 + ao + 4), s0 = *(const f32x4*)(sin32 + ao), s1 = *(const f32x4*)(sin32 + ao + 4);
; #pragma unroll
;             for (int e = 0; e < 8; ++e) {
;               const float own = v[bj][e] * rn * gn[32 * bj + 8 * fq + e];
;               const float oth = lane32_partner(own, lane);
;               const float cc = e < 4 ? c0[e & 3] : c1[e & 3], sn = e < 4 ? s0[e & 3] : s1[e & 3];
;               v[bj][e] = (fq < 2) ? own * cc - oth * sn : oth * sn + own * cc;
;               kk += v[bj][e] * v[bj][e];
;             }
;           }
.LBB0_1147:
	s_nop 1
	v_pk_mul_f32 v[128:129], v[116:117], v[162:163] op_sel_hi:[1,0]
	v_pk_mul_f32 v[130:131], v[118:119], v[162:163] op_sel_hi:[1,0]
	v_pk_mul_f32 v[132:133], v[100:101], v[162:163] op_sel_hi:[1,0]
	v_pk_mul_f32 v[134:135], v[102:103], v[162:163] op_sel_hi:[1,0]
	v_pk_mul_f32 v[168:169], v[84:85], v[162:163] op_sel_hi:[1,0]
	v_pk_mul_f32 v[170:171], v[86:87], v[162:163] op_sel_hi:[1,0]
	v_pk_mul_f32 v[172:173], v[68:69], v[162:163] op_sel_hi:[1,0]
	v_pk_mul_f32 v[174:175], v[70:71], v[162:163] op_sel_hi:[1,0]
	s_and_b64 vcc, exec, s[16:17]
	s_mov_b64 s[92:93], -1
	s_cbranch_vccnz .LBB0_1155
	s_andn2_b64 vcc, exec, s[90:91]
	s_cbranch_vccnz .LBB0_1152
	v_pk_mul_f32 v[178:179], v[128:129], v[128:129]
	v_pk_mul_f32 v[180:181], v[130:131], v[130:131]
	v_add_f32_e32 v144, v178, v179
	v_add_f32_e32 v144, v180, v144
	v_pk_mul_f32 v[182:183], v[132:133], v[132:133]
	v_add_f32_e32 v144, v181, v144
	v_add_f32_e32 v144, v182, v144
	v_pk_mul_f32 v[220:221], v[134:135], v[134:135]
	v_add_f32_e32 v144, v183, v144
	v_add_f32_e32 v144, v220, v144
	v_pk_mul_f32 v[222:223], v[168:169], v[168:169]
	v_add_f32_e32 v144, v221, v144
	v_add_f32_e32 v144, v222, v144
	v_pk_mul_f32 v[224:225], v[170:171], v[170:171]
	v_add_f32_e32 v144, v223, v144
	v_add_f32_e32 v144, v224, v144
	v_pk_mul_f32 v[228:229], v[172:173], v[172:173]
	v_add_f32_e32 v144, v225, v144
	v_add_f32_e32 v144, v228, v144
	v_pk_mul_f32 v[230:231], v[174:175], v[174:175]
	v_add_f32_e32 v144, v229, v144
	v_add_f32_e32 v144, v230, v144
	v_add_f32_e32 v144, v231, v144
	v_mov_b32_e32 v167, v144
	s_nop 1
	v_permlane16_swap_b32_e32 v144, v167
	s_and_b64 s[92:93], s[14:15], exec
	v_readlane_b32 s92, v252, 21
	v_readlane_b32 s93, v252, 22
	s_load_dwordx4 s[56:59], s[92:93], 0xe0
	s_waitcnt lgkmcnt(0)
	v_add_f32_e32 v144, v144, v167
	v_mov_b32_e32 v167, v144
	s_nop 1
	v_permlane32_swap_b32_e32 v144, v167
	v_readlane_b32 s93, v252, 16
	v_ashrrev_i32_e32 v157, 13, v218
	s_cselect_b32 s63, s57, s59
	s_cselect_b32 s92, s56, s58
	s_waitcnt lgkmcnt(0)
	v_add_f32_e32 v144, v144, v167
	v_fmamk_f32 v144, v144, 0x3c800000, v206
	v_cmp_gt_f32_e32 vcc, s21, v144
	v_mul_f32_e32 v167, 0x4b800000, v144
	s_movk_i32 s56, 0x7f0
	v_cndmask_b32_e32 v144, v144, v167, vcc
	v_rsq_f32_e32 v144, v144
	v_mov_b32_e32 v176, s92
	v_mov_b32_e32 v177, s63
	v_lshl_add_u64 v[178:179], v[154:155], 2, v[176:177]
	v_mul_f32_e32 v167, 0x45800000, v144
	v_cndmask_b32_e32 v144, v144, v167, vcc
	v_lshrrev_b32_e32 v167, 2, v218
	v_and_or_b32 v167, v167, s56, v213
	v_lshlrev_b32_e32 v167, 2, v167
	global_load_dwordx4 v[180:183], v167, s[54:55] offset:16
	global_load_dwordx4 v[220:223], v167, s[54:55]
	global_load_dwordx4 v[228:231], v167, s[50:51] offset:16
	global_load_dwordx4 v[232:235], v167, s[50:51]
	global_load_dwordx4 v[236:239], v[178:179], off offset:16
	global_load_dwordx4 v[240:243], v[178:179], off
	v_mul_f32_e32 v144, v214, v144
	v_mul_f32_e32 v167, v128, v144
	s_movk_i32 s56, 0x3f0
	v_and_or_b32 v166, v166, s56, v213
	v_lshlrev_b32_e32 v166, 2, v166
	v_readlane_b32 vcc_lo, v252, 6
	v_and_b32_e32 v184, 0x1fff, v218
	s_cselect_b32 s63, s62, s24
	s_cselect_b32 s92, 22, 20
	s_cselect_b32 s93, s93, vcc_lo
	v_readlane_b32 vcc_lo, v252, 14
	v_readlane_b32 vcc_hi, v252, 4
	s_cselect_b32 vcc_lo, vcc_lo, vcc_hi
	v_lshlrev_b32_e32 v157, s92, v157
	s_waitcnt vmcnt(0)
	v_mul_f32_e32 v167, v240, v167
	v_mov_b32_e32 v176, v167
	v_mov_b32_e32 v177, v167
	s_nop 1
	v_permlane32_swap_b32_e32 v176, v177
	v_cndmask_b32_e64 v176, v176, v177, s[12:13]
	v_mul_f32_e32 v176, v232, v176
	v_cndmask_b32_e64 v185, v176, -v176, s[10:11]
	v_fmac_f32_e32 v185, v220, v167
	v_mul_f32_e32 v167, v129, v144
	v_mul_f32_e32 v167, v241, v167
	v_mov_b32_e32 v176, v167
	v_mov_b32_e32 v177, v167
	s_nop 1
	v_permlane32_swap_b32_e32 v176, v177
	v_cndmask_b32_e64 v176, v176, v177, s[12:13]
	v_mul_f32_e32 v176, v233, v176
	v_cndmask_b32_e64 v219, v176, -v176, s[10:11]
	v_fmac_f32_e32 v219, v221, v167
	v_mul_f32_e32 v167, v130, v144
	v_mul_f32_e32 v167, v242, v167
	v_mov_b32_e32 v176, v167
	v_mov_b32_e32 v177, v167
	s_nop 1
	v_permlane32_swap_b32_e32 v176, v177
	v_cndmask_b32_e64 v176, v176, v177, s[12:13]
	v_mul_f32_e32 v176, v234, v176
	v_cndmask_b32_e64 v220, v176, -v176, s[10:11]
	v_fmac_f32_e32 v220, v222, v167
	v_mul_f32_e32 v167, v131, v144
	v_mul_f32_e32 v167, v167, v243
	v_mov_b32_e32 v176, v167
	v_mov_b32_e32 v177, v167
	s_nop 1
	v_permlane32_swap_b32_e32 v176, v177
	v_cndmask_b32_e64 v176, v176, v177, s[12:13]
	v_mul_f32_e32 v176, v235, v176
	v_cndmask_b32_e64 v221, v176, -v176, s[10:11]
	v_fmac_f32_e32 v221, v223, v167
	v_mul_f32_e32 v167, v132, v144
	v_mul_f32_e32 v167, v167, v236
	v_mov_b32_e32 v176, v167
	v_mov_b32_e32 v177, v167
	s_nop 1
	v_permlane32_swap_b32_e32 v176, v177
	v_cndmask_b32_e64 v176, v176, v177, s[12:13]
	v_mul_f32_e32 v176, v228, v176
	v_cndmask_b32_e64 v222, v176, -v176, s[10:11]
	v_fmac_f32_e32 v222, v180, v167
	v_mul_f32_e32 v167, v133, v144
	v_mul_f32_e32 v167, v167, v237
	v_mov_b32_e32 v176, v167
	v_mov_b32_e32 v177, v167
	s_nop 1
	v_permlane32_swap_b32_e32 v176, v177
	v_cndmask_b32_e64 v176, v176, v177, s[12:13]
	v_mul_f32_e32 v176, v229, v176
	v_cndmask_b32_e64 v223, v176, -v176, s[10:11]
	v_pk_mul_f32 v[176:177], v[134:135], v[144:145] op_sel_hi:[1,0]
	v_fmac_f32_e32 v223, v181, v167
	v_pk_mul_f32 v[176:177], v[176:177], v[238:239]
	s_nop 0
	v_mov_b32_e32 v167, v176
	v_mov_b32_e32 v180, v176
	v_mov_b32_e32 v181, v177
	v_mov_b32_e32 v224, v177
	v_permlane32_swap_b32_e32 v167, v180
	s_nop 0
	v_permlane32_swap_b32_e32 v181, v224
	v_cndmask_b32_e64 v181, v181, v224, s[12:13]
	v_cndmask_b32_e64 v180, v167, v180, s[12:13]
	v_pk_mul_f32 v[180:181], v[230:231], v[180:181]
	s_nop 0
	v_cndmask_b32_e64 v181, v181, -v181, s[10:11]
	v_cndmask_b32_e64 v180, v180, -v180, s[10:11]
	v_pk_fma_f32 v[176:177], v[182:183], v[176:177], v[180:181]
	global_load_dwordx4 v[180:183], v166, s[54:55] offset:16
	global_load_dwordx4 v[228:231], v166, s[54:55]
	global_load_dwordx4 v[232:235], v166, s[50:51] offset:16
	global_load_dwordx4 v[236:239], v166, s[50:51]
	global_load_dwordx4 v[240:243], v[178:179], off offset:144
	global_load_dwordx4 v[244:247], v[178:179], off offset:128
	v_pk_mul_f32 v[166:167], v[168:169], v[144:145] op_sel_hi:[1,0]
	s_waitcnt vmcnt(0)
; __device__ __forceinline__ float grp_sum(float v) { v += __shfl_xor(v, 16); v += __shfl_xor(v, 32); return v; }
; __device__ __forceinline__ void st8_bf16(bf16_t* dst, const float (&v)[8]) { u32x4 w; w.x = pk2(v[0], v[1]); w.y = pk2(v[2], v[3]); w.z = pk2(v[4], v[5]); w.w = pk2(v[6], v[7]); *(u32x4*)dst = w; }
;   __device__ __forceinline__ void operator()(const pg8::f32x4 (&acc)[2][2][4][2], const pg8::Unit& u, int wr, int wc, int fr, int fq0) const {
;     ...
;             for (int e = 0; e < 8; ++e) {
;               const float own = v[bj][e] * rn * gn[32 * bj + 8 * fq + e];
;               const float oth = lane32_partner(own, lane);
;               const float cc = e < 4 ? c0[e & 3] : c1[e & 3], sn = e < 4 ? s0[e & 3] : s1[e & 3];
;               v[bj][e] = (fq < 2) ? own * cc - oth * sn : oth * sn + own * cc;
;               kk += v[bj][e] * v[bj][e];
;             }
;           }
;           bf16_t* dst = isq ? qd + ((unsigned)(bb * 8 + (gi - 7)) * S + pos) * 64 + 8 * fq : kd + ((unsigned)(bb * 2 + (gi - 15)) * S + pos) * 64 + 8 * fq;
;           st8_bf16(dst, v[0]); st8_bf16(dst + 32, v[1]);
;           if (!isq) kmx_run = fmaxf(kmx_run, grp_sum(kk));
	v_pk_mul_f32 v[166:167], v[166:167], v[244:245]
	s_nop 0
	v_mov_b32_e32 v178, v166
	v_mov_b32_e32 v224, v166
	v_mov_b32_e32 v179, v167
	v_mov_b32_e32 v225, v167
	v_permlane32_swap_b32_e32 v178, v224
	s_nop 0
	v_permlane32_swap_b32_e32 v179, v225
	v_cndmask_b32_e64 v179, v179, v225, s[12:13]
	v_cndmask_b32_e64 v178, v178, v224, s[12:13]
	v_pk_mul_f32 v[178:179], v[236:237], v[178:179]
	s_nop 0
	v_cndmask_b32_e64 v179, v179, -v179, s[10:11]
	v_cndmask_b32_e64 v178, v178, -v178, s[10:11]
	v_pk_fma_f32 v[166:167], v[228:229], v[166:167], v[178:179]
	v_pk_mul_f32 v[178:179], v[170:171], v[144:145] op_sel_hi:[1,0]
	s_nop 0
	v_pk_mul_f32 v[178:179], v[178:179], v[246:247]
	s_nop 0
	v_mov_b32_e32 v224, v178
	v_mov_b32_e32 v227, v178
	v_mov_b32_e32 v225, v179
	v_mov_b32_e32 v228, v179
	v_permlane32_swap_b32_e32 v224, v227
	s_nop 0
	v_permlane32_swap_b32_e32 v225, v228
	v_cndmask_b32_e64 v225, v225, v228, s[12:13]
	v_cndmask_b32_e64 v224, v224, v227, s[12:13]
	v_pk_mul_f32 v[224:225], v[238:239], v[224:225]
	s_nop 0
	v_cndmask_b32_e64 v225, v225, -v225, s[10:11]
	v_cndmask_b32_e64 v224, v224, -v224, s[10:11]
	v_pk_fma_f32 v[178:179], v[230:231], v[178:179], v[224:225]
	v_pk_mul_f32 v[224:225], v[172:173], v[144:145] op_sel_hi:[1,0]
	v_cvt_pk_bf16_f32 v231, v176, v177
	v_pk_mul_f32 v[224:225], v[224:225], v[240:241]
	s_nop 0
	v_mov_b32_e32 v227, v224
	v_mov_b32_e32 v228, v224
	v_mov_b32_e32 v229, v225
	v_mov_b32_e32 v230, v225
	v_permlane32_swap_b32_e32 v227, v228
	s_nop 0
	v_permlane32_swap_b32_e32 v229, v230
	v_cndmask_b32_e64 v229, v229, v230, s[12:13]
	v_cndmask_b32_e64 v228, v227, v228, s[12:13]
	v_pk_mul_f32 v[228:229], v[232:233], v[228:229]
	v_cvt_pk_bf16_f32 v230, v222, v223
	v_cndmask_b32_e64 v229, v229, -v229, s[10:11]
	v_cndmask_b32_e64 v228, v228, -v228, s[10:11]
	v_pk_fma_f32 v[180:181], v[180:181], v[224:225], v[228:229]
	v_pk_mul_f32 v[224:225], v[174:175], v[144:145] op_sel_hi:[1,0]
	s_nop 0
	v_pk_mul_f32 v[224:225], v[224:225], v[242:243]
	s_nop 0
	v_mov_b32_e32 v144, v224
	v_mov_b32_e32 v227, v224
	v_mov_b32_e32 v228, v225
	v_mov_b32_e32 v229, v225
	v_permlane32_swap_b32_e32 v144, v227
	s_nop 0
	v_permlane32_swap_b32_e32 v228, v229
	v_cndmask_b32_e64 v229, v228, v229, s[12:13]
	v_cndmask_b32_e64 v228, v144, v227, s[12:13]
	v_pk_mul_f32 v[228:229], v[234:235], v[228:229]
	v_or_b32_e32 v144, s63, v184
	v_cndmask_b32_e64 v229, v229, -v229, s[10:11]
	v_cndmask_b32_e64 v228, v228, -v228, s[10:11]
	v_pk_fma_f32 v[182:183], v[182:183], v[224:225], v[228:229]
	v_mov_b32_e32 v224, vcc_lo
	v_mov_b32_e32 v225, s93
	v_lshl_add_u32 v144, v144, 6, v157
	v_lshl_add_u64 v[224:225], v[144:145], 1, v[224:225]
	v_lshl_add_u64 v[224:225], v[154:155], 1, v[224:225]
	v_cvt_pk_bf16_f32 v228, v185, v219
	v_cvt_pk_bf16_f32 v229, v220, v221
	global_store_dwordx4 v[224:225], v[228:231], off
	s_andn2_b64 vcc, exec, s[86:87]
	v_mov_b32_e32 v184, v165
	v_cvt_pk_bf16_f32 v228, v166, v167
	v_cvt_pk_bf16_f32 v229, v178, v179
	v_cvt_pk_bf16_f32 v230, v180, v181
	v_cvt_pk_bf16_f32 v231, v182, v183
	global_store_dwordx4 v[224:225], v[228:231], off offset:64
	s_cbranch_vccnz .LBB0_1151
	v_mul_f32_e32 v144, v219, v219
	v_fmac_f32_e32 v144, v185, v185
	v_fmac_f32_e32 v144, v220, v220
	v_fmac_f32_e32 v144, v221, v221
	v_fmac_f32_e32 v144, v222, v222
	v_fmac_f32_e32 v144, v223, v223
	v_pk_mul_f32 v[176:177], v[176:177], v[176:177]
	v_pk_mul_f32 v[166:167], v[166:167], v[166:167]
	v_add_f32_e32 v144, v144, v176
	v_add_f32_e32 v144, v144, v177
	v_add_f32_e32 v144, v144, v166
	v_add_f32_e32 v144, v144, v167
	v_pk_mul_f32 v[166:167], v[178:179], v[178:179]
	s_nop 0
	v_add_f32_e32 v144, v144, v166
	v_add_f32_e32 v144, v144, v167
	v_pk_mul_f32 v[166:167], v[180:181], v[180:181]
	s_nop 0
	v_add_f32_e32 v144, v144, v166
	v_add_f32_e32 v144, v144, v167
	v_pk_mul_f32 v[166:167], v[182:183], v[182:183]
	s_nop 0
	v_add_f32_e32 v144, v144, v166
	v_add_f32_e32 v144, v144, v167
	v_mov_b32_e32 v157, v144
	s_nop 1
	v_permlane16_swap_b32_e32 v144, v157
	s_waitcnt lgkmcnt(0)
	v_add_f32_e32 v144, v144, v157
	v_mov_b32_e32 v157, v144
	s_nop 1
	v_permlane32_swap_b32_e32 v144, v157
	s_waitcnt lgkmcnt(0)
	v_add_f32_e32 v144, v144, v157
	v_max_f32_e32 v157, v165, v165
	v_max_f32_e32 v184, v157, v144

; __device__ __forceinline__ float grp_sum(float v) { v += __shfl_xor(v, 16); v += __shfl_xor(v, 32); return v; }
;   __device__ __forceinline__ void operator()(const pg8::f32x4 (&acc)[2][2][4][2], const pg8::Unit& u, int wr, int wc, int fr, int fq0) const {
;     ...
;         if (gi < 6) {
;           float ss = 0.f;
; #pragma unroll
;           for (int bj = 0; bj < 2; ++bj)
; #pragma unroll
;             for (int e = 0; e < 8; ++e) ss += v[bj][e] * v[bj][e];
;           ss = grp_sum(ss);
;           if (fq == 0) ssq2[(unsigned)tok * 8 + gi] = ss;
.LBB0_1155:
	s_andn2_b64 vcc, exec, s[92:93]
	s_cbranch_vccnz .LBB0_1159
	v_pk_mul_f32 v[166:167], v[128:129], v[128:129]
	v_pk_mul_f32 v[176:177], v[130:131], v[130:131]
	v_add_f32_e32 v144, v166, v167
	v_add_f32_e32 v144, v176, v144
	v_pk_mul_f32 v[178:179], v[132:133], v[132:133]
	v_add_f32_e32 v144, v177, v144
	v_add_f32_e32 v144, v178, v144
	v_pk_mul_f32 v[180:181], v[134:135], v[134:135]
	v_add_f32_e32 v144, v179, v144
	v_add_f32_e32 v144, v180, v144
	v_pk_mul_f32 v[182:183], v[168:169], v[168:169]
	v_add_f32_e32 v144, v181, v144
	v_add_f32_e32 v144, v182, v144
	v_pk_mul_f32 v[184:185], v[170:171], v[170:171]
	v_add_f32_e32 v144, v183, v144
	v_add_f32_e32 v144, v184, v144
	v_pk_mul_f32 v[220:221], v[172:173], v[172:173]
	v_add_f32_e32 v144, v185, v144
	v_add_f32_e32 v144, v220, v144
	v_pk_mul_f32 v[222:223], v[174:175], v[174:175]
	v_add_f32_e32 v144, v221, v144
	v_add_f32_e32 v144, v222, v144
	v_add_f32_e32 v144, v223, v144
	v_mov_b32_e32 v157, v144
	s_nop 1
	v_permlane16_swap_b32_e32 v144, v157
	s_waitcnt lgkmcnt(0)
	v_add_f32_e32 v144, v144, v157
	ds_bpermute_b32 v157, v212, v144
	s_and_saveexec_b64 s[92:93], s[8:9]
	s_cbranch_execz .LBB0_1158
	s_waitcnt lgkmcnt(0)
	v_add_f32_e32 v157, v144, v157
	v_lshl_add_u32 v144, v218, 3, s68
	v_lshl_add_u64 v[166:167], v[144:145], 2, s[52:53]
	global_store_dword v[166:167], v157, off

; __device__ __forceinline__ float grp_sum(float v) { v += __shfl_xor(v, 16); v += __shfl_xor(v, 32); return v; }
;   __device__ __forceinline__ void operator()(const pg8::f32x4 (&acc)[2][2][4][2], const pg8::Unit& u, int wr, int wc, int fr, int fq0) const {
;     ...
;         for (int bj = 0; bj < 2; ++bj)
; #pragma unroll
;           for (int n = 0; n < 2; ++n)
; #pragma unroll
;             for (int c = 0; c < 4; ++c) v[bj][4 * n + c] = acc[ai][bj][m][n][c] * rs[m];
;     ...
;           const bool isq = gi < 15; const float* gn = isq ? gq_norm : gk_norm;
;           float ss = 0.f;
; #pragma unroll
;           for (int bj = 0; bj < 2; ++bj)
; #pragma unroll
;             for (int e = 0; e < 8; ++e) ss += v[bj][e] * v[bj][e];
;           const float rn = rsqrtf(grp_sum(ss) * (1.f / 64.f) + EPS) * (isq ? 0.125f * LOG2E : 1.f);
;           float kk = 0.f;
; #pragma unroll
;           for (int bj = 0; bj < 2; ++bj) {
;             const unsigned ao = (unsigned)(bj == 0 ? (pos >> 6) : (pos & 63)) * 16 + 8 * (fq & 1);
;             const f32x4 c0 = *(const f32x4*)(cos32 + ao), c1 = *(const f32x4*)(cos32 + ao + 4), s0 = *(const f32x4*)(sin32 + ao), s1 = *(const f32x4*)(sin32 + ao + 4);
; #pragma unroll
;             for (int e = 0; e < 8; ++e) {
;               const float own = v[bj][e] * rn * gn[32 * bj + 8 * fq + e];
;               const float oth = lane32_partner(own, lane);
;               const float cc = e < 4 ? c0[e & 3] : c1[e & 3], sn = e < 4 ? s0[e & 3] : s1[e & 3];
;               v[bj][e] = (fq < 2) ? own * cc - oth * sn : oth * sn + own * cc;
;               kk += v[bj][e] * v[bj][e];
;             }
;           }
.LBB0_1159:
	s_nop 1
	v_pk_mul_f32 v[128:129], v[112:113], v[162:163] op_sel:[0,1]
	v_pk_mul_f32 v[130:131], v[114:115], v[162:163] op_sel:[0,1]
	v_pk_mul_f32 v[132:133], v[96:97], v[162:163] op_sel:[0,1]
	v_pk_mul_f32 v[134:135], v[98:99], v[162:163] op_sel:[0,1]
	v_pk_mul_f32 v[166:167], v[80:81], v[162:163] op_sel:[0,1]
	v_pk_mul_f32 v[168:169], v[82:83], v[162:163] op_sel:[0,1]
	v_pk_mul_f32 v[170:171], v[64:65], v[162:163] op_sel:[0,1]
	v_pk_mul_f32 v[172:173], v[66:67], v[162:163] op_sel:[0,1]
	s_and_b64 vcc, exec, s[16:17]
	s_mov_b64 s[16:17], -1
	s_cbranch_vccnz .LBB0_1167
	s_andn2_b64 vcc, exec, s[90:91]
	s_cbranch_vccnz .LBB0_1164
	v_pk_mul_f32 v[176:177], v[128:129], v[128:129]
	v_pk_mul_f32 v[178:179], v[130:131], v[130:131]
	v_add_f32_e32 v144, v176, v177
	v_add_f32_e32 v144, v178, v144
	v_pk_mul_f32 v[180:181], v[132:133], v[132:133]
	v_add_f32_e32 v144, v179, v144
	v_add_f32_e32 v144, v180, v144
	v_pk_mul_f32 v[218:219], v[134:135], v[134:135]
	v_add_f32_e32 v144, v181, v144
	v_add_f32_e32 v144, v218, v144
	v_pk_mul_f32 v[220:221], v[166:167], v[166:167]
	v_add_f32_e32 v144, v219, v144
	v_add_f32_e32 v144, v220, v144
	v_pk_mul_f32 v[222:223], v[168:169], v[168:169]
	v_add_f32_e32 v144, v221, v144
	v_add_f32_e32 v144, v222, v144
	v_pk_mul_f32 v[224:225], v[170:171], v[170:171]
	v_add_f32_e32 v144, v223, v144
	v_add_f32_e32 v144, v224, v144
	v_pk_mul_f32 v[228:229], v[172:173], v[172:173]
	v_add_f32_e32 v144, v225, v144
	v_add_f32_e32 v144, v228, v144
	v_add_f32_e32 v144, v229, v144
	v_mov_b32_e32 v165, v144
	s_nop 1
	v_permlane16_swap_b32_e32 v144, v165
	s_and_b64 s[16:17], s[14:15], exec
	v_readlane_b32 s16, v252, 21
	v_readlane_b32 s17, v252, 22
	s_load_dwordx4 s[56:59], s[16:17], 0xe0
	s_waitcnt lgkmcnt(0)
	v_add_f32_e32 v144, v144, v165
	v_mov_b32_e32 v165, v144
	s_nop 1
	v_permlane32_swap_b32_e32 v144, v165
	v_readlane_b32 s63, v252, 16
	v_readlane_b32 s92, v252, 6
	s_cselect_b32 s16, s57, s59
	s_cselect_b32 s17, s56, s58
	s_waitcnt lgkmcnt(0)
	v_add_f32_e32 v144, v144, v165
	v_fmamk_f32 v144, v144, 0x3c800000, v206
	v_cmp_gt_f32_e32 vcc, s21, v144
	v_mul_f32_e32 v165, 0x4b800000, v144
	v_mov_b32_e32 v175, s16
	v_cndmask_b32_e32 v144, v144, v165, vcc
	v_rsq_f32_e32 v144, v144
	s_movk_i32 s16, 0x7f0
	v_mov_b32_e32 v174, s17
	v_lshl_add_u64 v[176:177], v[154:155], 2, v[174:175]
	v_mul_f32_e32 v165, 0x45800000, v144
	v_cndmask_b32_e32 v144, v144, v165, vcc
	v_lshrrev_b32_e32 v165, 2, v217
	v_and_or_b32 v165, v165, s16, v213
	v_lshlrev_b32_e32 v165, 2, v165
	global_load_dwordx4 v[178:181], v165, s[54:55] offset:16
	global_load_dwordx4 v[218:221], v165, s[54:55]
	global_load_dwordx4 v[222:225], v165, s[50:51] offset:16
	global_load_dwordx4 v[228:231], v165, s[50:51]
	global_load_dwordx4 v[232:235], v[176:177], off offset:16
	global_load_dwordx4 v[236:239], v[176:177], off
	v_mul_f32_e32 v144, v214, v144
	v_mul_f32_e32 v165, v128, v144
	s_movk_i32 s16, 0x3f0
	v_and_or_b32 v164, v164, s16, v213
	v_lshlrev_b32_e32 v164, 2, v164
	v_ashrrev_i32_e32 v157, 13, v217
	v_and_b32_e32 v182, 0x1fff, v217
	s_cselect_b32 s16, s62, s24
	s_cselect_b32 s17, 22, 20
	s_cselect_b32 s63, s63, s92
	v_readlane_b32 s92, v252, 14
	v_readlane_b32 s93, v252, 4
	s_cselect_b32 s92, s92, s93
	v_lshlrev_b32_e32 v157, s17, v157
	s_andn2_b64 vcc, exec, s[86:87]
	s_waitcnt vmcnt(0)
	v_mul_f32_e32 v165, v236, v165
	v_mov_b32_e32 v174, v165
	v_mov_b32_e32 v175, v165
	s_nop 1
	v_permlane32_swap_b32_e32 v174, v175
	v_cndmask_b32_e64 v174, v174, v175, s[12:13]
	v_mul_f32_e32 v174, v228, v174
	v_cndmask_b32_e64 v183, v174, -v174, s[10:11]
	v_fmac_f32_e32 v183, v218, v165
	v_mul_f32_e32 v165, v129, v144
	v_mul_f32_e32 v165, v237, v165
	v_mov_b32_e32 v174, v165
	v_mov_b32_e32 v175, v165
	s_nop 1
	v_permlane32_swap_b32_e32 v174, v175
	v_cndmask_b32_e64 v174, v174, v175, s[12:13]
	v_mul_f32_e32 v174, v229, v174
	v_cndmask_b32_e64 v185, v174, -v174, s[10:11]
	v_fmac_f32_e32 v185, v219, v165
	v_mul_f32_e32 v165, v130, v144
	v_mul_f32_e32 v165, v238, v165
	v_mov_b32_e32 v174, v165
	v_mov_b32_e32 v175, v165
	s_nop 1
	v_permlane32_swap_b32_e32 v174, v175
	v_cndmask_b32_e64 v174, v174, v175, s[12:13]
	v_mul_f32_e32 v174, v230, v174
	v_cndmask_b32_e64 v218, v174, -v174, s[10:11]
	v_fmac_f32_e32 v218, v220, v165
	v_mul_f32_e32 v165, v131, v144
	v_mul_f32_e32 v165, v165, v239
	v_mov_b32_e32 v174, v165
	v_mov_b32_e32 v175, v165
	s_nop 1
	v_permlane32_swap_b32_e32 v174, v175
	v_cndmask_b32_e64 v174, v174, v175, s[12:13]
	v_mul_f32_e32 v174, v231, v174
	v_cndmask_b32_e64 v219, v174, -v174, s[10:11]
	v_fmac_f32_e32 v219, v221, v165
	v_mul_f32_e32 v165, v132, v144
	v_mul_f32_e32 v165, v165, v232
	v_mov_b32_e32 v174, v165
	v_mov_b32_e32 v175, v165
	s_nop 1
	v_permlane32_swap_b32_e32 v174, v175
	v_cndmask_b32_e64 v174, v174, v175, s[12:13]
	v_mul_f32_e32 v174, v222, v174
	v_cndmask_b32_e64 v220, v174, -v174, s[10:11]
	v_fmac_f32_e32 v220, v178, v165
	v_mul_f32_e32 v165, v133, v144
	v_mul_f32_e32 v165, v165, v233
	v_mov_b32_e32 v174, v165
	v_mov_b32_e32 v175, v165
	s_nop 1
	v_permlane32_swap_b32_e32 v174, v175
	v_cndmask_b32_e64 v174, v174, v175, s[12:13]
	v_mul_f32_e32 v174, v223, v174
	v_cndmask_b32_e64 v221, v174, -v174, s[10:11]
	v_pk_mul_f32 v[174:175], v[134:135], v[144:145] op_sel_hi:[1,0]
	v_fmac_f32_e32 v221, v179, v165
	v_pk_mul_f32 v[174:175], v[174:175], v[234:235]
	s_nop 0
	v_mov_b32_e32 v165, v174
	v_mov_b32_e32 v178, v174
	v_mov_b32_e32 v179, v175
	v_mov_b32_e32 v222, v175
	v_permlane32_swap_b32_e32 v165, v178
	s_nop 0
	v_permlane32_swap_b32_e32 v179, v222
	v_cndmask_b32_e64 v179, v179, v222, s[12:13]
	v_cndmask_b32_e64 v178, v165, v178, s[12:13]
	v_pk_mul_f32 v[178:179], v[224:225], v[178:179]
	s_nop 0
	v_cndmask_b32_e64 v179, v179, -v179, s[10:11]
	v_cndmask_b32_e64 v178, v178, -v178, s[10:11]
	v_pk_fma_f32 v[174:175], v[180:181], v[174:175], v[178:179]
	global_load_dwordx4 v[178:181], v164, s[54:55] offset:16
	global_load_dwordx4 v[222:225], v164, s[54:55]
	global_load_dwordx4 v[228:231], v164, s[50:51] offset:16
	global_load_dwordx4 v[232:235], v164, s[50:51]
	global_load_dwordx4 v[236:239], v[176:177], off offset:144
	global_load_dwordx4 v[240:243], v[176:177], off offset:128
	v_pk_mul_f32 v[164:165], v[166:167], v[144:145] op_sel_hi:[1,0]
	s_waitcnt vmcnt(0)
; __device__ __forceinline__ float grp_sum(float v) { v += __shfl_xor(v, 16); v += __shfl_xor(v, 32); return v; }
; __device__ __forceinline__ void st8_bf16(bf16_t* dst, const float (&v)[8]) { u32x4 w; w.x = pk2(v[0], v[1]); w.y = pk2(v[2], v[3]); w.z = pk2(v[4], v[5]); w.w = pk2(v[6], v[7]); *(u32x4*)dst = w; }
;   __device__ __forceinline__ void operator()(const pg8::f32x4 (&acc)[2][2][4][2], const pg8::Unit& u, int wr, int wc, int fr, int fq0) const {
;     ...
;             for (int e = 0; e < 8; ++e) {
;               const float own = v[bj][e] * rn * gn[32 * bj + 8 * fq + e];
;               const float oth = lane32_partner(own, lane);
;               const float cc = e < 4 ? c0[e & 3] : c1[e & 3], sn = e < 4 ? s0[e & 3] : s1[e & 3];
;               v[bj][e] = (fq < 2) ? own * cc - oth * sn : oth * sn + own * cc;
;               kk += v[bj][e] * v[bj][e];
;             }
;           }
;           bf16_t* dst = isq ? qd + ((unsigned)(bb * 8 + (gi - 7)) * S + pos) * 64 + 8 * fq : kd + ((unsigned)(bb * 2 + (gi - 15)) * S + pos) * 64 + 8 * fq;
;           st8_bf16(dst, v[0]); st8_bf16(dst + 32, v[1]);
;           if (!isq) kmx_run = fmaxf(kmx_run, grp_sum(kk));
	v_pk_mul_f32 v[164:165], v[164:165], v[240:241]
	s_nop 0
	v_mov_b32_e32 v176, v164
	v_mov_b32_e32 v227, v164
	v_mov_b32_e32 v177, v165
	v_mov_b32_e32 v240, v165
	v_permlane32_swap_b32_e32 v176, v227
	s_nop 0
	v_permlane32_swap_b32_e32 v177, v240
	v_cndmask_b32_e64 v177, v177, v240, s[12:13]
	v_cndmask_b32_e64 v176, v176, v227, s[12:13]
	v_pk_mul_f32 v[176:177], v[232:233], v[176:177]
	s_nop 0
	v_cndmask_b32_e64 v177, v177, -v177, s[10:11]
	v_cndmask_b32_e64 v176, v176, -v176, s[10:11]
	v_pk_fma_f32 v[164:165], v[222:223], v[164:165], v[176:177]
	v_pk_mul_f32 v[176:177], v[168:169], v[144:145] op_sel_hi:[1,0]
	s_nop 0
	v_pk_mul_f32 v[176:177], v[176:177], v[242:243]
	s_nop 0
	v_mov_b32_e32 v222, v176
	v_mov_b32_e32 v227, v176
	v_mov_b32_e32 v223, v177
	v_mov_b32_e32 v232, v177
	v_permlane32_swap_b32_e32 v222, v227
	s_nop 0
	v_permlane32_swap_b32_e32 v223, v232
	v_cndmask_b32_e64 v223, v223, v232, s[12:13]
	v_cndmask_b32_e64 v222, v222, v227, s[12:13]
	v_pk_mul_f32 v[222:223], v[234:235], v[222:223]
	s_nop 0
	v_cndmask_b32_e64 v223, v223, -v223, s[10:11]
	v_cndmask_b32_e64 v222, v222, -v222, s[10:11]
	v_pk_fma_f32 v[176:177], v[224:225], v[176:177], v[222:223]
	v_pk_mul_f32 v[222:223], v[170:171], v[144:145] op_sel_hi:[1,0]
	s_nop 0
	v_pk_mul_f32 v[222:223], v[222:223], v[236:237]
	s_nop 0
	v_mov_b32_e32 v224, v222
	v_mov_b32_e32 v227, v222
	v_mov_b32_e32 v225, v223
	v_mov_b32_e32 v232, v223
	v_permlane32_swap_b32_e32 v224, v227
	s_nop 0
	v_permlane32_swap_b32_e32 v225, v232
	v_cndmask_b32_e64 v225, v225, v232, s[12:13]
	v_cndmask_b32_e64 v224, v224, v227, s[12:13]
	v_pk_mul_f32 v[224:225], v[228:229], v[224:225]
	s_nop 0
	v_cndmask_b32_e64 v225, v225, -v225, s[10:11]
	v_cndmask_b32_e64 v224, v224, -v224, s[10:11]
	v_pk_fma_f32 v[178:179], v[178:179], v[222:223], v[224:225]
	v_pk_mul_f32 v[222:223], v[172:173], v[144:145] op_sel_hi:[1,0]
	s_nop 0
	v_pk_mul_f32 v[222:223], v[222:223], v[238:239]
	s_nop 0
	v_mov_b32_e32 v144, v222
	v_mov_b32_e32 v224, v222
	v_mov_b32_e32 v225, v223
	v_mov_b32_e32 v227, v223
	v_permlane32_swap_b32_e32 v144, v224
	s_nop 0
	v_permlane32_swap_b32_e32 v225, v227
	v_cndmask_b32_e64 v225, v225, v227, s[12:13]
	v_cndmask_b32_e64 v224, v144, v224, s[12:13]
	v_pk_mul_f32 v[224:225], v[230:231], v[224:225]
	v_or_b32_e32 v144, s16, v182
	v_cndmask_b32_e64 v225, v225, -v225, s[10:11]
	v_cndmask_b32_e64 v224, v224, -v224, s[10:11]
	v_pk_fma_f32 v[180:181], v[180:181], v[222:223], v[224:225]
	v_mov_b32_e32 v222, s92
	v_mov_b32_e32 v223, s63
	v_lshl_add_u32 v144, v144, 6, v157
	v_lshl_add_u64 v[222:223], v[144:145], 1, v[222:223]
	v_lshl_add_u64 v[228:229], v[154:155], 1, v[222:223]
	v_cvt_pk_bf16_f32 v222, v183, v185
	v_cvt_pk_bf16_f32 v223, v218, v219
	v_cvt_pk_bf16_f32 v224, v220, v221
	v_cvt_pk_bf16_f32 v225, v174, v175
	global_store_dwordx4 v[228:229], v[222:225], off
	v_mov_b32_e32 v157, v184
	s_nop 0
	v_cvt_pk_bf16_f32 v222, v164, v165
	v_cvt_pk_bf16_f32 v223, v176, v177
	v_cvt_pk_bf16_f32 v224, v178, v179
	v_cvt_pk_bf16_f32 v225, v180, v181
	global_store_dwordx4 v[228:229], v[222:225], off offset:64
	s_cbranch_vccnz .LBB0_1163
	v_mul_f32_e32 v144, v185, v185
	v_fmac_f32_e32 v144, v183, v183
	v_fmac_f32_e32 v144, v218, v218
	v_fmac_f32_e32 v144, v219, v219
	v_fmac_f32_e32 v144, v220, v220
	v_fmac_f32_e32 v144, v221, v221
	v_pk_mul_f32 v[174:175], v[174:175], v[174:175]
	v_pk_mul_f32 v[164:165], v[164:165], v[164:165]
	v_add_f32_e32 v144, v144, v174
	v_add_f32_e32 v144, v144, v175
	v_add_f32_e32 v144, v144, v164
	v_add_f32_e32 v144, v144, v165
	v_pk_mul_f32 v[164:165], v[176:177], v[176:177]
	s_nop 0
	v_add_f32_e32 v144, v144, v164
	v_add_f32_e32 v144, v144, v165
	v_pk_mul_f32 v[164:165], v[178:179], v[178:179]
	s_nop 0
	v_add_f32_e32 v144, v144, v164
	v_add_f32_e32 v144, v144, v165
	v_pk_mul_f32 v[164:165], v[180:181], v[180:181]
	s_nop 0
	v_add_f32_e32 v144, v144, v164
	v_add_f32_e32 v144, v144, v165
	v_mov_b32_e32 v157, v144
	s_nop 1
	v_permlane16_swap_b32_e32 v144, v157
	s_waitcnt lgkmcnt(0)
	v_add_f32_e32 v144, v144, v157
	v_mov_b32_e32 v157, v144
	s_nop 1
	v_permlane32_swap_b32_e32 v144, v157
	s_waitcnt lgkmcnt(0)
	v_add_f32_e32 v144, v144, v157
	v_max_f32_e32 v157, v184, v184
	v_max_f32_e32 v157, v157, v144

; __device__ __forceinline__ float grp_sum(float v) { v += __shfl_xor(v, 16); v += __shfl_xor(v, 32); return v; }
;   __device__ __forceinline__ void operator()(const pg8::f32x4 (&acc)[2][2][4][2], const pg8::Unit& u, int wr, int wc, int fr, int fq0) const {
;     ...
;         if (gi < 6) {
;           float ss = 0.f;
; #pragma unroll
;           for (int bj = 0; bj < 2; ++bj)
; #pragma unroll
;             for (int e = 0; e < 8; ++e) ss += v[bj][e] * v[bj][e];
;           ss = grp_sum(ss);
;           if (fq == 0) ssq2[(unsigned)tok * 8 + gi] = ss;
.LBB0_1167:
	s_andn2_b64 vcc, exec, s[16:17]
	s_cbranch_vccnz .LBB0_1171
	v_pk_mul_f32 v[164:165], v[128:129], v[128:129]
	v_pk_mul_f32 v[174:175], v[130:131], v[130:131]
	v_add_f32_e32 v144, v164, v165
	v_add_f32_e32 v144, v174, v144
	v_pk_mul_f32 v[176:177], v[132:133], v[132:133]
	v_add_f32_e32 v144, v175, v144
	v_add_f32_e32 v144, v176, v144
	v_pk_mul_f32 v[178:179], v[134:135], v[134:135]
	v_add_f32_e32 v144, v177, v144
	v_add_f32_e32 v144, v178, v144
	v_pk_mul_f32 v[180:181], v[166:167], v[166:167]
	v_add_f32_e32 v144, v179, v144
	v_add_f32_e32 v144, v180, v144
	v_pk_mul_f32 v[182:183], v[168:169], v[168:169]
	v_add_f32_e32 v144, v181, v144
	v_add_f32_e32 v144, v182, v144
	v_pk_mul_f32 v[218:219], v[170:171], v[170:171]
	v_add_f32_e32 v144, v183, v144
	v_add_f32_e32 v144, v218, v144
	v_pk_mul_f32 v[220:221], v[172:173], v[172:173]
	v_add_f32_e32 v144, v219, v144
	v_add_f32_e32 v144, v220, v144
	v_add_f32_e32 v144, v221, v144
	s_waitcnt lgkmcnt(0)
	v_mov_b32_e32 v157, v144
	s_nop 1
	v_permlane16_swap_b32_e32 v144, v157
	s_waitcnt lgkmcnt(0)
	v_add_f32_e32 v144, v144, v157
	ds_bpermute_b32 v157, v212, v144
	s_and_saveexec_b64 s[16:17], s[8:9]
	s_cbranch_execz .LBB0_1170
	s_waitcnt lgkmcnt(0)
	v_add_f32_e32 v157, v144, v157
	v_lshl_add_u32 v144, v217, 3, s68
	v_lshl_add_u64 v[164:165], v[144:145], 2, s[52:53]
	global_store_dword v[164:165], v157, off

;   __device__ __forceinline__ void operator()(const pg8::f32x4 (&acc)[2][2][4][2], const pg8::Unit& u, int wr, int wc, int fr, int fq0) const {
;     ...
;       for (int m = 0; m < 4; ++m) { const f32x4 a = *(const f32x4*)(ssq + (unsigned)(row0 + ai * 128 + m) * 16 + 4 * fq); rs[m] = (a[0] + a[1]) + (a[2] + a[3]); }
; #pragma unroll
;       for (int m = 0; m < 4; ++m) rs[m] = rsqrtf(grp_sum(rs[m]) * (1.f / 1024.f) + EPS);
;       if (gi >= 17) {
;         const int tok0 = row0 + ai * 128, bb0 = tok0 >> 13, pos0 = tok0 & (S - 1);
;         bf16_t* dst = vtd + ((unsigned)(bb0 * 2 + (gi - 17)) * 64 + 8 * fq) * S + pos0;
; #pragma unroll
;         for (int bj = 0; bj < 2; ++bj)
; #pragma unroll
;           for (int n = 0; n < 2; ++n)
; #pragma unroll
;             for (int c = 0; c < 4; ++c) {
;               u32x2 w; w.x = pk2(acc[ai][bj][0][n][c] * rs[0], acc[ai][bj][1][n][c] * rs[1]); w.y = pk2(acc[ai][bj][2][n][c] * rs[2], acc[ai][bj][3][n][c] * rs[3]);
;               *(u32x2*)(dst + (unsigned)(32 * bj + 4 * n + c) * S) = w;
;             }
;         asm volatile("" ::: "memory");
;         continue;
;       }
; #pragma unroll
;       for (int m = 0; m < 4; ++m) {
;         const int tok = row0 + ai * 128 + m, bb = tok >> 13, pos = tok & (S - 1);
;         float v[2][8];
; #pragma unroll
;         for (int bj = 0; bj < 2; ++bj)
; #pragma unroll
;           for (int n = 0; n < 2; ++n)
; #pragma unroll
;             for (int c = 0; c < 4; ++c) v[bj][4 * n + c] = acc[ai][bj][m][n][c] * rs[m];
;         if (gi < 6) {
;           float ss = 0.f;
; #pragma unroll
;           for (int bj = 0; bj < 2; ++bj)
; #pragma unroll
;             for (int e = 0; e < 8; ++e) ss += v[bj][e] * v[bj][e];
;           ss = grp_sum(ss);
;           if (fq == 0) ssq2[(unsigned)tok * 8 + gi] = ss;
;           bf16_t* dst = (gi < 4) ? cq + (unsigned)tok * 256 + gi * 64 + 8 * fq : ckv + (unsigned)tok * 128 + (gi - 4) * 64 + 8 * fq;
;           st8_bf16(dst, v[0]); st8_bf16(dst + 32, v[1]);
;         } else if (gi == 6) {
;           float* dst = kpe + (unsigned)tok * 32 + 8 * fq;
;           *(f32x4*)dst = (f32x4){v[0][0], v[0][1], v[0][2], v[0][3]}; *(f32x4*)(dst + 4) = (f32x4){v[0][4], v[0][5], v[0][6], v[0][7]};
;         } else if (gi < 17) {
;           const bool isq = gi < 15; const float* gn = isq ? gq_norm : gk_norm;
;           float ss = 0.f;
; #pragma unroll
.LBB0_1174:
	v_add_u32_e32 v98, 0x80, v215
	v_lshlrev_b32_e32 v144, 4, v98
	v_add_u32_e32 v101, 0x81, v215
	v_lshl_add_u64 v[64:65], v[144:145], 2, v[158:159]
	v_lshlrev_b32_e32 v144, 4, v101
	v_lshl_add_u64 v[68:69], v[144:145], 2, v[158:159]
	global_load_dwordx4 v[64:67], v[64:65], off
	v_add_u32_e32 v100, 0x82, v215
	global_load_dwordx4 v[68:71], v[68:69], off
	v_lshlrev_b32_e32 v78, 4, v100
	v_mov_b32_e32 v79, v145
	v_add_u32_e32 v99, 0x83, v215
	v_lshl_add_u64 v[72:73], v[78:79], 2, v[158:159]
	v_lshlrev_b32_e32 v76, 4, v99
	v_mov_b32_e32 v77, v145
	global_load_dwordx4 v[80:83], v[72:73], off
	v_lshl_add_u64 v[72:73], v[76:77], 2, v[158:159]
	global_load_dwordx4 v[84:87], v[72:73], off
	s_waitcnt vmcnt(3)
	v_mov_b32_e32 v72, v64
	s_waitcnt vmcnt(2)
	v_mov_b32_e32 v73, v68
	v_mov_b32_e32 v68, v65
	v_pk_add_f32 v[64:65], v[72:73], v[68:69]
	v_mov_b32_e32 v68, v66
	v_mov_b32_e32 v69, v70
	v_mov_b32_e32 v70, v67
	v_pk_add_f32 v[66:67], v[68:69], v[70:71]
	s_nop 0
	v_pk_add_f32 v[64:65], v[64:65], v[66:67]
	v_mov_b32_e32 v66, v64
	s_nop 1
	v_permlane16_swap_b32_e32 v64, v66
	v_mov_b32_e32 v67, v65
	s_nop 1
	v_permlane16_swap_b32_e32 v65, v67
	s_waitcnt lgkmcnt(0)
	v_pk_add_f32 v[64:65], v[64:65], v[66:67]
	v_mov_b32_e32 v66, v64
	s_nop 1
	v_permlane32_swap_b32_e32 v64, v66
	v_mov_b32_e32 v67, v65
	s_nop 1
	v_permlane32_swap_b32_e32 v65, v67
	s_waitcnt lgkmcnt(0)
	v_pk_add_f32 v[64:65], v[64:65], v[66:67]
	v_mov_b64_e32 v[66:67], s[56:57]
	v_pk_fma_f32 v[64:65], v[64:65], s[70:71], v[66:67] op_sel_hi:[1,0,0]
	s_nop 0
	v_mul_f32_e32 v68, 0x4b800000, v64
	v_cmp_gt_f32_e64 s[16:17], s21, v64
	v_cmp_gt_f32_e32 vcc, s21, v65
	s_nop 0
	v_cndmask_b32_e64 v64, v64, v68, s[16:17]
	v_mul_f32_e32 v68, 0x4b800000, v65
	v_cndmask_b32_e32 v65, v65, v68, vcc
	v_rsq_f32_e32 v64, v64
	v_rsq_f32_e32 v65, v65
	s_nop 0
	v_pk_mul_f32 v[68:69], v[64:65], s[74:75] op_sel_hi:[1,0]
	s_nop 0
	v_cndmask_b32_e32 v73, v65, v69, vcc
	v_cndmask_b32_e64 v72, v64, v68, s[16:17]
	s_waitcnt vmcnt(1)
	v_mov_b32_e32 v64, v80
	s_waitcnt vmcnt(0)
	v_mov_b32_e32 v65, v84
	v_mov_b32_e32 v84, v81
	v_mov_b32_e32 v68, v82
	v_mov_b32_e32 v69, v86
	v_mov_b32_e32 v86, v83
	v_pk_add_f32 v[64:65], v[64:65], v[84:85]
	v_pk_add_f32 v[68:69], v[68:69], v[86:87]
	s_nop 0
	v_pk_add_f32 v[64:65], v[64:65], v[68:69]
	v_mov_b32_e32 v68, v64
	s_nop 1
	v_permlane16_swap_b32_e32 v64, v68
	v_mov_b32_e32 v69, v65
	s_nop 1
	v_permlane16_swap_b32_e32 v65, v69
	s_waitcnt lgkmcnt(0)
	v_pk_add_f32 v[64:65], v[64:65], v[68:69]
	v_mov_b32_e32 v68, v64
	s_nop 1
	v_permlane32_swap_b32_e32 v64, v68
	v_mov_b32_e32 v69, v65
	s_nop 1
	v_permlane32_swap_b32_e32 v65, v69
	s_waitcnt lgkmcnt(0)
	v_pk_add_f32 v[64:65], v[64:65], v[68:69]
	s_nop 0
	v_pk_fma_f32 v[64:65], v[64:65], s[70:71], v[66:67] op_sel_hi:[1,0,0]
	s_nop 0
	v_mul_f32_e32 v66, 0x4b800000, v64
	v_cmp_gt_f32_e64 s[16:17], s21, v64
	v_cmp_gt_f32_e32 vcc, s21, v65
	s_nop 0
	v_cndmask_b32_e64 v64, v64, v66, s[16:17]
	v_mul_f32_e32 v66, 0x4b800000, v65
	v_cndmask_b32_e32 v65, v65, v66, vcc
	v_rsq_f32_e32 v64, v64
	v_rsq_f32_e32 v65, v65
	s_nop 0
	v_pk_mul_f32 v[66:67], v[64:65], s[74:75] op_sel_hi:[1,0]
	s_nop 0
	v_cndmask_b32_e32 v75, v65, v67, vcc
	v_cndmask_b32_e64 v74, v64, v66, s[16:17]
	s_mov_b64 s[16:17], -1
	s_andn2_b64 vcc, exec, s[18:19]
	s_cbranch_vccnz .LBB0_1231
	v_cndmask_b32_e64 v77, 0, 1, s[88:89]
	v_cmp_ne_u32_e64 s[18:19], 1, v77
	v_cndmask_b32_e64 v77, 0, 1, s[90:91]
	v_pk_mul_f32 v[64:65], v[60:61], v[72:73] op_sel_hi:[1,0]
	v_pk_mul_f32 v[66:67], v[62:63], v[72:73] op_sel_hi:[1,0]
	v_pk_mul_f32 v[68:69], v[44:45], v[72:73] op_sel_hi:[1,0]
	v_pk_mul_f32 v[70:71], v[46:47], v[72:73] op_sel_hi:[1,0]
	v_pk_mul_f32 v[80:81], v[28:29], v[72:73] op_sel_hi:[1,0]
	v_pk_mul_f32 v[82:83], v[30:31], v[72:73] op_sel_hi:[1,0]
	v_pk_mul_f32 v[84:85], v[12:13], v[72:73] op_sel_hi:[1,0]
	v_pk_mul_f32 v[86:87], v[14:15], v[72:73] op_sel_hi:[1,0]
	s_mov_b64 s[92:93], -1
	s_andn2_b64 vcc, exec, s[88:89]
	v_cmp_ne_u32_e64 s[16:17], 1, v77
	s_cbranch_vccnz .LBB0_1183
	s_and_b64 vcc, exec, s[16:17]
	s_mov_b64 s[88:89], -1
	s_cbranch_vccnz .LBB0_1180
	v_pk_mul_f32 v[88:89], v[64:65], v[64:65]
	v_pk_mul_f32 v[92:93], v[66:67], v[66:67]
	v_add_f32_e32 v88, v88, v89
	v_add_f32_e32 v88, v92, v88
	v_pk_mul_f32 v[94:95], v[68:69], v[68:69]
	v_add_f32_e32 v88, v93, v88
	v_add_f32_e32 v88, v94, v88
	v_pk_mul_f32 v[96:97], v[70:71], v[70:71]
	v_add_f32_e32 v88, v95, v88
	v_add_f32_e32 v88, v96, v88
	v_pk_mul_f32 v[102:103], v[80:81], v[80:81]
	v_add_f32_e32 v88, v97, v88
	v_add_f32_e32 v88, v102, v88
	v_pk_mul_f32 v[104:105], v[82:83], v[82:83]
	v_add_f32_e32 v88, v103, v88
	v_add_f32_e32 v88, v104, v88
	v_pk_mul_f32 v[106:107], v[84:85], v[84:85]
	v_add_f32_e32 v88, v105, v88
	v_add_f32_e32 v88, v106, v88
	v_pk_mul_f32 v[108:109], v[86:87], v[86:87]
	v_add_f32_e32 v88, v107, v88
	v_add_f32_e32 v88, v108, v88
	v_add_f32_e32 v88, v109, v88
	v_mov_b32_e32 v89, v88
	s_nop 1
	v_permlane16_swap_b32_e32 v88, v89
	s_and_b64 s[88:89], s[14:15], exec
	v_readlane_b32 s88, v252, 21
	v_readlane_b32 s89, v252, 22
	s_load_dwordx4 s[56:59], s[88:89], 0xe0
	s_waitcnt lgkmcnt(0)
	v_add_f32_e32 v88, v88, v89
	v_mov_b32_e32 v89, v88
	s_nop 1
	v_permlane32_swap_b32_e32 v88, v89
	v_readlane_b32 s90, v252, 16
	v_readlane_b32 s91, v252, 6
	s_cselect_b32 s88, s57, s59
	s_cselect_b32 s89, s56, s58
	s_waitcnt lgkmcnt(0)
; __device__ __forceinline__ float grp_sum(float v) { v += __shfl_xor(v, 16); v += __shfl_xor(v, 32); return v; }
; __device__ __forceinline__ void st8_bf16(bf16_t* dst, const float (&v)[8]) { u32x4 w; w.x = pk2(v[0], v[1]); w.y = pk2(v[2], v[3]); w.z = pk2(v[4], v[5]); w.w = pk2(v[6], v[7]); *(u32x4*)dst = w; }
;   __device__ __forceinline__ void operator()(const pg8::f32x4 (&acc)[2][2][4][2], const pg8::Unit& u, int wr, int wc, int fr, int fq0) const {
;     ...
;           const float rn = rsqrtf(grp_sum(ss) * (1.f / 64.f) + EPS) * (isq ? 0.125f * LOG2E : 1.f);
;           float kk = 0.f;
; #pragma unroll
;           for (int bj = 0; bj < 2; ++bj) {
;             const unsigned ao = (unsigned)(bj == 0 ? (pos >> 6) : (pos & 63)) * 16 + 8 * (fq & 1);
;             const f32x4 c0 = *(const f32x4*)(cos32 + ao), c1 = *(const f32x4*)(cos32 + ao + 4), s0 = *(const f32x4*)(sin32 + ao), s1 = *(const f32x4*)(sin32 + ao + 4);
; #pragma unroll
;             for (int e = 0; e < 8; ++e) {
;               const float own = v[bj][e] * rn * gn[32 * bj + 8 * fq + e];
;               const float oth = lane32_partner(own, lane);
;               const float cc = e < 4 ? c0[e & 3] : c1[e & 3], sn = e < 4 ? s0[e & 3] : s1[e & 3];
;               v[bj][e] = (fq < 2) ? own * cc - oth * sn : oth * sn + own * cc;
;               kk += v[bj][e] * v[bj][e];
;             }
;           }
;           bf16_t* dst = isq ? qd + ((unsigned)(bb * 8 + (gi - 7)) * S + pos) * 64 + 8 * fq : kd + ((unsigned)(bb * 2 + (gi - 15)) * S + pos) * 64 + 8 * fq;
;           st8_bf16(dst, v[0]); st8_bf16(dst + 32, v[1]);
	v_add_f32_e32 v88, v88, v89
	v_fmamk_f32 v88, v88, 0x3c800000, v206
	v_cmp_gt_f32_e32 vcc, s21, v88
	v_mul_f32_e32 v89, 0x4b800000, v88
	s_movk_i32 s56, 0x7f0
	v_cndmask_b32_e32 v88, v88, v89, vcc
	v_rsq_f32_e32 v88, v88
	v_mov_b32_e32 v90, s89
	v_mov_b32_e32 v91, s88
	v_lshl_add_u64 v[92:93], v[154:155], 2, v[90:91]
	v_mul_f32_e32 v89, 0x45800000, v88
	v_cndmask_b32_e32 v88, v88, v89, vcc
	v_lshrrev_b32_e32 v89, 2, v98
	v_and_or_b32 v89, v89, s56, v213
	v_lshlrev_b32_e32 v89, 2, v89
	global_load_dwordx4 v[94:97], v89, s[54:55] offset:16
	global_load_dwordx4 v[104:107], v89, s[54:55]
	global_load_dwordx4 v[108:111], v89, s[50:51] offset:16
	global_load_dwordx4 v[112:115], v89, s[50:51]
	global_load_dwordx4 v[116:119], v[92:93], off offset:16
	global_load_dwordx4 v[120:123], v[92:93], off
	v_mul_f32_e32 v88, v214, v88
	v_mul_f32_e32 v89, v64, v88
	s_movk_i32 s56, 0x3f0
	v_ashrrev_i32_e32 v77, 13, v98
	v_and_b32_e32 v79, 0x1fff, v98
	s_cselect_b32 s88, s62, s24
	s_cselect_b32 s89, 22, 20
	s_cselect_b32 s90, s90, s91
	v_readlane_b32 s91, v252, 14
	v_readlane_b32 s92, v252, 4
	s_cselect_b32 s91, s91, s92
	v_or_b32_e32 v79, s88, v79
	v_lshlrev_b32_e32 v77, s89, v77
	s_andn2_b64 vcc, exec, s[86:87]
	s_waitcnt vmcnt(0)
	v_mul_f32_e32 v89, v120, v89
	v_mov_b32_e32 v90, v89
	v_mov_b32_e32 v91, v89
	s_nop 1
	v_permlane32_swap_b32_e32 v90, v91
	v_cndmask_b32_e64 v90, v90, v91, s[12:13]
	v_mul_f32_e32 v90, v112, v90
	v_cndmask_b32_e64 v102, v90, -v90, s[10:11]
	v_fmac_f32_e32 v102, v104, v89
	v_mul_f32_e32 v89, v65, v88
	v_mul_f32_e32 v89, v121, v89
	v_mov_b32_e32 v90, v89
	v_mov_b32_e32 v91, v89
	s_nop 1
	v_permlane32_swap_b32_e32 v90, v91
	v_cndmask_b32_e64 v90, v90, v91, s[12:13]
	v_mul_f32_e32 v90, v113, v90
	v_cndmask_b32_e64 v103, v90, -v90, s[10:11]
	v_fmac_f32_e32 v103, v105, v89
	v_mul_f32_e32 v89, v66, v88
	v_mul_f32_e32 v89, v122, v89
	v_mov_b32_e32 v90, v89
	v_mov_b32_e32 v91, v89
	s_nop 1
	v_permlane32_swap_b32_e32 v90, v91
	v_cndmask_b32_e64 v90, v90, v91, s[12:13]
	v_mul_f32_e32 v90, v114, v90
	v_cndmask_b32_e64 v104, v90, -v90, s[10:11]
	v_fmac_f32_e32 v104, v106, v89
	v_mul_f32_e32 v89, v67, v88
	v_mul_f32_e32 v89, v89, v123
	v_mov_b32_e32 v90, v89
	v_mov_b32_e32 v91, v89
	s_nop 1
	v_permlane32_swap_b32_e32 v90, v91
	v_cndmask_b32_e64 v90, v90, v91, s[12:13]
	v_mul_f32_e32 v90, v115, v90
	v_cndmask_b32_e64 v105, v90, -v90, s[10:11]
	v_fmac_f32_e32 v105, v107, v89
	v_mul_f32_e32 v89, v68, v88
	v_mul_f32_e32 v89, v89, v116
	v_mov_b32_e32 v90, v89
	v_mov_b32_e32 v91, v89
	s_nop 1
	v_permlane32_swap_b32_e32 v90, v91
	v_cndmask_b32_e64 v90, v90, v91, s[12:13]
	v_mul_f32_e32 v90, v108, v90
	v_cndmask_b32_e64 v106, v90, -v90, s[10:11]
	v_fmac_f32_e32 v106, v94, v89
	v_mul_f32_e32 v89, v69, v88
	v_mul_f32_e32 v89, v89, v117
	v_mov_b32_e32 v90, v89
	v_mov_b32_e32 v91, v89
	s_nop 1
	v_permlane32_swap_b32_e32 v90, v91
	v_cndmask_b32_e64 v90, v90, v91, s[12:13]
	v_mul_f32_e32 v90, v109, v90
	v_cndmask_b32_e64 v107, v90, -v90, s[10:11]
	v_pk_mul_f32 v[90:91], v[70:71], v[88:89] op_sel_hi:[1,0]
	v_fmac_f32_e32 v107, v95, v89
	v_pk_mul_f32 v[90:91], v[90:91], v[118:119]
	s_nop 0
	v_mov_b32_e32 v89, v90
	v_mov_b32_e32 v94, v90
	v_mov_b32_e32 v95, v91
	v_mov_b32_e32 v108, v91
	v_permlane32_swap_b32_e32 v89, v94
	s_nop 0
	v_permlane32_swap_b32_e32 v95, v108
	v_cndmask_b32_e64 v95, v95, v108, s[12:13]
	v_cndmask_b32_e64 v94, v89, v94, s[12:13]
	v_pk_mul_f32 v[94:95], v[110:111], v[94:95]
	v_and_or_b32 v89, v156, s56, v213
	v_cndmask_b32_e64 v95, v95, -v95, s[10:11]
	v_cndmask_b32_e64 v94, v94, -v94, s[10:11]
	v_lshlrev_b32_e32 v89, 2, v89
	v_pk_fma_f32 v[90:91], v[96:97], v[90:91], v[94:95]
	global_load_dwordx4 v[108:111], v89, s[54:55] offset:16
	global_load_dwordx4 v[94:97], v89, s[54:55]
	global_load_dwordx4 v[112:115], v89, s[50:51] offset:16
	global_load_dwordx4 v[116:119], v89, s[50:51]
	global_load_dwordx4 v[120:123], v[92:93], off offset:144
	global_load_dwordx4 v[124:127], v[92:93], off offset:128
	v_pk_mul_f32 v[128:129], v[80:81], v[88:89] op_sel_hi:[1,0]
	s_waitcnt vmcnt(0)
	v_pk_mul_f32 v[92:93], v[128:129], v[124:125]
	s_nop 0
	v_mov_b32_e32 v89, v92
	v_mov_b32_e32 v124, v92
	v_mov_b32_e32 v125, v93
	v_mov_b32_e32 v128, v93
	v_permlane32_swap_b32_e32 v89, v124
	s_nop 0
	v_permlane32_swap_b32_e32 v125, v128
	v_cndmask_b32_e64 v125, v125, v128, s[12:13]
	v_cndmask_b32_e64 v124, v89, v124, s[12:13]
	v_pk_mul_f32 v[116:117], v[116:117], v[124:125]
	s_nop 0
	v_cndmask_b32_e64 v117, v117, -v117, s[10:11]
	v_cndmask_b32_e64 v116, v116, -v116, s[10:11]
	v_pk_fma_f32 v[92:93], v[94:95], v[92:93], v[116:117]
	v_pk_mul_f32 v[94:95], v[82:83], v[88:89] op_sel_hi:[1,0]
	s_nop 0
	v_pk_mul_f32 v[94:95], v[94:95], v[126:127]
	s_nop 0
	v_mov_b32_e32 v89, v94
	v_mov_b32_e32 v116, v94
	v_mov_b32_e32 v117, v95
	v_mov_b32_e32 v124, v95
	v_permlane32_swap_b32_e32 v89, v116
	s_nop 0
	v_permlane32_swap_b32_e32 v117, v124
	v_cndmask_b32_e64 v117, v117, v124, s[12:13]
	v_cndmask_b32_e64 v116, v89, v116, s[12:13]
	v_pk_mul_f32 v[116:117], v[118:119], v[116:117]
	s_nop 0
	v_cndmask_b32_e64 v117, v117, -v117, s[10:11]
	v_cndmask_b32_e64 v116, v116, -v116, s[10:11]
	v_pk_fma_f32 v[94:95], v[96:97], v[94:95], v[116:117]
	v_pk_mul_f32 v[96:97], v[84:85], v[88:89] op_sel_hi:[1,0]
	s_nop 0
	v_pk_mul_f32 v[96:97], v[96:97], v[120:121]
	s_nop 0
	v_mov_b32_e32 v89, v96
	v_mov_b32_e32 v116, v96
	v_mov_b32_e32 v117, v97
	v_mov_b32_e32 v118, v97
	v_permlane32_swap_b32_e32 v89, v116
	s_nop 0
	v_permlane32_swap_b32_e32 v117, v118
	v_cndmask_b32_e64 v117, v117, v118, s[12:13]
	v_cndmask_b32_e64 v116, v89, v116, s[12:13]
	v_pk_mul_f32 v[112:113], v[112:113], v[116:117]
	v_pk_mul_f32 v[88:89], v[86:87], v[88:89] op_sel_hi:[1,0]
	v_cndmask_b32_e64 v113, v113, -v113, s[10:11]
	v_cndmask_b32_e64 v112, v112, -v112, s[10:11]
	v_pk_mul_f32 v[88:89], v[88:89], v[122:123]
	v_pk_fma_f32 v[96:97], v[108:109], v[96:97], v[112:113]
	v_mov_b32_e32 v108, v88
	v_mov_b32_e32 v112, v88
	v_mov_b32_e32 v109, v89
	v_mov_b32_e32 v113, v89
	v_permlane32_swap_b32_e32 v108, v112
	s_nop 0
	v_permlane32_swap_b32_e32 v109, v113
	v_cndmask_b32_e64 v109, v109, v113, s[12:13]
	v_cndmask_b32_e64 v108, v108, v112, s[12:13]
	v_pk_mul_f32 v[108:109], v[114:115], v[108:109]
	s_nop 0
	v_cndmask_b32_e64 v109, v109, -v109, s[10:11]
	v_cndmask_b32_e64 v108, v108, -v108, s[10:11]
	v_pk_fma_f32 v[88:89], v[110:111], v[88:89], v[108:109]
	v_mov_b32_e32 v108, s91
	v_mov_b32_e32 v109, s90
	v_lshl_add_u32 v110, v79, 6, v77
	v_mov_b32_e32 v111, v145
	v_lshl_add_u64 v[108:109], v[110:111], 1, v[108:109]
	v_lshl_add_u64 v[112:113], v[154:155], 1, v[108:109]
	v_cvt_pk_bf16_f32 v108, v102, v103
	v_cvt_pk_bf16_f32 v109, v104, v105
	v_cvt_pk_bf16_f32 v110, v106, v107
	v_cvt_pk_bf16_f32 v111, v90, v91
	global_store_dwordx4 v[112:113], v[108:111], off
	v_mov_b32_e32 v79, v157
	s_nop 0
	v_cvt_pk_bf16_f32 v108, v92, v93
	v_cvt_pk_bf16_f32 v109, v94, v95
	v_cvt_pk_bf16_f32 v110, v96, v97
	v_cvt_pk_bf16_f32 v111, v88, v89
	global_store_dwordx4 v[112:113], v[108:111], off offset:64
	s_cbranch_vccnz .LBB0_1179
; __device__ __forceinline__ float grp_sum(float v) { v += __shfl_xor(v, 16); v += __shfl_xor(v, 32); return v; }
; __device__ __forceinline__ void st8_bf16(bf16_t* dst, const float (&v)[8]) { u32x4 w; w.x = pk2(v[0], v[1]); w.y = pk2(v[2], v[3]); w.z = pk2(v[4], v[5]); w.w = pk2(v[6], v[7]); *(u32x4*)dst = w; }
;   __device__ __forceinline__ void operator()(const pg8::f32x4 (&acc)[2][2][4][2], const pg8::Unit& u, int wr, int wc, int fr, int fq0) const {
;     ...
;           float kk = 0.f;
; #pragma unroll
;           for (int bj = 0; bj < 2; ++bj) {
;             const unsigned ao = (unsigned)(bj == 0 ? (pos >> 6) : (pos & 63)) * 16 + 8 * (fq & 1);
;             const f32x4 c0 = *(const f32x4*)(cos32 + ao), c1 = *(const f32x4*)(cos32 + ao + 4), s0 = *(const f32x4*)(sin32 + ao), s1 = *(const f32x4*)(sin32 + ao + 4);
; #pragma unroll
;             for (int e = 0; e < 8; ++e) {
;               const float own = v[bj][e] * rn * gn[32 * bj + 8 * fq + e];
;               const float oth = lane32_partner(own, lane);
;               const float cc = e < 4 ? c0[e & 3] : c1[e & 3], sn = e < 4 ? s0[e & 3] : s1[e & 3];
;               v[bj][e] = (fq < 2) ? own * cc - oth * sn : oth * sn + own * cc;
;               kk += v[bj][e] * v[bj][e];
;             }
;           }
;           bf16_t* dst = isq ? qd + ((unsigned)(bb * 8 + (gi - 7)) * S + pos) * 64 + 8 * fq : kd + ((unsigned)(bb * 2 + (gi - 15)) * S + pos) * 64 + 8 * fq;
;           st8_bf16(dst, v[0]); st8_bf16(dst + 32, v[1]);
;           if (!isq) kmx_run = fmaxf(kmx_run, grp_sum(kk));
	v_mul_f32_e32 v77, v103, v103
	v_fmac_f32_e32 v77, v102, v102
	v_fmac_f32_e32 v77, v104, v104
	v_fmac_f32_e32 v77, v105, v105
	v_fmac_f32_e32 v77, v106, v106
	v_fmac_f32_e32 v77, v107, v107
	v_pk_mul_f32 v[90:91], v[90:91], v[90:91]
	v_pk_mul_f32 v[88:89], v[88:89], v[88:89]
	v_add_f32_e32 v77, v77, v90
	v_add_f32_e32 v77, v77, v91
	v_pk_mul_f32 v[90:91], v[92:93], v[92:93]
	s_nop 0
	v_add_f32_e32 v77, v77, v90
	v_add_f32_e32 v77, v77, v91
	v_pk_mul_f32 v[90:91], v[94:95], v[94:95]
	s_nop 0
	v_add_f32_e32 v77, v77, v90
	v_add_f32_e32 v77, v77, v91
	v_pk_mul_f32 v[90:91], v[96:97], v[96:97]
	s_nop 0
	v_add_f32_e32 v77, v77, v90
	v_add_f32_e32 v77, v77, v91
	v_add_f32_e32 v77, v77, v88
	v_add_f32_e32 v77, v77, v89
	v_mov_b32_e32 v79, v77
	s_nop 1
	v_permlane16_swap_b32_e32 v77, v79
	s_waitcnt lgkmcnt(0)
	v_add_f32_e32 v77, v77, v79
	v_mov_b32_e32 v79, v77
	s_nop 1
	v_permlane32_swap_b32_e32 v77, v79
	s_waitcnt lgkmcnt(0)
	v_add_f32_e32 v77, v77, v79
	v_max_f32_e32 v79, v157, v157
	v_max_f32_e32 v79, v79, v77

; __device__ __forceinline__ float grp_sum(float v) { v += __shfl_xor(v, 16); v += __shfl_xor(v, 32); return v; }
;   __device__ __forceinline__ void operator()(const pg8::f32x4 (&acc)[2][2][4][2], const pg8::Unit& u, int wr, int wc, int fr, int fq0) const {
;     ...
;         if (gi < 6) {
;           float ss = 0.f;
; #pragma unroll
;           for (int bj = 0; bj < 2; ++bj)
; #pragma unroll
;             for (int e = 0; e < 8; ++e) ss += v[bj][e] * v[bj][e];
;           ss = grp_sum(ss);
;           if (fq == 0) ssq2[(unsigned)tok * 8 + gi] = ss;
.LBB0_1183:
	s_andn2_b64 vcc, exec, s[92:93]
	s_cbranch_vccnz .LBB0_1187
	v_pk_mul_f32 v[88:89], v[64:65], v[64:65]
	v_pk_mul_f32 v[90:91], v[66:67], v[66:67]
	v_add_f32_e32 v77, v88, v89
	v_add_f32_e32 v77, v90, v77
	v_pk_mul_f32 v[92:93], v[68:69], v[68:69]
	v_add_f32_e32 v77, v91, v77
	v_add_f32_e32 v77, v92, v77
	v_pk_mul_f32 v[94:95], v[70:71], v[70:71]
	v_add_f32_e32 v77, v93, v77
	v_add_f32_e32 v77, v94, v77
	v_pk_mul_f32 v[96:97], v[80:81], v[80:81]
	v_add_f32_e32 v77, v95, v77
	v_add_f32_e32 v77, v96, v77
	v_pk_mul_f32 v[102:103], v[82:83], v[82:83]
	v_add_f32_e32 v77, v97, v77
	v_add_f32_e32 v77, v102, v77
	v_pk_mul_f32 v[104:105], v[84:85], v[84:85]
	v_add_f32_e32 v77, v103, v77
	v_add_f32_e32 v77, v104, v77
	v_pk_mul_f32 v[106:107], v[86:87], v[86:87]
	v_add_f32_e32 v77, v105, v77
	v_add_f32_e32 v77, v106, v77
	v_add_f32_e32 v77, v107, v77
	v_mov_b32_e32 v79, v77
	s_nop 1
	v_permlane16_swap_b32_e32 v77, v79
	s_waitcnt lgkmcnt(0)
	v_add_f32_e32 v77, v77, v79
	ds_bpermute_b32 v79, v212, v77
	s_and_saveexec_b64 s[88:89], s[8:9]
	s_cbranch_execz .LBB0_1186
	v_lshl_add_u32 v88, v98, 3, s68
	v_mov_b32_e32 v89, v145
	s_waitcnt lgkmcnt(0)
	v_add_f32_e32 v77, v77, v79
	v_lshl_add_u64 v[88:89], v[88:89], 2, s[52:53]
	global_store_dword v[88:89], v77, off

;   __device__ __forceinline__ void operator()(const pg8::f32x4 (&acc)[2][2][4][2], const pg8::Unit& u, int wr, int wc, int fr, int fq0) const {
;     ...
;             for (int c = 0; c < 4; ++c) v[bj][4 * n + c] = acc[ai][bj][m][n][c] * rs[m];
;         if (gi < 6) {
;           float ss = 0.f;
; #pragma unroll
;           for (int bj = 0; bj < 2; ++bj)
; #pragma unroll
;             for (int e = 0; e < 8; ++e) ss += v[bj][e] * v[bj][e];
;           ss = grp_sum(ss);
;           if (fq == 0) ssq2[(unsigned)tok * 8 + gi] = ss;
;           bf16_t* dst = (gi < 4) ? cq + (unsigned)tok * 256 + gi * 64 + 8 * fq : ckv + (unsigned)tok * 128 + (gi - 4) * 64 + 8 * fq;
;           st8_bf16(dst, v[0]); st8_bf16(dst + 32, v[1]);
;         } else if (gi == 6) {
;           float* dst = kpe + (unsigned)tok * 32 + 8 * fq;
;           *(f32x4*)dst = (f32x4){v[0][0], v[0][1], v[0][2], v[0][3]}; *(f32x4*)(dst + 4) = (f32x4){v[0][4], v[0][5], v[0][6], v[0][7]};
;         } else if (gi < 17) {
;           const bool isq = gi < 15; const float* gn = isq ? gq_norm : gk_norm;
;           float ss = 0.f;
; #pragma unroll
;           for (int bj = 0; bj < 2; ++bj)
; #pragma unroll
;             for (int e = 0; e < 8; ++e) ss += v[bj][e] * v[bj][e];
;           const float rn = rsqrtf(grp_sum(ss) * (1.f / 64.f) + EPS) * (isq ? 0.125f * LOG2E : 1.f);
;           float kk = 0.f;
; #pragma unroll
;           for (int bj = 0; bj < 2; ++bj) {
;             const unsigned ao = (unsigned)(bj == 0 ? (pos >> 6) : (pos & 63)) * 16 + 8 * (fq & 1);
;             const f32x4 c0 = *(const f32x4*)(cos32 + ao), c1 = *(const f32x4*)(cos32 + ao + 4), s0 = *(const f32x4*)(sin32 + ao), s1 = *(const f32x4*)(sin32 + ao + 4);
; #pragma unroll
;             for (int e = 0; e < 8; ++e) {
;               const float own = v[bj][e] * rn * gn[32 * bj + 8 * fq + e];
;               const float oth = lane32_partner(own, lane);
;               const float cc = e < 4 ? c0[e & 3] : c1[e & 3], sn = e < 4 ? s0[e & 3] : s1[e & 3];
;               v[bj][e] = (fq < 2) ? own * cc - oth * sn : oth * sn + own * cc;
;               kk += v[bj][e] * v[bj][e];
;             }
;           }
;           bf16_t* dst = isq ? qd + ((unsigned)(bb * 8 + (gi - 7)) * S + pos) * 64 + 8 * fq : kd + ((unsigned)(bb * 2 + (gi - 15)) * S + pos) * 64 + 8 * fq;
;           st8_bf16(dst, v[0]); st8_bf16(dst + 32, v[1]);
.LBB0_1187:
	s_nop 1
	v_pk_mul_f32 v[64:65], v[56:57], v[72:73] op_sel:[0,1]
	v_pk_mul_f32 v[66:67], v[58:59], v[72:73] op_sel:[0,1]
	v_pk_mul_f32 v[68:69], v[40:41], v[72:73] op_sel:[0,1]
	v_pk_mul_f32 v[70:71], v[42:43], v[72:73] op_sel:[0,1]
	v_pk_mul_f32 v[80:81], v[24:25], v[72:73] op_sel:[0,1]
	v_pk_mul_f32 v[82:83], v[26:27], v[72:73] op_sel:[0,1]
	v_pk_mul_f32 v[84:85], v[8:9], v[72:73] op_sel:[0,1]
	v_pk_mul_f32 v[86:87], v[10:11], v[72:73] op_sel:[0,1]
	s_and_b64 vcc, exec, s[18:19]
	s_mov_b64 s[88:89], -1
	s_cbranch_vccnz .LBB0_1195
	s_and_b64 vcc, exec, s[16:17]
	s_cbranch_vccnz .LBB0_1192
	v_pk_mul_f32 v[88:89], v[64:65], v[64:65]
	v_pk_mul_f32 v[92:93], v[66:67], v[66:67]
	v_add_f32_e32 v88, v88, v89
	v_add_f32_e32 v88, v92, v88
	v_pk_mul_f32 v[94:95], v[68:69], v[68:69]
	v_add_f32_e32 v88, v93, v88
	v_add_f32_e32 v88, v94, v88
	v_pk_mul_f32 v[96:97], v[70:71], v[70:71]
	v_add_f32_e32 v88, v95, v88
	v_add_f32_e32 v88, v96, v88
	v_pk_mul_f32 v[104:105], v[80:81], v[80:81]
	v_add_f32_e32 v88, v97, v88
	v_add_f32_e32 v88, v104, v88
	v_pk_mul_f32 v[106:107], v[82:83], v[82:83]
	v_add_f32_e32 v88, v105, v88
	v_add_f32_e32 v88, v106, v88
	v_pk_mul_f32 v[108:109], v[84:85], v[84:85]
	v_add_f32_e32 v88, v107, v88
	v_add_f32_e32 v88, v108, v88
	v_pk_mul_f32 v[110:111], v[86:87], v[86:87]
	v_add_f32_e32 v88, v109, v88
	v_add_f32_e32 v88, v110, v88
	v_add_f32_e32 v88, v111, v88
	v_mov_b32_e32 v89, v88
	s_nop 1
	v_permlane16_swap_b32_e32 v88, v89
	s_and_b64 s[88:89], s[14:15], exec
	v_readlane_b32 s88, v252, 21
	v_readlane_b32 s89, v252, 22
	s_load_dwordx4 s[56:59], s[88:89], 0xe0
	s_waitcnt lgkmcnt(0)
	v_add_f32_e32 v88, v88, v89
	v_mov_b32_e32 v89, v88
	s_nop 1
	v_permlane32_swap_b32_e32 v88, v89
	v_readlane_b32 s90, v252, 16
	v_readlane_b32 s91, v252, 6
	s_cselect_b32 s88, s57, s59
	s_cselect_b32 s89, s56, s58
	s_waitcnt lgkmcnt(0)
	v_add_f32_e32 v88, v88, v89
	v_fmamk_f32 v88, v88, 0x3c800000, v206
	v_cmp_gt_f32_e32 vcc, s21, v88
	v_mul_f32_e32 v89, 0x4b800000, v88
	s_movk_i32 s56, 0x7f0
	v_cndmask_b32_e32 v88, v88, v89, vcc
	v_rsq_f32_e32 v88, v88
	v_mov_b32_e32 v90, s89
	v_mov_b32_e32 v91, s88
	v_lshl_add_u64 v[92:93], v[154:155], 2, v[90:91]
	v_mul_f32_e32 v89, 0x45800000, v88
	v_cndmask_b32_e32 v88, v88, v89, vcc
	v_lshrrev_b32_e32 v89, 2, v101
	v_and_or_b32 v89, v89, s56, v213
	v_lshlrev_b32_e32 v89, 2, v89
	global_load_dwordx4 v[94:97], v89, s[54:55] offset:16
	global_load_dwordx4 v[104:107], v89, s[54:55]
	global_load_dwordx4 v[108:111], v89, s[50:51] offset:16
	global_load_dwordx4 v[112:115], v89, s[50:51]
	global_load_dwordx4 v[116:119], v[92:93], off offset:16
	global_load_dwordx4 v[120:123], v[92:93], off
	v_mul_f32_e32 v88, v214, v88
	v_mul_f32_e32 v89, v64, v88
	s_movk_i32 s56, 0x3f0
	v_ashrrev_i32_e32 v77, 13, v101
	v_and_b32_e32 v102, 0x1fff, v101
	s_cselect_b32 s88, s62, s24
	s_cselect_b32 s89, 22, 20
	s_cselect_b32 s90, s90, s91
	v_readlane_b32 s91, v252, 14
	v_readlane_b32 s92, v252, 4
	s_cselect_b32 s91, s91, s92
	v_or_b32_e32 v102, s88, v102
	v_lshlrev_b32_e32 v77, s89, v77
	s_andn2_b64 vcc, exec, s[86:87]
	s_waitcnt vmcnt(0)
	v_mul_f32_e32 v89, v120, v89
	v_mov_b32_e32 v90, v89
	v_mov_b32_e32 v91, v89
	s_nop 1
	v_permlane32_swap_b32_e32 v90, v91
	v_cndmask_b32_e64 v90, v90, v91, s[12:13]
	v_mul_f32_e32 v90, v112, v90
	v_cndmask_b32_e64 v103, v90, -v90, s[10:11]
	v_fmac_f32_e32 v103, v104, v89
	v_mul_f32_e32 v89, v65, v88
	v_mul_f32_e32 v89, v121, v89
	v_mov_b32_e32 v90, v89
	v_mov_b32_e32 v91, v89
	s_nop 1
	v_permlane32_swap_b32_e32 v90, v91
	v_cndmask_b32_e64 v90, v90, v91, s[12:13]
	v_mul_f32_e32 v90, v113, v90
	v_cndmask_b32_e64 v104, v90, -v90, s[10:11]
	v_fmac_f32_e32 v104, v105, v89
	v_mul_f32_e32 v89, v66, v88
	v_mul_f32_e32 v89, v122, v89
	v_mov_b32_e32 v90, v89
	v_mov_b32_e32 v91, v89
	s_nop 1
	v_permlane32_swap_b32_e32 v90, v91
	v_cndmask_b32_e64 v90, v90, v91, s[12:13]
	v_mul_f32_e32 v90, v114, v90
	v_cndmask_b32_e64 v105, v90, -v90, s[10:11]
	v_fmac_f32_e32 v105, v106, v89
	v_mul_f32_e32 v89, v67, v88
	v_mul_f32_e32 v89, v89, v123
	v_mov_b32_e32 v90, v89
	v_mov_b32_e32 v91, v89
	s_nop 1
	v_permlane32_swap_b32_e32 v90, v91
	v_cndmask_b32_e64 v90, v90, v91, s[12:13]
	v_mul_f32_e32 v90, v115, v90
	v_cndmask_b32_e64 v106, v90, -v90, s[10:11]
	v_fmac_f32_e32 v106, v107, v89
	v_mul_f32_e32 v89, v68, v88
	v_mul_f32_e32 v89, v89, v116
	v_mov_b32_e32 v90, v89
	v_mov_b32_e32 v91, v89
	s_nop 1
	v_permlane32_swap_b32_e32 v90, v91
	v_cndmask_b32_e64 v90, v90, v91, s[12:13]
	v_mul_f32_e32 v90, v108, v90
	v_cndmask_b32_e64 v107, v90, -v90, s[10:11]
	v_fmac_f32_e32 v107, v94, v89
	v_mul_f32_e32 v89, v69, v88
	v_mul_f32_e32 v89, v89, v117
	v_mov_b32_e32 v90, v89
	v_mov_b32_e32 v91, v89
	s_nop 1
	v_permlane32_swap_b32_e32 v90, v91
	v_cndmask_b32_e64 v90, v90, v91, s[12:13]
	v_mul_f32_e32 v90, v109, v90
	v_cndmask_b32_e64 v108, v90, -v90, s[10:11]
	v_pk_mul_f32 v[90:91], v[70:71], v[88:89] op_sel_hi:[1,0]
	v_fmac_f32_e32 v108, v95, v89
	v_pk_mul_f32 v[90:91], v[90:91], v[118:119]
	s_nop 0
	v_mov_b32_e32 v89, v90
	v_mov_b32_e32 v94, v90
	v_mov_b32_e32 v95, v91
	v_mov_b32_e32 v109, v91
	v_permlane32_swap_b32_e32 v89, v94
	s_nop 0
	v_permlane32_swap_b32_e32 v95, v109
	v_cndmask_b32_e64 v95, v95, v109, s[12:13]
	v_cndmask_b32_e64 v94, v89, v94, s[12:13]
	v_pk_mul_f32 v[94:95], v[110:111], v[94:95]
	v_and_or_b32 v89, v144, s56, v213
	v_cndmask_b32_e64 v95, v95, -v95, s[10:11]
	v_cndmask_b32_e64 v94, v94, -v94, s[10:11]
	v_lshlrev_b32_e32 v89, 2, v89
	v_pk_fma_f32 v[90:91], v[96:97], v[90:91], v[94:95]
	global_load_dwordx4 v[110:113], v89, s[54:55] offset:16
	global_load_dwordx4 v[94:97], v89, s[54:55]
	global_load_dwordx4 v[114:117], v89, s[50:51] offset:16
	global_load_dwordx4 v[118:121], v89, s[50:51]
	global_load_dwordx4 v[122:125], v[92:93], off offset:144
	global_load_dwordx4 v[126:129], v[92:93], off offset:128
	v_pk_mul_f32 v[132:133], v[80:81], v[88:89] op_sel_hi:[1,0]
	v_lshl_add_u32 v144, v102, 6, v77
	v_mov_b32_e32 v77, v79
	s_waitcnt vmcnt(0)
; __device__ __forceinline__ float grp_sum(float v) { v += __shfl_xor(v, 16); v += __shfl_xor(v, 32); return v; }
; __device__ __forceinline__ void st8_bf16(bf16_t* dst, const float (&v)[8]) { u32x4 w; w.x = pk2(v[0], v[1]); w.y = pk2(v[2], v[3]); w.z = pk2(v[4], v[5]); w.w = pk2(v[6], v[7]); *(u32x4*)dst = w; }
;   __device__ __forceinline__ void operator()(const pg8::f32x4 (&acc)[2][2][4][2], const pg8::Unit& u, int wr, int wc, int fr, int fq0) const {
;     ...
;           for (int bj = 0; bj < 2; ++bj) {
;             const unsigned ao = (unsigned)(bj == 0 ? (pos >> 6) : (pos & 63)) * 16 + 8 * (fq & 1);
;             const f32x4 c0 = *(const f32x4*)(cos32 + ao), c1 = *(const f32x4*)(cos32 + ao + 4), s0 = *(const f32x4*)(sin32 + ao), s1 = *(const f32x4*)(sin32 + ao + 4);
; #pragma unroll
;             for (int e = 0; e < 8; ++e) {
;               const float own = v[bj][e] * rn * gn[32 * bj + 8 * fq + e];
;               const float oth = lane32_partner(own, lane);
;               const float cc = e < 4 ? c0[e & 3] : c1[e & 3], sn = e < 4 ? s0[e & 3] : s1[e & 3];
;               v[bj][e] = (fq < 2) ? own * cc - oth * sn : oth * sn + own * cc;
;               kk += v[bj][e] * v[bj][e];
;             }
;           }
;           bf16_t* dst = isq ? qd + ((unsigned)(bb * 8 + (gi - 7)) * S + pos) * 64 + 8 * fq : kd + ((unsigned)(bb * 2 + (gi - 15)) * S + pos) * 64 + 8 * fq;
;           st8_bf16(dst, v[0]); st8_bf16(dst + 32, v[1]);
;           if (!isq) kmx_run = fmaxf(kmx_run, grp_sum(kk));
	v_pk_mul_f32 v[92:93], v[132:133], v[126:127]
	s_nop 0
	v_mov_b32_e32 v89, v92
	v_mov_b32_e32 v109, v92
	v_mov_b32_e32 v126, v93
	v_mov_b32_e32 v127, v93
	v_permlane32_swap_b32_e32 v89, v109
	s_nop 0
	v_permlane32_swap_b32_e32 v126, v127
	v_cndmask_b32_e64 v127, v126, v127, s[12:13]
	v_cndmask_b32_e64 v126, v89, v109, s[12:13]
	v_pk_mul_f32 v[118:119], v[118:119], v[126:127]
	s_nop 0
	v_cndmask_b32_e64 v119, v119, -v119, s[10:11]
	v_cndmask_b32_e64 v118, v118, -v118, s[10:11]
	v_pk_fma_f32 v[92:93], v[94:95], v[92:93], v[118:119]
	v_pk_mul_f32 v[94:95], v[82:83], v[88:89] op_sel_hi:[1,0]
	s_nop 0
	v_pk_mul_f32 v[94:95], v[94:95], v[128:129]
	s_nop 0
	v_mov_b32_e32 v89, v94
	v_mov_b32_e32 v109, v94
	v_mov_b32_e32 v118, v95
	v_mov_b32_e32 v119, v95
	v_permlane32_swap_b32_e32 v89, v109
	s_nop 0
	v_permlane32_swap_b32_e32 v118, v119
	v_cndmask_b32_e64 v119, v118, v119, s[12:13]
	v_cndmask_b32_e64 v118, v89, v109, s[12:13]
	v_pk_mul_f32 v[118:119], v[120:121], v[118:119]
	s_nop 0
	v_cndmask_b32_e64 v119, v119, -v119, s[10:11]
	v_cndmask_b32_e64 v118, v118, -v118, s[10:11]
	v_pk_fma_f32 v[94:95], v[96:97], v[94:95], v[118:119]
	v_pk_mul_f32 v[96:97], v[84:85], v[88:89] op_sel_hi:[1,0]
	s_nop 0
	v_pk_mul_f32 v[96:97], v[96:97], v[122:123]
	s_nop 0
	v_mov_b32_e32 v89, v96
	v_mov_b32_e32 v109, v96
	v_mov_b32_e32 v118, v97
	v_mov_b32_e32 v119, v97
	v_permlane32_swap_b32_e32 v89, v109
	s_nop 0
	v_permlane32_swap_b32_e32 v118, v119
	v_cndmask_b32_e64 v119, v118, v119, s[12:13]
	v_cndmask_b32_e64 v118, v89, v109, s[12:13]
	v_pk_mul_f32 v[114:115], v[114:115], v[118:119]
	v_pk_mul_f32 v[88:89], v[86:87], v[88:89] op_sel_hi:[1,0]
	v_cndmask_b32_e64 v115, v115, -v115, s[10:11]
	v_cndmask_b32_e64 v114, v114, -v114, s[10:11]
	v_pk_mul_f32 v[88:89], v[88:89], v[124:125]
	v_pk_fma_f32 v[96:97], v[110:111], v[96:97], v[114:115]
	v_mov_b32_e32 v109, v88
	v_mov_b32_e32 v110, v88
	v_mov_b32_e32 v111, v89
	v_mov_b32_e32 v114, v89
	v_permlane32_swap_b32_e32 v109, v110
	s_nop 0
	v_permlane32_swap_b32_e32 v111, v114
	v_cndmask_b32_e64 v111, v111, v114, s[12:13]
	v_cndmask_b32_e64 v110, v109, v110, s[12:13]
	v_pk_mul_f32 v[110:111], v[116:117], v[110:111]
	s_nop 0
	v_cndmask_b32_e64 v111, v111, -v111, s[10:11]
	v_cndmask_b32_e64 v110, v110, -v110, s[10:11]
	v_pk_fma_f32 v[88:89], v[112:113], v[88:89], v[110:111]
	v_mov_b32_e32 v110, s91
	v_mov_b32_e32 v111, s90
	v_lshl_add_u64 v[110:111], v[144:145], 1, v[110:111]
	v_lshl_add_u64 v[114:115], v[154:155], 1, v[110:111]
	v_cvt_pk_bf16_f32 v110, v103, v104
	v_cvt_pk_bf16_f32 v111, v105, v106
	v_cvt_pk_bf16_f32 v112, v107, v108
	v_cvt_pk_bf16_f32 v113, v90, v91
	global_store_dwordx4 v[114:115], v[110:113], off
	s_nop 1
	v_cvt_pk_bf16_f32 v110, v92, v93
	v_cvt_pk_bf16_f32 v111, v94, v95
	v_cvt_pk_bf16_f32 v112, v96, v97
	v_cvt_pk_bf16_f32 v113, v88, v89
	global_store_dwordx4 v[114:115], v[110:113], off offset:64
	s_cbranch_vccnz .LBB0_1191
	v_mul_f32_e32 v77, v104, v104
	v_fmac_f32_e32 v77, v103, v103
	v_fmac_f32_e32 v77, v105, v105
	v_fmac_f32_e32 v77, v106, v106
	v_fmac_f32_e32 v77, v107, v107
	v_fmac_f32_e32 v77, v108, v108
	v_pk_mul_f32 v[90:91], v[90:91], v[90:91]
	v_pk_mul_f32 v[88:89], v[88:89], v[88:89]
	v_add_f32_e32 v77, v77, v90
	v_add_f32_e32 v77, v77, v91
	v_pk_mul_f32 v[90:91], v[92:93], v[92:93]
	s_nop 0
	v_add_f32_e32 v77, v77, v90
	v_add_f32_e32 v77, v77, v91
	v_pk_mul_f32 v[90:91], v[94:95], v[94:95]
	s_nop 0
	v_add_f32_e32 v77, v77, v90
	v_add_f32_e32 v77, v77, v91
	v_pk_mul_f32 v[90:91], v[96:97], v[96:97]
	s_nop 0
	v_add_f32_e32 v77, v77, v90
	v_add_f32_e32 v77, v77, v91
	v_add_f32_e32 v77, v77, v88
	v_add_f32_e32 v77, v77, v89
	v_mov_b32_e32 v88, v77
	s_nop 1
	v_permlane16_swap_b32_e32 v77, v88
	s_waitcnt lgkmcnt(0)
	v_add_f32_e32 v77, v77, v88
	v_mov_b32_e32 v88, v77
	s_nop 1
	v_permlane32_swap_b32_e32 v77, v88
	s_waitcnt lgkmcnt(0)
	v_add_f32_e32 v77, v77, v88
	v_max_f32_e32 v88, v79, v79
	v_max_f32_e32 v77, v88, v77

; __device__ __forceinline__ float grp_sum(float v) { v += __shfl_xor(v, 16); v += __shfl_xor(v, 32); return v; }
;   __device__ __forceinline__ void operator()(const pg8::f32x4 (&acc)[2][2][4][2], const pg8::Unit& u, int wr, int wc, int fr, int fq0) const {
;     ...
;         if (gi < 6) {
;           float ss = 0.f;
; #pragma unroll
;           for (int bj = 0; bj < 2; ++bj)
; #pragma unroll
;             for (int e = 0; e < 8; ++e) ss += v[bj][e] * v[bj][e];
;           ss = grp_sum(ss);
;           if (fq == 0) ssq2[(unsigned)tok * 8 + gi] = ss;
.LBB0_1195:
	s_andn2_b64 vcc, exec, s[88:89]
	s_cbranch_vccnz .LBB0_1199
	v_pk_mul_f32 v[88:89], v[64:65], v[64:65]
	v_pk_mul_f32 v[90:91], v[66:67], v[66:67]
	v_add_f32_e32 v77, v88, v89
	v_add_f32_e32 v77, v90, v77
	v_pk_mul_f32 v[92:93], v[68:69], v[68:69]
	v_add_f32_e32 v77, v91, v77
	v_add_f32_e32 v77, v92, v77
	v_pk_mul_f32 v[94:95], v[70:71], v[70:71]
	v_add_f32_e32 v77, v93, v77
	v_add_f32_e32 v77, v94, v77
	v_pk_mul_f32 v[96:97], v[80:81], v[80:81]
	v_add_f32_e32 v77, v95, v77
	v_add_f32_e32 v77, v96, v77
	v_pk_mul_f32 v[102:103], v[82:83], v[82:83]
	v_add_f32_e32 v77, v97, v77
	v_add_f32_e32 v77, v102, v77
	v_pk_mul_f32 v[104:105], v[84:85], v[84:85]
	v_add_f32_e32 v77, v103, v77
	v_add_f32_e32 v77, v104, v77
	v_pk_mul_f32 v[106:107], v[86:87], v[86:87]
	v_add_f32_e32 v77, v105, v77
	v_add_f32_e32 v77, v106, v77
	v_add_f32_e32 v77, v107, v77
	v_mov_b32_e32 v88, v77
	s_nop 1
	v_permlane16_swap_b32_e32 v77, v88
	s_waitcnt lgkmcnt(0)
	v_add_f32_e32 v77, v77, v88
	ds_bpermute_b32 v88, v212, v77
	s_and_saveexec_b64 s[88:89], s[8:9]
	s_cbranch_execz .LBB0_1198
	v_lshl_add_u32 v144, v101, 3, s68
	s_waitcnt lgkmcnt(0)
	v_add_f32_e32 v77, v77, v88
	v_lshl_add_u64 v[88:89], v[144:145], 2, s[52:53]
	global_store_dword v[88:89], v77, off

;   __device__ __forceinline__ void operator()(const pg8::f32x4 (&acc)[2][2][4][2], const pg8::Unit& u, int wr, int wc, int fr, int fq0) const {
;     ...
;             for (int c = 0; c < 4; ++c) v[bj][4 * n + c] = acc[ai][bj][m][n][c] * rs[m];
;         if (gi < 6) {
;           float ss = 0.f;
; #pragma unroll
;           for (int bj = 0; bj < 2; ++bj)
; #pragma unroll
;             for (int e = 0; e < 8; ++e) ss += v[bj][e] * v[bj][e];
;           ss = grp_sum(ss);
;           if (fq == 0) ssq2[(unsigned)tok * 8 + gi] = ss;
;           bf16_t* dst = (gi < 4) ? cq + (unsigned)tok * 256 + gi * 64 + 8 * fq : ckv + (unsigned)tok * 128 + (gi - 4) * 64 + 8 * fq;
;           st8_bf16(dst, v[0]); st8_bf16(dst + 32, v[1]);
;         } else if (gi == 6) {
;           float* dst = kpe + (unsigned)tok * 32 + 8 * fq;
;           *(f32x4*)dst = (f32x4){v[0][0], v[0][1], v[0][2], v[0][3]}; *(f32x4*)(dst + 4) = (f32x4){v[0][4], v[0][5], v[0][6], v[0][7]};
;         } else if (gi < 17) {
;           const bool isq = gi < 15; const float* gn = isq ? gq_norm : gk_norm;
;           float ss = 0.f;
; #pragma unroll
;           for (int bj = 0; bj < 2; ++bj)
; #pragma unroll
;             for (int e = 0; e < 8; ++e) ss += v[bj][e] * v[bj][e];
;           const float rn = rsqrtf(grp_sum(ss) * (1.f / 64.f) + EPS) * (isq ? 0.125f * LOG2E : 1.f);
;           float kk = 0.f;
; #pragma unroll
;           for (int bj = 0; bj < 2; ++bj) {
;             const unsigned ao = (unsigned)(bj == 0 ? (pos >> 6) : (pos & 63)) * 16 + 8 * (fq & 1);
;             const f32x4 c0 = *(const f32x4*)(cos32 + ao), c1 = *(const f32x4*)(cos32 + ao + 4), s0 = *(const f32x4*)(sin32 + ao), s1 = *(const f32x4*)(sin32 + ao + 4);
; #pragma unroll
;             for (int e = 0; e < 8; ++e) {
;               const float own = v[bj][e] * rn * gn[32 * bj + 8 * fq + e];
;               const float oth = lane32_partner(own, lane);
;               const float cc = e < 4 ? c0[e & 3] : c1[e & 3], sn = e < 4 ? s0[e & 3] : s1[e & 3];
;               v[bj][e] = (fq < 2) ? own * cc - oth * sn : oth * sn + own * cc;
;               kk += v[bj][e] * v[bj][e];
;             }
;           }
;           bf16_t* dst = isq ? qd + ((unsigned)(bb * 8 + (gi - 7)) * S + pos) * 64 + 8 * fq : kd + ((unsigned)(bb * 2 + (gi - 15)) * S + pos) * 64 + 8 * fq;
;           st8_bf16(dst, v[0]); st8_bf16(dst + 32, v[1]);
.LBB0_1199:
	s_nop 1
	v_pk_mul_f32 v[64:65], v[52:53], v[74:75] op_sel_hi:[1,0]
	v_pk_mul_f32 v[66:67], v[54:55], v[74:75] op_sel_hi:[1,0]
	v_pk_mul_f32 v[68:69], v[36:37], v[74:75] op_sel_hi:[1,0]
	v_pk_mul_f32 v[70:71], v[38:39], v[74:75] op_sel_hi:[1,0]
	v_pk_mul_f32 v[80:81], v[20:21], v[74:75] op_sel_hi:[1,0]
	v_pk_mul_f32 v[82:83], v[22:23], v[74:75] op_sel_hi:[1,0]
	v_pk_mul_f32 v[84:85], v[4:5], v[74:75] op_sel_hi:[1,0]
	v_pk_mul_f32 v[86:87], v[6:7], v[74:75] op_sel_hi:[1,0]
	s_and_b64 vcc, exec, s[18:19]
	s_mov_b64 s[88:89], -1
	s_cbranch_vccnz .LBB0_1207
	s_and_b64 vcc, exec, s[16:17]
	s_cbranch_vccnz .LBB0_1204
	v_pk_mul_f32 v[88:89], v[64:65], v[64:65]
	v_pk_mul_f32 v[92:93], v[66:67], v[66:67]
	v_add_f32_e32 v79, v88, v89
	v_add_f32_e32 v79, v92, v79
	v_pk_mul_f32 v[94:95], v[68:69], v[68:69]
	v_add_f32_e32 v79, v93, v79
	v_add_f32_e32 v79, v94, v79
	v_pk_mul_f32 v[102:103], v[70:71], v[70:71]
	v_add_f32_e32 v79, v95, v79
	v_add_f32_e32 v79, v102, v79
	v_pk_mul_f32 v[104:105], v[80:81], v[80:81]
	v_add_f32_e32 v79, v103, v79
	v_add_f32_e32 v79, v104, v79
	v_pk_mul_f32 v[106:107], v[82:83], v[82:83]
	v_add_f32_e32 v79, v105, v79
	v_add_f32_e32 v79, v106, v79
	v_pk_mul_f32 v[108:109], v[84:85], v[84:85]
	v_add_f32_e32 v79, v107, v79
	v_add_f32_e32 v79, v108, v79
	v_pk_mul_f32 v[110:111], v[86:87], v[86:87]
	v_add_f32_e32 v79, v109, v79
	v_add_f32_e32 v79, v110, v79
	v_add_f32_e32 v79, v111, v79
	v_mov_b32_e32 v88, v79
	s_nop 1
	v_permlane16_swap_b32_e32 v79, v88
	s_and_b64 s[88:89], s[14:15], exec
	v_readlane_b32 s88, v252, 21
	v_readlane_b32 s89, v252, 22
	s_load_dwordx4 s[56:59], s[88:89], 0xe0
	s_waitcnt lgkmcnt(0)
	v_add_f32_e32 v79, v79, v88
	v_mov_b32_e32 v88, v79
	s_nop 1
	v_permlane32_swap_b32_e32 v79, v88
	v_readlane_b32 s90, v252, 16
	v_readlane_b32 s91, v252, 6
	s_cselect_b32 s88, s57, s59
	s_cselect_b32 s89, s56, s58
	s_waitcnt lgkmcnt(0)
	v_add_f32_e32 v79, v79, v88
	v_fmamk_f32 v79, v79, 0x3c800000, v206
	v_cmp_gt_f32_e32 vcc, s21, v79
	v_mul_f32_e32 v88, 0x4b800000, v79
	s_movk_i32 s56, 0x7f0
	v_cndmask_b32_e32 v79, v79, v88, vcc
	v_rsq_f32_e32 v79, v79
	v_mov_b32_e32 v90, s89
	v_mov_b32_e32 v91, s88
	v_lshl_add_u64 v[92:93], v[154:155], 2, v[90:91]
	v_mul_f32_e32 v88, 0x45800000, v79
	v_cndmask_b32_e32 v79, v79, v88, vcc
	v_mul_f32_e32 v88, v214, v79
	v_lshrrev_b32_e32 v79, 2, v100
	v_and_or_b32 v79, v79, s56, v213
	v_lshlrev_b32_e32 v79, 2, v79
	global_load_dwordx4 v[106:109], v79, s[54:55] offset:16
	global_load_dwordx4 v[102:105], v79, s[54:55]
	global_load_dwordx4 v[110:113], v79, s[50:51] offset:16
	global_load_dwordx4 v[114:117], v79, s[50:51]
	global_load_dwordx4 v[118:121], v[92:93], off offset:16
	global_load_dwordx4 v[122:125], v[92:93], off
	v_mul_f32_e32 v79, v64, v88
	s_movk_i32 s56, 0x3f0
	v_and_or_b32 v78, v78, s56, v213
	v_lshlrev_b32_e32 v78, 2, v78
	v_ashrrev_i32_e32 v96, 13, v100
	v_and_b32_e32 v97, 0x1fff, v100
	s_cselect_b32 s88, s62, s24
	s_cselect_b32 s89, 22, 20
	s_cselect_b32 s90, s90, s91
	v_readlane_b32 s91, v252, 14
	v_readlane_b32 s92, v252, 4
	s_cselect_b32 s91, s91, s92
	v_or_b32_e32 v97, s88, v97
	v_lshlrev_b32_e32 v96, s89, v96
	v_lshl_add_u32 v144, v97, 6, v96
	s_andn2_b64 vcc, exec, s[86:87]
	s_waitcnt vmcnt(0)
	v_mul_f32_e32 v79, v122, v79
	v_mov_b32_e32 v89, v79
	v_mov_b32_e32 v90, v79
	s_nop 1
	v_permlane32_swap_b32_e32 v89, v90
	v_cndmask_b32_e64 v89, v89, v90, s[12:13]
	v_mul_f32_e32 v89, v114, v89
	v_cndmask_b32_e64 v101, v89, -v89, s[10:11]
	v_fmac_f32_e32 v101, v102, v79
	v_mul_f32_e32 v79, v65, v88
	v_mul_f32_e32 v79, v123, v79
	v_mov_b32_e32 v89, v79
	v_mov_b32_e32 v90, v79
	s_nop 1
	v_permlane32_swap_b32_e32 v89, v90
	v_cndmask_b32_e64 v89, v89, v90, s[12:13]
	v_mul_f32_e32 v89, v115, v89
	v_cndmask_b32_e64 v102, v89, -v89, s[10:11]
	v_fmac_f32_e32 v102, v103, v79
	v_mul_f32_e32 v79, v66, v88
	v_mul_f32_e32 v79, v124, v79
	v_mov_b32_e32 v89, v79
	v_mov_b32_e32 v90, v79
	s_nop 1
	v_permlane32_swap_b32_e32 v89, v90
	v_cndmask_b32_e64 v89, v89, v90, s[12:13]
	v_mul_f32_e32 v89, v116, v89
	v_cndmask_b32_e64 v103, v89, -v89, s[10:11]
	v_fmac_f32_e32 v103, v104, v79
	v_mul_f32_e32 v79, v67, v88
	v_mul_f32_e32 v79, v79, v125
	v_mov_b32_e32 v89, v79
	v_mov_b32_e32 v90, v79
	s_nop 1
	v_permlane32_swap_b32_e32 v89, v90
	v_cndmask_b32_e64 v89, v89, v90, s[12:13]
	v_mul_f32_e32 v89, v117, v89
	v_cndmask_b32_e64 v104, v89, -v89, s[10:11]
	v_fmac_f32_e32 v104, v105, v79
	v_mul_f32_e32 v79, v68, v88
	v_mul_f32_e32 v79, v79, v118
	v_mov_b32_e32 v89, v79
	v_mov_b32_e32 v90, v79
	s_nop 1
	v_permlane32_swap_b32_e32 v89, v90
	v_cndmask_b32_e64 v89, v89, v90, s[12:13]
	v_mul_f32_e32 v89, v110, v89
	v_cndmask_b32_e64 v105, v89, -v89, s[10:11]
	v_fmac_f32_e32 v105, v106, v79
	v_mul_f32_e32 v79, v69, v88
	v_mul_f32_e32 v79, v79, v119
	v_mov_b32_e32 v89, v79
	v_mov_b32_e32 v90, v79
	s_nop 1
	v_permlane32_swap_b32_e32 v89, v90
	v_cndmask_b32_e64 v89, v89, v90, s[12:13]
	v_mul_f32_e32 v89, v111, v89
	v_pk_mul_f32 v[90:91], v[70:71], v[88:89] op_sel_hi:[1,0]
	v_cndmask_b32_e64 v106, v89, -v89, s[10:11]
	v_pk_mul_f32 v[90:91], v[90:91], v[120:121]
	v_fmac_f32_e32 v106, v107, v79
	v_mov_b32_e32 v79, v90
	v_mov_b32_e32 v89, v90
	v_mov_b32_e32 v94, v91
	v_mov_b32_e32 v95, v91
	v_permlane32_swap_b32_e32 v79, v89
	s_nop 0
	v_permlane32_swap_b32_e32 v94, v95
	v_cndmask_b32_e64 v95, v94, v95, s[12:13]
	v_cndmask_b32_e64 v94, v79, v89, s[12:13]
	v_pk_mul_f32 v[94:95], v[112:113], v[94:95]
	s_nop 0
	v_cndmask_b32_e64 v95, v95, -v95, s[10:11]
	v_cndmask_b32_e64 v94, v94, -v94, s[10:11]
	v_pk_fma_f32 v[90:91], v[108:109], v[90:91], v[94:95]
	global_load_dwordx4 v[108:111], v78, s[54:55] offset:16
	global_load_dwordx4 v[112:115], v78, s[54:55]
	global_load_dwordx4 v[116:119], v78, s[50:51] offset:16
	global_load_dwordx4 v[120:123], v78, s[50:51]
	global_load_dwordx4 v[124:127], v[92:93], off offset:144
	s_nop 0
	global_load_dwordx4 v[92:95], v[92:93], off offset:128
	v_pk_mul_f32 v[78:79], v[80:81], v[88:89] op_sel_hi:[1,0]
	s_waitcnt vmcnt(0)
; __device__ __forceinline__ float grp_sum(float v) { v += __shfl_xor(v, 16); v += __shfl_xor(v, 32); return v; }
; __device__ __forceinline__ void st8_bf16(bf16_t* dst, const float (&v)[8]) { u32x4 w; w.x = pk2(v[0], v[1]); w.y = pk2(v[2], v[3]); w.z = pk2(v[4], v[5]); w.w = pk2(v[6], v[7]); *(u32x4*)dst = w; }
;   __device__ __forceinline__ void operator()(const pg8::f32x4 (&acc)[2][2][4][2], const pg8::Unit& u, int wr, int wc, int fr, int fq0) const {
;     ...
;           for (int bj = 0; bj < 2; ++bj) {
;             const unsigned ao = (unsigned)(bj == 0 ? (pos >> 6) : (pos & 63)) * 16 + 8 * (fq & 1);
;             const f32x4 c0 = *(const f32x4*)(cos32 + ao), c1 = *(const f32x4*)(cos32 + ao + 4), s0 = *(const f32x4*)(sin32 + ao), s1 = *(const f32x4*)(sin32 + ao + 4);
; #pragma unroll
;             for (int e = 0; e < 8; ++e) {
;               const float own = v[bj][e] * rn * gn[32 * bj + 8 * fq + e];
;               const float oth = lane32_partner(own, lane);
;               const float cc = e < 4 ? c0[e & 3] : c1[e & 3], sn = e < 4 ? s0[e & 3] : s1[e & 3];
;               v[bj][e] = (fq < 2) ? own * cc - oth * sn : oth * sn + own * cc;
;               kk += v[bj][e] * v[bj][e];
;             }
;           }
;           bf16_t* dst = isq ? qd + ((unsigned)(bb * 8 + (gi - 7)) * S + pos) * 64 + 8 * fq : kd + ((unsigned)(bb * 2 + (gi - 15)) * S + pos) * 64 + 8 * fq;
;           st8_bf16(dst, v[0]); st8_bf16(dst + 32, v[1]);
;           if (!isq) kmx_run = fmaxf(kmx_run, grp_sum(kk));
	v_pk_mul_f32 v[78:79], v[78:79], v[92:93]
	s_nop 0
	v_mov_b32_e32 v89, v78
	v_mov_b32_e32 v92, v78
	v_mov_b32_e32 v93, v79
	v_mov_b32_e32 v107, v79
	v_permlane32_swap_b32_e32 v89, v92
	s_nop 0
	v_permlane32_swap_b32_e32 v93, v107
	v_cndmask_b32_e64 v93, v93, v107, s[12:13]
	v_cndmask_b32_e64 v92, v89, v92, s[12:13]
	v_pk_mul_f32 v[92:93], v[120:121], v[92:93]
	s_nop 0
	v_cndmask_b32_e64 v93, v93, -v93, s[10:11]
	v_cndmask_b32_e64 v92, v92, -v92, s[10:11]
	v_pk_fma_f32 v[78:79], v[112:113], v[78:79], v[92:93]
	v_pk_mul_f32 v[92:93], v[82:83], v[88:89] op_sel_hi:[1,0]
	s_nop 0
	v_pk_mul_f32 v[92:93], v[92:93], v[94:95]
	s_nop 0
	v_mov_b32_e32 v89, v92
	v_mov_b32_e32 v94, v92
	v_mov_b32_e32 v95, v93
	v_mov_b32_e32 v107, v93
	v_permlane32_swap_b32_e32 v89, v94
	s_nop 0
	v_permlane32_swap_b32_e32 v95, v107
	v_cndmask_b32_e64 v95, v95, v107, s[12:13]
	v_cndmask_b32_e64 v94, v89, v94, s[12:13]
	v_pk_mul_f32 v[94:95], v[122:123], v[94:95]
	s_nop 0
	v_cndmask_b32_e64 v95, v95, -v95, s[10:11]
	v_cndmask_b32_e64 v94, v94, -v94, s[10:11]
	v_pk_fma_f32 v[92:93], v[114:115], v[92:93], v[94:95]
	v_pk_mul_f32 v[94:95], v[84:85], v[88:89] op_sel_hi:[1,0]
	s_nop 0
	v_pk_mul_f32 v[94:95], v[94:95], v[124:125]
	s_nop 0
	v_mov_b32_e32 v89, v94
	v_mov_b32_e32 v107, v94
	v_mov_b32_e32 v112, v95
	v_mov_b32_e32 v113, v95
	v_permlane32_swap_b32_e32 v89, v107
	s_nop 0
	v_permlane32_swap_b32_e32 v112, v113
	v_cndmask_b32_e64 v113, v112, v113, s[12:13]
	v_cndmask_b32_e64 v112, v89, v107, s[12:13]
	v_pk_mul_f32 v[112:113], v[116:117], v[112:113]
	v_pk_mul_f32 v[88:89], v[86:87], v[88:89] op_sel_hi:[1,0]
	v_cndmask_b32_e64 v113, v113, -v113, s[10:11]
	v_cndmask_b32_e64 v112, v112, -v112, s[10:11]
	v_pk_mul_f32 v[88:89], v[88:89], v[126:127]
	v_pk_fma_f32 v[94:95], v[108:109], v[94:95], v[112:113]
	v_mov_b32_e32 v107, v88
	v_mov_b32_e32 v108, v88
	v_mov_b32_e32 v109, v89
	v_mov_b32_e32 v112, v89
	v_permlane32_swap_b32_e32 v107, v108
	s_nop 0
	v_permlane32_swap_b32_e32 v109, v112
	v_cndmask_b32_e64 v109, v109, v112, s[12:13]
	v_cndmask_b32_e64 v108, v107, v108, s[12:13]
	v_pk_mul_f32 v[108:109], v[118:119], v[108:109]
	s_nop 0
	v_cndmask_b32_e64 v109, v109, -v109, s[10:11]
	v_cndmask_b32_e64 v108, v108, -v108, s[10:11]
	v_pk_fma_f32 v[88:89], v[110:111], v[88:89], v[108:109]
	v_mov_b32_e32 v108, s91
	v_mov_b32_e32 v109, s90
	v_lshl_add_u64 v[96:97], v[144:145], 1, v[108:109]
	v_lshl_add_u64 v[96:97], v[154:155], 1, v[96:97]
	v_cvt_pk_bf16_f32 v108, v101, v102
	v_cvt_pk_bf16_f32 v109, v103, v104
	v_cvt_pk_bf16_f32 v110, v105, v106
	v_cvt_pk_bf16_f32 v111, v90, v91
	global_store_dwordx4 v[96:97], v[108:111], off
	s_nop 1
	v_cvt_pk_bf16_f32 v108, v78, v79
	v_cvt_pk_bf16_f32 v109, v92, v93
	v_cvt_pk_bf16_f32 v110, v94, v95
	v_cvt_pk_bf16_f32 v111, v88, v89
	global_store_dwordx4 v[96:97], v[108:111], off offset:64
	v_mov_b32_e32 v96, v77
	s_cbranch_vccnz .LBB0_1203
	v_mul_f32_e32 v96, v102, v102
	v_fmac_f32_e32 v96, v101, v101
	v_fmac_f32_e32 v96, v103, v103
	v_fmac_f32_e32 v96, v104, v104
	v_fmac_f32_e32 v96, v105, v105
	v_fmac_f32_e32 v96, v106, v106
	v_pk_mul_f32 v[90:91], v[90:91], v[90:91]
	v_pk_mul_f32 v[78:79], v[78:79], v[78:79]
	v_add_f32_e32 v90, v96, v90
	v_add_f32_e32 v90, v90, v91
	v_add_f32_e32 v78, v90, v78
	v_add_f32_e32 v90, v78, v79
	v_pk_mul_f32 v[78:79], v[92:93], v[92:93]
	s_nop 0
	v_add_f32_e32 v78, v90, v78
	v_add_f32_e32 v90, v78, v79
	v_pk_mul_f32 v[78:79], v[94:95], v[94:95]
	s_nop 0
	v_add_f32_e32 v78, v90, v78
	v_add_f32_e32 v90, v78, v79
	v_pk_mul_f32 v[78:79], v[88:89], v[88:89]
	s_nop 0
	v_add_f32_e32 v78, v90, v78
	v_add_f32_e32 v78, v78, v79
	v_mov_b32_e32 v79, v78
	s_nop 1
	v_permlane16_swap_b32_e32 v78, v79
	s_waitcnt lgkmcnt(0)
	v_add_f32_e32 v78, v78, v79
	v_mov_b32_e32 v79, v78
	s_nop 1
	v_permlane32_swap_b32_e32 v78, v79
	s_waitcnt lgkmcnt(0)
	v_add_f32_e32 v78, v78, v79
	v_max_f32_e32 v79, v77, v77
	v_max_f32_e32 v96, v79, v78

; __device__ __forceinline__ float grp_sum(float v) { v += __shfl_xor(v, 16); v += __shfl_xor(v, 32); return v; }
;   __device__ __forceinline__ void operator()(const pg8::f32x4 (&acc)[2][2][4][2], const pg8::Unit& u, int wr, int wc, int fr, int fq0) const {
;     ...
;         if (gi < 6) {
;           float ss = 0.f;
; #pragma unroll
;           for (int bj = 0; bj < 2; ++bj)
; #pragma unroll
;             for (int e = 0; e < 8; ++e) ss += v[bj][e] * v[bj][e];
;           ss = grp_sum(ss);
;           if (fq == 0) ssq2[(unsigned)tok * 8 + gi] = ss;
.LBB0_1207:
	s_andn2_b64 vcc, exec, s[88:89]
	s_cbranch_vccnz .LBB0_1211
	v_pk_mul_f32 v[78:79], v[64:65], v[64:65]
	v_pk_mul_f32 v[88:89], v[66:67], v[66:67]
	v_add_f32_e32 v78, v78, v79
	v_add_f32_e32 v78, v88, v78
	v_pk_mul_f32 v[90:91], v[68:69], v[68:69]
	v_add_f32_e32 v78, v89, v78
	v_add_f32_e32 v78, v90, v78
	v_pk_mul_f32 v[92:93], v[70:71], v[70:71]
	v_add_f32_e32 v78, v91, v78
	v_add_f32_e32 v78, v92, v78
	v_pk_mul_f32 v[94:95], v[80:81], v[80:81]
	v_add_f32_e32 v78, v93, v78
	v_add_f32_e32 v78, v94, v78
	v_pk_mul_f32 v[96:97], v[82:83], v[82:83]
	v_add_f32_e32 v78, v95, v78
	v_add_f32_e32 v78, v96, v78
	v_pk_mul_f32 v[102:103], v[84:85], v[84:85]
	v_add_f32_e32 v78, v97, v78
	v_add_f32_e32 v78, v102, v78
	v_pk_mul_f32 v[104:105], v[86:87], v[86:87]
	v_add_f32_e32 v78, v103, v78
	v_add_f32_e32 v78, v104, v78
	v_add_f32_e32 v78, v105, v78
	v_mov_b32_e32 v79, v78
	s_nop 1
	v_permlane16_swap_b32_e32 v78, v79
	s_waitcnt lgkmcnt(0)
	v_add_f32_e32 v78, v78, v79
	ds_bpermute_b32 v79, v212, v78
	s_and_saveexec_b64 s[88:89], s[8:9]
	s_cbranch_execz .LBB0_1210
	v_lshl_add_u32 v144, v100, 3, s68
	s_waitcnt lgkmcnt(0)
	v_add_f32_e32 v88, v78, v79
	v_lshl_add_u64 v[78:79], v[144:145], 2, s[52:53]
	global_store_dword v[78:79], v88, off

;   __device__ __forceinline__ void operator()(const pg8::f32x4 (&acc)[2][2][4][2], const pg8::Unit& u, int wr, int wc, int fr, int fq0) const {
;     ...
;             for (int c = 0; c < 4; ++c) v[bj][4 * n + c] = acc[ai][bj][m][n][c] * rs[m];
;         if (gi < 6) {
;           float ss = 0.f;
; #pragma unroll
;           for (int bj = 0; bj < 2; ++bj)
; #pragma unroll
;             for (int e = 0; e < 8; ++e) ss += v[bj][e] * v[bj][e];
;           ss = grp_sum(ss);
;           if (fq == 0) ssq2[(unsigned)tok * 8 + gi] = ss;
;           bf16_t* dst = (gi < 4) ? cq + (unsigned)tok * 256 + gi * 64 + 8 * fq : ckv + (unsigned)tok * 128 + (gi - 4) * 64 + 8 * fq;
;           st8_bf16(dst, v[0]); st8_bf16(dst + 32, v[1]);
;         } else if (gi == 6) {
;           float* dst = kpe + (unsigned)tok * 32 + 8 * fq;
;           *(f32x4*)dst = (f32x4){v[0][0], v[0][1], v[0][2], v[0][3]}; *(f32x4*)(dst + 4) = (f32x4){v[0][4], v[0][5], v[0][6], v[0][7]};
;         } else if (gi < 17) {
;           const bool isq = gi < 15; const float* gn = isq ? gq_norm : gk_norm;
;           float ss = 0.f;
; #pragma unroll
;           for (int bj = 0; bj < 2; ++bj)
; #pragma unroll
;             for (int e = 0; e < 8; ++e) ss += v[bj][e] * v[bj][e];
;           const float rn = rsqrtf(grp_sum(ss) * (1.f / 64.f) + EPS) * (isq ? 0.125f * LOG2E : 1.f);
;           float kk = 0.f;
; #pragma unroll
;           for (int bj = 0; bj < 2; ++bj) {
;             const unsigned ao = (unsigned)(bj == 0 ? (pos >> 6) : (pos & 63)) * 16 + 8 * (fq & 1);
;             const f32x4 c0 = *(const f32x4*)(cos32 + ao), c1 = *(const f32x4*)(cos32 + ao + 4), s0 = *(const f32x4*)(sin32 + ao), s1 = *(const f32x4*)(sin32 + ao + 4);
; #pragma unroll
;             for (int e = 0; e < 8; ++e) {
;               const float own = v[bj][e] * rn * gn[32 * bj + 8 * fq + e];
;               const float oth = lane32_partner(own, lane);
;               const float cc = e < 4 ? c0[e & 3] : c1[e & 3], sn = e < 4 ? s0[e & 3] : s1[e & 3];
;               v[bj][e] = (fq < 2) ? own * cc - oth * sn : oth * sn + own * cc;
;               kk += v[bj][e] * v[bj][e];
;             }
;           }
;           bf16_t* dst = isq ? qd + ((unsigned)(bb * 8 + (gi - 7)) * S + pos) * 64 + 8 * fq : kd + ((unsigned)(bb * 2 + (gi - 15)) * S + pos) * 64 + 8 * fq;
;           st8_bf16(dst, v[0]); st8_bf16(dst + 32, v[1]);
.LBB0_1211:
	s_nop 1
	v_pk_mul_f32 v[64:65], v[48:49], v[74:75] op_sel:[0,1]
	v_pk_mul_f32 v[66:67], v[50:51], v[74:75] op_sel:[0,1]
	v_pk_mul_f32 v[68:69], v[32:33], v[74:75] op_sel:[0,1]
	v_pk_mul_f32 v[70:71], v[34:35], v[74:75] op_sel:[0,1]
	v_pk_mul_f32 v[78:79], v[16:17], v[74:75] op_sel:[0,1]
	v_pk_mul_f32 v[80:81], v[18:19], v[74:75] op_sel:[0,1]
	v_pk_mul_f32 v[82:83], v[0:1], v[74:75] op_sel:[0,1]
	v_pk_mul_f32 v[84:85], v[2:3], v[74:75] op_sel:[0,1]
	s_and_b64 vcc, exec, s[18:19]
	s_mov_b64 s[18:19], -1
	s_cbranch_vccnz .LBB0_1219
	s_and_b64 vcc, exec, s[16:17]
	s_mov_b64 s[16:17], -1
	s_cbranch_vccnz .LBB0_1216
	v_pk_mul_f32 v[86:87], v[64:65], v[64:65]
	v_pk_mul_f32 v[90:91], v[66:67], v[66:67]
	v_add_f32_e32 v77, v86, v87
	v_add_f32_e32 v77, v90, v77
	v_pk_mul_f32 v[92:93], v[68:69], v[68:69]
	v_add_f32_e32 v77, v91, v77
	v_add_f32_e32 v77, v92, v77
	v_pk_mul_f32 v[100:101], v[70:71], v[70:71]
	v_add_f32_e32 v77, v93, v77
	v_add_f32_e32 v77, v100, v77
	v_pk_mul_f32 v[102:103], v[78:79], v[78:79]
	v_add_f32_e32 v77, v101, v77
	v_add_f32_e32 v77, v102, v77
	v_pk_mul_f32 v[104:105], v[80:81], v[80:81]
	v_add_f32_e32 v77, v103, v77
	v_add_f32_e32 v77, v104, v77
	v_pk_mul_f32 v[106:107], v[82:83], v[82:83]
	v_add_f32_e32 v77, v105, v77
	v_add_f32_e32 v77, v106, v77
	v_pk_mul_f32 v[108:109], v[84:85], v[84:85]
	v_add_f32_e32 v77, v107, v77
	v_add_f32_e32 v77, v108, v77
	v_add_f32_e32 v77, v109, v77
	v_mov_b32_e32 v86, v77
	s_nop 1
	v_permlane16_swap_b32_e32 v77, v86
	s_and_b64 s[14:15], s[14:15], exec
	v_readlane_b32 s14, v252, 21
	v_readlane_b32 s15, v252, 22
	s_load_dwordx4 s[16:19], s[14:15], 0xe0
	s_waitcnt lgkmcnt(0)
	v_add_f32_e32 v77, v77, v86
	v_mov_b32_e32 v86, v77
	s_nop 1
	v_permlane32_swap_b32_e32 v77, v86
	v_ashrrev_i32_e32 v94, 13, v99
	v_and_b32_e32 v95, 0x1fff, v99
	s_cselect_b32 s14, s17, s19
	s_cselect_b32 s15, s16, s18
	s_waitcnt lgkmcnt(0)
	v_add_f32_e32 v77, v77, v86
	v_fmamk_f32 v77, v77, 0x3c800000, v206
	v_cmp_gt_f32_e32 vcc, s21, v77
	v_mul_f32_e32 v86, 0x4b800000, v77
	v_mov_b32_e32 v89, s14
	v_cndmask_b32_e32 v77, v77, v86, vcc
	v_rsq_f32_e32 v77, v77
	s_movk_i32 s14, 0x7f0
	v_mov_b32_e32 v88, s15
	v_lshl_add_u64 v[90:91], v[154:155], 2, v[88:89]
	v_mul_f32_e32 v86, 0x45800000, v77
	v_cndmask_b32_e32 v77, v77, v86, vcc
	v_mul_f32_e32 v86, v214, v77
	v_lshrrev_b32_e32 v77, 2, v99
	v_and_or_b32 v77, v77, s14, v213
	v_lshlrev_b32_e32 v77, 2, v77
	global_load_dwordx4 v[104:107], v77, s[54:55] offset:16
	global_load_dwordx4 v[100:103], v77, s[54:55]
	global_load_dwordx4 v[108:111], v77, s[50:51] offset:16
	global_load_dwordx4 v[112:115], v77, s[50:51]
	global_load_dwordx4 v[116:119], v[90:91], off offset:16
	global_load_dwordx4 v[120:123], v[90:91], off
	v_mul_f32_e32 v77, v64, v86
	s_movk_i32 s14, 0x3f0
	v_and_or_b32 v76, v76, s14, v213
	v_lshlrev_b32_e32 v76, 2, v76
	v_readlane_b32 s14, v252, 4
	s_waitcnt vmcnt(0)
	v_mul_f32_e32 v77, v120, v77
	v_mov_b32_e32 v87, v77
	v_mov_b32_e32 v88, v77
	s_nop 1
	v_permlane32_swap_b32_e32 v87, v88
	v_cndmask_b32_e64 v87, v87, v88, s[12:13]
	v_mul_f32_e32 v87, v112, v87
	v_cndmask_b32_e64 v97, v87, -v87, s[10:11]
	v_fmac_f32_e32 v97, v100, v77
	v_mul_f32_e32 v77, v65, v86
	v_mul_f32_e32 v77, v121, v77
	v_mov_b32_e32 v87, v77
	v_mov_b32_e32 v88, v77
	s_nop 1
	v_permlane32_swap_b32_e32 v87, v88
	v_cndmask_b32_e64 v87, v87, v88, s[12:13]
	v_mul_f32_e32 v87, v113, v87
	v_cndmask_b32_e64 v100, v87, -v87, s[10:11]
	v_fmac_f32_e32 v100, v101, v77
	v_mul_f32_e32 v77, v66, v86
	v_mul_f32_e32 v77, v122, v77
	v_mov_b32_e32 v87, v77
	v_mov_b32_e32 v88, v77
	s_nop 1
	v_permlane32_swap_b32_e32 v87, v88
	v_cndmask_b32_e64 v87, v87, v88, s[12:13]
	v_mul_f32_e32 v87, v114, v87
	v_cndmask_b32_e64 v101, v87, -v87, s[10:11]
	v_fmac_f32_e32 v101, v102, v77
	v_mul_f32_e32 v77, v67, v86
	v_mul_f32_e32 v77, v77, v123
	v_mov_b32_e32 v87, v77
	v_mov_b32_e32 v88, v77
	s_nop 1
	v_permlane32_swap_b32_e32 v87, v88
	v_cndmask_b32_e64 v87, v87, v88, s[12:13]
	v_mul_f32_e32 v87, v115, v87
	v_cndmask_b32_e64 v102, v87, -v87, s[10:11]
	v_fmac_f32_e32 v102, v103, v77
	v_mul_f32_e32 v77, v68, v86
	v_mul_f32_e32 v77, v77, v116
	v_mov_b32_e32 v87, v77
	v_mov_b32_e32 v88, v77
	s_nop 1
	v_permlane32_swap_b32_e32 v87, v88
	v_cndmask_b32_e64 v87, v87, v88, s[12:13]
	v_mul_f32_e32 v87, v108, v87
	v_cndmask_b32_e64 v103, v87, -v87, s[10:11]
	v_fmac_f32_e32 v103, v104, v77
	v_mul_f32_e32 v77, v69, v86
	v_mul_f32_e32 v77, v77, v117
	v_mov_b32_e32 v87, v77
	v_mov_b32_e32 v88, v77
	s_nop 1
	v_permlane32_swap_b32_e32 v87, v88
	v_cndmask_b32_e64 v87, v87, v88, s[12:13]
	v_mul_f32_e32 v87, v109, v87
	v_pk_mul_f32 v[88:89], v[70:71], v[86:87] op_sel_hi:[1,0]
	v_cndmask_b32_e64 v104, v87, -v87, s[10:11]
	v_pk_mul_f32 v[88:89], v[88:89], v[118:119]
	v_fmac_f32_e32 v104, v105, v77
	v_mov_b32_e32 v77, v88
	v_mov_b32_e32 v87, v88
	v_mov_b32_e32 v92, v89
	v_mov_b32_e32 v93, v89
	v_permlane32_swap_b32_e32 v77, v87
	s_nop 0
	v_permlane32_swap_b32_e32 v92, v93
	v_cndmask_b32_e64 v93, v92, v93, s[12:13]
	v_cndmask_b32_e64 v92, v77, v87, s[12:13]
	v_pk_mul_f32 v[92:93], v[110:111], v[92:93]
	s_nop 0
	v_cndmask_b32_e64 v93, v93, -v93, s[10:11]
	v_cndmask_b32_e64 v92, v92, -v92, s[10:11]
	v_pk_fma_f32 v[88:89], v[106:107], v[88:89], v[92:93]
	global_load_dwordx4 v[106:109], v76, s[54:55] offset:16
	global_load_dwordx4 v[110:113], v76, s[54:55]
	global_load_dwordx4 v[114:117], v76, s[50:51] offset:16
	global_load_dwordx4 v[118:121], v76, s[50:51]
	global_load_dwordx4 v[122:125], v[90:91], off offset:144
	s_nop 0
	global_load_dwordx4 v[90:93], v[90:91], off offset:128
	v_pk_mul_f32 v[76:77], v[78:79], v[86:87] op_sel_hi:[1,0]
	s_waitcnt vmcnt(0)
; __device__ __forceinline__ float grp_sum(float v) { v += __shfl_xor(v, 16); v += __shfl_xor(v, 32); return v; }
; __device__ __forceinline__ void st8_bf16(bf16_t* dst, const float (&v)[8]) { u32x4 w; w.x = pk2(v[0], v[1]); w.y = pk2(v[2], v[3]); w.z = pk2(v[4], v[5]); w.w = pk2(v[6], v[7]); *(u32x4*)dst = w; }
;   __device__ __forceinline__ void operator()(const pg8::f32x4 (&acc)[2][2][4][2], const pg8::Unit& u, int wr, int wc, int fr, int fq0) const {
;     ...
;           for (int bj = 0; bj < 2; ++bj) {
;             const unsigned ao = (unsigned)(bj == 0 ? (pos >> 6) : (pos & 63)) * 16 + 8 * (fq & 1);
;             const f32x4 c0 = *(const f32x4*)(cos32 + ao), c1 = *(const f32x4*)(cos32 + ao + 4), s0 = *(const f32x4*)(sin32 + ao), s1 = *(const f32x4*)(sin32 + ao + 4);
; #pragma unroll
;             for (int e = 0; e < 8; ++e) {
;               const float own = v[bj][e] * rn * gn[32 * bj + 8 * fq + e];
;               const float oth = lane32_partner(own, lane);
;               const float cc = e < 4 ? c0[e & 3] : c1[e & 3], sn = e < 4 ? s0[e & 3] : s1[e & 3];
;               v[bj][e] = (fq < 2) ? own * cc - oth * sn : oth * sn + own * cc;
;               kk += v[bj][e] * v[bj][e];
;             }
;           }
;           bf16_t* dst = isq ? qd + ((unsigned)(bb * 8 + (gi - 7)) * S + pos) * 64 + 8 * fq : kd + ((unsigned)(bb * 2 + (gi - 15)) * S + pos) * 64 + 8 * fq;
;           st8_bf16(dst, v[0]); st8_bf16(dst + 32, v[1]);
;           if (!isq) kmx_run = fmaxf(kmx_run, grp_sum(kk));
	v_pk_mul_f32 v[76:77], v[76:77], v[90:91]
	s_nop 0
	v_mov_b32_e32 v87, v76
	v_mov_b32_e32 v90, v76
	v_mov_b32_e32 v91, v77
	v_mov_b32_e32 v105, v77
	v_permlane32_swap_b32_e32 v87, v90
	s_nop 0
	v_permlane32_swap_b32_e32 v91, v105
	v_cndmask_b32_e64 v91, v91, v105, s[12:13]
	v_cndmask_b32_e64 v90, v87, v90, s[12:13]
	v_pk_mul_f32 v[90:91], v[118:119], v[90:91]
	s_nop 0
	v_cndmask_b32_e64 v91, v91, -v91, s[10:11]
	v_cndmask_b32_e64 v90, v90, -v90, s[10:11]
	v_pk_fma_f32 v[76:77], v[110:111], v[76:77], v[90:91]
	v_pk_mul_f32 v[90:91], v[80:81], v[86:87] op_sel_hi:[1,0]
	s_nop 0
	v_pk_mul_f32 v[90:91], v[90:91], v[92:93]
	s_nop 0
	v_mov_b32_e32 v87, v90
	v_mov_b32_e32 v92, v90
	v_mov_b32_e32 v93, v91
	v_mov_b32_e32 v105, v91
	v_permlane32_swap_b32_e32 v87, v92
	s_nop 0
	v_permlane32_swap_b32_e32 v93, v105
	v_cndmask_b32_e64 v93, v93, v105, s[12:13]
	v_cndmask_b32_e64 v92, v87, v92, s[12:13]
	v_pk_mul_f32 v[92:93], v[120:121], v[92:93]
	s_nop 0
	v_cndmask_b32_e64 v93, v93, -v93, s[10:11]
	v_cndmask_b32_e64 v92, v92, -v92, s[10:11]
	v_pk_fma_f32 v[90:91], v[112:113], v[90:91], v[92:93]
	v_pk_mul_f32 v[92:93], v[82:83], v[86:87] op_sel_hi:[1,0]
	s_nop 0
	v_pk_mul_f32 v[92:93], v[92:93], v[122:123]
	s_nop 0
	v_mov_b32_e32 v87, v92
	v_mov_b32_e32 v105, v92
	v_mov_b32_e32 v110, v93
	v_mov_b32_e32 v111, v93
	v_permlane32_swap_b32_e32 v87, v105
	s_nop 0
	v_permlane32_swap_b32_e32 v110, v111
	v_cndmask_b32_e64 v111, v110, v111, s[12:13]
	v_cndmask_b32_e64 v110, v87, v105, s[12:13]
	v_pk_mul_f32 v[110:111], v[114:115], v[110:111]
	v_pk_mul_f32 v[86:87], v[84:85], v[86:87] op_sel_hi:[1,0]
	v_cndmask_b32_e64 v111, v111, -v111, s[10:11]
	v_cndmask_b32_e64 v110, v110, -v110, s[10:11]
	v_pk_mul_f32 v[86:87], v[86:87], v[124:125]
	v_pk_fma_f32 v[92:93], v[106:107], v[92:93], v[110:111]
	v_mov_b32_e32 v105, v86
	v_mov_b32_e32 v106, v86
	v_mov_b32_e32 v107, v87
	v_mov_b32_e32 v110, v87
	v_permlane32_swap_b32_e32 v105, v106
	s_nop 0
	v_permlane32_swap_b32_e32 v107, v110
	v_cndmask_b32_e64 v107, v107, v110, s[12:13]
	v_cndmask_b32_e64 v106, v105, v106, s[12:13]
	v_pk_mul_f32 v[106:107], v[116:117], v[106:107]
	v_readlane_b32 s12, v252, 16
	v_readlane_b32 s13, v252, 6
	v_cndmask_b32_e64 v107, v107, -v107, s[10:11]
	v_cndmask_b32_e64 v106, v106, -v106, s[10:11]
	s_cselect_b32 s10, s62, s24
	s_cselect_b32 s11, 22, 20
	s_cselect_b32 s12, s12, s13
	v_readlane_b32 s13, v252, 14
	s_cselect_b32 s13, s13, s14
	v_or_b32_e32 v95, s10, v95
	v_lshlrev_b32_e32 v94, s11, v94
	v_pk_fma_f32 v[86:87], v[108:109], v[86:87], v[106:107]
	v_mov_b32_e32 v106, s13
	v_mov_b32_e32 v107, s12
	v_lshl_add_u32 v144, v95, 6, v94
	v_lshl_add_u64 v[94:95], v[144:145], 1, v[106:107]
	v_lshl_add_u64 v[94:95], v[154:155], 1, v[94:95]
	v_cvt_pk_bf16_f32 v106, v97, v100
	v_cvt_pk_bf16_f32 v107, v101, v102
	v_cvt_pk_bf16_f32 v108, v103, v104
	v_cvt_pk_bf16_f32 v109, v88, v89
	global_store_dwordx4 v[94:95], v[106:109], off
	s_andn2_b64 vcc, exec, s[86:87]
	s_nop 0
	v_cvt_pk_bf16_f32 v106, v76, v77
	v_cvt_pk_bf16_f32 v107, v90, v91
	v_cvt_pk_bf16_f32 v108, v92, v93
	v_cvt_pk_bf16_f32 v109, v86, v87
	global_store_dwordx4 v[94:95], v[106:109], off offset:64
	v_mov_b32_e32 v94, v96
	s_cbranch_vccnz .LBB0_1215
	v_mul_f32_e32 v94, v100, v100
	v_fmac_f32_e32 v94, v97, v97
	v_fmac_f32_e32 v94, v101, v101
	v_fmac_f32_e32 v94, v102, v102
	v_fmac_f32_e32 v94, v103, v103
	v_fmac_f32_e32 v94, v104, v104
	v_pk_mul_f32 v[88:89], v[88:89], v[88:89]
	v_pk_mul_f32 v[76:77], v[76:77], v[76:77]
	v_add_f32_e32 v88, v94, v88
	v_add_f32_e32 v88, v88, v89
	v_add_f32_e32 v76, v88, v76
	v_add_f32_e32 v88, v76, v77
	v_pk_mul_f32 v[76:77], v[90:91], v[90:91]
	s_nop 0
	v_add_f32_e32 v76, v88, v76
	v_add_f32_e32 v88, v76, v77
	v_pk_mul_f32 v[76:77], v[92:93], v[92:93]
	s_nop 0
	v_add_f32_e32 v76, v88, v76
	v_add_f32_e32 v88, v76, v77
	v_pk_mul_f32 v[76:77], v[86:87], v[86:87]
	s_nop 0
	v_add_f32_e32 v76, v88, v76
	v_add_f32_e32 v76, v76, v77
	v_mov_b32_e32 v77, v76
	s_nop 1
	v_permlane16_swap_b32_e32 v76, v77
	s_waitcnt lgkmcnt(0)
	v_add_f32_e32 v76, v76, v77
	v_mov_b32_e32 v77, v76
	s_nop 1
	v_permlane32_swap_b32_e32 v76, v77
	s_waitcnt lgkmcnt(0)
	v_add_f32_e32 v76, v76, v77
	v_max_f32_e32 v77, v96, v96
	v_max_f32_e32 v94, v77, v76

; __device__ __forceinline__ float grp_sum(float v) { v += __shfl_xor(v, 16); v += __shfl_xor(v, 32); return v; }
;   __device__ __forceinline__ void operator()(const pg8::f32x4 (&acc)[2][2][4][2], const pg8::Unit& u, int wr, int wc, int fr, int fq0) const {
;     ...
;         if (gi < 6) {
;           float ss = 0.f;
; #pragma unroll
;           for (int bj = 0; bj < 2; ++bj)
; #pragma unroll
;             for (int e = 0; e < 8; ++e) ss += v[bj][e] * v[bj][e];
;           ss = grp_sum(ss);
;           if (fq == 0) ssq2[(unsigned)tok * 8 + gi] = ss;
.LBB0_1219:
	s_andn2_b64 vcc, exec, s[18:19]
	s_cbranch_vccnz .LBB0_1223
	v_pk_mul_f32 v[76:77], v[64:65], v[64:65]
	v_pk_mul_f32 v[86:87], v[66:67], v[66:67]
	v_add_f32_e32 v76, v76, v77
	v_add_f32_e32 v76, v86, v76
	v_pk_mul_f32 v[88:89], v[68:69], v[68:69]
	v_add_f32_e32 v76, v87, v76
	v_add_f32_e32 v76, v88, v76
	v_pk_mul_f32 v[90:91], v[70:71], v[70:71]
	v_add_f32_e32 v76, v89, v76
	v_add_f32_e32 v76, v90, v76
	v_pk_mul_f32 v[92:93], v[78:79], v[78:79]
	v_add_f32_e32 v76, v91, v76
	v_add_f32_e32 v76, v92, v76
	v_pk_mul_f32 v[94:95], v[80:81], v[80:81]
	v_add_f32_e32 v76, v93, v76
	v_add_f32_e32 v76, v94, v76
	v_pk_mul_f32 v[100:101], v[82:83], v[82:83]
	v_add_f32_e32 v76, v95, v76
	v_add_f32_e32 v76, v100, v76
	v_pk_mul_f32 v[102:103], v[84:85], v[84:85]
	v_add_f32_e32 v76, v101, v76
	v_add_f32_e32 v76, v102, v76
	v_add_f32_e32 v76, v103, v76
	v_mov_b32_e32 v77, v76
	s_nop 1
	v_permlane16_swap_b32_e32 v76, v77
	s_waitcnt lgkmcnt(0)
	v_add_f32_e32 v76, v76, v77
	ds_bpermute_b32 v77, v212, v76
	s_and_saveexec_b64 s[10:11], s[8:9]
	s_cbranch_execz .LBB0_1222
	v_lshl_add_u32 v144, v99, 3, s68
	s_waitcnt lgkmcnt(0)
	v_add_f32_e32 v86, v76, v77
	v_lshl_add_u64 v[76:77], v[144:145], 2, s[52:53]
	global_store_dword v[76:77], v86, off
